# v32_noprio
# speedup vs baseline: 1.0034x; 1.0034x over previous
; #define PG8_STAGE(bufoff, gbase, voff) do { _Pragma("unroll") for (int _i = 0; _i < 2; ++_i) \
;         __builtin_amdgcn_global_load_lds((const unsigned*)((const char*)(gbase) + (voff)[_i]), (PG8_LAS unsigned*)(lds + (bufoff) + ldsw + _i * 8192), 16, 0, 0); } while (0)
; #define PG8_LDA(dst, b, h) do { _Pragma("unroll") for (int m = 0; m < 4; ++m) _Pragma("unroll") for (int k = 0; k < 2; ++k) dst[m][k] = *(const PG8_LAS bf16x8*)(lds + PG8_SA(b, h) + aoff + m * 2048 + k * 1024); } while (0)
; #define PG8_LDB(dst, b, h) do { _Pragma("unroll") for (int n = 0; n < 2; ++n) _Pragma("unroll") for (int k = 0; k < 2; ++k) dst[n][k] = *(const PG8_LAS bf16x8*)(lds + PG8_SB(b, h) + boff + n * 2048 + k * 1024); } while (0)
; #define PG8_MMA(ai, bj, At, Bt) do { __builtin_amdgcn_s_setprio(1); _Pragma("unroll") for (int m = 0; m < 4; ++m) _Pragma("unroll") for (int n = 0; n < 2; ++n) _Pragma("unroll") for (int k = 0; k < 2; ++k) \
;         acc[ai][bj][m][n] = __builtin_amdgcn_mfma_f32_16x16x32_bf16(Bt[n][k], At[m][k], acc[ai][bj][m][n], 0, 0, 0); __builtin_amdgcn_s_setprio(0); } while (0)
; #define PG8_WAIT_V(n) asm volatile("s_waitcnt vmcnt(" #n ")" ::: "memory")
; #define PG8_WAIT_L(n) asm volatile("s_waitcnt lgkmcnt(" #n ")" ::: "memory")
; #define PG8_BAR __builtin_amdgcn_s_barrier()
; #define PG8_SCHED __builtin_amdgcn_sched_barrier(0)
; template <class Epi, class Sched, bool ALIGN_EPI = false, bool SP2 = false>
; __device__ __forceinline__ void gemm_phase(PG8_LAS unsigned char* lds, const Gemm g, const Sched& S, const Epi& E) {
;     ...
;             PG8_LDB(B0, 0, 0); PG8_LDB(B1, 0, 1); PG8_SCHED; PG8_LDA(At, 0, 0); PG8_STAGE(PG8_SA(1, 1), a1 + hstep, voffA);
;             PG8_WAIT_V(8); PG8_WAIT_L(0); PG8_BAR; PG8_MMA(0, 0, At, B0); PG8_MMA(0, 1, At, B1); PG8_BAR; PG8_SCHED;
;             PG8_LDA(At, 0, 1); PG8_STAGE(PG8_SB(0, 0), b2, voffB); PG8_STAGE(PG8_SB(0, 1), b2 + hstep, voffB); PG8_STAGE(PG8_SA(0, 0), a2, voffA);
;             PG8_WAIT_V(8); PG8_WAIT_L(0); PG8_BAR; PG8_MMA(1, 0, At, B0); PG8_MMA(1, 1, At, B1); PG8_BAR; PG8_SCHED;
.LBB0_169:
	ds_read_b128 v[152:155], v149
	ds_read_b128 v[156:159], v149 offset:1024
	ds_read_b128 v[160:163], v149 offset:2048
	ds_read_b128 v[164:167], v149 offset:3072
	ds_read_b128 v[168:171], v150
	ds_read_b128 v[172:175], v150 offset:1024
	ds_read_b128 v[176:179], v150 offset:2048
	ds_read_b128 v[180:183], v150 offset:3072
	s_add_u32 s40, s38, 0xfff80080
	s_addc_u32 s41, s39, -1
	s_cmp_eq_u32 s61, 28
	s_cselect_b32 s43, s29, s41
	s_cselect_b32 s42, s57, s40
	s_cselect_b32 s41, s27, s60
	s_cselect_b32 s40, s58, s59
	s_add_i32 m0, s37, 0xc000
	ds_read_b128 v[184:187], v151
	ds_read_b128 v[188:191], v151 offset:1024
	ds_read_b128 v[192:195], v151 offset:2048
	ds_read_b128 v[196:199], v151 offset:3072
	ds_read_b128 v[200:203], v151 offset:4096
	ds_read_b128 v[204:207], v151 offset:5120
	ds_read_b128 v[208:211], v151 offset:6144
	ds_read_b128 v[214:217], v151 offset:7168
	global_load_lds_dwordx4 v136, s[38:39]
	s_add_i32 m0, s37, 0xe000
	s_nop 0
	global_load_lds_dwordx4 v138, s[38:39]
	s_waitcnt vmcnt(8)
	s_waitcnt lgkmcnt(0)
	s_barrier
	s_waitcnt lgkmcnt(0)
	v_mfma_f32_16x16x32_bf16 v[124:127], v[152:155], v[184:187], v[124:127]
	v_mfma_f32_16x16x32_bf16 v[120:123], v[160:163], v[184:187], v[120:123]
	v_mfma_f32_16x16x32_bf16 v[108:111], v[152:155], v[192:195], v[108:111]
	v_mfma_f32_16x16x32_bf16 v[104:107], v[160:163], v[192:195], v[104:107]
	v_mfma_f32_16x16x32_bf16 v[92:95], v[152:155], v[200:203], v[92:95]
	v_mfma_f32_16x16x32_bf16 v[88:91], v[160:163], v[200:203], v[88:91]
	v_mfma_f32_16x16x32_bf16 v[76:79], v[152:155], v[208:211], v[76:79]
	v_mfma_f32_16x16x32_bf16 v[72:75], v[160:163], v[208:211], v[72:75]
	v_mfma_f32_16x16x32_bf16 v[124:127], v[156:159], v[188:191], v[124:127]
	v_mfma_f32_16x16x32_bf16 v[120:123], v[164:167], v[188:191], v[120:123]
	v_mfma_f32_16x16x32_bf16 v[108:111], v[156:159], v[196:199], v[108:111]
	v_mfma_f32_16x16x32_bf16 v[104:107], v[164:167], v[196:199], v[104:107]
	v_mfma_f32_16x16x32_bf16 v[92:95], v[156:159], v[204:207], v[92:95]
	v_mfma_f32_16x16x32_bf16 v[88:91], v[164:167], v[204:207], v[88:91]
	v_mfma_f32_16x16x32_bf16 v[76:79], v[156:159], v[214:217], v[76:79]
	v_mfma_f32_16x16x32_bf16 v[72:75], v[164:167], v[214:217], v[72:75]
	v_mfma_f32_16x16x32_bf16 v[116:119], v[168:171], v[184:187], v[116:119]
	v_mfma_f32_16x16x32_bf16 v[112:115], v[176:179], v[184:187], v[112:115]
	v_mfma_f32_16x16x32_bf16 v[100:103], v[168:171], v[192:195], v[100:103]
	v_mfma_f32_16x16x32_bf16 v[96:99], v[176:179], v[192:195], v[96:99]
	v_mfma_f32_16x16x32_bf16 v[84:87], v[168:171], v[200:203], v[84:87]
	v_mfma_f32_16x16x32_bf16 v[80:83], v[176:179], v[200:203], v[80:83]
	v_mfma_f32_16x16x32_bf16 v[68:71], v[168:171], v[208:211], v[68:71]
	v_mfma_f32_16x16x32_bf16 v[64:67], v[176:179], v[208:211], v[64:67]
	v_mfma_f32_16x16x32_bf16 v[116:119], v[172:175], v[188:191], v[116:119]
	v_mfma_f32_16x16x32_bf16 v[112:115], v[180:183], v[188:191], v[112:115]
	v_mfma_f32_16x16x32_bf16 v[100:103], v[172:175], v[196:199], v[100:103]
	v_mfma_f32_16x16x32_bf16 v[96:99], v[180:183], v[196:199], v[96:99]
	v_mfma_f32_16x16x32_bf16 v[84:87], v[172:175], v[204:207], v[84:87]
	v_mfma_f32_16x16x32_bf16 v[80:83], v[180:183], v[204:207], v[80:83]
	v_mfma_f32_16x16x32_bf16 v[68:71], v[172:175], v[214:217], v[68:71]
	v_mfma_f32_16x16x32_bf16 v[64:67], v[180:183], v[214:217], v[64:67]
	s_barrier
	s_add_i32 s62, s53, s24
	s_mov_b32 m0, s62
	ds_read_b128 v[184:187], v151 offset:16384
	ds_read_b128 v[188:191], v151 offset:17408
	ds_read_b128 v[192:195], v151 offset:18432
	ds_read_b128 v[196:199], v151 offset:19456
	ds_read_b128 v[200:203], v151 offset:20480
	ds_read_b128 v[204:207], v151 offset:21504
	ds_read_b128 v[208:211], v151 offset:22528
	ds_read_b128 v[214:217], v151 offset:23552
	global_load_lds_dwordx4 v132, s[40:41]
	s_add_i32 m0, s62, 0x2000
	s_add_u32 s62, s40, 0x80000
	s_addc_u32 s63, s41, 0
	s_add_i32 s64, s54, s24
	global_load_lds_dwordx4 v128, s[40:41]
	s_mov_b32 m0, s64
	s_nop 0
	global_load_lds_dwordx4 v132, s[62:63]
	s_add_i32 m0, s64, 0x2000
	s_nop 0
	global_load_lds_dwordx4 v128, s[62:63]
	s_mov_b32 m0, s37
	s_nop 0
	global_load_lds_dwordx4 v134, s[42:43]
	s_mov_b32 m0, s45
	s_nop 0
	global_load_lds_dwordx4 v130, s[42:43]
	s_waitcnt vmcnt(8)
	s_waitcnt lgkmcnt(0)
	s_barrier
	s_waitcnt lgkmcnt(0)
	v_mfma_f32_16x16x32_bf16 v[60:63], v[152:155], v[184:187], v[60:63]
	v_mfma_f32_16x16x32_bf16 v[56:59], v[160:163], v[184:187], v[56:59]
	v_mfma_f32_16x16x32_bf16 v[44:47], v[152:155], v[192:195], v[44:47]
	v_mfma_f32_16x16x32_bf16 v[40:43], v[160:163], v[192:195], v[40:43]
	v_mfma_f32_16x16x32_bf16 v[28:31], v[152:155], v[200:203], v[28:31]
	v_mfma_f32_16x16x32_bf16 v[24:27], v[160:163], v[200:203], v[24:27]
	v_mfma_f32_16x16x32_bf16 v[12:15], v[152:155], v[208:211], v[12:15]
	v_mfma_f32_16x16x32_bf16 v[8:11], v[160:163], v[208:211], v[8:11]
	v_mfma_f32_16x16x32_bf16 v[60:63], v[156:159], v[188:191], v[60:63]
	v_mfma_f32_16x16x32_bf16 v[56:59], v[164:167], v[188:191], v[56:59]
	v_mfma_f32_16x16x32_bf16 v[44:47], v[156:159], v[196:199], v[44:47]
	v_mfma_f32_16x16x32_bf16 v[40:43], v[164:167], v[196:199], v[40:43]
	v_mfma_f32_16x16x32_bf16 v[28:31], v[156:159], v[204:207], v[28:31]
	v_mfma_f32_16x16x32_bf16 v[24:27], v[164:167], v[204:207], v[24:27]
	v_mfma_f32_16x16x32_bf16 v[12:15], v[156:159], v[214:217], v[12:15]
	v_mfma_f32_16x16x32_bf16 v[8:11], v[164:167], v[214:217], v[8:11]
	v_mfma_f32_16x16x32_bf16 v[52:55], v[168:171], v[184:187], v[52:55]
	v_mfma_f32_16x16x32_bf16 v[48:51], v[176:179], v[184:187], v[48:51]
	v_mfma_f32_16x16x32_bf16 v[36:39], v[168:171], v[192:195], v[36:39]
	v_mfma_f32_16x16x32_bf16 v[32:35], v[176:179], v[192:195], v[32:35]
	v_mfma_f32_16x16x32_bf16 v[20:23], v[168:171], v[200:203], v[20:23]
	v_mfma_f32_16x16x32_bf16 v[16:19], v[176:179], v[200:203], v[16:19]
	v_mfma_f32_16x16x32_bf16 v[4:7], v[168:171], v[208:211], v[4:7]
	v_mfma_f32_16x16x32_bf16 v[0:3], v[176:179], v[208:211], v[0:3]
	v_mfma_f32_16x16x32_bf16 v[52:55], v[172:175], v[188:191], v[52:55]
	v_mfma_f32_16x16x32_bf16 v[48:51], v[180:183], v[188:191], v[48:51]
	v_mfma_f32_16x16x32_bf16 v[36:39], v[172:175], v[196:199], v[36:39]
	v_mfma_f32_16x16x32_bf16 v[32:35], v[180:183], v[196:199], v[32:35]
	v_mfma_f32_16x16x32_bf16 v[20:23], v[172:175], v[204:207], v[20:23]
	v_mfma_f32_16x16x32_bf16 v[16:19], v[180:183], v[204:207], v[16:19]
	v_mfma_f32_16x16x32_bf16 v[4:7], v[172:175], v[214:217], v[4:7]
	v_mfma_f32_16x16x32_bf16 v[0:3], v[180:183], v[214:217], v[0:3]
	s_barrier
; #define PG8_STAGE(bufoff, gbase, voff) do { _Pragma("unroll") for (int _i = 0; _i < 2; ++_i) \
;         __builtin_amdgcn_global_load_lds((const unsigned*)((const char*)(gbase) + (voff)[_i]), (PG8_LAS unsigned*)(lds + (bufoff) + ldsw + _i * 8192), 16, 0, 0); } while (0)
; #define PG8_LDA(dst, b, h) do { _Pragma("unroll") for (int m = 0; m < 4; ++m) _Pragma("unroll") for (int k = 0; k < 2; ++k) dst[m][k] = *(const PG8_LAS bf16x8*)(lds + PG8_SA(b, h) + aoff + m * 2048 + k * 1024); } while (0)
; #define PG8_LDB(dst, b, h) do { _Pragma("unroll") for (int n = 0; n < 2; ++n) _Pragma("unroll") for (int k = 0; k < 2; ++k) dst[n][k] = *(const PG8_LAS bf16x8*)(lds + PG8_SB(b, h) + boff + n * 2048 + k * 1024); } while (0)
; #define PG8_MMA(ai, bj, At, Bt) do { __builtin_amdgcn_s_setprio(1); _Pragma("unroll") for (int m = 0; m < 4; ++m) _Pragma("unroll") for (int n = 0; n < 2; ++n) _Pragma("unroll") for (int k = 0; k < 2; ++k) \
;         acc[ai][bj][m][n] = __builtin_amdgcn_mfma_f32_16x16x32_bf16(Bt[n][k], At[m][k], acc[ai][bj][m][n], 0, 0, 0); __builtin_amdgcn_s_setprio(0); } while (0)
; #define PG8_WAIT_V(n) asm volatile("s_waitcnt vmcnt(" #n ")" ::: "memory")
; #define PG8_WAIT_L(n) asm volatile("s_waitcnt lgkmcnt(" #n ")" ::: "memory")
; #define PG8_BAR __builtin_amdgcn_s_barrier()
; #define PG8_SCHED __builtin_amdgcn_sched_barrier(0)
; template <class Epi, class Sched, bool ALIGN_EPI = false, bool SP2 = false>
; __device__ __forceinline__ void gemm_phase(PG8_LAS unsigned char* lds, const Gemm g, const Sched& S, const Epi& E) {
;     ...
;             PG8_LDB(B0, 1, 0); PG8_LDB(B1, 1, 1); PG8_SCHED; PG8_LDA(At, 1, 0); PG8_STAGE(PG8_SA(0, 1), a2 + hstep, voffA);
;             PG8_WAIT_V(8); PG8_WAIT_L(0); PG8_BAR; PG8_MMA(0, 0, At, B0); PG8_MMA(0, 1, At, B1); PG8_BAR; PG8_SCHED;
;             PG8_LDA(At, 1, 1); PG8_STAGE(PG8_SB(1, 0), b3, voffB); PG8_STAGE(PG8_SB(1, 1), b3 + hstep, voffB); PG8_STAGE(PG8_SA(1, 0), a3, voffA);
;             PG8_WAIT_V(8); PG8_WAIT_L(0); PG8_BAR; PG8_MMA(1, 0, At, B0); PG8_MMA(1, 1, At, B1); PG8_BAR; PG8_SCHED;
	s_add_i32 s62, 0, 0x18000
	s_add_i32 s63, 0, 0x1c000
	v_add_u32_e32 v164, s62, v147
	v_add_u32_e32 v180, s63, v147
	ds_read_b128 v[152:155], v164
	ds_read_b128 v[156:159], v164 offset:1024
	ds_read_b128 v[160:163], v164 offset:2048
	ds_read_b128 v[164:167], v164 offset:3072
	ds_read_b128 v[168:171], v180
	ds_read_b128 v[172:175], v180 offset:1024
	ds_read_b128 v[176:179], v180 offset:2048
	ds_read_b128 v[180:183], v180 offset:3072
	s_add_u32 s84, s42, 0x80
	s_addc_u32 s85, s43, 0
	s_add_u32 s42, s42, 0x80000
	s_addc_u32 s43, s43, 0
	s_mov_b32 m0, s46
	ds_read_b128 v[184:187], v151 offset:32768
	ds_read_b128 v[188:191], v151 offset:33792
	ds_read_b128 v[192:195], v151 offset:34816
	ds_read_b128 v[196:199], v151 offset:35840
	ds_read_b128 v[200:203], v151 offset:36864
	ds_read_b128 v[204:207], v151 offset:37888
	ds_read_b128 v[208:211], v151 offset:38912
	ds_read_b128 v[214:217], v151 offset:39936
	global_load_lds_dwordx4 v134, s[42:43]
	s_mov_b32 m0, s47
	s_nop 0
	global_load_lds_dwordx4 v130, s[42:43]
	s_waitcnt vmcnt(8)
	s_waitcnt lgkmcnt(0)
	s_barrier
	s_waitcnt lgkmcnt(0)
	v_mfma_f32_16x16x32_bf16 v[124:127], v[152:155], v[184:187], v[124:127]
	v_mfma_f32_16x16x32_bf16 v[120:123], v[160:163], v[184:187], v[120:123]
	v_mfma_f32_16x16x32_bf16 v[108:111], v[152:155], v[192:195], v[108:111]
	v_mfma_f32_16x16x32_bf16 v[104:107], v[160:163], v[192:195], v[104:107]
	v_mfma_f32_16x16x32_bf16 v[92:95], v[152:155], v[200:203], v[92:95]
	v_mfma_f32_16x16x32_bf16 v[88:91], v[160:163], v[200:203], v[88:91]
	v_mfma_f32_16x16x32_bf16 v[76:79], v[152:155], v[208:211], v[76:79]
	v_mfma_f32_16x16x32_bf16 v[72:75], v[160:163], v[208:211], v[72:75]
	v_mfma_f32_16x16x32_bf16 v[124:127], v[156:159], v[188:191], v[124:127]
	v_mfma_f32_16x16x32_bf16 v[120:123], v[164:167], v[188:191], v[120:123]
	v_mfma_f32_16x16x32_bf16 v[108:111], v[156:159], v[196:199], v[108:111]
	v_mfma_f32_16x16x32_bf16 v[104:107], v[164:167], v[196:199], v[104:107]
	v_mfma_f32_16x16x32_bf16 v[92:95], v[156:159], v[204:207], v[92:95]
	v_mfma_f32_16x16x32_bf16 v[88:91], v[164:167], v[204:207], v[88:91]
	v_mfma_f32_16x16x32_bf16 v[76:79], v[156:159], v[214:217], v[76:79]
	v_mfma_f32_16x16x32_bf16 v[72:75], v[164:167], v[214:217], v[72:75]
	v_mfma_f32_16x16x32_bf16 v[116:119], v[168:171], v[184:187], v[116:119]
	v_mfma_f32_16x16x32_bf16 v[112:115], v[176:179], v[184:187], v[112:115]
	v_mfma_f32_16x16x32_bf16 v[100:103], v[168:171], v[192:195], v[100:103]
	v_mfma_f32_16x16x32_bf16 v[96:99], v[176:179], v[192:195], v[96:99]
	v_mfma_f32_16x16x32_bf16 v[84:87], v[168:171], v[200:203], v[84:87]
	v_mfma_f32_16x16x32_bf16 v[80:83], v[176:179], v[200:203], v[80:83]
	v_mfma_f32_16x16x32_bf16 v[68:71], v[168:171], v[208:211], v[68:71]
	v_mfma_f32_16x16x32_bf16 v[64:67], v[176:179], v[208:211], v[64:67]
	v_mfma_f32_16x16x32_bf16 v[116:119], v[172:175], v[188:191], v[116:119]
	v_mfma_f32_16x16x32_bf16 v[112:115], v[180:183], v[188:191], v[112:115]
	v_mfma_f32_16x16x32_bf16 v[100:103], v[172:175], v[196:199], v[100:103]
	v_mfma_f32_16x16x32_bf16 v[96:99], v[180:183], v[196:199], v[96:99]
	v_mfma_f32_16x16x32_bf16 v[84:87], v[172:175], v[204:207], v[84:87]
	v_mfma_f32_16x16x32_bf16 v[80:83], v[180:183], v[204:207], v[80:83]
	v_mfma_f32_16x16x32_bf16 v[68:71], v[172:175], v[214:217], v[68:71]
	v_mfma_f32_16x16x32_bf16 v[64:67], v[180:183], v[214:217], v[64:67]
	s_barrier
	s_add_i32 s42, s62, s24
	s_add_u32 s86, s40, 0x80
	s_addc_u32 s87, s41, 0
	s_mov_b32 m0, s42
	ds_read_b128 v[184:187], v151 offset:49152
	ds_read_b128 v[188:191], v151 offset:50176
	ds_read_b128 v[192:195], v151 offset:51200
	ds_read_b128 v[196:199], v151 offset:52224
	ds_read_b128 v[200:203], v151 offset:53248
	ds_read_b128 v[204:207], v151 offset:54272
	ds_read_b128 v[208:211], v151 offset:55296
	ds_read_b128 v[214:217], v151 offset:56320
	global_load_lds_dwordx4 v132, s[86:87]
	s_add_i32 m0, s42, 0x2000
	s_add_u32 s40, s40, 0x80080
	s_addc_u32 s41, s41, 0
	s_add_i32 s42, s63, s24
	global_load_lds_dwordx4 v128, s[86:87]
	s_mov_b32 m0, s42
	s_nop 0
	global_load_lds_dwordx4 v132, s[40:41]
	s_add_i32 m0, s42, 0x2000
	s_nop 0
	global_load_lds_dwordx4 v128, s[40:41]
	s_mov_b32 m0, s49
	s_nop 0
	global_load_lds_dwordx4 v134, s[84:85]
	s_mov_b32 m0, s50
	s_nop 0
	global_load_lds_dwordx4 v130, s[84:85]
	s_waitcnt vmcnt(8)
	s_waitcnt lgkmcnt(0)
	s_barrier
	s_waitcnt lgkmcnt(0)
	v_mfma_f32_16x16x32_bf16 v[60:63], v[152:155], v[184:187], v[60:63]
	v_mfma_f32_16x16x32_bf16 v[56:59], v[160:163], v[184:187], v[56:59]
	v_mfma_f32_16x16x32_bf16 v[44:47], v[152:155], v[192:195], v[44:47]
	v_mfma_f32_16x16x32_bf16 v[40:43], v[160:163], v[192:195], v[40:43]
	v_mfma_f32_16x16x32_bf16 v[28:31], v[152:155], v[200:203], v[28:31]
	v_mfma_f32_16x16x32_bf16 v[24:27], v[160:163], v[200:203], v[24:27]
	v_mfma_f32_16x16x32_bf16 v[12:15], v[152:155], v[208:211], v[12:15]
	v_mfma_f32_16x16x32_bf16 v[8:11], v[160:163], v[208:211], v[8:11]
	v_mfma_f32_16x16x32_bf16 v[60:63], v[156:159], v[188:191], v[60:63]
	v_mfma_f32_16x16x32_bf16 v[56:59], v[164:167], v[188:191], v[56:59]
	v_mfma_f32_16x16x32_bf16 v[44:47], v[156:159], v[196:199], v[44:47]
	v_mfma_f32_16x16x32_bf16 v[40:43], v[164:167], v[196:199], v[40:43]
	v_mfma_f32_16x16x32_bf16 v[28:31], v[156:159], v[204:207], v[28:31]
	v_mfma_f32_16x16x32_bf16 v[24:27], v[164:167], v[204:207], v[24:27]
	v_mfma_f32_16x16x32_bf16 v[12:15], v[156:159], v[214:217], v[12:15]
	v_mfma_f32_16x16x32_bf16 v[8:11], v[164:167], v[214:217], v[8:11]
	v_mfma_f32_16x16x32_bf16 v[52:55], v[168:171], v[184:187], v[52:55]
	v_mfma_f32_16x16x32_bf16 v[48:51], v[176:179], v[184:187], v[48:51]
	v_mfma_f32_16x16x32_bf16 v[36:39], v[168:171], v[192:195], v[36:39]
	v_mfma_f32_16x16x32_bf16 v[32:35], v[176:179], v[192:195], v[32:35]
	v_mfma_f32_16x16x32_bf16 v[20:23], v[168:171], v[200:203], v[20:23]
	v_mfma_f32_16x16x32_bf16 v[16:19], v[176:179], v[200:203], v[16:19]
	v_mfma_f32_16x16x32_bf16 v[4:7], v[168:171], v[208:211], v[4:7]
	v_mfma_f32_16x16x32_bf16 v[0:3], v[176:179], v[208:211], v[0:3]
	v_mfma_f32_16x16x32_bf16 v[52:55], v[172:175], v[188:191], v[52:55]
	v_mfma_f32_16x16x32_bf16 v[48:51], v[180:183], v[188:191], v[48:51]
	v_mfma_f32_16x16x32_bf16 v[36:39], v[172:175], v[196:199], v[36:39]
	v_mfma_f32_16x16x32_bf16 v[32:35], v[180:183], v[196:199], v[32:35]
	v_mfma_f32_16x16x32_bf16 v[20:23], v[172:175], v[204:207], v[20:23]
	v_mfma_f32_16x16x32_bf16 v[16:19], v[180:183], v[204:207], v[16:19]
	v_mfma_f32_16x16x32_bf16 v[4:7], v[172:175], v[214:217], v[4:7]
	v_mfma_f32_16x16x32_bf16 v[0:3], v[180:183], v[214:217], v[0:3]
	s_barrier
; __device__ __forceinline__ float fsilu(float v) { return v * fsigmoid(v); }
; __device__ __forceinline__ u32x4 pack8(const f32x4 a, const f32x4 b) { u32x4 w; w.x = cvt_pk_bf16(a[0], a[1]); w.y = cvt_pk_bf16(a[2], a[3]); w.z = cvt_pk_bf16(b[0], b[1]); w.w = cvt_pk_bf16(b[2], b[3]); return w; }
;     __device__ __forceinline__ void operator()(const f32x4 (&acc)[2][2][4][2], const Unit& u, int wr, int wc, int fr, int fq) const {
;         const int row0 = u.pm * BM + wr * 64 + fr, col0 = u.pn * 128 + wc * 32 + 8 * fq;
; #pragma unroll
;         for (int ai = 0; ai < 2; ++ai)
; #pragma unroll
;             for (int m = 0; m < 4; ++m) {
;                 bf16_t* rowp = O + (size_t)(row0 + ai * HALF + m * 16) * ldc + col0;
;                 f32x4 h0, h1;
; #pragma unroll
;                 for (int j = 0; j < 4; ++j) { h0[j] = fsilu(acc[ai][0][m][0][j]) * acc[ai][1][m][0][j]; h1[j] = fsilu(acc[ai][0][m][1][j]) * acc[ai][1][m][1][j]; }
;                 *(u32x4*)rowp = pack8(h0, h1);
; template <class Epi, class Sched, bool ALIGN_EPI = false, bool SP2 = false>
; __device__ __forceinline__ void gemm_phase(PG8_LAS unsigned char* lds, const Gemm g, const Sched& S, const Epi& E) {
;     ...
;         for (int t = 0; t < nt; t += 2) {
;             const bool last = (t == nt - 2);
	s_add_i32 s61, s61, 2
	s_add_u32 s38, s38, 0x100
	s_addc_u32 s39, s39, 0
	s_add_u32 s59, s59, 0x100
	s_addc_u32 s60, s60, 0
	s_cmp_gt_u32 s61, 29
	s_cbranch_scc0 .LBB0_169
	v_mul_f32_e32 v153, 0xbfb8aa3b, v124
	v_mul_f32_e32 v158, 0xbfb8aa3b, v120
	v_exp_f32_e32 v153, v153
	v_exp_f32_e32 v159, v158
	v_mul_f32_e32 v158, 0xbfb8aa3b, v125
	v_exp_f32_e32 v160, v158
	v_add_f32_e32 v153, 1.0, v153
	v_rcp_f32_e32 v158, v153
	v_add_f32_e32 v153, 1.0, v159
	v_add_f32_e32 v159, 1.0, v160
	v_rcp_f32_e32 v159, v159
	v_mul_f32_e32 v160, 0xbfb8aa3b, v121
	v_exp_f32_e32 v161, v160
	v_rcp_f32_e32 v160, v153
	v_pk_mul_f32 v[124:125], v[124:125], v[158:159]
	v_mul_f32_e32 v153, 0xbfb8aa3b, v127
	v_pk_mul_f32 v[116:117], v[124:125], v[116:117]
	v_add_f32_e32 v124, 1.0, v161
	v_mul_f32_e32 v125, 0xbfb8aa3b, v122
	v_rcp_f32_e32 v161, v124
	v_mul_f32_e32 v124, 0xbfb8aa3b, v126
	v_exp_f32_e32 v125, v125
	v_exp_f32_e32 v124, v124
	v_exp_f32_e32 v153, v153
	v_mul_f32_e32 v158, 0xbfb8aa3b, v123
	v_exp_f32_e32 v159, v158
	v_add_f32_e32 v125, 1.0, v125
	v_add_f32_e32 v124, 1.0, v124
	v_rcp_f32_e32 v158, v125
	v_add_f32_e32 v125, 1.0, v153
	v_rcp_f32_e32 v124, v124
	v_rcp_f32_e32 v125, v125
	v_add_f32_e32 v153, 1.0, v159
	v_rcp_f32_e32 v159, v153
	v_pk_mul_f32 v[120:121], v[120:121], v[160:161]
	v_lshl_or_b32 v154, s56, 7, v148
	v_pk_mul_f32 v[120:121], v[120:121], v[112:113]
	v_pk_mul_f32 v[112:113], v[126:127], v[124:125]
	v_lshl_add_u32 v152, s36, 8, v146
	v_ashrrev_i32_e32 v155, 31, v154
	v_mov_b64_e32 v[144:145], s[10:11]
	v_pk_mul_f32 v[118:119], v[112:113], v[118:119]
	v_pk_mul_f32 v[112:113], v[122:123], v[158:159]
	v_mad_i64_i32 v[156:157], s[38:39], v152, s55, v[144:145]
	v_pk_mul_f32 v[122:123], v[112:113], v[114:115]
	v_lshlrev_b64 v[112:113], 1, v[154:155]
	v_lshl_add_u64 v[124:125], v[156:157], 0, v[112:113]
	v_cvt_pk_bf16_f32 v114, v116, v117
	v_cvt_pk_bf16_f32 v115, v118, v119
	v_cvt_pk_bf16_f32 v116, v120, v121
	v_cvt_pk_bf16_f32 v117, v122, v123
	global_store_dwordx4 v[124:125], v[114:117], off
	v_mul_f32_e32 v118, 0xbfb8aa3b, v109
	v_exp_f32_e32 v118, v118
	v_mul_f32_e32 v116, 0xbfb8aa3b, v108
	v_mul_f32_e32 v117, 0xbfb8aa3b, v104
	v_exp_f32_e32 v116, v116
	v_exp_f32_e32 v117, v117
	v_or_b32_e32 v114, 16, v152
	v_mad_i64_i32 v[114:115], s[38:39], v114, s55, v[144:145]
	v_add_f32_e32 v116, 1.0, v116
	v_add_f32_e32 v119, 1.0, v117
	v_add_f32_e32 v117, 1.0, v118
	v_rcp_f32_e32 v116, v116
	v_rcp_f32_e32 v117, v117
	v_mul_f32_e32 v118, 0xbfb8aa3b, v105
	v_exp_f32_e32 v120, v118
	v_rcp_f32_e32 v118, v119
	v_pk_mul_f32 v[108:109], v[108:109], v[116:117]
	v_mul_f32_e32 v116, 0xbfb8aa3b, v111
	v_pk_mul_f32 v[100:101], v[108:109], v[100:101]
	v_add_f32_e32 v108, 1.0, v120
	v_rcp_f32_e32 v119, v108
	v_mul_f32_e32 v109, 0xbfb8aa3b, v106
	v_mul_f32_e32 v108, 0xbfb8aa3b, v110
	v_exp_f32_e32 v109, v109
	v_exp_f32_e32 v108, v108
	v_exp_f32_e32 v117, v116
	v_mul_f32_e32 v116, 0xbfb8aa3b, v107
	v_pk_mul_f32 v[104:105], v[104:105], v[118:119]
	v_exp_f32_e32 v118, v116
	v_add_f32_e32 v109, 1.0, v109
	v_add_f32_e32 v108, 1.0, v108
	v_rcp_f32_e32 v116, v109
	v_add_f32_e32 v109, 1.0, v117
	v_rcp_f32_e32 v108, v108
	v_rcp_f32_e32 v109, v109
	v_add_f32_e32 v117, 1.0, v118
	v_rcp_f32_e32 v117, v117
	v_pk_mul_f32 v[104:105], v[104:105], v[96:97]
	v_pk_mul_f32 v[96:97], v[110:111], v[108:109]
	v_lshl_add_u64 v[108:109], v[114:115], 0, v[112:113]
	v_pk_mul_f32 v[102:103], v[96:97], v[102:103]
	v_pk_mul_f32 v[96:97], v[106:107], v[116:117]
	s_and_b64 vcc, exec, s[8:9]
	v_pk_mul_f32 v[106:107], v[96:97], v[98:99]
	v_cvt_pk_bf16_f32 v96, v100, v101
	v_cvt_pk_bf16_f32 v97, v102, v103
	v_cvt_pk_bf16_f32 v98, v104, v105
	v_cvt_pk_bf16_f32 v99, v106, v107
	global_store_dwordx4 v[108:109], v[96:99], off
	v_mul_f32_e32 v100, 0xbfb8aa3b, v93
	v_exp_f32_e32 v100, v100
	v_mul_f32_e32 v98, 0xbfb8aa3b, v92
	v_mul_f32_e32 v99, 0xbfb8aa3b, v88
	v_exp_f32_e32 v98, v98
	v_exp_f32_e32 v99, v99
	v_or_b32_e32 v96, 32, v152
	v_mad_i64_i32 v[96:97], s[38:39], v96, s55, v[144:145]
	v_add_f32_e32 v98, 1.0, v98
	v_add_f32_e32 v101, 1.0, v99
	v_add_f32_e32 v99, 1.0, v100
	v_rcp_f32_e32 v98, v98
	v_rcp_f32_e32 v99, v99
	v_mul_f32_e32 v100, 0xbfb8aa3b, v89
	v_exp_f32_e32 v102, v100
	v_rcp_f32_e32 v100, v101
	v_pk_mul_f32 v[92:93], v[92:93], v[98:99]
	v_mul_f32_e32 v98, 0xbfb8aa3b, v95
	v_pk_mul_f32 v[84:85], v[92:93], v[84:85]
	v_add_f32_e32 v92, 1.0, v102
	v_rcp_f32_e32 v101, v92
	v_mul_f32_e32 v93, 0xbfb8aa3b, v90
	v_mul_f32_e32 v92, 0xbfb8aa3b, v94
	v_exp_f32_e32 v93, v93
	v_exp_f32_e32 v92, v92
	v_exp_f32_e32 v99, v98
	v_mul_f32_e32 v98, 0xbfb8aa3b, v91
	v_pk_mul_f32 v[88:89], v[88:89], v[100:101]
	v_exp_f32_e32 v100, v98
	v_add_f32_e32 v93, 1.0, v93
	v_add_f32_e32 v92, 1.0, v92
	v_rcp_f32_e32 v98, v93
	v_add_f32_e32 v93, 1.0, v99
	v_rcp_f32_e32 v92, v92
	v_rcp_f32_e32 v93, v93
	v_add_f32_e32 v99, 1.0, v100
	v_rcp_f32_e32 v99, v99
	v_pk_mul_f32 v[88:89], v[88:89], v[80:81]
	v_pk_mul_f32 v[80:81], v[94:95], v[92:93]
	v_lshl_add_u64 v[92:93], v[96:97], 0, v[112:113]
	v_pk_mul_f32 v[86:87], v[80:81], v[86:87]
	v_pk_mul_f32 v[80:81], v[90:91], v[98:99]
	s_mov_b32 s56, s26
	v_pk_mul_f32 v[90:91], v[80:81], v[82:83]
	v_cvt_pk_bf16_f32 v80, v84, v85
	v_cvt_pk_bf16_f32 v81, v86, v87
	v_cvt_pk_bf16_f32 v82, v88, v89
	v_cvt_pk_bf16_f32 v83, v90, v91
	global_store_dwordx4 v[92:93], v[80:83], off
	v_mul_f32_e32 v84, 0xbfb8aa3b, v77
	v_exp_f32_e32 v84, v84
	v_mul_f32_e32 v82, 0xbfb8aa3b, v76
	v_mul_f32_e32 v83, 0xbfb8aa3b, v72
	v_exp_f32_e32 v82, v82
	v_exp_f32_e32 v83, v83
	v_or_b32_e32 v80, 48, v152
	v_mad_i64_i32 v[80:81], s[38:39], v80, s55, v[144:145]
	v_add_f32_e32 v82, 1.0, v82
	v_add_f32_e32 v85, 1.0, v83
; __device__ __forceinline__ float fsilu(float v) { return v * fsigmoid(v); }
; __device__ __forceinline__ u32x4 pack8(const f32x4 a, const f32x4 b) { u32x4 w; w.x = cvt_pk_bf16(a[0], a[1]); w.y = cvt_pk_bf16(a[2], a[3]); w.z = cvt_pk_bf16(b[0], b[1]); w.w = cvt_pk_bf16(b[2], b[3]); return w; }
;     __device__ __forceinline__ void operator()(const f32x4 (&acc)[2][2][4][2], const Unit& u, int wr, int wc, int fr, int fq) const {
;     ...
;                 bf16_t* rowp = O + (size_t)(row0 + ai * HALF + m * 16) * ldc + col0;
;                 f32x4 h0, h1;
; #pragma unroll
;                 for (int j = 0; j < 4; ++j) { h0[j] = fsilu(acc[ai][0][m][0][j]) * acc[ai][1][m][0][j]; h1[j] = fsilu(acc[ai][0][m][1][j]) * acc[ai][1][m][1][j]; }
;                 *(u32x4*)rowp = pack8(h0, h1);
	v_add_f32_e32 v83, 1.0, v84
	v_rcp_f32_e32 v82, v82
	v_rcp_f32_e32 v83, v83
	v_mul_f32_e32 v84, 0xbfb8aa3b, v73
	v_exp_f32_e32 v86, v84
	v_rcp_f32_e32 v84, v85
	v_pk_mul_f32 v[76:77], v[76:77], v[82:83]
	v_mul_f32_e32 v82, 0xbfb8aa3b, v79
	v_pk_mul_f32 v[68:69], v[76:77], v[68:69]
	v_add_f32_e32 v76, 1.0, v86
	v_rcp_f32_e32 v85, v76
	v_mul_f32_e32 v77, 0xbfb8aa3b, v74
	v_mul_f32_e32 v76, 0xbfb8aa3b, v78
	v_exp_f32_e32 v77, v77
	v_exp_f32_e32 v76, v76
	v_exp_f32_e32 v83, v82
	v_mul_f32_e32 v82, 0xbfb8aa3b, v75
	v_pk_mul_f32 v[72:73], v[72:73], v[84:85]
	v_exp_f32_e32 v84, v82
	v_add_f32_e32 v77, 1.0, v77
	v_add_f32_e32 v76, 1.0, v76
	v_rcp_f32_e32 v82, v77
	v_add_f32_e32 v77, 1.0, v83
	v_rcp_f32_e32 v76, v76
	v_rcp_f32_e32 v77, v77
	v_add_f32_e32 v83, 1.0, v84
	v_rcp_f32_e32 v83, v83
	v_pk_mul_f32 v[72:73], v[72:73], v[64:65]
	v_pk_mul_f32 v[64:65], v[78:79], v[76:77]
	v_lshl_add_u64 v[76:77], v[80:81], 0, v[112:113]
	v_pk_mul_f32 v[70:71], v[64:65], v[70:71]
	v_pk_mul_f32 v[64:65], v[74:75], v[82:83]
	s_mov_b32 s36, s28
	v_pk_mul_f32 v[74:75], v[64:65], v[66:67]
	v_cvt_pk_bf16_f32 v64, v68, v69
	v_cvt_pk_bf16_f32 v65, v70, v71
	v_cvt_pk_bf16_f32 v66, v72, v73
	v_cvt_pk_bf16_f32 v67, v74, v75
	global_store_dwordx4 v[76:77], v[64:67], off
	v_mul_f32_e32 v68, 0xbfb8aa3b, v61
	v_exp_f32_e32 v68, v68
	v_mul_f32_e32 v66, 0xbfb8aa3b, v60
	v_mul_f32_e32 v67, 0xbfb8aa3b, v56
	v_exp_f32_e32 v66, v66
	v_exp_f32_e32 v67, v67
	v_add_u32_e32 v64, 0x80, v152
	v_mad_i64_i32 v[64:65], s[38:39], v64, s55, v[144:145]
	v_add_f32_e32 v66, 1.0, v66
	v_add_f32_e32 v69, 1.0, v67
	v_add_f32_e32 v67, 1.0, v68
	v_rcp_f32_e32 v66, v66
	v_rcp_f32_e32 v67, v67
	v_mul_f32_e32 v68, 0xbfb8aa3b, v57
	v_exp_f32_e32 v70, v68
	v_rcp_f32_e32 v68, v69
	v_pk_mul_f32 v[60:61], v[60:61], v[66:67]
	v_mul_f32_e32 v66, 0xbfb8aa3b, v63
	v_pk_mul_f32 v[52:53], v[60:61], v[52:53]
	v_add_f32_e32 v60, 1.0, v70
	v_rcp_f32_e32 v69, v60
	v_mul_f32_e32 v61, 0xbfb8aa3b, v58
	v_mul_f32_e32 v60, 0xbfb8aa3b, v62
	v_exp_f32_e32 v61, v61
	v_exp_f32_e32 v60, v60
	v_exp_f32_e32 v67, v66
	v_mul_f32_e32 v66, 0xbfb8aa3b, v59
	v_pk_mul_f32 v[56:57], v[56:57], v[68:69]
	v_exp_f32_e32 v68, v66
	v_add_f32_e32 v61, 1.0, v61
	v_add_f32_e32 v60, 1.0, v60
	v_rcp_f32_e32 v66, v61
	v_add_f32_e32 v61, 1.0, v67
	v_rcp_f32_e32 v60, v60
	v_rcp_f32_e32 v61, v61
	v_add_f32_e32 v67, 1.0, v68
	v_rcp_f32_e32 v67, v67
	v_pk_mul_f32 v[56:57], v[56:57], v[48:49]
	v_pk_mul_f32 v[48:49], v[62:63], v[60:61]
	v_lshl_add_u64 v[60:61], v[64:65], 0, v[112:113]
	v_pk_mul_f32 v[54:55], v[48:49], v[54:55]
	v_pk_mul_f32 v[48:49], v[58:59], v[66:67]
	s_mov_b64 s[40:41], s[34:35]
	v_pk_mul_f32 v[58:59], v[48:49], v[50:51]
	v_cvt_pk_bf16_f32 v48, v52, v53
	v_cvt_pk_bf16_f32 v49, v54, v55
	v_cvt_pk_bf16_f32 v50, v56, v57
	v_cvt_pk_bf16_f32 v51, v58, v59
	global_store_dwordx4 v[60:61], v[48:51], off
	v_mul_f32_e32 v52, 0xbfb8aa3b, v45
	v_exp_f32_e32 v52, v52
	v_mul_f32_e32 v50, 0xbfb8aa3b, v44
	v_mul_f32_e32 v51, 0xbfb8aa3b, v40
	v_exp_f32_e32 v50, v50
	v_exp_f32_e32 v51, v51
	v_add_u32_e32 v48, 0x90, v152
	v_mad_i64_i32 v[48:49], s[38:39], v48, s55, v[144:145]
	v_add_f32_e32 v50, 1.0, v50
	v_add_f32_e32 v53, 1.0, v51
	v_add_f32_e32 v51, 1.0, v52
	v_rcp_f32_e32 v50, v50
	v_rcp_f32_e32 v51, v51
	v_mul_f32_e32 v52, 0xbfb8aa3b, v41
	v_exp_f32_e32 v54, v52
	v_rcp_f32_e32 v52, v53
	v_pk_mul_f32 v[44:45], v[44:45], v[50:51]
	v_mul_f32_e32 v50, 0xbfb8aa3b, v47
	v_pk_mul_f32 v[36:37], v[44:45], v[36:37]
	v_add_f32_e32 v44, 1.0, v54
	v_rcp_f32_e32 v53, v44
	v_mul_f32_e32 v45, 0xbfb8aa3b, v42
	v_mul_f32_e32 v44, 0xbfb8aa3b, v46
	v_exp_f32_e32 v45, v45
	v_exp_f32_e32 v44, v44
	v_exp_f32_e32 v51, v50
	v_mul_f32_e32 v50, 0xbfb8aa3b, v43
	v_pk_mul_f32 v[40:41], v[40:41], v[52:53]
	v_exp_f32_e32 v52, v50
	v_add_f32_e32 v45, 1.0, v45
	v_add_f32_e32 v44, 1.0, v44
; __device__ __forceinline__ float fsilu(float v) { return v * fsigmoid(v); }
; __device__ __forceinline__ u32x4 pack8(const f32x4 a, const f32x4 b) { u32x4 w; w.x = cvt_pk_bf16(a[0], a[1]); w.y = cvt_pk_bf16(a[2], a[3]); w.z = cvt_pk_bf16(b[0], b[1]); w.w = cvt_pk_bf16(b[2], b[3]); return w; }
; #define PG8_WAIT_V(n) asm volatile("s_waitcnt vmcnt(" #n ")" ::: "memory")
; #define PG8_BAR __builtin_amdgcn_s_barrier()
;     __device__ __forceinline__ void operator()(const f32x4 (&acc)[2][2][4][2], const Unit& u, int wr, int wc, int fr, int fq) const {
;     ...
;                 bf16_t* rowp = O + (size_t)(row0 + ai * HALF + m * 16) * ldc + col0;
;                 f32x4 h0, h1;
; #pragma unroll
;                 for (int j = 0; j < 4; ++j) { h0[j] = fsilu(acc[ai][0][m][0][j]) * acc[ai][1][m][0][j]; h1[j] = fsilu(acc[ai][0][m][1][j]) * acc[ai][1][m][1][j]; }
;                 *(u32x4*)rowp = pack8(h0, h1);
; template <class Epi, class Sched, bool ALIGN_EPI = false, bool SP2 = false>
; __device__ __forceinline__ void gemm_phase(PG8_LAS unsigned char* lds, const Gemm g, const Sched& S, const Epi& E) {
;     ...
;         if constexpr (!Epi::AFTER_DRAIN) { E(acc, cur, wr, wc, fr, fq); S.done(cur); }
;         if (!has_next) break;
; #pragma unroll
;         for (int a = 0; a < 2; ++a)
; #pragma unroll
;             for (int b = 0; b < 2; ++b)
; #pragma unroll
;                 for (int m = 0; m < 4; ++m)
; #pragma unroll
;                     for (int n = 0; n < 2; ++n) acc[a][b][m][n] = (f32x4){0.f, 0.f, 0.f, 0.f};
;         cur = nxt; cA = nA; cB = nB; ++ui;
;         if constexpr (ALIGN_EPI) { if (wr == 1) PG8_BAR; }
;     }
;     PG8_WAIT_V(0);
;     if constexpr (!ALIGN_EPI) { if (wr == 0) PG8_BAR; }
;     PG8_BAR;
	v_rcp_f32_e32 v50, v45
	v_add_f32_e32 v45, 1.0, v51
	v_rcp_f32_e32 v44, v44
	v_rcp_f32_e32 v45, v45
	v_add_f32_e32 v51, 1.0, v52
	v_rcp_f32_e32 v51, v51
	v_pk_mul_f32 v[40:41], v[40:41], v[32:33]
	v_pk_mul_f32 v[32:33], v[46:47], v[44:45]
	v_lshl_add_u64 v[44:45], v[48:49], 0, v[112:113]
	v_pk_mul_f32 v[38:39], v[32:33], v[38:39]
	v_pk_mul_f32 v[32:33], v[42:43], v[50:51]
	s_nop 0
	v_pk_mul_f32 v[42:43], v[32:33], v[34:35]
	v_cvt_pk_bf16_f32 v32, v36, v37
	v_cvt_pk_bf16_f32 v33, v38, v39
	v_cvt_pk_bf16_f32 v34, v40, v41
	v_cvt_pk_bf16_f32 v35, v42, v43
	global_store_dwordx4 v[44:45], v[32:35], off
	v_mul_f32_e32 v36, 0xbfb8aa3b, v29
	v_exp_f32_e32 v36, v36
	v_mul_f32_e32 v34, 0xbfb8aa3b, v28
	v_mul_f32_e32 v35, 0xbfb8aa3b, v24
	v_exp_f32_e32 v34, v34
	v_exp_f32_e32 v35, v35
	v_add_u32_e32 v32, 0xa0, v152
	v_mad_i64_i32 v[32:33], s[38:39], v32, s55, v[144:145]
	v_add_f32_e32 v34, 1.0, v34
	v_add_f32_e32 v37, 1.0, v35
	v_add_f32_e32 v35, 1.0, v36
	v_rcp_f32_e32 v34, v34
	v_rcp_f32_e32 v35, v35
	v_mul_f32_e32 v36, 0xbfb8aa3b, v25
	v_exp_f32_e32 v38, v36
	v_rcp_f32_e32 v36, v37
	v_pk_mul_f32 v[28:29], v[28:29], v[34:35]
	v_mul_f32_e32 v34, 0xbfb8aa3b, v31
	v_pk_mul_f32 v[20:21], v[28:29], v[20:21]
	v_add_f32_e32 v28, 1.0, v38
	v_rcp_f32_e32 v37, v28
	v_mul_f32_e32 v29, 0xbfb8aa3b, v26
	v_mul_f32_e32 v28, 0xbfb8aa3b, v30
	v_exp_f32_e32 v29, v29
	v_exp_f32_e32 v28, v28
	v_exp_f32_e32 v35, v34
	v_mul_f32_e32 v34, 0xbfb8aa3b, v27
	v_pk_mul_f32 v[24:25], v[24:25], v[36:37]
	v_exp_f32_e32 v36, v34
	v_add_f32_e32 v29, 1.0, v29
	v_add_f32_e32 v28, 1.0, v28
	v_rcp_f32_e32 v34, v29
	v_add_f32_e32 v29, 1.0, v35
	v_rcp_f32_e32 v28, v28
	v_rcp_f32_e32 v29, v29
	v_add_f32_e32 v35, 1.0, v36
	v_rcp_f32_e32 v35, v35
	v_pk_mul_f32 v[24:25], v[24:25], v[16:17]
	v_pk_mul_f32 v[16:17], v[30:31], v[28:29]
	v_lshl_add_u64 v[28:29], v[32:33], 0, v[112:113]
	v_pk_mul_f32 v[22:23], v[16:17], v[22:23]
	v_pk_mul_f32 v[16:17], v[26:27], v[34:35]
	s_nop 0
	v_pk_mul_f32 v[26:27], v[16:17], v[18:19]
	v_cvt_pk_bf16_f32 v16, v20, v21
	v_cvt_pk_bf16_f32 v17, v22, v23
	v_cvt_pk_bf16_f32 v18, v24, v25
	v_cvt_pk_bf16_f32 v19, v26, v27
	global_store_dwordx4 v[28:29], v[16:19], off
	v_mul_f32_e32 v20, 0xbfb8aa3b, v13
	v_exp_f32_e32 v20, v20
	v_mul_f32_e32 v18, 0xbfb8aa3b, v12
	v_mul_f32_e32 v19, 0xbfb8aa3b, v8
	v_exp_f32_e32 v18, v18
	v_exp_f32_e32 v19, v19
	v_add_u32_e32 v16, 0xb0, v152
	v_mad_i64_i32 v[16:17], s[38:39], v16, s55, v[144:145]
	v_add_f32_e32 v18, 1.0, v18
	v_add_f32_e32 v21, 1.0, v19
	v_add_f32_e32 v19, 1.0, v20
	v_rcp_f32_e32 v18, v18
	v_rcp_f32_e32 v19, v19
	v_mul_f32_e32 v20, 0xbfb8aa3b, v9
	v_exp_f32_e32 v22, v20
	v_rcp_f32_e32 v20, v21
	v_pk_mul_f32 v[12:13], v[12:13], v[18:19]
	v_mul_f32_e32 v18, 0xbfb8aa3b, v15
	v_pk_mul_f32 v[4:5], v[12:13], v[4:5]
	v_add_f32_e32 v12, 1.0, v22
	v_rcp_f32_e32 v21, v12
	v_mul_f32_e32 v13, 0xbfb8aa3b, v10
	v_mul_f32_e32 v12, 0xbfb8aa3b, v14
	v_exp_f32_e32 v13, v13
	v_exp_f32_e32 v12, v12
	v_exp_f32_e32 v19, v18
	v_mul_f32_e32 v18, 0xbfb8aa3b, v11
	v_pk_mul_f32 v[8:9], v[8:9], v[20:21]
	v_exp_f32_e32 v20, v18
	v_add_f32_e32 v13, 1.0, v13
	v_add_f32_e32 v12, 1.0, v12
	v_rcp_f32_e32 v18, v13
	v_add_f32_e32 v13, 1.0, v19
	v_rcp_f32_e32 v12, v12
	v_rcp_f32_e32 v13, v13
	v_add_f32_e32 v19, 1.0, v20
	v_rcp_f32_e32 v19, v19
	v_pk_mul_f32 v[8:9], v[8:9], v[0:1]
	v_pk_mul_f32 v[0:1], v[14:15], v[12:13]
	v_lshl_add_u64 v[12:13], v[16:17], 0, v[112:113]
	v_pk_mul_f32 v[6:7], v[0:1], v[6:7]
	v_pk_mul_f32 v[0:1], v[10:11], v[18:19]
	s_mov_b64 s[38:39], s[30:31]
	v_pk_mul_f32 v[10:11], v[0:1], v[2:3]
	v_cvt_pk_bf16_f32 v0, v4, v5
	v_cvt_pk_bf16_f32 v1, v6, v7
	v_cvt_pk_bf16_f32 v2, v8, v9
	v_cvt_pk_bf16_f32 v3, v10, v11
	global_store_dwordx4 v[12:13], v[0:3], off
	s_cbranch_vccz .LBB0_166
	s_waitcnt vmcnt(0)
	s_cmpk_gt_u32 s3, 0xff
	s_cbranch_scc1 .LBB0_173
	s_barrier

; #define PG8_STAGE(bufoff, gbase, voff) do { _Pragma("unroll") for (int _i = 0; _i < 2; ++_i) \
;         __builtin_amdgcn_global_load_lds((const unsigned*)((const char*)(gbase) + (voff)[_i]), (PG8_LAS unsigned*)(lds + (bufoff) + ldsw + _i * 8192), 16, 0, 0); } while (0)
; #define PG8_LDA(dst, b, h) do { _Pragma("unroll") for (int m = 0; m < 4; ++m) _Pragma("unroll") for (int k = 0; k < 2; ++k) dst[m][k] = *(const PG8_LAS bf16x8*)(lds + PG8_SA(b, h) + aoff + m * 2048 + k * 1024); } while (0)
; #define PG8_LDB(dst, b, h) do { _Pragma("unroll") for (int n = 0; n < 2; ++n) _Pragma("unroll") for (int k = 0; k < 2; ++k) dst[n][k] = *(const PG8_LAS bf16x8*)(lds + PG8_SB(b, h) + boff + n * 2048 + k * 1024); } while (0)
; #define PG8_MMA(ai, bj, At, Bt) do { __builtin_amdgcn_s_setprio(1); _Pragma("unroll") for (int m = 0; m < 4; ++m) _Pragma("unroll") for (int n = 0; n < 2; ++n) _Pragma("unroll") for (int k = 0; k < 2; ++k) \
;         acc[ai][bj][m][n] = __builtin_amdgcn_mfma_f32_16x16x32_bf16(Bt[n][k], At[m][k], acc[ai][bj][m][n], 0, 0, 0); __builtin_amdgcn_s_setprio(0); } while (0)
; #define PG8_WAIT_V(n) asm volatile("s_waitcnt vmcnt(" #n ")" ::: "memory")
; #define PG8_WAIT_L(n) asm volatile("s_waitcnt lgkmcnt(" #n ")" ::: "memory")
; #define PG8_BAR __builtin_amdgcn_s_barrier()
; #define PG8_SCHED __builtin_amdgcn_sched_barrier(0)
; template <class Epi, class Sched, bool ALIGN_EPI = false, bool SP2 = false>
; __device__ __forceinline__ void gemm_phase(PG8_LAS unsigned char* lds, const Gemm g, const Sched& S, const Epi& E) {
;     ...
;             PG8_LDB(B0, 0, 0); PG8_LDB(B1, 0, 1); PG8_SCHED; PG8_LDA(At, 0, 0); PG8_STAGE(PG8_SA(1, 1), a1 + hstep, voffA);
;             PG8_WAIT_V(8); PG8_WAIT_L(0); PG8_BAR; PG8_MMA(0, 0, At, B0); PG8_MMA(0, 1, At, B1); PG8_BAR; PG8_SCHED;
;             PG8_LDA(At, 0, 1); PG8_STAGE(PG8_SB(0, 0), b2, voffB); PG8_STAGE(PG8_SB(0, 1), b2 + hstep, voffB); PG8_STAGE(PG8_SA(0, 0), a2, voffA);
;             PG8_WAIT_V(8); PG8_WAIT_L(0); PG8_BAR; PG8_MMA(1, 0, At, B0); PG8_MMA(1, 1, At, B1); PG8_BAR; PG8_SCHED;
.LBB0_245:
	ds_read_b128 v[140:143], v169
	ds_read_b128 v[144:147], v169 offset:1024
	ds_read_b128 v[148:151], v169 offset:2048
	ds_read_b128 v[152:155], v169 offset:3072
	ds_read_b128 v[156:159], v170
	ds_read_b128 v[160:163], v170 offset:1024
	ds_read_b128 v[172:175], v170 offset:2048
	ds_read_b128 v[176:179], v170 offset:3072
	s_add_u32 s46, s44, 0x100
	s_addc_u32 s47, s45, 0
	s_cmpk_eq_i32 s69, 0x54
	s_cselect_b32 s51, s11, s47
	s_cselect_b32 s50, s10, s46
	s_cselect_b32 s49, s13, s68
	s_cselect_b32 s48, s12, s67
	s_add_i32 m0, s26, 0xc000
	ds_read_b128 v[180:183], v171
	ds_read_b128 v[184:187], v171 offset:1024
	ds_read_b128 v[188:191], v171 offset:2048
	ds_read_b128 v[192:195], v171 offset:3072
	ds_read_b128 v[196:199], v171 offset:4096
	ds_read_b128 v[200:203], v171 offset:5120
	ds_read_b128 v[204:207], v171 offset:6144
	ds_read_b128 v[208:211], v171 offset:7168
	global_load_lds_dwordx4 v136, s[44:45]
	s_add_i32 m0, s26, 0xe000
	s_nop 0
	global_load_lds_dwordx4 v138, s[44:45]
	s_waitcnt vmcnt(8)
	s_waitcnt lgkmcnt(0)
	s_barrier
	s_waitcnt lgkmcnt(0)
	v_mfma_f32_16x16x32_bf16 v[124:127], v[140:143], v[180:183], v[124:127]
	v_mfma_f32_16x16x32_bf16 v[120:123], v[148:151], v[180:183], v[120:123]
	v_mfma_f32_16x16x32_bf16 v[116:119], v[140:143], v[188:191], v[116:119]
	v_mfma_f32_16x16x32_bf16 v[112:115], v[148:151], v[188:191], v[112:115]
	v_mfma_f32_16x16x32_bf16 v[108:111], v[140:143], v[196:199], v[108:111]
	v_mfma_f32_16x16x32_bf16 v[96:99], v[148:151], v[196:199], v[96:99]
	v_mfma_f32_16x16x32_bf16 v[84:87], v[140:143], v[204:207], v[84:87]
	v_mfma_f32_16x16x32_bf16 v[76:79], v[148:151], v[204:207], v[76:79]
	v_mfma_f32_16x16x32_bf16 v[124:127], v[144:147], v[184:187], v[124:127]
	v_mfma_f32_16x16x32_bf16 v[120:123], v[152:155], v[184:187], v[120:123]
	v_mfma_f32_16x16x32_bf16 v[116:119], v[144:147], v[192:195], v[116:119]
	v_mfma_f32_16x16x32_bf16 v[112:115], v[152:155], v[192:195], v[112:115]
	v_mfma_f32_16x16x32_bf16 v[108:111], v[144:147], v[200:203], v[108:111]
	v_mfma_f32_16x16x32_bf16 v[96:99], v[152:155], v[200:203], v[96:99]
	v_mfma_f32_16x16x32_bf16 v[84:87], v[144:147], v[208:211], v[84:87]
	v_mfma_f32_16x16x32_bf16 v[76:79], v[152:155], v[208:211], v[76:79]
	v_mfma_f32_16x16x32_bf16 v[104:107], v[156:159], v[180:183], v[104:107]
	v_mfma_f32_16x16x32_bf16 v[100:103], v[172:175], v[180:183], v[100:103]
	v_mfma_f32_16x16x32_bf16 v[92:95], v[156:159], v[188:191], v[92:95]
	v_mfma_f32_16x16x32_bf16 v[88:91], v[172:175], v[188:191], v[88:91]
	v_mfma_f32_16x16x32_bf16 v[80:83], v[156:159], v[196:199], v[80:83]
	v_mfma_f32_16x16x32_bf16 v[72:75], v[172:175], v[196:199], v[72:75]
	v_mfma_f32_16x16x32_bf16 v[68:71], v[156:159], v[204:207], v[68:71]
	v_mfma_f32_16x16x32_bf16 v[64:67], v[172:175], v[204:207], v[64:67]
	v_mfma_f32_16x16x32_bf16 v[104:107], v[160:163], v[184:187], v[104:107]
	v_mfma_f32_16x16x32_bf16 v[100:103], v[176:179], v[184:187], v[100:103]
	v_mfma_f32_16x16x32_bf16 v[92:95], v[160:163], v[192:195], v[92:95]
	v_mfma_f32_16x16x32_bf16 v[88:91], v[176:179], v[192:195], v[88:91]
	v_mfma_f32_16x16x32_bf16 v[80:83], v[160:163], v[200:203], v[80:83]
	v_mfma_f32_16x16x32_bf16 v[72:75], v[176:179], v[200:203], v[72:75]
	v_mfma_f32_16x16x32_bf16 v[68:71], v[160:163], v[208:211], v[68:71]
	v_mfma_f32_16x16x32_bf16 v[64:67], v[176:179], v[208:211], v[64:67]
	s_barrier
	s_add_i32 s44, s61, s25
	s_mov_b32 m0, s44
	ds_read_b128 v[180:183], v171 offset:16384
	ds_read_b128 v[184:187], v171 offset:17408
	ds_read_b128 v[188:191], v171 offset:18432
	ds_read_b128 v[192:195], v171 offset:19456
	ds_read_b128 v[196:199], v171 offset:20480
	ds_read_b128 v[200:203], v171 offset:21504
	ds_read_b128 v[204:207], v171 offset:22528
	ds_read_b128 v[208:211], v171 offset:23552
	global_load_lds_dwordx4 v130, s[48:49]
	s_add_i32 m0, s44, 0x2000
	s_add_u32 s44, s48, 0x160000
	s_addc_u32 s45, s49, 0
	s_add_i32 s70, s62, s25
	global_load_lds_dwordx4 v134, s[48:49]
	s_mov_b32 m0, s70
	s_nop 0
	global_load_lds_dwordx4 v130, s[44:45]
	s_add_i32 m0, s70, 0x2000
	s_nop 0
	global_load_lds_dwordx4 v134, s[44:45]
	s_mov_b32 m0, s26
	s_nop 0
	global_load_lds_dwordx4 v128, s[50:51]
	s_mov_b32 m0, s27
	s_nop 0
	global_load_lds_dwordx4 v132, s[50:51]
	s_waitcnt vmcnt(8)
	s_waitcnt lgkmcnt(0)
	s_barrier
	s_waitcnt lgkmcnt(0)
	v_mfma_f32_16x16x32_bf16 v[60:63], v[140:143], v[180:183], v[60:63]
	v_mfma_f32_16x16x32_bf16 v[56:59], v[148:151], v[180:183], v[56:59]
	v_mfma_f32_16x16x32_bf16 v[52:55], v[140:143], v[188:191], v[52:55]
	v_mfma_f32_16x16x32_bf16 v[48:51], v[148:151], v[188:191], v[48:51]
	v_mfma_f32_16x16x32_bf16 v[44:47], v[140:143], v[196:199], v[44:47]
	v_mfma_f32_16x16x32_bf16 v[32:35], v[148:151], v[196:199], v[32:35]
	v_mfma_f32_16x16x32_bf16 v[20:23], v[140:143], v[204:207], v[20:23]
	v_mfma_f32_16x16x32_bf16 v[12:15], v[148:151], v[204:207], v[12:15]
	v_mfma_f32_16x16x32_bf16 v[60:63], v[144:147], v[184:187], v[60:63]
	v_mfma_f32_16x16x32_bf16 v[56:59], v[152:155], v[184:187], v[56:59]
	v_mfma_f32_16x16x32_bf16 v[52:55], v[144:147], v[192:195], v[52:55]
	v_mfma_f32_16x16x32_bf16 v[48:51], v[152:155], v[192:195], v[48:51]
	v_mfma_f32_16x16x32_bf16 v[44:47], v[144:147], v[200:203], v[44:47]
	v_mfma_f32_16x16x32_bf16 v[32:35], v[152:155], v[200:203], v[32:35]
	v_mfma_f32_16x16x32_bf16 v[20:23], v[144:147], v[208:211], v[20:23]
	v_mfma_f32_16x16x32_bf16 v[12:15], v[152:155], v[208:211], v[12:15]
	v_mfma_f32_16x16x32_bf16 v[40:43], v[156:159], v[180:183], v[40:43]
	v_mfma_f32_16x16x32_bf16 v[36:39], v[172:175], v[180:183], v[36:39]
	v_mfma_f32_16x16x32_bf16 v[28:31], v[156:159], v[188:191], v[28:31]
	v_mfma_f32_16x16x32_bf16 v[24:27], v[172:175], v[188:191], v[24:27]
	v_mfma_f32_16x16x32_bf16 v[16:19], v[156:159], v[196:199], v[16:19]
	v_mfma_f32_16x16x32_bf16 v[8:11], v[172:175], v[196:199], v[8:11]
	v_mfma_f32_16x16x32_bf16 v[4:7], v[156:159], v[204:207], v[4:7]
	v_mfma_f32_16x16x32_bf16 v[0:3], v[172:175], v[204:207], v[0:3]
	v_mfma_f32_16x16x32_bf16 v[40:43], v[160:163], v[184:187], v[40:43]
	v_mfma_f32_16x16x32_bf16 v[36:39], v[176:179], v[184:187], v[36:39]
	v_mfma_f32_16x16x32_bf16 v[28:31], v[160:163], v[192:195], v[28:31]
	v_mfma_f32_16x16x32_bf16 v[24:27], v[176:179], v[192:195], v[24:27]
	v_mfma_f32_16x16x32_bf16 v[16:19], v[160:163], v[200:203], v[16:19]
	v_mfma_f32_16x16x32_bf16 v[8:11], v[176:179], v[200:203], v[8:11]
	v_mfma_f32_16x16x32_bf16 v[4:7], v[160:163], v[208:211], v[4:7]
	v_mfma_f32_16x16x32_bf16 v[0:3], v[176:179], v[208:211], v[0:3]
	s_barrier
; #define PG8_STAGE(bufoff, gbase, voff) do { _Pragma("unroll") for (int _i = 0; _i < 2; ++_i) \
;         __builtin_amdgcn_global_load_lds((const unsigned*)((const char*)(gbase) + (voff)[_i]), (PG8_LAS unsigned*)(lds + (bufoff) + ldsw + _i * 8192), 16, 0, 0); } while (0)
; #define PG8_LDA(dst, b, h) do { _Pragma("unroll") for (int m = 0; m < 4; ++m) _Pragma("unroll") for (int k = 0; k < 2; ++k) dst[m][k] = *(const PG8_LAS bf16x8*)(lds + PG8_SA(b, h) + aoff + m * 2048 + k * 1024); } while (0)
; #define PG8_LDB(dst, b, h) do { _Pragma("unroll") for (int n = 0; n < 2; ++n) _Pragma("unroll") for (int k = 0; k < 2; ++k) dst[n][k] = *(const PG8_LAS bf16x8*)(lds + PG8_SB(b, h) + boff + n * 2048 + k * 1024); } while (0)
; #define PG8_MMA(ai, bj, At, Bt) do { __builtin_amdgcn_s_setprio(1); _Pragma("unroll") for (int m = 0; m < 4; ++m) _Pragma("unroll") for (int n = 0; n < 2; ++n) _Pragma("unroll") for (int k = 0; k < 2; ++k) \
;         acc[ai][bj][m][n] = __builtin_amdgcn_mfma_f32_16x16x32_bf16(Bt[n][k], At[m][k], acc[ai][bj][m][n], 0, 0, 0); __builtin_amdgcn_s_setprio(0); } while (0)
; #define PG8_WAIT_V(n) asm volatile("s_waitcnt vmcnt(" #n ")" ::: "memory")
; #define PG8_WAIT_L(n) asm volatile("s_waitcnt lgkmcnt(" #n ")" ::: "memory")
; #define PG8_BAR __builtin_amdgcn_s_barrier()
; #define PG8_SCHED __builtin_amdgcn_sched_barrier(0)
; template <class Epi, class Sched, bool ALIGN_EPI = false, bool SP2 = false>
; __device__ __forceinline__ void gemm_phase(PG8_LAS unsigned char* lds, const Gemm g, const Sched& S, const Epi& E) {
;     ...
;             PG8_LDB(B0, 1, 0); PG8_LDB(B1, 1, 1); PG8_SCHED; PG8_LDA(At, 1, 0); PG8_STAGE(PG8_SA(0, 1), a2 + hstep, voffA);
;             PG8_WAIT_V(8); PG8_WAIT_L(0); PG8_BAR; PG8_MMA(0, 0, At, B0); PG8_MMA(0, 1, At, B1); PG8_BAR; PG8_SCHED;
;             PG8_LDA(At, 1, 1); PG8_STAGE(PG8_SB(1, 0), b3, voffB); PG8_STAGE(PG8_SB(1, 1), b3 + hstep, voffB); PG8_STAGE(PG8_SA(1, 0), a3, voffA);
;             PG8_WAIT_V(8); PG8_WAIT_L(0); PG8_BAR; PG8_MMA(1, 0, At, B0); PG8_MMA(1, 1, At, B1); PG8_BAR; PG8_SCHED;
	s_add_i32 s70, 0, 0x18000
	s_add_i32 s71, 0, 0x1c000
	v_add_u32_e32 v152, s70, v167
	v_add_u32_e32 v176, s71, v167
	ds_read_b128 v[140:143], v152
	ds_read_b128 v[144:147], v152 offset:1024
	ds_read_b128 v[148:151], v152 offset:2048
	ds_read_b128 v[152:155], v152 offset:3072
	ds_read_b128 v[156:159], v176
	ds_read_b128 v[160:163], v176 offset:1024
	ds_read_b128 v[172:175], v176 offset:2048
	ds_read_b128 v[176:179], v176 offset:3072
	s_add_u32 s44, s50, 0x160000
	s_addc_u32 s45, s51, 0
	s_mov_b32 m0, s52
	ds_read_b128 v[180:183], v171 offset:32768
	ds_read_b128 v[184:187], v171 offset:33792
	ds_read_b128 v[188:191], v171 offset:34816
	ds_read_b128 v[192:195], v171 offset:35840
	ds_read_b128 v[196:199], v171 offset:36864
	ds_read_b128 v[200:203], v171 offset:37888
	ds_read_b128 v[204:207], v171 offset:38912
	ds_read_b128 v[208:211], v171 offset:39936
	global_load_lds_dwordx4 v128, s[44:45]
	s_mov_b32 m0, s53
	s_nop 0
	global_load_lds_dwordx4 v132, s[44:45]
	s_waitcnt vmcnt(8)
	s_waitcnt lgkmcnt(0)
	s_barrier
	s_waitcnt lgkmcnt(0)
	v_mfma_f32_16x16x32_bf16 v[124:127], v[140:143], v[180:183], v[124:127]
	v_mfma_f32_16x16x32_bf16 v[120:123], v[148:151], v[180:183], v[120:123]
	v_mfma_f32_16x16x32_bf16 v[116:119], v[140:143], v[188:191], v[116:119]
	v_mfma_f32_16x16x32_bf16 v[112:115], v[148:151], v[188:191], v[112:115]
	v_mfma_f32_16x16x32_bf16 v[108:111], v[140:143], v[196:199], v[108:111]
	v_mfma_f32_16x16x32_bf16 v[96:99], v[148:151], v[196:199], v[96:99]
	v_mfma_f32_16x16x32_bf16 v[84:87], v[140:143], v[204:207], v[84:87]
	v_mfma_f32_16x16x32_bf16 v[76:79], v[148:151], v[204:207], v[76:79]
	v_mfma_f32_16x16x32_bf16 v[124:127], v[144:147], v[184:187], v[124:127]
	v_mfma_f32_16x16x32_bf16 v[120:123], v[152:155], v[184:187], v[120:123]
	v_mfma_f32_16x16x32_bf16 v[116:119], v[144:147], v[192:195], v[116:119]
	v_mfma_f32_16x16x32_bf16 v[112:115], v[152:155], v[192:195], v[112:115]
	v_mfma_f32_16x16x32_bf16 v[108:111], v[144:147], v[200:203], v[108:111]
	v_mfma_f32_16x16x32_bf16 v[96:99], v[152:155], v[200:203], v[96:99]
	v_mfma_f32_16x16x32_bf16 v[84:87], v[144:147], v[208:211], v[84:87]
	v_mfma_f32_16x16x32_bf16 v[76:79], v[152:155], v[208:211], v[76:79]
	v_mfma_f32_16x16x32_bf16 v[104:107], v[156:159], v[180:183], v[104:107]
	v_mfma_f32_16x16x32_bf16 v[100:103], v[172:175], v[180:183], v[100:103]
	v_mfma_f32_16x16x32_bf16 v[92:95], v[156:159], v[188:191], v[92:95]
	v_mfma_f32_16x16x32_bf16 v[88:91], v[172:175], v[188:191], v[88:91]
	v_mfma_f32_16x16x32_bf16 v[80:83], v[156:159], v[196:199], v[80:83]
	v_mfma_f32_16x16x32_bf16 v[72:75], v[172:175], v[196:199], v[72:75]
	v_mfma_f32_16x16x32_bf16 v[68:71], v[156:159], v[204:207], v[68:71]
	v_mfma_f32_16x16x32_bf16 v[64:67], v[172:175], v[204:207], v[64:67]
	v_mfma_f32_16x16x32_bf16 v[104:107], v[160:163], v[184:187], v[104:107]
	v_mfma_f32_16x16x32_bf16 v[100:103], v[176:179], v[184:187], v[100:103]
	v_mfma_f32_16x16x32_bf16 v[92:95], v[160:163], v[192:195], v[92:95]
	v_mfma_f32_16x16x32_bf16 v[88:91], v[176:179], v[192:195], v[88:91]
	v_mfma_f32_16x16x32_bf16 v[80:83], v[160:163], v[200:203], v[80:83]
	v_mfma_f32_16x16x32_bf16 v[72:75], v[176:179], v[200:203], v[72:75]
	v_mfma_f32_16x16x32_bf16 v[68:71], v[160:163], v[208:211], v[68:71]
	v_mfma_f32_16x16x32_bf16 v[64:67], v[176:179], v[208:211], v[64:67]
	s_barrier
	s_add_i32 s44, s70, s25
	s_add_u32 s86, s48, 0x80
	s_addc_u32 s87, s49, 0
	s_mov_b32 m0, s44
	ds_read_b128 v[180:183], v171 offset:49152
	ds_read_b128 v[184:187], v171 offset:50176
	ds_read_b128 v[188:191], v171 offset:51200
	ds_read_b128 v[192:195], v171 offset:52224
	ds_read_b128 v[196:199], v171 offset:53248
	ds_read_b128 v[200:203], v171 offset:54272
	ds_read_b128 v[204:207], v171 offset:55296
	ds_read_b128 v[208:211], v171 offset:56320
	global_load_lds_dwordx4 v130, s[86:87]
	s_add_i32 m0, s44, 0x2000
	s_add_u32 s44, s48, 0x160080
	s_addc_u32 s45, s49, 0
	s_add_i32 s48, s71, s25
	global_load_lds_dwordx4 v134, s[86:87]
	s_mov_b32 m0, s48
	s_nop 0
	global_load_lds_dwordx4 v130, s[44:45]
	s_add_i32 m0, s48, 0x2000
	s_nop 0
	global_load_lds_dwordx4 v134, s[44:45]
	s_add_u32 s84, s50, 0x80
	s_addc_u32 s85, s51, 0
	s_mov_b32 m0, s57
	s_nop 0
	global_load_lds_dwordx4 v128, s[84:85]
	s_mov_b32 m0, s58
	s_nop 0
	global_load_lds_dwordx4 v132, s[84:85]
	s_waitcnt vmcnt(8)
	s_waitcnt lgkmcnt(0)
	s_barrier
	s_waitcnt lgkmcnt(0)
	v_mfma_f32_16x16x32_bf16 v[60:63], v[140:143], v[180:183], v[60:63]
	v_mfma_f32_16x16x32_bf16 v[56:59], v[148:151], v[180:183], v[56:59]
	v_mfma_f32_16x16x32_bf16 v[52:55], v[140:143], v[188:191], v[52:55]
	v_mfma_f32_16x16x32_bf16 v[48:51], v[148:151], v[188:191], v[48:51]
	v_mfma_f32_16x16x32_bf16 v[44:47], v[140:143], v[196:199], v[44:47]
	v_mfma_f32_16x16x32_bf16 v[32:35], v[148:151], v[196:199], v[32:35]
	v_mfma_f32_16x16x32_bf16 v[20:23], v[140:143], v[204:207], v[20:23]
	v_mfma_f32_16x16x32_bf16 v[12:15], v[148:151], v[204:207], v[12:15]
	v_mfma_f32_16x16x32_bf16 v[60:63], v[144:147], v[184:187], v[60:63]
	v_mfma_f32_16x16x32_bf16 v[56:59], v[152:155], v[184:187], v[56:59]
	v_mfma_f32_16x16x32_bf16 v[52:55], v[144:147], v[192:195], v[52:55]
	v_mfma_f32_16x16x32_bf16 v[48:51], v[152:155], v[192:195], v[48:51]
	v_mfma_f32_16x16x32_bf16 v[44:47], v[144:147], v[200:203], v[44:47]
	v_mfma_f32_16x16x32_bf16 v[32:35], v[152:155], v[200:203], v[32:35]
	v_mfma_f32_16x16x32_bf16 v[20:23], v[144:147], v[208:211], v[20:23]
	v_mfma_f32_16x16x32_bf16 v[12:15], v[152:155], v[208:211], v[12:15]
	v_mfma_f32_16x16x32_bf16 v[40:43], v[156:159], v[180:183], v[40:43]
	v_mfma_f32_16x16x32_bf16 v[36:39], v[172:175], v[180:183], v[36:39]
	v_mfma_f32_16x16x32_bf16 v[28:31], v[156:159], v[188:191], v[28:31]
	v_mfma_f32_16x16x32_bf16 v[24:27], v[172:175], v[188:191], v[24:27]
	v_mfma_f32_16x16x32_bf16 v[16:19], v[156:159], v[196:199], v[16:19]
	v_mfma_f32_16x16x32_bf16 v[8:11], v[172:175], v[196:199], v[8:11]
	v_mfma_f32_16x16x32_bf16 v[4:7], v[156:159], v[204:207], v[4:7]
	v_mfma_f32_16x16x32_bf16 v[0:3], v[172:175], v[204:207], v[0:3]
	v_mfma_f32_16x16x32_bf16 v[40:43], v[160:163], v[184:187], v[40:43]
	v_mfma_f32_16x16x32_bf16 v[36:39], v[176:179], v[184:187], v[36:39]
	v_mfma_f32_16x16x32_bf16 v[28:31], v[160:163], v[192:195], v[28:31]
	v_mfma_f32_16x16x32_bf16 v[24:27], v[176:179], v[192:195], v[24:27]
	v_mfma_f32_16x16x32_bf16 v[16:19], v[160:163], v[200:203], v[16:19]
	v_mfma_f32_16x16x32_bf16 v[8:11], v[176:179], v[200:203], v[8:11]
	v_mfma_f32_16x16x32_bf16 v[4:7], v[160:163], v[208:211], v[4:7]
	v_mfma_f32_16x16x32_bf16 v[0:3], v[176:179], v[208:211], v[0:3]
	s_barrier
;     __device__ __forceinline__ void operator()(const f32x4 (&acc)[2][2][4][2], const Unit& u, int wr, int wc, int fr, int fq) const {
;         const int row0 = u.pm * BM + wr * 64 + fr, col0 = u.pn * BM + wc * 32 + 8 * fq;
;         const float* gp = gate + (u.pm >> 5) * 18432 + col0;
;         f32x4 gv[2][2];
; #pragma unroll
;         for (int bj = 0; bj < 2; ++bj)
; #pragma unroll
;             for (int n = 0; n < 2; ++n) gv[bj][n] = *(const f32x4*)(gp + bj * HALF + 4 * n) * scale;
; #pragma unroll
;         for (int ai = 0; ai < 2; ++ai) { f32x4 r[4][2][2];
; #pragma unroll
;             for (int m = 0; m < 4; ++m) { const size_t off = (size_t)(row0 + ai * HALF + m * 16) * 2048 + col0;
; #pragma unroll
;                 for (int bj = 0; bj < 2; ++bj)
; #pragma unroll
;                     for (int n = 0; n < 2; ++n) r[m][bj][n] = *(const f32x4*)(res + off + bj * HALF + 4 * n); }
; #pragma unroll
;             for (int m = 0; m < 4; ++m) { const size_t off = (size_t)(row0 + ai * HALF + m * 16) * 2048 + col0;
; #pragma unroll
;                 for (int bj = 0; bj < 2; ++bj)
; #pragma unroll
;                     for (int n = 0; n < 2; ++n) *(f32x4*)(out + off + bj * HALF + 4 * n) = r[m][bj][n] + gv[bj][n] * acc[ai][bj][m][n]; } }
	s_add_i32 s69, s69, 2
	s_add_u32 s67, s67, 0x100
	s_addc_u32 s68, s68, 0
	s_cmpk_gt_u32 s69, 0x55
	s_mov_b64 s[44:45], s[46:47]
	s_cbranch_scc0 .LBB0_245
	s_lshr_b32 s44, s65, 5
	s_mulk_i32 s44, 0x4800
	s_ashr_i32 s45, s44, 31
	v_lshl_or_b32 v140, s66, 8, v168
	s_lshl_b64 s[44:45], s[44:45], 2
	s_add_u32 s44, s55, s44
	v_ashrrev_i32_e32 v141, 31, v140
	s_addc_u32 s45, s56, s45
	v_lshlrev_b64 v[144:145], 2, v[140:141]
	v_lshl_add_u64 v[140:141], s[44:45], 0, v[144:145]
	global_load_dwordx4 v[146:149], v[140:141], off offset:16
	global_load_dwordx4 v[150:153], v[140:141], off
	global_load_dwordx4 v[172:175], v[140:141], off offset:528
	global_load_dwordx4 v[176:179], v[140:141], off offset:512
	v_lshl_add_u32 v140, s65, 8, v166
	v_ashrrev_i32_e32 v141, 31, v140
	v_lshl_add_u64 v[162:163], s[28:29], 0, v[144:145]
	v_lshlrev_b64 v[164:165], 13, v[140:141]
	v_lshl_add_u64 v[142:143], v[162:163], 0, v[164:165]
	global_load_dwordx4 v[180:183], v[142:143], off
	global_load_dwordx4 v[184:187], v[142:143], off offset:16
	global_load_dwordx4 v[188:191], v[142:143], off offset:528
	global_load_dwordx4 v[192:195], v[142:143], off offset:512
	v_or_b32_e32 v142, 16, v140
	v_ashrrev_i32_e32 v143, 31, v142
	v_lshlrev_b64 v[154:155], 13, v[142:143]
	v_lshl_add_u64 v[142:143], v[162:163], 0, v[154:155]
	global_load_dwordx4 v[196:199], v[142:143], off
	global_load_dwordx4 v[200:203], v[142:143], off offset:16
	global_load_dwordx4 v[204:207], v[142:143], off offset:528
	global_load_dwordx4 v[208:211], v[142:143], off offset:512
	v_or_b32_e32 v142, 32, v140
	v_ashrrev_i32_e32 v143, 31, v142
	v_lshlrev_b64 v[156:157], 13, v[142:143]
	v_or_b32_e32 v140, 48, v140
	v_lshl_add_u64 v[142:143], v[162:163], 0, v[156:157]
	v_ashrrev_i32_e32 v141, 31, v140
	global_load_dwordx4 v[214:217], v[142:143], off
	global_load_dwordx4 v[222:225], v[142:143], off offset:16
	global_load_dwordx4 v[232:235], v[142:143], off offset:512
	global_load_dwordx4 v[236:239], v[142:143], off offset:528
	v_lshlrev_b64 v[212:213], 13, v[140:141]
	v_lshl_add_u64 v[140:141], v[162:163], 0, v[212:213]
	global_load_dwordx4 v[240:243], v[140:141], off
	global_load_dwordx4 v[244:247], v[140:141], off offset:16
	global_load_dwordx4 v[248:251], v[140:141], off offset:512
	s_nop 0
	global_load_dwordx4 v[140:143], v[140:141], off offset:528
	v_lshl_add_u64 v[158:159], s[30:31], 0, v[164:165]
	v_lshl_add_u64 v[230:231], v[158:159], 0, v[144:145]
	v_lshl_add_u64 v[154:155], s[30:31], 0, v[154:155]
	v_lshl_add_u64 v[156:157], s[30:31], 0, v[156:157]
	v_lshl_add_u64 v[218:219], v[154:155], 0, v[144:145]
	v_lshl_add_u64 v[252:253], v[156:157], 0, v[144:145]
	s_and_b64 vcc, exec, s[8:9]
	s_mov_b32 s66, s63
	s_mov_b32 s65, s64
	s_mov_b64 s[46:47], s[12:13]
	s_mov_b64 s[44:45], s[10:11]
	s_waitcnt vmcnt(0)
	v_pk_mul_f32 v[154:155], v[148:149], 0.5 op_sel_hi:[1,0]
	v_pk_mul_f32 v[158:159], v[152:153], 0.5 op_sel_hi:[1,0]
	v_pk_mul_f32 v[160:161], v[150:151], 0.5 op_sel_hi:[1,0]
	v_pk_mul_f32 v[150:151], v[178:179], 0.5 op_sel_hi:[1,0]
	v_pk_mul_f32 v[152:153], v[176:177], 0.5 op_sel_hi:[1,0]
	v_pk_mul_f32 v[156:157], v[146:147], 0.5 op_sel_hi:[1,0]
	v_pk_mul_f32 v[146:147], v[174:175], 0.5 op_sel_hi:[1,0]
	v_pk_mul_f32 v[148:149], v[172:173], 0.5 op_sel_hi:[1,0]
	v_pk_fma_f32 v[126:127], v[126:127], v[158:159], v[182:183]
	v_pk_fma_f32 v[124:125], v[124:125], v[160:161], v[180:181]
	v_pk_fma_f32 v[122:123], v[122:123], v[154:155], v[186:187]
	v_pk_fma_f32 v[120:121], v[120:121], v[156:157], v[184:185]
	v_pk_fma_f32 v[106:107], v[106:107], v[150:151], v[194:195]
	v_pk_fma_f32 v[104:105], v[104:105], v[152:153], v[192:193]
	v_pk_fma_f32 v[102:103], v[102:103], v[146:147], v[190:191]
	v_pk_fma_f32 v[100:101], v[100:101], v[148:149], v[188:189]
	v_pk_fma_f32 v[118:119], v[118:119], v[158:159], v[198:199]
	v_pk_fma_f32 v[116:117], v[116:117], v[160:161], v[196:197]
	v_pk_fma_f32 v[114:115], v[114:115], v[154:155], v[202:203]
	v_pk_fma_f32 v[112:113], v[112:113], v[156:157], v[200:201]
	v_pk_fma_f32 v[82:83], v[82:83], v[150:151], v[234:235]
	v_pk_fma_f32 v[80:81], v[80:81], v[152:153], v[232:233]
	v_pk_fma_f32 v[94:95], v[94:95], v[150:151], v[210:211]
	v_pk_fma_f32 v[92:93], v[92:93], v[152:153], v[208:209]
	v_pk_fma_f32 v[90:91], v[90:91], v[146:147], v[206:207]
	v_pk_fma_f32 v[88:89], v[88:89], v[148:149], v[204:205]
	v_pk_fma_f32 v[110:111], v[110:111], v[158:159], v[216:217]
	v_pk_fma_f32 v[108:109], v[108:109], v[160:161], v[214:215]
	v_pk_fma_f32 v[98:99], v[98:99], v[154:155], v[224:225]
	v_pk_fma_f32 v[96:97], v[96:97], v[156:157], v[222:223]
	global_store_dwordx4 v[230:231], v[124:127], off
	global_store_dwordx4 v[230:231], v[120:123], off offset:16
	global_store_dwordx4 v[230:231], v[104:107], off offset:512
	global_store_dwordx4 v[230:231], v[100:103], off offset:528
	global_store_dwordx4 v[218:219], v[116:119], off
	global_store_dwordx4 v[218:219], v[112:115], off offset:16
	global_store_dwordx4 v[218:219], v[92:95], off offset:512
	global_store_dwordx4 v[218:219], v[88:91], off offset:528
	global_store_dwordx4 v[252:253], v[108:111], off
	global_store_dwordx4 v[252:253], v[96:99], off offset:16
	global_store_dwordx4 v[252:253], v[80:83], off offset:512
	v_pk_fma_f32 v[74:75], v[74:75], v[146:147], v[238:239]
	v_pk_fma_f32 v[72:73], v[72:73], v[148:149], v[236:237]
	v_lshl_add_u64 v[80:81], s[30:31], 0, v[212:213]
	global_store_dwordx4 v[252:253], v[72:75], off offset:528
; #define PG8_WAIT_V(n) asm volatile("s_waitcnt vmcnt(" #n ")" ::: "memory")
; #define PG8_BAR __builtin_amdgcn_s_barrier()
;     __device__ __forceinline__ void operator()(const f32x4 (&acc)[2][2][4][2], const Unit& u, int wr, int wc, int fr, int fq) const {
;     ...
;             for (int m = 0; m < 4; ++m) { const size_t off = (size_t)(row0 + ai * HALF + m * 16) * 2048 + col0;
; #pragma unroll
;                 for (int bj = 0; bj < 2; ++bj)
; #pragma unroll
;                     for (int n = 0; n < 2; ++n) r[m][bj][n] = *(const f32x4*)(res + off + bj * HALF + 4 * n); }
; #pragma unroll
;             for (int m = 0; m < 4; ++m) { const size_t off = (size_t)(row0 + ai * HALF + m * 16) * 2048 + col0;
; #pragma unroll
;                 for (int bj = 0; bj < 2; ++bj)
; #pragma unroll
;                     for (int n = 0; n < 2; ++n) *(f32x4*)(out + off + bj * HALF + 4 * n) = r[m][bj][n] + gv[bj][n] * acc[ai][bj][m][n]; } }
; template <class Epi, class Sched, bool ALIGN_EPI = false, bool SP2 = false>
; __device__ __forceinline__ void gemm_phase(PG8_LAS unsigned char* lds, const Gemm g, const Sched& S, const Epi& E) {
;     ...
;         if constexpr (!Epi::AFTER_DRAIN) { E(acc, cur, wr, wc, fr, fq); S.done(cur); }
;         if (!has_next) break;
; #pragma unroll
;         for (int a = 0; a < 2; ++a)
; #pragma unroll
;             for (int b = 0; b < 2; ++b)
; #pragma unroll
;                 for (int m = 0; m < 4; ++m)
; #pragma unroll
;                     for (int n = 0; n < 2; ++n) acc[a][b][m][n] = (f32x4){0.f, 0.f, 0.f, 0.f};
;         cur = nxt; cA = nA; cB = nB; ++ui;
;         if constexpr (ALIGN_EPI) { if (wr == 1) PG8_BAR; }
;     }
;     PG8_WAIT_V(0);
;     if constexpr (!ALIGN_EPI) { if (wr == 0) PG8_BAR; }
;     PG8_BAR;
	v_lshl_add_u64 v[80:81], v[80:81], 0, v[144:145]
	v_pk_fma_f32 v[70:71], v[70:71], v[150:151], v[250:251]
	v_pk_fma_f32 v[74:75], v[86:87], v[158:159], v[242:243]
	v_pk_fma_f32 v[72:73], v[84:85], v[160:161], v[240:241]
	global_store_dwordx4 v[80:81], v[72:75], off
	v_pk_fma_f32 v[68:69], v[68:69], v[152:153], v[248:249]
	v_pk_fma_f32 v[66:67], v[66:67], v[146:147], v[142:143]
	v_pk_fma_f32 v[74:75], v[78:79], v[154:155], v[246:247]
	v_pk_fma_f32 v[72:73], v[76:77], v[156:157], v[244:245]
	v_pk_fma_f32 v[64:65], v[64:65], v[148:149], v[140:141]
	v_lshl_add_u64 v[140:141], v[164:165], 0, s[38:39]
	v_lshl_add_u64 v[142:143], v[164:165], 0, s[40:41]
	v_lshl_add_u64 v[172:173], v[164:165], 0, s[42:43]
	global_store_dwordx4 v[80:81], v[72:75], off offset:16
	global_store_dwordx4 v[80:81], v[68:71], off offset:512
	global_store_dwordx4 v[80:81], v[64:67], off offset:528
	v_lshl_add_u64 v[76:77], v[162:163], 0, v[140:141]
	v_lshl_add_u64 v[92:93], v[162:163], 0, v[142:143]
	v_lshl_add_u64 v[108:109], v[162:163], 0, v[172:173]
	global_load_dwordx4 v[64:67], v[76:77], off
	global_load_dwordx4 v[68:71], v[76:77], off offset:16
	global_load_dwordx4 v[72:75], v[76:77], off offset:512
	s_nop 0
	global_load_dwordx4 v[76:79], v[76:77], off offset:528
	s_nop 0
	global_load_dwordx4 v[80:83], v[92:93], off
	global_load_dwordx4 v[84:87], v[92:93], off offset:16
	global_load_dwordx4 v[88:91], v[92:93], off offset:512
	s_nop 0
	global_load_dwordx4 v[92:95], v[92:93], off offset:528
	s_nop 0
	global_load_dwordx4 v[96:99], v[108:109], off
	global_load_dwordx4 v[100:103], v[108:109], off offset:16
	global_load_dwordx4 v[104:107], v[108:109], off offset:512
	s_nop 0
	global_load_dwordx4 v[108:111], v[108:109], off offset:528
	v_lshl_add_u64 v[164:165], v[164:165], 0, s[34:35]
	v_lshl_add_u64 v[124:125], v[162:163], 0, v[164:165]
	global_load_dwordx4 v[112:115], v[124:125], off
	global_load_dwordx4 v[116:119], v[124:125], off offset:16
	global_load_dwordx4 v[120:123], v[124:125], off offset:512
	s_nop 0
	global_load_dwordx4 v[124:127], v[124:125], off offset:528
	v_lshl_add_u64 v[140:141], s[30:31], 0, v[140:141]
	v_lshl_add_u64 v[162:163], s[30:31], 0, v[172:173]
	v_lshl_add_u64 v[142:143], s[30:31], 0, v[142:143]
	v_lshl_add_u64 v[140:141], v[140:141], 0, v[144:145]
	v_lshl_add_u64 v[162:163], v[162:163], 0, v[144:145]
	v_lshl_add_u64 v[142:143], v[142:143], 0, v[144:145]
	v_mov_b32_e32 v251, v220
	s_waitcnt vmcnt(15)
	v_pk_fma_f32 v[62:63], v[62:63], v[158:159], v[66:67]
	v_pk_fma_f32 v[60:61], v[60:61], v[160:161], v[64:65]
	s_waitcnt vmcnt(14)
	v_pk_fma_f32 v[58:59], v[58:59], v[154:155], v[70:71]
	v_pk_fma_f32 v[56:57], v[56:57], v[156:157], v[68:69]
	s_waitcnt vmcnt(5)
	v_pk_fma_f32 v[18:19], v[18:19], v[150:151], v[106:107]
	v_pk_fma_f32 v[16:17], v[16:17], v[152:153], v[104:105]
	v_pk_fma_f32 v[42:43], v[42:43], v[150:151], v[74:75]
	v_pk_fma_f32 v[40:41], v[40:41], v[152:153], v[72:73]
	v_pk_fma_f32 v[38:39], v[38:39], v[146:147], v[78:79]
	v_pk_fma_f32 v[36:37], v[36:37], v[148:149], v[76:77]
	v_pk_fma_f32 v[54:55], v[54:55], v[158:159], v[82:83]
	v_pk_fma_f32 v[52:53], v[52:53], v[160:161], v[80:81]
	v_pk_fma_f32 v[50:51], v[50:51], v[154:155], v[86:87]
	v_pk_fma_f32 v[48:49], v[48:49], v[156:157], v[84:85]
	v_pk_fma_f32 v[30:31], v[30:31], v[150:151], v[90:91]
	v_pk_fma_f32 v[28:29], v[28:29], v[152:153], v[88:89]
	v_pk_fma_f32 v[26:27], v[26:27], v[146:147], v[94:95]
	v_pk_fma_f32 v[24:25], v[24:25], v[148:149], v[92:93]
	v_pk_fma_f32 v[46:47], v[46:47], v[158:159], v[98:99]
	v_pk_fma_f32 v[44:45], v[44:45], v[160:161], v[96:97]
	v_pk_fma_f32 v[34:35], v[34:35], v[154:155], v[102:103]
	v_pk_fma_f32 v[32:33], v[32:33], v[156:157], v[100:101]
	global_store_dwordx4 v[140:141], v[60:63], off
	global_store_dwordx4 v[140:141], v[56:59], off offset:16
	global_store_dwordx4 v[140:141], v[40:43], off offset:512
	global_store_dwordx4 v[140:141], v[36:39], off offset:528
	global_store_dwordx4 v[142:143], v[52:55], off
	global_store_dwordx4 v[142:143], v[48:51], off offset:16
	global_store_dwordx4 v[142:143], v[28:31], off offset:512
	global_store_dwordx4 v[142:143], v[24:27], off offset:528
	global_store_dwordx4 v[162:163], v[44:47], off
	global_store_dwordx4 v[162:163], v[32:35], off offset:16
	global_store_dwordx4 v[162:163], v[16:19], off offset:512
	s_waitcnt vmcnt(15)
	v_pk_fma_f32 v[10:11], v[10:11], v[146:147], v[110:111]
	v_pk_fma_f32 v[8:9], v[8:9], v[148:149], v[108:109]
	v_lshl_add_u64 v[16:17], s[30:31], 0, v[164:165]
	global_store_dwordx4 v[162:163], v[8:11], off offset:528
	v_lshl_add_u64 v[16:17], v[16:17], 0, v[144:145]
	s_waitcnt vmcnt(13)
	v_pk_fma_f32 v[6:7], v[6:7], v[150:151], v[122:123]
	v_pk_fma_f32 v[10:11], v[22:23], v[158:159], v[114:115]
	v_pk_fma_f32 v[8:9], v[20:21], v[160:161], v[112:113]
	global_store_dwordx4 v[16:17], v[8:11], off
	v_pk_fma_f32 v[4:5], v[4:5], v[152:153], v[120:121]
	s_waitcnt vmcnt(13)
	v_pk_fma_f32 v[2:3], v[2:3], v[146:147], v[126:127]
	v_pk_fma_f32 v[10:11], v[14:15], v[154:155], v[118:119]
	v_pk_fma_f32 v[8:9], v[12:13], v[156:157], v[116:117]
	v_pk_fma_f32 v[0:1], v[0:1], v[148:149], v[124:125]
	global_store_dwordx4 v[16:17], v[8:11], off offset:16
	global_store_dwordx4 v[16:17], v[4:7], off offset:512
	global_store_dwordx4 v[16:17], v[0:3], off offset:528
	s_cbranch_vccz .LBB0_234
	s_waitcnt vmcnt(0)
	s_cmpk_gt_u32 s3, 0xff
	s_cbranch_scc1 .LBB0_249
	s_barrier

; #define PG8_STAGE(bufoff, gbase, voff) do { _Pragma("unroll") for (int _i = 0; _i < 2; ++_i) \
;         __builtin_amdgcn_global_load_lds((const unsigned*)((const char*)(gbase) + (voff)[_i]), (PG8_LAS unsigned*)(lds + (bufoff) + ldsw + _i * 8192), 16, 0, 0); } while (0)
; #define PG8_LDA(dst, b, h) do { _Pragma("unroll") for (int m = 0; m < 4; ++m) _Pragma("unroll") for (int k = 0; k < 2; ++k) dst[m][k] = *(const PG8_LAS bf16x8*)(lds + PG8_SA(b, h) + aoff + m * 2048 + k * 1024); } while (0)
; #define PG8_LDB(dst, b, h) do { _Pragma("unroll") for (int n = 0; n < 2; ++n) _Pragma("unroll") for (int k = 0; k < 2; ++k) dst[n][k] = *(const PG8_LAS bf16x8*)(lds + PG8_SB(b, h) + boff + n * 2048 + k * 1024); } while (0)
; #define PG8_MMA(ai, bj, At, Bt) do { __builtin_amdgcn_s_setprio(1); _Pragma("unroll") for (int m = 0; m < 4; ++m) _Pragma("unroll") for (int n = 0; n < 2; ++n) _Pragma("unroll") for (int k = 0; k < 2; ++k) \
;         acc[ai][bj][m][n] = __builtin_amdgcn_mfma_f32_16x16x32_bf16(Bt[n][k], At[m][k], acc[ai][bj][m][n], 0, 0, 0); __builtin_amdgcn_s_setprio(0); } while (0)
; #define PG8_WAIT_V(n) asm volatile("s_waitcnt vmcnt(" #n ")" ::: "memory")
; #define PG8_WAIT_L(n) asm volatile("s_waitcnt lgkmcnt(" #n ")" ::: "memory")
; #define PG8_BAR __builtin_amdgcn_s_barrier()
; #define PG8_SCHED __builtin_amdgcn_sched_barrier(0)
; template <class Epi, class Sched, bool ALIGN_EPI = false, bool SP2 = false>
; __device__ __forceinline__ void gemm_phase(PG8_LAS unsigned char* lds, const Gemm g, const Sched& S, const Epi& E) {
;     ...
;             PG8_LDB(B0, 0, 0); PG8_LDB(B1, 0, 1); PG8_SCHED; PG8_LDA(At, 0, 0); PG8_STAGE(PG8_SA(1, 1), a1 + hstep, voffA);
;             PG8_WAIT_V(8); PG8_WAIT_L(0); PG8_BAR; PG8_MMA(0, 0, At, B0); PG8_MMA(0, 1, At, B1); PG8_BAR; PG8_SCHED;
;             PG8_LDA(At, 0, 1); PG8_STAGE(PG8_SB(0, 0), b2, voffB); PG8_STAGE(PG8_SB(0, 1), b2 + hstep, voffB); PG8_STAGE(PG8_SA(0, 0), a2, voffA);
;             PG8_WAIT_V(8); PG8_WAIT_L(0); PG8_BAR; PG8_MMA(1, 0, At, B0); PG8_MMA(1, 1, At, B1); PG8_BAR; PG8_SCHED;
.LBB0_364:
	ds_read_b128 v[128:131], v214
	ds_read_b128 v[132:135], v214 offset:1024
	ds_read_b128 v[136:139], v214 offset:2048
	ds_read_b128 v[140:143], v214 offset:3072
	ds_read_b128 v[144:147], v215
	ds_read_b128 v[148:151], v215 offset:1024
	ds_read_b128 v[152:155], v215 offset:2048
	ds_read_b128 v[156:159], v215 offset:3072
	s_add_u32 s58, s84, 0xfff80080
	s_addc_u32 s59, s85, -1
	s_cmp_eq_u32 s39, 28
	s_cselect_b32 s89, s77, s59
	s_cselect_b32 s88, s83, s58
	s_cselect_b32 s87, s75, s38
	s_cselect_b32 s86, vcc_lo, vcc_hi
	s_add_i32 m0, s7, 0xc000
	ds_read_b128 v[160:163], v216
	ds_read_b128 v[182:185], v216 offset:1024
	ds_read_b128 v[186:189], v216 offset:2048
	ds_read_b128 v[190:193], v216 offset:3072
	ds_read_b128 v[222:225], v216 offset:4096
	ds_read_b128 v[232:235], v216 offset:5120
	ds_read_b128 v[236:239], v216 offset:6144
	ds_read_b128 v[240:243], v216 offset:7168
	global_load_lds_dwordx4 v174, s[84:85]
	s_add_i32 m0, s7, 0xe000
	s_nop 0
	global_load_lds_dwordx4 v176, s[84:85]
	s_waitcnt vmcnt(8)
	s_waitcnt lgkmcnt(0)
	s_barrier
	s_waitcnt lgkmcnt(0)
	v_mfma_f32_16x16x32_bf16 v[124:127], v[128:131], v[160:163], v[124:127]
	v_mfma_f32_16x16x32_bf16 v[120:123], v[136:139], v[160:163], v[120:123]
	v_mfma_f32_16x16x32_bf16 v[116:119], v[128:131], v[186:189], v[116:119]
	v_mfma_f32_16x16x32_bf16 v[112:115], v[136:139], v[186:189], v[112:115]
	v_mfma_f32_16x16x32_bf16 v[100:103], v[128:131], v[222:225], v[100:103]
	v_mfma_f32_16x16x32_bf16 v[96:99], v[136:139], v[222:225], v[96:99]
	v_mfma_f32_16x16x32_bf16 v[84:87], v[128:131], v[236:239], v[84:87]
	v_mfma_f32_16x16x32_bf16 v[80:83], v[136:139], v[236:239], v[80:83]
	v_mfma_f32_16x16x32_bf16 v[124:127], v[132:135], v[182:185], v[124:127]
	v_mfma_f32_16x16x32_bf16 v[120:123], v[140:143], v[182:185], v[120:123]
	v_mfma_f32_16x16x32_bf16 v[116:119], v[132:135], v[190:193], v[116:119]
	v_mfma_f32_16x16x32_bf16 v[112:115], v[140:143], v[190:193], v[112:115]
	v_mfma_f32_16x16x32_bf16 v[100:103], v[132:135], v[232:235], v[100:103]
	v_mfma_f32_16x16x32_bf16 v[96:99], v[140:143], v[232:235], v[96:99]
	v_mfma_f32_16x16x32_bf16 v[84:87], v[132:135], v[240:243], v[84:87]
	v_mfma_f32_16x16x32_bf16 v[80:83], v[140:143], v[240:243], v[80:83]
	v_mfma_f32_16x16x32_bf16 v[108:111], v[144:147], v[160:163], v[108:111]
	v_mfma_f32_16x16x32_bf16 v[104:107], v[152:155], v[160:163], v[104:107]
	v_mfma_f32_16x16x32_bf16 v[92:95], v[144:147], v[186:189], v[92:95]
	v_mfma_f32_16x16x32_bf16 v[88:91], v[152:155], v[186:189], v[88:91]
	v_mfma_f32_16x16x32_bf16 v[76:79], v[144:147], v[222:225], v[76:79]
	v_mfma_f32_16x16x32_bf16 v[72:75], v[152:155], v[222:225], v[72:75]
	v_mfma_f32_16x16x32_bf16 v[68:71], v[144:147], v[236:239], v[68:71]
	v_mfma_f32_16x16x32_bf16 v[64:67], v[152:155], v[236:239], v[64:67]
	v_mfma_f32_16x16x32_bf16 v[108:111], v[148:151], v[182:185], v[108:111]
	v_mfma_f32_16x16x32_bf16 v[104:107], v[156:159], v[182:185], v[104:107]
	v_mfma_f32_16x16x32_bf16 v[92:95], v[148:151], v[190:193], v[92:95]
	v_mfma_f32_16x16x32_bf16 v[88:91], v[156:159], v[190:193], v[88:91]
	v_mfma_f32_16x16x32_bf16 v[76:79], v[148:151], v[232:235], v[76:79]
	v_mfma_f32_16x16x32_bf16 v[72:75], v[156:159], v[232:235], v[72:75]
	v_mfma_f32_16x16x32_bf16 v[68:71], v[148:151], v[240:243], v[68:71]
	v_mfma_f32_16x16x32_bf16 v[64:67], v[156:159], v[240:243], v[64:67]
	s_barrier
	s_add_i32 s58, s34, s24
	v_lshl_add_u64 v[194:195], s[86:87], 0, v[168:169]
	s_mov_b32 m0, s58
	ds_read_b128 v[160:163], v216 offset:16384
	ds_read_b128 v[182:185], v216 offset:17408
	ds_read_b128 v[186:189], v216 offset:18432
	ds_read_b128 v[190:193], v216 offset:19456
	ds_read_b128 v[222:225], v216 offset:20480
	ds_read_b128 v[232:235], v216 offset:21504
	ds_read_b128 v[236:239], v216 offset:22528
	ds_read_b128 v[240:243], v216 offset:23552
	global_load_lds_dwordx4 v168, s[86:87]
	s_add_i32 m0, s58, 0x2000
	s_add_u32 s58, s86, 0x80000
	v_lshl_add_u64 v[230:231], s[86:87], 0, v[164:165]
	s_addc_u32 s59, s87, 0
	s_add_i32 s48, s35, s24
	global_load_lds_dwordx4 v164, s[86:87]
	s_mov_b32 m0, s48
	v_lshl_add_u64 v[246:247], s[88:89], 0, v[166:167]
	global_load_lds_dwordx4 v168, s[58:59]
	s_add_i32 m0, s48, 0x2000
	s_nop 0
	global_load_lds_dwordx4 v164, s[58:59]
	v_lshl_add_u64 v[244:245], s[88:89], 0, v[170:171]
	s_mov_b32 m0, s7
	s_nop 0
	global_load_lds_dwordx4 v170, s[88:89]
	s_mov_b32 m0, s8
	s_nop 0
	global_load_lds_dwordx4 v166, s[88:89]
	s_waitcnt vmcnt(8)
	s_waitcnt lgkmcnt(0)
	s_barrier
	s_waitcnt lgkmcnt(0)
	v_mfma_f32_16x16x32_bf16 v[60:63], v[128:131], v[160:163], v[60:63]
	v_mfma_f32_16x16x32_bf16 v[56:59], v[136:139], v[160:163], v[56:59]
	v_mfma_f32_16x16x32_bf16 v[52:55], v[128:131], v[186:189], v[52:55]
	v_mfma_f32_16x16x32_bf16 v[48:51], v[136:139], v[186:189], v[48:51]
	v_mfma_f32_16x16x32_bf16 v[36:39], v[128:131], v[222:225], v[36:39]
	v_mfma_f32_16x16x32_bf16 v[32:35], v[136:139], v[222:225], v[32:35]
	v_mfma_f32_16x16x32_bf16 v[20:23], v[128:131], v[236:239], v[20:23]
	v_mfma_f32_16x16x32_bf16 v[16:19], v[136:139], v[236:239], v[16:19]
	v_mfma_f32_16x16x32_bf16 v[60:63], v[132:135], v[182:185], v[60:63]
	v_mfma_f32_16x16x32_bf16 v[56:59], v[140:143], v[182:185], v[56:59]
	v_mfma_f32_16x16x32_bf16 v[52:55], v[132:135], v[190:193], v[52:55]
	v_mfma_f32_16x16x32_bf16 v[48:51], v[140:143], v[190:193], v[48:51]
	v_mfma_f32_16x16x32_bf16 v[36:39], v[132:135], v[232:235], v[36:39]
	v_mfma_f32_16x16x32_bf16 v[32:35], v[140:143], v[232:235], v[32:35]
	v_mfma_f32_16x16x32_bf16 v[20:23], v[132:135], v[240:243], v[20:23]
	v_mfma_f32_16x16x32_bf16 v[16:19], v[140:143], v[240:243], v[16:19]
	v_mfma_f32_16x16x32_bf16 v[44:47], v[144:147], v[160:163], v[44:47]
	v_mfma_f32_16x16x32_bf16 v[40:43], v[152:155], v[160:163], v[40:43]
	v_mfma_f32_16x16x32_bf16 v[28:31], v[144:147], v[186:189], v[28:31]
	v_mfma_f32_16x16x32_bf16 v[24:27], v[152:155], v[186:189], v[24:27]
	v_mfma_f32_16x16x32_bf16 v[12:15], v[144:147], v[222:225], v[12:15]
	v_mfma_f32_16x16x32_bf16 v[8:11], v[152:155], v[222:225], v[8:11]
	v_mfma_f32_16x16x32_bf16 v[4:7], v[144:147], v[236:239], v[4:7]
	v_mfma_f32_16x16x32_bf16 v[0:3], v[152:155], v[236:239], v[0:3]
	v_mfma_f32_16x16x32_bf16 v[44:47], v[148:151], v[182:185], v[44:47]
	v_mfma_f32_16x16x32_bf16 v[40:43], v[156:159], v[182:185], v[40:43]
	v_mfma_f32_16x16x32_bf16 v[28:31], v[148:151], v[190:193], v[28:31]
	v_mfma_f32_16x16x32_bf16 v[24:27], v[156:159], v[190:193], v[24:27]
	v_mfma_f32_16x16x32_bf16 v[12:15], v[148:151], v[232:235], v[12:15]
	v_mfma_f32_16x16x32_bf16 v[8:11], v[156:159], v[232:235], v[8:11]
	v_mfma_f32_16x16x32_bf16 v[4:7], v[148:151], v[240:243], v[4:7]
	v_mfma_f32_16x16x32_bf16 v[0:3], v[156:159], v[240:243], v[0:3]
	s_barrier
; #define PG8_STAGE(bufoff, gbase, voff) do { _Pragma("unroll") for (int _i = 0; _i < 2; ++_i) \
;         __builtin_amdgcn_global_load_lds((const unsigned*)((const char*)(gbase) + (voff)[_i]), (PG8_LAS unsigned*)(lds + (bufoff) + ldsw + _i * 8192), 16, 0, 0); } while (0)
; #define PG8_LDA(dst, b, h) do { _Pragma("unroll") for (int m = 0; m < 4; ++m) _Pragma("unroll") for (int k = 0; k < 2; ++k) dst[m][k] = *(const PG8_LAS bf16x8*)(lds + PG8_SA(b, h) + aoff + m * 2048 + k * 1024); } while (0)
; #define PG8_LDB(dst, b, h) do { _Pragma("unroll") for (int n = 0; n < 2; ++n) _Pragma("unroll") for (int k = 0; k < 2; ++k) dst[n][k] = *(const PG8_LAS bf16x8*)(lds + PG8_SB(b, h) + boff + n * 2048 + k * 1024); } while (0)
; #define PG8_MMA(ai, bj, At, Bt) do { __builtin_amdgcn_s_setprio(1); _Pragma("unroll") for (int m = 0; m < 4; ++m) _Pragma("unroll") for (int n = 0; n < 2; ++n) _Pragma("unroll") for (int k = 0; k < 2; ++k) \
;         acc[ai][bj][m][n] = __builtin_amdgcn_mfma_f32_16x16x32_bf16(Bt[n][k], At[m][k], acc[ai][bj][m][n], 0, 0, 0); __builtin_amdgcn_s_setprio(0); } while (0)
; #define PG8_WAIT_V(n) asm volatile("s_waitcnt vmcnt(" #n ")" ::: "memory")
; #define PG8_WAIT_L(n) asm volatile("s_waitcnt lgkmcnt(" #n ")" ::: "memory")
; #define PG8_BAR __builtin_amdgcn_s_barrier()
; #define PG8_SCHED __builtin_amdgcn_sched_barrier(0)
; template <class Epi, class Sched, bool ALIGN_EPI = false, bool SP2 = false>
; __device__ __forceinline__ void gemm_phase(PG8_LAS unsigned char* lds, const Gemm g, const Sched& S, const Epi& E) {
;     ...
;             PG8_LDB(B0, 1, 0); PG8_LDB(B1, 1, 1); PG8_SCHED; PG8_LDA(At, 1, 0); PG8_STAGE(PG8_SA(0, 1), a2 + hstep, voffA);
;             PG8_WAIT_V(8); PG8_WAIT_L(0); PG8_BAR; PG8_MMA(0, 0, At, B0); PG8_MMA(0, 1, At, B1); PG8_BAR; PG8_SCHED;
;             PG8_LDA(At, 1, 1); PG8_STAGE(PG8_SB(1, 0), b3, voffB); PG8_STAGE(PG8_SB(1, 1), b3 + hstep, voffB); PG8_STAGE(PG8_SA(1, 0), a3, voffA);
;             PG8_WAIT_V(8); PG8_WAIT_L(0); PG8_BAR; PG8_MMA(1, 0, At, B0); PG8_MMA(1, 1, At, B1); PG8_BAR; PG8_SCHED;
	s_add_i32 s48, 0, 0x18000
	s_add_i32 s60, 0, 0x1c000
	v_add_u32_e32 v140, s48, v197
	v_add_u32_e32 v156, s60, v197
	ds_read_b128 v[128:131], v140
	ds_read_b128 v[132:135], v140 offset:1024
	ds_read_b128 v[136:139], v140 offset:2048
	ds_read_b128 v[140:143], v140 offset:3072
	ds_read_b128 v[144:147], v156
	ds_read_b128 v[148:151], v156 offset:1024
	ds_read_b128 v[152:155], v156 offset:2048
	ds_read_b128 v[156:159], v156 offset:3072
	s_add_u32 s58, s88, 0x80000
	s_addc_u32 s59, s89, 0
	s_mov_b32 m0, s9
	ds_read_b128 v[160:163], v216 offset:32768
	ds_read_b128 v[182:185], v216 offset:33792
	ds_read_b128 v[186:189], v216 offset:34816
	ds_read_b128 v[190:193], v216 offset:35840
	ds_read_b128 v[222:225], v216 offset:36864
	ds_read_b128 v[232:235], v216 offset:37888
	ds_read_b128 v[236:239], v216 offset:38912
	ds_read_b128 v[240:243], v216 offset:39936
	global_load_lds_dwordx4 v170, s[58:59]
	s_mov_b32 m0, s26
	s_nop 0
	global_load_lds_dwordx4 v166, s[58:59]
	s_waitcnt vmcnt(8)
	s_waitcnt lgkmcnt(0)
	s_barrier
	s_waitcnt lgkmcnt(0)
	v_mfma_f32_16x16x32_bf16 v[124:127], v[128:131], v[160:163], v[124:127]
	v_mfma_f32_16x16x32_bf16 v[120:123], v[136:139], v[160:163], v[120:123]
	v_mfma_f32_16x16x32_bf16 v[116:119], v[128:131], v[186:189], v[116:119]
	v_mfma_f32_16x16x32_bf16 v[112:115], v[136:139], v[186:189], v[112:115]
	v_mfma_f32_16x16x32_bf16 v[100:103], v[128:131], v[222:225], v[100:103]
	v_mfma_f32_16x16x32_bf16 v[96:99], v[136:139], v[222:225], v[96:99]
	v_mfma_f32_16x16x32_bf16 v[84:87], v[128:131], v[236:239], v[84:87]
	v_mfma_f32_16x16x32_bf16 v[80:83], v[136:139], v[236:239], v[80:83]
	v_mfma_f32_16x16x32_bf16 v[124:127], v[132:135], v[182:185], v[124:127]
	v_mfma_f32_16x16x32_bf16 v[120:123], v[140:143], v[182:185], v[120:123]
	v_mfma_f32_16x16x32_bf16 v[116:119], v[132:135], v[190:193], v[116:119]
	v_mfma_f32_16x16x32_bf16 v[112:115], v[140:143], v[190:193], v[112:115]
	v_mfma_f32_16x16x32_bf16 v[100:103], v[132:135], v[232:235], v[100:103]
	v_mfma_f32_16x16x32_bf16 v[96:99], v[140:143], v[232:235], v[96:99]
	v_mfma_f32_16x16x32_bf16 v[84:87], v[132:135], v[240:243], v[84:87]
	v_mfma_f32_16x16x32_bf16 v[80:83], v[140:143], v[240:243], v[80:83]
	v_mfma_f32_16x16x32_bf16 v[108:111], v[144:147], v[160:163], v[108:111]
	v_mfma_f32_16x16x32_bf16 v[104:107], v[152:155], v[160:163], v[104:107]
	v_mfma_f32_16x16x32_bf16 v[92:95], v[144:147], v[186:189], v[92:95]
	v_mfma_f32_16x16x32_bf16 v[88:91], v[152:155], v[186:189], v[88:91]
	v_mfma_f32_16x16x32_bf16 v[76:79], v[144:147], v[222:225], v[76:79]
	v_mfma_f32_16x16x32_bf16 v[72:75], v[152:155], v[222:225], v[72:75]
	v_mfma_f32_16x16x32_bf16 v[68:71], v[144:147], v[236:239], v[68:71]
	v_mfma_f32_16x16x32_bf16 v[64:67], v[152:155], v[236:239], v[64:67]
	v_mfma_f32_16x16x32_bf16 v[108:111], v[148:151], v[182:185], v[108:111]
	v_mfma_f32_16x16x32_bf16 v[104:107], v[156:159], v[182:185], v[104:107]
	v_mfma_f32_16x16x32_bf16 v[92:95], v[148:151], v[190:193], v[92:95]
	v_mfma_f32_16x16x32_bf16 v[88:91], v[156:159], v[190:193], v[88:91]
	v_mfma_f32_16x16x32_bf16 v[76:79], v[148:151], v[232:235], v[76:79]
	v_mfma_f32_16x16x32_bf16 v[72:75], v[156:159], v[232:235], v[72:75]
	v_mfma_f32_16x16x32_bf16 v[68:71], v[148:151], v[240:243], v[68:71]
	v_mfma_f32_16x16x32_bf16 v[64:67], v[156:159], v[240:243], v[64:67]
	s_barrier
	s_add_i32 s48, s48, s24
	v_lshl_add_u64 v[194:195], v[194:195], 0, s[54:55]
	s_mov_b32 m0, s48
	ds_read_b128 v[160:163], v216 offset:49152
	ds_read_b128 v[182:185], v216 offset:50176
	ds_read_b128 v[186:189], v216 offset:51200
	ds_read_b128 v[190:193], v216 offset:52224
	ds_read_b128 v[222:225], v216 offset:53248
	ds_read_b128 v[232:235], v216 offset:54272
	ds_read_b128 v[236:239], v216 offset:55296
	ds_read_b128 v[240:243], v216 offset:56320
	global_load_lds_dwordx4 v[194:195], off
	s_add_i32 m0, s48, 0x2000
	s_add_u32 s58, s86, 0x80080
	v_lshl_add_u64 v[194:195], v[230:231], 0, s[54:55]
	s_addc_u32 s59, s87, 0
	s_add_i32 s48, s60, s24
	global_load_lds_dwordx4 v[194:195], off
	s_mov_b32 m0, s48
	s_nop 0
	global_load_lds_dwordx4 v168, s[58:59]
	s_add_i32 m0, s48, 0x2000
	s_nop 0
	global_load_lds_dwordx4 v164, s[58:59]
	v_lshl_add_u64 v[194:195], v[244:245], 0, s[54:55]
	s_mov_b32 m0, s36
	s_nop 0
	global_load_lds_dwordx4 v[194:195], off
	v_lshl_add_u64 v[194:195], v[246:247], 0, s[54:55]
	s_mov_b32 m0, s37
	s_nop 0
	global_load_lds_dwordx4 v[194:195], off
	s_waitcnt vmcnt(8)
	s_waitcnt lgkmcnt(0)
	s_barrier
	s_waitcnt lgkmcnt(0)
	v_mfma_f32_16x16x32_bf16 v[60:63], v[128:131], v[160:163], v[60:63]
	v_mfma_f32_16x16x32_bf16 v[56:59], v[136:139], v[160:163], v[56:59]
	v_mfma_f32_16x16x32_bf16 v[52:55], v[128:131], v[186:189], v[52:55]
	v_mfma_f32_16x16x32_bf16 v[48:51], v[136:139], v[186:189], v[48:51]
	v_mfma_f32_16x16x32_bf16 v[36:39], v[128:131], v[222:225], v[36:39]
	v_mfma_f32_16x16x32_bf16 v[32:35], v[136:139], v[222:225], v[32:35]
	v_mfma_f32_16x16x32_bf16 v[20:23], v[128:131], v[236:239], v[20:23]
	v_mfma_f32_16x16x32_bf16 v[16:19], v[136:139], v[236:239], v[16:19]
	v_mfma_f32_16x16x32_bf16 v[60:63], v[132:135], v[182:185], v[60:63]
	v_mfma_f32_16x16x32_bf16 v[56:59], v[140:143], v[182:185], v[56:59]
	v_mfma_f32_16x16x32_bf16 v[52:55], v[132:135], v[190:193], v[52:55]
	v_mfma_f32_16x16x32_bf16 v[48:51], v[140:143], v[190:193], v[48:51]
	v_mfma_f32_16x16x32_bf16 v[36:39], v[132:135], v[232:235], v[36:39]
	v_mfma_f32_16x16x32_bf16 v[32:35], v[140:143], v[232:235], v[32:35]
	v_mfma_f32_16x16x32_bf16 v[20:23], v[132:135], v[240:243], v[20:23]
	v_mfma_f32_16x16x32_bf16 v[16:19], v[140:143], v[240:243], v[16:19]
	v_mfma_f32_16x16x32_bf16 v[44:47], v[144:147], v[160:163], v[44:47]
	v_mfma_f32_16x16x32_bf16 v[40:43], v[152:155], v[160:163], v[40:43]
	v_mfma_f32_16x16x32_bf16 v[28:31], v[144:147], v[186:189], v[28:31]
	v_mfma_f32_16x16x32_bf16 v[24:27], v[152:155], v[186:189], v[24:27]
	v_mfma_f32_16x16x32_bf16 v[12:15], v[144:147], v[222:225], v[12:15]
	v_mfma_f32_16x16x32_bf16 v[8:11], v[152:155], v[222:225], v[8:11]
	v_mfma_f32_16x16x32_bf16 v[4:7], v[144:147], v[236:239], v[4:7]
	v_mfma_f32_16x16x32_bf16 v[0:3], v[152:155], v[236:239], v[0:3]
	v_mfma_f32_16x16x32_bf16 v[44:47], v[148:151], v[182:185], v[44:47]
	v_mfma_f32_16x16x32_bf16 v[40:43], v[156:159], v[182:185], v[40:43]
	v_mfma_f32_16x16x32_bf16 v[28:31], v[148:151], v[190:193], v[28:31]
	v_mfma_f32_16x16x32_bf16 v[24:27], v[156:159], v[190:193], v[24:27]
	v_mfma_f32_16x16x32_bf16 v[12:15], v[148:151], v[232:235], v[12:15]
	v_mfma_f32_16x16x32_bf16 v[8:11], v[156:159], v[232:235], v[8:11]
	v_mfma_f32_16x16x32_bf16 v[4:7], v[148:151], v[240:243], v[4:7]
	v_mfma_f32_16x16x32_bf16 v[0:3], v[156:159], v[240:243], v[0:3]
	s_barrier
; __device__ __forceinline__ float fsigmoid(float v) { return __builtin_amdgcn_rcpf(1.0f + __builtin_amdgcn_exp2f(-LOG2E * v)); }
; __device__ __forceinline__ float fsilu(float v) { return v * fsigmoid(v); }
; __device__ __forceinline__ u32x4 pack8(const f32x4 a, const f32x4 b) { u32x4 w; w.x = cvt_pk_bf16(a[0], a[1]); w.y = cvt_pk_bf16(a[2], a[3]); w.z = cvt_pk_bf16(b[0], b[1]); w.w = cvt_pk_bf16(b[2], b[3]); return w; }
;     template <int ACT> __device__ __forceinline__ void ew(const f32x4 (&acc)[2][2][4][2], bf16_t* D, int ld, int row0, int col0) const {
; #pragma unroll
;         for (int ai = 0; ai < 2; ++ai)
; #pragma unroll
;             for (int m = 0; m < 4; ++m) { bf16_t* rowp = D + (size_t)(row0 + ai * HALF + m * 16) * ld + col0;
; #pragma unroll
;                 for (int bj = 0; bj < 2; ++bj) { f32x4 v0 = acc[ai][bj][m][0], v1 = acc[ai][bj][m][1];
;                     if (ACT == 1) {
; #pragma unroll
;                         for (int j = 0; j < 4; ++j) { v0[j] = fsilu(v0[j]); v1[j] = fsilu(v1[j]); } }
;                     if (ACT == 2) {
; #pragma unroll
;                         for (int j = 0; j < 4; ++j) { v0[j] = fsigmoid(v0[j]); v1[j] = fsigmoid(v1[j]); } }
;                     *(u32x4*)(rowp + bj * HALF) = pack8(v0, v1); } }
;     }
;     __device__ __forceinline__ void operator()(const f32x4 (&acc)[2][2][4][2], const Unit& u, int wr, int wc, int fr, int fq) const {
;     ...
;         else if (pn < 36) ew<2>(acc, SGA, 2048, row0, (pn - 28) * 256 + cl);
;         else ew<2>(acc, SGB, 2048, row0, (pn - 36) * 256 + cl);
	s_add_i32 s39, s39, 2
	s_add_u32 s84, s84, 0x100
	s_addc_u32 s85, s85, 0
	s_add_u32 vcc_hi, vcc_hi, 0x100
	s_addc_u32 s38, s38, 0
	s_cmp_gt_u32 s39, 29
	s_cbranch_scc0 .LBB0_364
	v_lshl_add_u32 v182, s82, 8, v196
	s_cmp_gt_i32 s23, 3
	s_mov_b64 s[82:83], -1
	s_cbranch_scc0 .LBB0_391
	s_cmp_gt_u32 s23, 7
	s_cbranch_scc0 .LBB0_388
	s_cmp_gt_u32 s23, 11
	s_cbranch_scc0 .LBB0_385
	s_cmp_gt_u32 s23, 15
	s_cbranch_scc0 .LBB0_382
	s_cmp_gt_u32 s23, 23
	s_cbranch_scc0 .LBB0_379
	s_lshl_b32 s75, s23, 8
	s_cmp_gt_u32 s23, 27
	s_cbranch_scc0 .LBB0_376
	v_mul_f32_e32 v129, 0xbfb8aa3b, v120
	v_exp_f32_e32 v129, v129
	v_mul_f32_e32 v130, 0xbfb8aa3b, v125
	v_mul_f32_e32 v131, 0xbfb8aa3b, v121
	v_exp_f32_e32 v130, v130
	v_exp_f32_e32 v131, v131
	v_add_f32_e32 v129, 1.0, v129
	v_mul_f32_e32 v128, 0xbfb8aa3b, v124
	v_rcp_f32_e32 v132, v129
	v_add_f32_e32 v129, 1.0, v130
	v_add_f32_e32 v130, 1.0, v131
	v_mul_f32_e32 v131, 0xbfb8aa3b, v126
	v_mul_f32_e32 v134, 0xbfb8aa3b, v127
	v_exp_f32_e32 v128, v128
	v_exp_f32_e32 v131, v131
	v_exp_f32_e32 v134, v134
	v_rcp_f32_e32 v129, v129
	v_add_f32_e32 v128, 1.0, v128
	v_add_f32_e32 v131, 1.0, v131
	v_add_f32_e32 v134, 1.0, v134
	v_rcp_f32_e32 v128, v128
	v_mul_f32_e32 v133, 0xbfb8aa3b, v122
	v_rcp_f32_e32 v131, v131
	v_mul_f32_e32 v135, 0xbfb8aa3b, v123
	v_rcp_f32_e32 v134, v134
	v_exp_f32_e32 v133, v133
	v_rcp_f32_e32 v130, v130
	v_exp_f32_e32 v135, v135
	v_cvt_pk_bf16_f32 v128, v128, v129
	v_cvt_pk_bf16_f32 v129, v131, v134
	v_mul_f32_e32 v131, 0xbfb8aa3b, v108
	v_add_f32_e32 v133, 1.0, v133
	v_add_f32_e32 v135, 1.0, v135
	v_cvt_pk_bf16_f32 v130, v132, v130
	v_exp_f32_e32 v132, v131
	v_mul_f32_e32 v131, 0xbfb8aa3b, v104
	v_rcp_f32_e32 v133, v133
	v_rcp_f32_e32 v135, v135
	v_exp_f32_e32 v134, v131
	v_mul_f32_e32 v137, 0xbfb8aa3b, v106
	v_mul_f32_e32 v138, 0xbfb8aa3b, v111
	v_cvt_pk_bf16_f32 v131, v133, v135
	v_add_f32_e32 v133, 1.0, v134
	v_mul_f32_e32 v134, 0xbfb8aa3b, v109
	v_mul_f32_e32 v135, 0xbfb8aa3b, v105
	v_exp_f32_e32 v134, v134
	v_exp_f32_e32 v135, v135
	v_rcp_f32_e32 v136, v133
	v_mul_f32_e32 v139, 0xbfb8aa3b, v107
	v_add_f32_e32 v133, 1.0, v134
	v_add_f32_e32 v134, 1.0, v135
	v_mul_f32_e32 v135, 0xbfb8aa3b, v110
	v_exp_f32_e32 v135, v135
	v_exp_f32_e32 v137, v137
	v_exp_f32_e32 v138, v138
	v_exp_f32_e32 v139, v139
	v_add_f32_e32 v132, 1.0, v132
	v_add_f32_e32 v135, 1.0, v135
	v_add_f32_e32 v137, 1.0, v137
	v_add_f32_e32 v138, 1.0, v138
	v_add_f32_e32 v139, 1.0, v139
	v_rcp_f32_e32 v132, v132
	v_rcp_f32_e32 v133, v133
	v_rcp_f32_e32 v135, v135
	v_rcp_f32_e32 v137, v137
	v_rcp_f32_e32 v138, v138
	v_rcp_f32_e32 v139, v139
	v_rcp_f32_e32 v134, v134
	v_cvt_pk_bf16_f32 v132, v132, v133
	v_cvt_pk_bf16_f32 v133, v135, v138
	v_cvt_pk_bf16_f32 v135, v137, v139
	v_mul_f32_e32 v138, 0xbfb8aa3b, v116
	v_mul_f32_e32 v139, 0xbfb8aa3b, v112
	v_exp_f32_e32 v138, v138
	v_exp_f32_e32 v139, v139
	v_cvt_pk_bf16_f32 v134, v136, v134
	v_or_b32_e32 v136, 16, v182
	v_ashrrev_i32_e32 v137, 31, v136
	v_lshlrev_b64 v[186:187], 12, v[136:137]
	v_add_f32_e32 v136, 1.0, v138
	v_add_f32_e32 v137, 1.0, v139
	v_mul_f32_e32 v138, 0xbfb8aa3b, v117
	v_mul_f32_e32 v139, 0xbfb8aa3b, v113
	v_exp_f32_e32 v138, v138
	v_exp_f32_e32 v139, v139
	v_rcp_f32_e32 v140, v137
	v_mul_f32_e32 v142, 0xbfb8aa3b, v119
	v_add_f32_e32 v137, 1.0, v138
	v_add_f32_e32 v138, 1.0, v139
	v_mul_f32_e32 v139, 0xbfb8aa3b, v118
	v_exp_f32_e32 v139, v139
	v_exp_f32_e32 v142, v142
	v_rcp_f32_e32 v136, v136
	v_rcp_f32_e32 v137, v137
	v_add_f32_e32 v139, 1.0, v139
	v_add_f32_e32 v142, 1.0, v142
	v_mul_f32_e32 v141, 0xbfb8aa3b, v114
	v_rcp_f32_e32 v139, v139
	v_mul_f32_e32 v143, 0xbfb8aa3b, v115
	v_rcp_f32_e32 v142, v142
	v_exp_f32_e32 v141, v141
	v_rcp_f32_e32 v138, v138
	v_exp_f32_e32 v143, v143
	v_cvt_pk_bf16_f32 v136, v136, v137
	v_cvt_pk_bf16_f32 v137, v139, v142
	v_mul_f32_e32 v139, 0xbfb8aa3b, v92
	v_add_f32_e32 v141, 1.0, v141
	v_add_f32_e32 v143, 1.0, v143
	v_cvt_pk_bf16_f32 v138, v140, v138
	v_exp_f32_e32 v140, v139
	v_mul_f32_e32 v139, 0xbfb8aa3b, v88
	v_rcp_f32_e32 v141, v141
	v_rcp_f32_e32 v143, v143
	v_exp_f32_e32 v142, v139
	v_mul_f32_e32 v145, 0xbfb8aa3b, v90
	v_mul_f32_e32 v146, 0xbfb8aa3b, v95
	v_cvt_pk_bf16_f32 v139, v141, v143
	v_add_f32_e32 v141, 1.0, v142
	v_mul_f32_e32 v142, 0xbfb8aa3b, v93
	v_mul_f32_e32 v143, 0xbfb8aa3b, v89
	v_exp_f32_e32 v142, v142
	v_exp_f32_e32 v143, v143
	v_rcp_f32_e32 v144, v141
	v_mul_f32_e32 v147, 0xbfb8aa3b, v91
	v_add_f32_e32 v141, 1.0, v142
	v_add_f32_e32 v142, 1.0, v143
	v_mul_f32_e32 v143, 0xbfb8aa3b, v94
	v_exp_f32_e32 v143, v143
	v_exp_f32_e32 v145, v145
	v_exp_f32_e32 v146, v146
	v_exp_f32_e32 v147, v147
	v_add_f32_e32 v140, 1.0, v140
	v_add_f32_e32 v143, 1.0, v143
	v_add_f32_e32 v145, 1.0, v145
	v_add_f32_e32 v146, 1.0, v146
	v_add_f32_e32 v147, 1.0, v147
	v_rcp_f32_e32 v140, v140
	v_rcp_f32_e32 v141, v141
	v_rcp_f32_e32 v143, v143
	v_rcp_f32_e32 v145, v145
	v_rcp_f32_e32 v146, v146
	v_rcp_f32_e32 v147, v147
	v_rcp_f32_e32 v142, v142
	v_cvt_pk_bf16_f32 v140, v140, v141
	v_cvt_pk_bf16_f32 v141, v143, v146
	v_cvt_pk_bf16_f32 v143, v145, v147
	v_mul_f32_e32 v146, 0xbfb8aa3b, v100
	v_mul_f32_e32 v147, 0xbfb8aa3b, v96
	v_exp_f32_e32 v146, v146
	v_exp_f32_e32 v147, v147
	v_cvt_pk_bf16_f32 v142, v144, v142
	v_or_b32_e32 v144, 32, v182
	v_ashrrev_i32_e32 v145, 31, v144
	v_lshlrev_b64 v[188:189], 12, v[144:145]
	v_add_f32_e32 v144, 1.0, v146
	v_add_f32_e32 v145, 1.0, v147
	v_mul_f32_e32 v146, 0xbfb8aa3b, v101
	v_mul_f32_e32 v147, 0xbfb8aa3b, v97
	v_exp_f32_e32 v146, v146
	v_exp_f32_e32 v147, v147
	v_rcp_f32_e32 v148, v145
	v_mul_f32_e32 v150, 0xbfb8aa3b, v103
	v_add_f32_e32 v145, 1.0, v146
	v_add_f32_e32 v146, 1.0, v147
; __device__ __forceinline__ float fsigmoid(float v) { return __builtin_amdgcn_rcpf(1.0f + __builtin_amdgcn_exp2f(-LOG2E * v)); }
; __device__ __forceinline__ float fsilu(float v) { return v * fsigmoid(v); }
; __device__ __forceinline__ u32x4 pack8(const f32x4 a, const f32x4 b) { u32x4 w; w.x = cvt_pk_bf16(a[0], a[1]); w.y = cvt_pk_bf16(a[2], a[3]); w.z = cvt_pk_bf16(b[0], b[1]); w.w = cvt_pk_bf16(b[2], b[3]); return w; }
;     template <int ACT> __device__ __forceinline__ void ew(const f32x4 (&acc)[2][2][4][2], bf16_t* D, int ld, int row0, int col0) const {
; #pragma unroll
;         for (int ai = 0; ai < 2; ++ai)
; #pragma unroll
;             for (int m = 0; m < 4; ++m) { bf16_t* rowp = D + (size_t)(row0 + ai * HALF + m * 16) * ld + col0;
; #pragma unroll
;                 for (int bj = 0; bj < 2; ++bj) { f32x4 v0 = acc[ai][bj][m][0], v1 = acc[ai][bj][m][1];
;                     if (ACT == 1) {
; #pragma unroll
;                         for (int j = 0; j < 4; ++j) { v0[j] = fsilu(v0[j]); v1[j] = fsilu(v1[j]); } }
;                     if (ACT == 2) {
; #pragma unroll
;                         for (int j = 0; j < 4; ++j) { v0[j] = fsigmoid(v0[j]); v1[j] = fsigmoid(v1[j]); } }
;                     *(u32x4*)(rowp + bj * HALF) = pack8(v0, v1); } }
;     }
	v_mul_f32_e32 v147, 0xbfb8aa3b, v102
	v_exp_f32_e32 v147, v147
	v_exp_f32_e32 v150, v150
	v_rcp_f32_e32 v144, v144
	v_rcp_f32_e32 v145, v145
	v_add_f32_e32 v147, 1.0, v147
	v_add_f32_e32 v150, 1.0, v150
	v_mul_f32_e32 v149, 0xbfb8aa3b, v98
	v_rcp_f32_e32 v147, v147
	v_mul_f32_e32 v151, 0xbfb8aa3b, v99
	v_rcp_f32_e32 v150, v150
	v_exp_f32_e32 v149, v149
	v_rcp_f32_e32 v146, v146
	v_exp_f32_e32 v151, v151
	v_cvt_pk_bf16_f32 v144, v144, v145
	v_cvt_pk_bf16_f32 v145, v147, v150
	v_mul_f32_e32 v147, 0xbfb8aa3b, v76
	v_add_f32_e32 v149, 1.0, v149
	v_add_f32_e32 v151, 1.0, v151
	v_cvt_pk_bf16_f32 v146, v148, v146
	v_exp_f32_e32 v148, v147
	v_mul_f32_e32 v147, 0xbfb8aa3b, v72
	v_rcp_f32_e32 v149, v149
	v_rcp_f32_e32 v151, v151
	v_exp_f32_e32 v150, v147
	v_mul_f32_e32 v153, 0xbfb8aa3b, v74
	v_mul_f32_e32 v154, 0xbfb8aa3b, v79
	v_cvt_pk_bf16_f32 v147, v149, v151
	v_add_f32_e32 v149, 1.0, v150
	v_mul_f32_e32 v150, 0xbfb8aa3b, v77
	v_mul_f32_e32 v151, 0xbfb8aa3b, v73
	v_exp_f32_e32 v150, v150
	v_exp_f32_e32 v151, v151
	v_rcp_f32_e32 v152, v149
	v_mul_f32_e32 v155, 0xbfb8aa3b, v75
	v_add_f32_e32 v149, 1.0, v150
	v_add_f32_e32 v150, 1.0, v151
	v_mul_f32_e32 v151, 0xbfb8aa3b, v78
	v_exp_f32_e32 v151, v151
	v_exp_f32_e32 v153, v153
	v_exp_f32_e32 v154, v154
	v_exp_f32_e32 v155, v155
	v_add_f32_e32 v148, 1.0, v148
	v_add_f32_e32 v151, 1.0, v151
	v_add_f32_e32 v153, 1.0, v153
	v_add_f32_e32 v154, 1.0, v154
	v_add_f32_e32 v155, 1.0, v155
	v_rcp_f32_e32 v148, v148
	v_rcp_f32_e32 v149, v149
	v_rcp_f32_e32 v151, v151
	v_rcp_f32_e32 v153, v153
	v_rcp_f32_e32 v154, v154
	v_rcp_f32_e32 v155, v155
	v_rcp_f32_e32 v150, v150
	v_cvt_pk_bf16_f32 v148, v148, v149
	v_cvt_pk_bf16_f32 v149, v151, v154
	v_cvt_pk_bf16_f32 v151, v153, v155
	v_mul_f32_e32 v154, 0xbfb8aa3b, v84
	v_mul_f32_e32 v155, 0xbfb8aa3b, v80
	v_exp_f32_e32 v154, v154
	v_exp_f32_e32 v155, v155
	v_cvt_pk_bf16_f32 v150, v152, v150
	v_or_b32_e32 v152, 48, v182
	v_ashrrev_i32_e32 v153, 31, v152
	v_lshlrev_b64 v[190:191], 12, v[152:153]
	v_add_f32_e32 v152, 1.0, v154
	v_add_f32_e32 v153, 1.0, v155
	v_mul_f32_e32 v154, 0xbfb8aa3b, v85
	v_mul_f32_e32 v155, 0xbfb8aa3b, v81
	v_exp_f32_e32 v154, v154
	v_exp_f32_e32 v155, v155
	v_rcp_f32_e32 v156, v153
	v_mul_f32_e32 v158, 0xbfb8aa3b, v87
	v_add_f32_e32 v153, 1.0, v154
	v_add_f32_e32 v154, 1.0, v155
	v_mul_f32_e32 v155, 0xbfb8aa3b, v86
	v_exp_f32_e32 v155, v155
	v_exp_f32_e32 v158, v158
	v_rcp_f32_e32 v152, v152
	v_rcp_f32_e32 v153, v153
	v_add_f32_e32 v155, 1.0, v155
	v_add_f32_e32 v158, 1.0, v158
	v_mul_f32_e32 v157, 0xbfb8aa3b, v82
	v_rcp_f32_e32 v155, v155
	v_mul_f32_e32 v159, 0xbfb8aa3b, v83
	v_rcp_f32_e32 v158, v158
	v_exp_f32_e32 v157, v157
	v_rcp_f32_e32 v154, v154
	v_exp_f32_e32 v159, v159
	v_cvt_pk_bf16_f32 v152, v152, v153
	v_cvt_pk_bf16_f32 v153, v155, v158
	v_mul_f32_e32 v155, 0xbfb8aa3b, v68
	v_add_f32_e32 v157, 1.0, v157
	v_add_f32_e32 v159, 1.0, v159
	v_cvt_pk_bf16_f32 v154, v156, v154
	v_exp_f32_e32 v156, v155
	v_mul_f32_e32 v155, 0xbfb8aa3b, v64
	v_rcp_f32_e32 v157, v157
	v_rcp_f32_e32 v159, v159
	v_exp_f32_e32 v158, v155
	v_mul_f32_e32 v161, 0xbfb8aa3b, v66
	v_mul_f32_e32 v162, 0xbfb8aa3b, v71
	v_cvt_pk_bf16_f32 v155, v157, v159
	v_add_f32_e32 v157, 1.0, v158
	v_mul_f32_e32 v158, 0xbfb8aa3b, v69
	v_mul_f32_e32 v159, 0xbfb8aa3b, v65
	v_exp_f32_e32 v158, v158
	v_exp_f32_e32 v159, v159
	v_rcp_f32_e32 v160, v157
	v_mul_f32_e32 v163, 0xbfb8aa3b, v67
	v_add_f32_e32 v157, 1.0, v158
	v_add_f32_e32 v158, 1.0, v159
	v_mul_f32_e32 v159, 0xbfb8aa3b, v70
	v_exp_f32_e32 v159, v159
	v_exp_f32_e32 v161, v161
	v_exp_f32_e32 v162, v162
	v_exp_f32_e32 v163, v163
	v_add_f32_e32 v156, 1.0, v156
	v_add_f32_e32 v159, 1.0, v159
	v_add_f32_e32 v161, 1.0, v161
	v_add_f32_e32 v162, 1.0, v162
	v_add_f32_e32 v163, 1.0, v163
	v_rcp_f32_e32 v156, v156
	v_rcp_f32_e32 v157, v157
	v_rcp_f32_e32 v159, v159
	v_rcp_f32_e32 v161, v161
	v_rcp_f32_e32 v162, v162
	v_rcp_f32_e32 v163, v163
	v_cvt_pk_bf16_f32 v156, v156, v157
	v_rcp_f32_e32 v158, v158
	v_cvt_pk_bf16_f32 v157, v159, v162
	v_cvt_pk_bf16_f32 v159, v161, v163
	v_mul_f32_e32 v161, 0xbfb8aa3b, v56
	v_exp_f32_e32 v161, v161
	v_mul_f32_e32 v162, 0xbfb8aa3b, v61
	v_mul_f32_e32 v163, 0xbfb8aa3b, v57
	v_exp_f32_e32 v162, v162
	v_exp_f32_e32 v163, v163
	v_add_f32_e32 v161, 1.0, v161
	v_cvt_pk_bf16_f32 v158, v160, v158
	v_mul_f32_e32 v160, 0xbfb8aa3b, v60
	v_rcp_f32_e32 v172, v161
	v_add_f32_e32 v161, 1.0, v162
	v_add_f32_e32 v162, 1.0, v163
	v_mul_f32_e32 v163, 0xbfb8aa3b, v62
	v_mul_f32_e32 v194, 0xbfb8aa3b, v58
	v_mul_f32_e32 v195, 0xbfb8aa3b, v63
	v_mul_f32_e32 v212, 0xbfb8aa3b, v59
	v_exp_f32_e32 v160, v160
	v_exp_f32_e32 v163, v163
	v_exp_f32_e32 v194, v194
	v_exp_f32_e32 v195, v195
	v_exp_f32_e32 v212, v212
	v_add_f32_e32 v160, 1.0, v160
	v_add_f32_e32 v163, 1.0, v163
	v_add_f32_e32 v194, 1.0, v194
	v_add_f32_e32 v195, 1.0, v195
	v_add_f32_e32 v212, 1.0, v212
	v_rcp_f32_e32 v160, v160
	v_rcp_f32_e32 v161, v161
	v_rcp_f32_e32 v162, v162
	v_rcp_f32_e32 v163, v163
	v_rcp_f32_e32 v194, v194
	v_rcp_f32_e32 v195, v195
	v_rcp_f32_e32 v212, v212
	v_ashrrev_i32_e32 v183, 31, v182
	v_lshlrev_b64 v[184:185], 12, v[182:183]
	s_mov_b64 s[38:39], 0x80000
	s_cmp_gt_u32 s23, 35
	v_lshl_add_u64 v[192:193], v[184:185], 0, s[38:39]
	v_cvt_pk_bf16_f32 v160, v160, v161
	v_cvt_pk_bf16_f32 v161, v163, v195
	v_cvt_pk_bf16_f32 v162, v172, v162
	v_cvt_pk_bf16_f32 v163, v194, v212
	s_cbranch_scc0 .LBB0_373
; __device__ __forceinline__ float fsigmoid(float v) { return __builtin_amdgcn_rcpf(1.0f + __builtin_amdgcn_exp2f(-LOG2E * v)); }
; __device__ __forceinline__ float fsilu(float v) { return v * fsigmoid(v); }
; __device__ __forceinline__ u32x4 pack8(const f32x4 a, const f32x4 b) { u32x4 w; w.x = cvt_pk_bf16(a[0], a[1]); w.y = cvt_pk_bf16(a[2], a[3]); w.z = cvt_pk_bf16(b[0], b[1]); w.w = cvt_pk_bf16(b[2], b[3]); return w; }
;     template <int ACT> __device__ __forceinline__ void ew(const f32x4 (&acc)[2][2][4][2], bf16_t* D, int ld, int row0, int col0) const {
; #pragma unroll
;         for (int ai = 0; ai < 2; ++ai)
; #pragma unroll
;             for (int m = 0; m < 4; ++m) { bf16_t* rowp = D + (size_t)(row0 + ai * HALF + m * 16) * ld + col0;
; #pragma unroll
;                 for (int bj = 0; bj < 2; ++bj) { f32x4 v0 = acc[ai][bj][m][0], v1 = acc[ai][bj][m][1];
;                     if (ACT == 1) {
; #pragma unroll
;                         for (int j = 0; j < 4; ++j) { v0[j] = fsilu(v0[j]); v1[j] = fsilu(v1[j]); } }
;                     if (ACT == 2) {
; #pragma unroll
;                         for (int j = 0; j < 4; ++j) { v0[j] = fsigmoid(v0[j]); v1[j] = fsigmoid(v1[j]); } }
;                     *(u32x4*)(rowp + bj * HALF) = pack8(v0, v1); } }
;     }
;     __device__ __forceinline__ void operator()(const f32x4 (&acc)[2][2][4][2], const Unit& u, int wr, int wc, int fr, int fq) const {
;     ...
;         else if (pn < 36) ew<2>(acc, SGA, 2048, row0, (pn - 28) * 256 + cl);
;         else ew<2>(acc, SGB, 2048, row0, (pn - 36) * 256 + cl);
	v_readlane_b32 s38, v255, 23
	v_add_u32_e32 v172, s75, v199
	v_readlane_b32 s39, v255, 24
	v_mul_f32_e32 v212, 0xbfb8aa3b, v40
	v_mul_f32_e32 v220, 0xbfb8aa3b, v45
	v_lshl_add_u64 v[222:223], v[172:173], 1, s[38:39]
	v_lshl_add_u64 v[194:195], v[222:223], 0, v[184:185]
	v_lshl_add_u64 v[224:225], v[222:223], 0, v[186:187]
	global_store_dwordx4 v[194:195], v[128:131], off
	global_store_dwordx4 v[194:195], v[132:135], off offset:256
	global_store_dwordx4 v[224:225], v[136:139], off
	global_store_dwordx4 v[224:225], v[140:143], off offset:256
	v_lshl_add_u64 v[224:225], v[222:223], 0, v[188:189]
	global_store_dwordx4 v[224:225], v[144:147], off
	global_store_dwordx4 v[224:225], v[148:151], off offset:256
	v_lshl_add_u64 v[224:225], v[222:223], 0, v[190:191]
	v_lshl_add_u64 v[230:231], v[222:223], 0, v[192:193]
	v_mul_f32_e32 v222, 0xbfb8aa3b, v41
	v_exp_f32_e32 v222, v222
	v_mul_f32_e32 v223, 0xbfb8aa3b, v46
	global_store_dwordx4 v[224:225], v[152:155], off
	global_store_dwordx4 v[224:225], v[156:159], off offset:256
	v_exp_f32_e32 v223, v223
	v_mul_f32_e32 v224, 0xbfb8aa3b, v42
	v_exp_f32_e32 v224, v224
	v_add_f32_e32 v222, 1.0, v222
	v_rcp_f32_e32 v225, v222
	v_add_f32_e32 v222, 1.0, v223
	v_rcp_f32_e32 v223, v222
	v_add_f32_e32 v222, 1.0, v224
	v_mul_f32_e32 v224, 0xbfb8aa3b, v47
	v_mul_f32_e32 v172, 0xbfb8aa3b, v44
	v_exp_f32_e32 v224, v224
	v_mul_f32_e32 v232, 0xbfb8aa3b, v43
	v_exp_f32_e32 v172, v172
	v_exp_f32_e32 v212, v212
	v_exp_f32_e32 v220, v220
	v_exp_f32_e32 v232, v232
	v_rcp_f32_e32 v233, v222
	v_add_f32_e32 v222, 1.0, v224
	v_add_f32_e32 v172, 1.0, v172
	v_add_f32_e32 v212, 1.0, v212
	v_add_f32_e32 v220, 1.0, v220
	v_rcp_f32_e32 v224, v222
	v_add_f32_e32 v222, 1.0, v232
	v_rcp_f32_e32 v172, v172
	v_rcp_f32_e32 v212, v212
	v_rcp_f32_e32 v220, v220
	v_rcp_f32_e32 v232, v222
	v_cvt_pk_bf16_f32 v223, v223, v224
	v_cvt_pk_bf16_f32 v224, v212, v225
	v_cvt_pk_bf16_f32 v222, v172, v220
	v_cvt_pk_bf16_f32 v225, v233, v232
	global_store_dwordx4 v[230:231], v[222:225], off offset:256
	v_mul_f32_e32 v212, 0xbfb8aa3b, v48
	v_mul_f32_e32 v232, 0xbfb8aa3b, v51
	v_mul_f32_e32 v222, 0xbfb8aa3b, v49
	v_exp_f32_e32 v222, v222
	v_mul_f32_e32 v223, 0xbfb8aa3b, v54
	v_exp_f32_e32 v223, v223
	v_mul_f32_e32 v224, 0xbfb8aa3b, v50
	v_exp_f32_e32 v224, v224
	v_add_f32_e32 v222, 1.0, v222
	v_rcp_f32_e32 v225, v222
	v_add_f32_e32 v222, 1.0, v223
	v_rcp_f32_e32 v223, v222
	v_add_f32_e32 v222, 1.0, v224
	v_mul_f32_e32 v224, 0xbfb8aa3b, v55
	v_exp_f32_e32 v224, v224
	v_mul_f32_e32 v172, 0xbfb8aa3b, v52
	v_exp_f32_e32 v212, v212
	v_mul_f32_e32 v220, 0xbfb8aa3b, v53
	v_exp_f32_e32 v232, v232
	v_exp_f32_e32 v172, v172
	v_exp_f32_e32 v220, v220
	v_rcp_f32_e32 v233, v222
	v_add_f32_e32 v222, 1.0, v224
	v_add_f32_e32 v212, 1.0, v212
	v_rcp_f32_e32 v224, v222
	v_add_f32_e32 v222, 1.0, v232
	v_add_f32_e32 v172, 1.0, v172
	v_rcp_f32_e32 v212, v212
	v_add_f32_e32 v220, 1.0, v220
	v_rcp_f32_e32 v232, v222
	v_rcp_f32_e32 v172, v172
	v_rcp_f32_e32 v220, v220
	s_mov_b64 s[38:39], 0x90000
	global_store_dwordx4 v[230:231], v[160:163], off
	v_lshl_add_u64 v[230:231], v[194:195], 0, s[38:39]
	s_mov_b32 s38, 0x90000
	v_cvt_pk_bf16_f32 v223, v223, v224
	v_cvt_pk_bf16_f32 v224, v212, v225
	v_cvt_pk_bf16_f32 v225, v233, v232
	v_add_co_u32_e32 v232, vcc, s38, v194
	v_cvt_pk_bf16_f32 v222, v172, v220
	s_nop 0
	v_addc_co_u32_e32 v233, vcc, 0, v195, vcc
	global_store_dwordx4 v[232:233], v[222:225], off
	v_mul_f32_e32 v172, 0xbfb8aa3b, v28
	v_mul_f32_e32 v212, 0xbfb8aa3b, v24
	v_mul_f32_e32 v222, 0xbfb8aa3b, v25
	v_exp_f32_e32 v222, v222
	v_mul_f32_e32 v223, 0xbfb8aa3b, v30
	v_exp_f32_e32 v223, v223
	v_mul_f32_e32 v224, 0xbfb8aa3b, v26
	v_exp_f32_e32 v224, v224
	v_add_f32_e32 v222, 1.0, v222
	v_rcp_f32_e32 v225, v222
	v_add_f32_e32 v222, 1.0, v223
	v_rcp_f32_e32 v223, v222
	v_add_f32_e32 v222, 1.0, v224
	v_mul_f32_e32 v224, 0xbfb8aa3b, v31
	v_mul_f32_e32 v220, 0xbfb8aa3b, v29
	v_exp_f32_e32 v224, v224
	v_mul_f32_e32 v232, 0xbfb8aa3b, v27
	v_exp_f32_e32 v172, v172
	v_exp_f32_e32 v212, v212
	v_exp_f32_e32 v220, v220
	v_exp_f32_e32 v232, v232
	v_rcp_f32_e32 v233, v222
	v_add_f32_e32 v222, 1.0, v224
	v_add_f32_e32 v172, 1.0, v172
	v_add_f32_e32 v212, 1.0, v212
	v_add_f32_e32 v220, 1.0, v220
	v_rcp_f32_e32 v224, v222
	v_add_f32_e32 v222, 1.0, v232
	v_rcp_f32_e32 v172, v172
	v_rcp_f32_e32 v212, v212
	v_rcp_f32_e32 v220, v220
	v_rcp_f32_e32 v232, v222
	v_cvt_pk_bf16_f32 v223, v223, v224
	v_cvt_pk_bf16_f32 v224, v212, v225
	v_cvt_pk_bf16_f32 v222, v172, v220
	v_cvt_pk_bf16_f32 v225, v233, v232
	global_store_dwordx4 v[230:231], v[222:225], off offset:256
	v_mul_f32_e32 v212, 0xbfb8aa3b, v32
	v_mul_f32_e32 v232, 0xbfb8aa3b, v35
	v_mul_f32_e32 v222, 0xbfb8aa3b, v33
	v_exp_f32_e32 v222, v222
	v_mul_f32_e32 v223, 0xbfb8aa3b, v38
; __device__ __forceinline__ float fsigmoid(float v) { return __builtin_amdgcn_rcpf(1.0f + __builtin_amdgcn_exp2f(-LOG2E * v)); }
; __device__ __forceinline__ float fsilu(float v) { return v * fsigmoid(v); }
; __device__ __forceinline__ u32x4 pack8(const f32x4 a, const f32x4 b) { u32x4 w; w.x = cvt_pk_bf16(a[0], a[1]); w.y = cvt_pk_bf16(a[2], a[3]); w.z = cvt_pk_bf16(b[0], b[1]); w.w = cvt_pk_bf16(b[2], b[3]); return w; }
;     template <int ACT> __device__ __forceinline__ void ew(const f32x4 (&acc)[2][2][4][2], bf16_t* D, int ld, int row0, int col0) const {
; #pragma unroll
;         for (int ai = 0; ai < 2; ++ai)
; #pragma unroll
;             for (int m = 0; m < 4; ++m) { bf16_t* rowp = D + (size_t)(row0 + ai * HALF + m * 16) * ld + col0;
; #pragma unroll
;                 for (int bj = 0; bj < 2; ++bj) { f32x4 v0 = acc[ai][bj][m][0], v1 = acc[ai][bj][m][1];
;                     if (ACT == 1) {
; #pragma unroll
;                         for (int j = 0; j < 4; ++j) { v0[j] = fsilu(v0[j]); v1[j] = fsilu(v1[j]); } }
;                     if (ACT == 2) {
; #pragma unroll
;                         for (int j = 0; j < 4; ++j) { v0[j] = fsigmoid(v0[j]); v1[j] = fsigmoid(v1[j]); } }
;                     *(u32x4*)(rowp + bj * HALF) = pack8(v0, v1); } }
;     }
	v_exp_f32_e32 v223, v223
	v_mul_f32_e32 v224, 0xbfb8aa3b, v34
	v_exp_f32_e32 v224, v224
	v_add_f32_e32 v222, 1.0, v222
	v_rcp_f32_e32 v225, v222
	v_add_f32_e32 v222, 1.0, v223
	v_rcp_f32_e32 v223, v222
	v_add_f32_e32 v222, 1.0, v224
	v_mul_f32_e32 v224, 0xbfb8aa3b, v39
	v_exp_f32_e32 v224, v224
	v_mul_f32_e32 v172, 0xbfb8aa3b, v36
	v_exp_f32_e32 v212, v212
	v_mul_f32_e32 v220, 0xbfb8aa3b, v37
	v_exp_f32_e32 v232, v232
	v_exp_f32_e32 v172, v172
	v_exp_f32_e32 v220, v220
	v_rcp_f32_e32 v233, v222
	v_add_f32_e32 v222, 1.0, v224
	v_add_f32_e32 v212, 1.0, v212
	v_rcp_f32_e32 v224, v222
	v_add_f32_e32 v222, 1.0, v232
	v_add_f32_e32 v172, 1.0, v172
	v_rcp_f32_e32 v212, v212
	v_add_f32_e32 v220, 1.0, v220
	v_rcp_f32_e32 v232, v222
	v_rcp_f32_e32 v172, v172
	v_rcp_f32_e32 v220, v220
	v_cvt_pk_bf16_f32 v223, v223, v224
	v_cvt_pk_bf16_f32 v224, v212, v225
	v_cvt_pk_bf16_f32 v225, v233, v232
	v_add_co_u32_e32 v232, vcc, s49, v194
	v_cvt_pk_bf16_f32 v222, v172, v220
	s_nop 0
	v_addc_co_u32_e32 v233, vcc, 0, v195, vcc
	global_store_dwordx4 v[232:233], v[222:225], off
	v_mul_f32_e32 v172, 0xbfb8aa3b, v12
	v_mul_f32_e32 v212, 0xbfb8aa3b, v8
	v_mul_f32_e32 v222, 0xbfb8aa3b, v9
	v_exp_f32_e32 v222, v222
	v_mul_f32_e32 v223, 0xbfb8aa3b, v14
	v_exp_f32_e32 v223, v223
	v_mul_f32_e32 v224, 0xbfb8aa3b, v10
	v_exp_f32_e32 v224, v224
	v_add_f32_e32 v222, 1.0, v222
	v_rcp_f32_e32 v225, v222
	v_add_f32_e32 v222, 1.0, v223
	v_rcp_f32_e32 v223, v222
	v_add_f32_e32 v222, 1.0, v224
	v_mul_f32_e32 v224, 0xbfb8aa3b, v15
	v_mul_f32_e32 v220, 0xbfb8aa3b, v13
	v_exp_f32_e32 v224, v224
	v_mul_f32_e32 v232, 0xbfb8aa3b, v11
	v_exp_f32_e32 v172, v172
	v_exp_f32_e32 v212, v212
	v_exp_f32_e32 v220, v220
	v_exp_f32_e32 v232, v232
	v_rcp_f32_e32 v233, v222
	v_add_f32_e32 v222, 1.0, v224
	v_add_f32_e32 v172, 1.0, v172
	v_add_f32_e32 v212, 1.0, v212
	v_add_f32_e32 v220, 1.0, v220
	v_rcp_f32_e32 v224, v222
	v_add_f32_e32 v222, 1.0, v232
	v_rcp_f32_e32 v172, v172
	v_rcp_f32_e32 v212, v212
	v_rcp_f32_e32 v220, v220
	v_rcp_f32_e32 v232, v222
	s_mov_b64 s[38:39], 0xa0000
	v_lshl_add_u64 v[230:231], v[194:195], 0, s[38:39]
	v_cvt_pk_bf16_f32 v222, v172, v220
	v_cvt_pk_bf16_f32 v223, v223, v224
	v_cvt_pk_bf16_f32 v224, v212, v225
	v_cvt_pk_bf16_f32 v225, v233, v232
	global_store_dwordx4 v[230:231], v[222:225], off offset:256
	v_mul_f32_e32 v212, 0xbfb8aa3b, v16
	v_exp_f32_e32 v212, v212
	v_mul_f32_e32 v222, 0xbfb8aa3b, v17
	v_exp_f32_e32 v222, v222
	v_mul_f32_e32 v223, 0xbfb8aa3b, v22
	v_exp_f32_e32 v223, v223
	v_mul_f32_e32 v224, 0xbfb8aa3b, v18
	v_exp_f32_e32 v224, v224
	v_add_f32_e32 v222, 1.0, v222
	v_rcp_f32_e32 v225, v222
	v_add_f32_e32 v222, 1.0, v223
	v_rcp_f32_e32 v223, v222
	v_add_f32_e32 v222, 1.0, v224
	v_mul_f32_e32 v224, 0xbfb8aa3b, v23
	v_exp_f32_e32 v224, v224
	v_mul_f32_e32 v172, 0xbfb8aa3b, v20
	v_mul_f32_e32 v220, 0xbfb8aa3b, v21
	v_mul_f32_e32 v232, 0xbfb8aa3b, v19
	v_exp_f32_e32 v172, v172
	v_exp_f32_e32 v220, v220
	v_exp_f32_e32 v232, v232
	v_add_f32_e32 v212, 1.0, v212
	v_rcp_f32_e32 v233, v222
	v_add_f32_e32 v222, 1.0, v224
	v_rcp_f32_e32 v212, v212
	v_rcp_f32_e32 v224, v222
	v_add_f32_e32 v172, 1.0, v172
	v_add_f32_e32 v220, 1.0, v220
	v_add_f32_e32 v222, 1.0, v232
	v_rcp_f32_e32 v172, v172
	v_rcp_f32_e32 v220, v220
	v_rcp_f32_e32 v232, v222
	v_cvt_pk_bf16_f32 v223, v223, v224
	v_cvt_pk_bf16_f32 v224, v212, v225
	v_mul_f32_e32 v212, 0xbfb8aa3b, v0
	v_lshl_add_u64 v[230:231], v[194:195], 0, s[62:63]
	v_add_co_u32_e32 v194, vcc, s50, v194
	v_exp_f32_e32 v212, v212
	v_cvt_pk_bf16_f32 v222, v172, v220
	v_cvt_pk_bf16_f32 v225, v233, v232
	v_addc_co_u32_e32 v195, vcc, 0, v195, vcc
	global_store_dwordx4 v[194:195], v[222:225], off
	v_mul_f32_e32 v172, 0xbfb8aa3b, v4
	v_add_f32_e32 v194, 1.0, v212
	v_mul_f32_e32 v222, 0xbfb8aa3b, v2
	v_exp_f32_e32 v222, v222
	v_mul_f32_e32 v223, 0xbfb8aa3b, v7
	v_mul_f32_e32 v195, 0xbfb8aa3b, v5
	v_mul_f32_e32 v212, 0xbfb8aa3b, v1
	v_mul_f32_e32 v220, 0xbfb8aa3b, v6
	v_exp_f32_e32 v223, v223
	v_mul_f32_e32 v224, 0xbfb8aa3b, v3
	v_exp_f32_e32 v172, v172
	v_exp_f32_e32 v195, v195
	v_exp_f32_e32 v212, v212
	v_exp_f32_e32 v220, v220
	v_exp_f32_e32 v224, v224
	v_add_f32_e32 v222, 1.0, v222
	v_rcp_f32_e32 v225, v222
	v_add_f32_e32 v222, 1.0, v223
	v_add_f32_e32 v172, 1.0, v172
	v_add_f32_e32 v195, 1.0, v195
	v_add_f32_e32 v212, 1.0, v212
	v_add_f32_e32 v220, 1.0, v220
	v_rcp_f32_e32 v223, v222
	v_add_f32_e32 v222, 1.0, v224
	v_rcp_f32_e32 v172, v172
	v_rcp_f32_e32 v194, v194
	v_rcp_f32_e32 v195, v195
	v_rcp_f32_e32 v212, v212
	v_rcp_f32_e32 v220, v220
	v_rcp_f32_e32 v232, v222
	v_cvt_pk_bf16_f32 v222, v172, v195
	v_cvt_pk_bf16_f32 v224, v194, v212
	v_cvt_pk_bf16_f32 v223, v220, v223
	v_cvt_pk_bf16_f32 v225, v225, v232
	global_store_dwordx4 v[230:231], v[222:225], off offset:256
	s_mov_b64 s[82:83], 0

; #define PG8_STAGE(bufoff, gbase, voff) do { _Pragma("unroll") for (int _i = 0; _i < 2; ++_i) \
;         __builtin_amdgcn_global_load_lds((const unsigned*)((const char*)(gbase) + (voff)[_i]), (PG8_LAS unsigned*)(lds + (bufoff) + ldsw + _i * 8192), 16, 0, 0); } while (0)
; #define PG8_LDA(dst, b, h) do { _Pragma("unroll") for (int m = 0; m < 4; ++m) _Pragma("unroll") for (int k = 0; k < 2; ++k) dst[m][k] = *(const PG8_LAS bf16x8*)(lds + PG8_SA(b, h) + aoff + m * 2048 + k * 1024); } while (0)
; #define PG8_LDB(dst, b, h) do { _Pragma("unroll") for (int n = 0; n < 2; ++n) _Pragma("unroll") for (int k = 0; k < 2; ++k) dst[n][k] = *(const PG8_LAS bf16x8*)(lds + PG8_SB(b, h) + boff + n * 2048 + k * 1024); } while (0)
; #define PG8_MMA(ai, bj, At, Bt) do { __builtin_amdgcn_s_setprio(1); _Pragma("unroll") for (int m = 0; m < 4; ++m) _Pragma("unroll") for (int n = 0; n < 2; ++n) _Pragma("unroll") for (int k = 0; k < 2; ++k) \
;         acc[ai][bj][m][n] = __builtin_amdgcn_mfma_f32_16x16x32_bf16(Bt[n][k], At[m][k], acc[ai][bj][m][n], 0, 0, 0); __builtin_amdgcn_s_setprio(0); } while (0)
; #define PG8_WAIT_V(n) asm volatile("s_waitcnt vmcnt(" #n ")" ::: "memory")
; #define PG8_WAIT_L(n) asm volatile("s_waitcnt lgkmcnt(" #n ")" ::: "memory")
; #define PG8_BAR __builtin_amdgcn_s_barrier()
; #define PG8_SCHED __builtin_amdgcn_sched_barrier(0)
; template <class Epi, class Sched, bool ALIGN_EPI = false, bool SP2 = false>
; __device__ __forceinline__ void gemm_phase(PG8_LAS unsigned char* lds, const Gemm g, const Sched& S, const Epi& E) {
;     ...
;             PG8_LDB(B0, 0, 0); PG8_LDB(B1, 0, 1); PG8_SCHED; PG8_LDA(At, 0, 0); PG8_STAGE(PG8_SA(1, 1), a1 + hstep, voffA);
;             PG8_WAIT_V(8); PG8_WAIT_L(0); PG8_BAR; PG8_MMA(0, 0, At, B0); PG8_MMA(0, 1, At, B1); PG8_BAR; PG8_SCHED;
;             PG8_LDA(At, 0, 1); PG8_STAGE(PG8_SB(0, 0), b2, voffB); PG8_STAGE(PG8_SB(0, 1), b2 + hstep, voffB); PG8_STAGE(PG8_SA(0, 0), a2, voffA);
;             PG8_WAIT_V(8); PG8_WAIT_L(0); PG8_BAR; PG8_MMA(1, 0, At, B0); PG8_MMA(1, 1, At, B1); PG8_BAR; PG8_SCHED;
.LBB0_735:
	ds_read_b128 v[144:147], v155
	ds_read_b128 v[148:151], v155 offset:1024
	ds_read_b128 v[158:161], v155 offset:2048
	ds_read_b128 v[162:165], v155 offset:3072
	ds_read_b128 v[166:169], v156
	ds_read_b128 v[170:173], v156 offset:1024
	ds_read_b128 v[174:177], v156 offset:2048
	ds_read_b128 v[178:181], v156 offset:3072
	s_add_u32 s48, s46, 0xfffc0080
	s_addc_u32 s49, s47, -1
	s_cmp_eq_u32 s69, 12
	s_cselect_b32 s51, s39, s49
	s_cselect_b32 s50, s65, s48
	s_cselect_b32 s49, s37, s68
	s_cselect_b32 s48, s66, s67
	s_add_i32 m0, s45, 0xc000
	ds_read_b128 v[182:185], v157
	ds_read_b128 v[186:189], v157 offset:1024
	ds_read_b128 v[190:193], v157 offset:2048
	ds_read_b128 v[194:197], v157 offset:3072
	ds_read_b128 v[198:201], v157 offset:4096
	ds_read_b128 v[202:205], v157 offset:5120
	ds_read_b128 v[206:209], v157 offset:6144
	ds_read_b128 v[214:217], v157 offset:7168
	global_load_lds_dwordx4 v136, s[46:47]
	s_add_i32 m0, s45, 0xe000
	s_nop 0
	global_load_lds_dwordx4 v138, s[46:47]
	s_waitcnt vmcnt(8)
	s_waitcnt lgkmcnt(0)
	s_barrier
	s_waitcnt lgkmcnt(0)
	v_mfma_f32_16x16x32_bf16 v[124:127], v[144:147], v[182:185], v[124:127]
	v_mfma_f32_16x16x32_bf16 v[120:123], v[158:161], v[182:185], v[120:123]
	v_mfma_f32_16x16x32_bf16 v[116:119], v[144:147], v[190:193], v[116:119]
	v_mfma_f32_16x16x32_bf16 v[112:115], v[158:161], v[190:193], v[112:115]
	v_mfma_f32_16x16x32_bf16 v[96:99], v[144:147], v[198:201], v[96:99]
	v_mfma_f32_16x16x32_bf16 v[88:91], v[158:161], v[198:201], v[88:91]
	v_mfma_f32_16x16x32_bf16 v[80:83], v[144:147], v[206:209], v[80:83]
	v_mfma_f32_16x16x32_bf16 v[72:75], v[158:161], v[206:209], v[72:75]
	v_mfma_f32_16x16x32_bf16 v[124:127], v[148:151], v[186:189], v[124:127]
	v_mfma_f32_16x16x32_bf16 v[120:123], v[162:165], v[186:189], v[120:123]
	v_mfma_f32_16x16x32_bf16 v[116:119], v[148:151], v[194:197], v[116:119]
	v_mfma_f32_16x16x32_bf16 v[112:115], v[162:165], v[194:197], v[112:115]
	v_mfma_f32_16x16x32_bf16 v[96:99], v[148:151], v[202:205], v[96:99]
	v_mfma_f32_16x16x32_bf16 v[88:91], v[162:165], v[202:205], v[88:91]
	v_mfma_f32_16x16x32_bf16 v[80:83], v[148:151], v[214:217], v[80:83]
	v_mfma_f32_16x16x32_bf16 v[72:75], v[162:165], v[214:217], v[72:75]
	v_mfma_f32_16x16x32_bf16 v[108:111], v[166:169], v[182:185], v[108:111]
	v_mfma_f32_16x16x32_bf16 v[104:107], v[174:177], v[182:185], v[104:107]
	v_mfma_f32_16x16x32_bf16 v[100:103], v[166:169], v[190:193], v[100:103]
	v_mfma_f32_16x16x32_bf16 v[92:95], v[174:177], v[190:193], v[92:95]
	v_mfma_f32_16x16x32_bf16 v[84:87], v[166:169], v[198:201], v[84:87]
	v_mfma_f32_16x16x32_bf16 v[76:79], v[174:177], v[198:201], v[76:79]
	v_mfma_f32_16x16x32_bf16 v[68:71], v[166:169], v[206:209], v[68:71]
	v_mfma_f32_16x16x32_bf16 v[64:67], v[174:177], v[206:209], v[64:67]
	v_mfma_f32_16x16x32_bf16 v[108:111], v[170:173], v[186:189], v[108:111]
	v_mfma_f32_16x16x32_bf16 v[104:107], v[178:181], v[186:189], v[104:107]
	v_mfma_f32_16x16x32_bf16 v[100:103], v[170:173], v[194:197], v[100:103]
	v_mfma_f32_16x16x32_bf16 v[92:95], v[178:181], v[194:197], v[92:95]
	v_mfma_f32_16x16x32_bf16 v[84:87], v[170:173], v[202:205], v[84:87]
	v_mfma_f32_16x16x32_bf16 v[76:79], v[178:181], v[202:205], v[76:79]
	v_mfma_f32_16x16x32_bf16 v[68:71], v[170:173], v[214:217], v[68:71]
	v_mfma_f32_16x16x32_bf16 v[64:67], v[178:181], v[214:217], v[64:67]
	s_barrier
	s_add_i32 s70, s62, s53
	s_mov_b32 m0, s70
	ds_read_b128 v[182:185], v157 offset:16384
	ds_read_b128 v[186:189], v157 offset:17408
	ds_read_b128 v[190:193], v157 offset:18432
	ds_read_b128 v[194:197], v157 offset:19456
	ds_read_b128 v[198:201], v157 offset:20480
	ds_read_b128 v[202:205], v157 offset:21504
	ds_read_b128 v[206:209], v157 offset:22528
	ds_read_b128 v[214:217], v157 offset:23552
	global_load_lds_dwordx4 v130, s[48:49]
	s_add_i32 m0, s70, 0x2000
	s_add_u32 s70, s48, 0x40000
	s_addc_u32 s71, s49, 0
	s_add_i32 s72, s63, s53
	global_load_lds_dwordx4 v134, s[48:49]
	s_mov_b32 m0, s72
	s_nop 0
	global_load_lds_dwordx4 v130, s[70:71]
	s_add_i32 m0, s72, 0x2000
	s_nop 0
	global_load_lds_dwordx4 v134, s[70:71]
	s_mov_b32 m0, s45
	s_nop 0
	global_load_lds_dwordx4 v128, s[50:51]
	s_mov_b32 m0, s54
	s_nop 0
	global_load_lds_dwordx4 v132, s[50:51]
	s_waitcnt vmcnt(8)
	s_waitcnt lgkmcnt(0)
	s_barrier
	s_waitcnt lgkmcnt(0)
	v_mfma_f32_16x16x32_bf16 v[60:63], v[144:147], v[182:185], v[60:63]
	v_mfma_f32_16x16x32_bf16 v[56:59], v[158:161], v[182:185], v[56:59]
	v_mfma_f32_16x16x32_bf16 v[48:51], v[144:147], v[190:193], v[48:51]
	v_mfma_f32_16x16x32_bf16 v[40:43], v[158:161], v[190:193], v[40:43]
	v_mfma_f32_16x16x32_bf16 v[32:35], v[144:147], v[198:201], v[32:35]
	v_mfma_f32_16x16x32_bf16 v[24:27], v[158:161], v[198:201], v[24:27]
	v_mfma_f32_16x16x32_bf16 v[16:19], v[144:147], v[206:209], v[16:19]
	v_mfma_f32_16x16x32_bf16 v[8:11], v[158:161], v[206:209], v[8:11]
	v_mfma_f32_16x16x32_bf16 v[60:63], v[148:151], v[186:189], v[60:63]
	v_mfma_f32_16x16x32_bf16 v[56:59], v[162:165], v[186:189], v[56:59]
	v_mfma_f32_16x16x32_bf16 v[48:51], v[148:151], v[194:197], v[48:51]
	v_mfma_f32_16x16x32_bf16 v[40:43], v[162:165], v[194:197], v[40:43]
	v_mfma_f32_16x16x32_bf16 v[32:35], v[148:151], v[202:205], v[32:35]
	v_mfma_f32_16x16x32_bf16 v[24:27], v[162:165], v[202:205], v[24:27]
	v_mfma_f32_16x16x32_bf16 v[16:19], v[148:151], v[214:217], v[16:19]
	v_mfma_f32_16x16x32_bf16 v[8:11], v[162:165], v[214:217], v[8:11]
	v_mfma_f32_16x16x32_bf16 v[52:55], v[166:169], v[182:185], v[52:55]
	v_mfma_f32_16x16x32_bf16 v[44:47], v[174:177], v[182:185], v[44:47]
	v_mfma_f32_16x16x32_bf16 v[36:39], v[166:169], v[190:193], v[36:39]
	v_mfma_f32_16x16x32_bf16 v[28:31], v[174:177], v[190:193], v[28:31]
	v_mfma_f32_16x16x32_bf16 v[20:23], v[166:169], v[198:201], v[20:23]
	v_mfma_f32_16x16x32_bf16 v[12:15], v[174:177], v[198:201], v[12:15]
	v_mfma_f32_16x16x32_bf16 v[4:7], v[166:169], v[206:209], v[4:7]
	v_mfma_f32_16x16x32_bf16 v[0:3], v[174:177], v[206:209], v[0:3]
	v_mfma_f32_16x16x32_bf16 v[52:55], v[170:173], v[186:189], v[52:55]
	v_mfma_f32_16x16x32_bf16 v[44:47], v[178:181], v[186:189], v[44:47]
	v_mfma_f32_16x16x32_bf16 v[36:39], v[170:173], v[194:197], v[36:39]
	v_mfma_f32_16x16x32_bf16 v[28:31], v[178:181], v[194:197], v[28:31]
	v_mfma_f32_16x16x32_bf16 v[20:23], v[170:173], v[202:205], v[20:23]
	v_mfma_f32_16x16x32_bf16 v[12:15], v[178:181], v[202:205], v[12:15]
	v_mfma_f32_16x16x32_bf16 v[4:7], v[170:173], v[214:217], v[4:7]
	v_mfma_f32_16x16x32_bf16 v[0:3], v[178:181], v[214:217], v[0:3]
	s_barrier
; #define PG8_STAGE(bufoff, gbase, voff) do { _Pragma("unroll") for (int _i = 0; _i < 2; ++_i) \
;         __builtin_amdgcn_global_load_lds((const unsigned*)((const char*)(gbase) + (voff)[_i]), (PG8_LAS unsigned*)(lds + (bufoff) + ldsw + _i * 8192), 16, 0, 0); } while (0)
; #define PG8_LDA(dst, b, h) do { _Pragma("unroll") for (int m = 0; m < 4; ++m) _Pragma("unroll") for (int k = 0; k < 2; ++k) dst[m][k] = *(const PG8_LAS bf16x8*)(lds + PG8_SA(b, h) + aoff + m * 2048 + k * 1024); } while (0)
; #define PG8_LDB(dst, b, h) do { _Pragma("unroll") for (int n = 0; n < 2; ++n) _Pragma("unroll") for (int k = 0; k < 2; ++k) dst[n][k] = *(const PG8_LAS bf16x8*)(lds + PG8_SB(b, h) + boff + n * 2048 + k * 1024); } while (0)
; #define PG8_MMA(ai, bj, At, Bt) do { __builtin_amdgcn_s_setprio(1); _Pragma("unroll") for (int m = 0; m < 4; ++m) _Pragma("unroll") for (int n = 0; n < 2; ++n) _Pragma("unroll") for (int k = 0; k < 2; ++k) \
;         acc[ai][bj][m][n] = __builtin_amdgcn_mfma_f32_16x16x32_bf16(Bt[n][k], At[m][k], acc[ai][bj][m][n], 0, 0, 0); __builtin_amdgcn_s_setprio(0); } while (0)
; #define PG8_WAIT_V(n) asm volatile("s_waitcnt vmcnt(" #n ")" ::: "memory")
; #define PG8_WAIT_L(n) asm volatile("s_waitcnt lgkmcnt(" #n ")" ::: "memory")
; #define PG8_BAR __builtin_amdgcn_s_barrier()
; #define PG8_SCHED __builtin_amdgcn_sched_barrier(0)
; template <class Epi, class Sched, bool ALIGN_EPI = false, bool SP2 = false>
; __device__ __forceinline__ void gemm_phase(PG8_LAS unsigned char* lds, const Gemm g, const Sched& S, const Epi& E) {
;     ...
;             PG8_LDB(B0, 1, 0); PG8_LDB(B1, 1, 1); PG8_SCHED; PG8_LDA(At, 1, 0); PG8_STAGE(PG8_SA(0, 1), a2 + hstep, voffA);
;             PG8_WAIT_V(8); PG8_WAIT_L(0); PG8_BAR; PG8_MMA(0, 0, At, B0); PG8_MMA(0, 1, At, B1); PG8_BAR; PG8_SCHED;
;             PG8_LDA(At, 1, 1); PG8_STAGE(PG8_SB(1, 0), b3, voffB); PG8_STAGE(PG8_SB(1, 1), b3 + hstep, voffB); PG8_STAGE(PG8_SA(1, 0), a3, voffA);
;             PG8_WAIT_V(8); PG8_WAIT_L(0); PG8_BAR; PG8_MMA(1, 0, At, B0); PG8_MMA(1, 1, At, B1); PG8_BAR; PG8_SCHED;
	s_add_i32 s70, 0, 0x18000
	s_add_i32 s71, 0, 0x1c000
	v_add_u32_e32 v162, s70, v153
	v_add_u32_e32 v178, s71, v153
	ds_read_b128 v[144:147], v162
	ds_read_b128 v[148:151], v162 offset:1024
	ds_read_b128 v[158:161], v162 offset:2048
	ds_read_b128 v[162:165], v162 offset:3072
	ds_read_b128 v[166:169], v178
	ds_read_b128 v[170:173], v178 offset:1024
	ds_read_b128 v[174:177], v178 offset:2048
	ds_read_b128 v[178:181], v178 offset:3072
	s_add_u32 s80, s50, 0x80
	s_addc_u32 s81, s51, 0
	s_add_u32 s50, s50, 0x40000
	s_addc_u32 s51, s51, 0
	s_mov_b32 m0, s55
	ds_read_b128 v[182:185], v157 offset:32768
	ds_read_b128 v[186:189], v157 offset:33792
	ds_read_b128 v[190:193], v157 offset:34816
	ds_read_b128 v[194:197], v157 offset:35840
	ds_read_b128 v[198:201], v157 offset:36864
	ds_read_b128 v[202:205], v157 offset:37888
	ds_read_b128 v[206:209], v157 offset:38912
	ds_read_b128 v[214:217], v157 offset:39936
	global_load_lds_dwordx4 v128, s[50:51]
	s_mov_b32 m0, s56
	s_nop 0
	global_load_lds_dwordx4 v132, s[50:51]
	s_waitcnt vmcnt(8)
	s_waitcnt lgkmcnt(0)
	s_barrier
	s_waitcnt lgkmcnt(0)
	v_mfma_f32_16x16x32_bf16 v[124:127], v[144:147], v[182:185], v[124:127]
	v_mfma_f32_16x16x32_bf16 v[120:123], v[158:161], v[182:185], v[120:123]
	v_mfma_f32_16x16x32_bf16 v[116:119], v[144:147], v[190:193], v[116:119]
	v_mfma_f32_16x16x32_bf16 v[112:115], v[158:161], v[190:193], v[112:115]
	v_mfma_f32_16x16x32_bf16 v[96:99], v[144:147], v[198:201], v[96:99]
	v_mfma_f32_16x16x32_bf16 v[88:91], v[158:161], v[198:201], v[88:91]
	v_mfma_f32_16x16x32_bf16 v[80:83], v[144:147], v[206:209], v[80:83]
	v_mfma_f32_16x16x32_bf16 v[72:75], v[158:161], v[206:209], v[72:75]
	v_mfma_f32_16x16x32_bf16 v[124:127], v[148:151], v[186:189], v[124:127]
	v_mfma_f32_16x16x32_bf16 v[120:123], v[162:165], v[186:189], v[120:123]
	v_mfma_f32_16x16x32_bf16 v[116:119], v[148:151], v[194:197], v[116:119]
	v_mfma_f32_16x16x32_bf16 v[112:115], v[162:165], v[194:197], v[112:115]
	v_mfma_f32_16x16x32_bf16 v[96:99], v[148:151], v[202:205], v[96:99]
	v_mfma_f32_16x16x32_bf16 v[88:91], v[162:165], v[202:205], v[88:91]
	v_mfma_f32_16x16x32_bf16 v[80:83], v[148:151], v[214:217], v[80:83]
	v_mfma_f32_16x16x32_bf16 v[72:75], v[162:165], v[214:217], v[72:75]
	v_mfma_f32_16x16x32_bf16 v[108:111], v[166:169], v[182:185], v[108:111]
	v_mfma_f32_16x16x32_bf16 v[104:107], v[174:177], v[182:185], v[104:107]
	v_mfma_f32_16x16x32_bf16 v[100:103], v[166:169], v[190:193], v[100:103]
	v_mfma_f32_16x16x32_bf16 v[92:95], v[174:177], v[190:193], v[92:95]
	v_mfma_f32_16x16x32_bf16 v[84:87], v[166:169], v[198:201], v[84:87]
	v_mfma_f32_16x16x32_bf16 v[76:79], v[174:177], v[198:201], v[76:79]
	v_mfma_f32_16x16x32_bf16 v[68:71], v[166:169], v[206:209], v[68:71]
	v_mfma_f32_16x16x32_bf16 v[64:67], v[174:177], v[206:209], v[64:67]
	v_mfma_f32_16x16x32_bf16 v[108:111], v[170:173], v[186:189], v[108:111]
	v_mfma_f32_16x16x32_bf16 v[104:107], v[178:181], v[186:189], v[104:107]
	v_mfma_f32_16x16x32_bf16 v[100:103], v[170:173], v[194:197], v[100:103]
	v_mfma_f32_16x16x32_bf16 v[92:95], v[178:181], v[194:197], v[92:95]
	v_mfma_f32_16x16x32_bf16 v[84:87], v[170:173], v[202:205], v[84:87]
	v_mfma_f32_16x16x32_bf16 v[76:79], v[178:181], v[202:205], v[76:79]
	v_mfma_f32_16x16x32_bf16 v[68:71], v[170:173], v[214:217], v[68:71]
	v_mfma_f32_16x16x32_bf16 v[64:67], v[178:181], v[214:217], v[64:67]
	s_barrier
	s_add_i32 s50, s70, s53
	s_add_u32 s82, s48, 0x80
	s_addc_u32 s83, s49, 0
	s_mov_b32 m0, s50
	ds_read_b128 v[182:185], v157 offset:49152
	ds_read_b128 v[186:189], v157 offset:50176
	ds_read_b128 v[190:193], v157 offset:51200
	ds_read_b128 v[194:197], v157 offset:52224
	ds_read_b128 v[198:201], v157 offset:53248
	ds_read_b128 v[202:205], v157 offset:54272
	ds_read_b128 v[206:209], v157 offset:55296
	ds_read_b128 v[214:217], v157 offset:56320
	global_load_lds_dwordx4 v130, s[82:83]
	s_add_i32 m0, s50, 0x2000
	s_add_u32 s48, s48, 0x40080
	s_addc_u32 s49, s49, 0
	s_add_i32 s50, s71, s53
	global_load_lds_dwordx4 v134, s[82:83]
	s_mov_b32 m0, s50
	s_nop 0
	global_load_lds_dwordx4 v130, s[48:49]
	s_add_i32 m0, s50, 0x2000
	s_nop 0
	global_load_lds_dwordx4 v134, s[48:49]
	s_mov_b32 m0, s58
	s_nop 0
	global_load_lds_dwordx4 v128, s[80:81]
	s_mov_b32 m0, s59
	s_nop 0
	global_load_lds_dwordx4 v132, s[80:81]
	s_waitcnt vmcnt(8)
	s_waitcnt lgkmcnt(0)
	s_barrier
	s_waitcnt lgkmcnt(0)
	v_mfma_f32_16x16x32_bf16 v[60:63], v[144:147], v[182:185], v[60:63]
	v_mfma_f32_16x16x32_bf16 v[56:59], v[158:161], v[182:185], v[56:59]
	v_mfma_f32_16x16x32_bf16 v[48:51], v[144:147], v[190:193], v[48:51]
	v_mfma_f32_16x16x32_bf16 v[40:43], v[158:161], v[190:193], v[40:43]
	v_mfma_f32_16x16x32_bf16 v[32:35], v[144:147], v[198:201], v[32:35]
	v_mfma_f32_16x16x32_bf16 v[24:27], v[158:161], v[198:201], v[24:27]
	v_mfma_f32_16x16x32_bf16 v[16:19], v[144:147], v[206:209], v[16:19]
	v_mfma_f32_16x16x32_bf16 v[8:11], v[158:161], v[206:209], v[8:11]
	v_mfma_f32_16x16x32_bf16 v[60:63], v[148:151], v[186:189], v[60:63]
	v_mfma_f32_16x16x32_bf16 v[56:59], v[162:165], v[186:189], v[56:59]
	v_mfma_f32_16x16x32_bf16 v[48:51], v[148:151], v[194:197], v[48:51]
	v_mfma_f32_16x16x32_bf16 v[40:43], v[162:165], v[194:197], v[40:43]
	v_mfma_f32_16x16x32_bf16 v[32:35], v[148:151], v[202:205], v[32:35]
	v_mfma_f32_16x16x32_bf16 v[24:27], v[162:165], v[202:205], v[24:27]
	v_mfma_f32_16x16x32_bf16 v[16:19], v[148:151], v[214:217], v[16:19]
	v_mfma_f32_16x16x32_bf16 v[8:11], v[162:165], v[214:217], v[8:11]
	v_mfma_f32_16x16x32_bf16 v[52:55], v[166:169], v[182:185], v[52:55]
	v_mfma_f32_16x16x32_bf16 v[44:47], v[174:177], v[182:185], v[44:47]
	v_mfma_f32_16x16x32_bf16 v[36:39], v[166:169], v[190:193], v[36:39]
	v_mfma_f32_16x16x32_bf16 v[28:31], v[174:177], v[190:193], v[28:31]
	v_mfma_f32_16x16x32_bf16 v[20:23], v[166:169], v[198:201], v[20:23]
	v_mfma_f32_16x16x32_bf16 v[12:15], v[174:177], v[198:201], v[12:15]
	v_mfma_f32_16x16x32_bf16 v[4:7], v[166:169], v[206:209], v[4:7]
	v_mfma_f32_16x16x32_bf16 v[0:3], v[174:177], v[206:209], v[0:3]
	v_mfma_f32_16x16x32_bf16 v[52:55], v[170:173], v[186:189], v[52:55]
	v_mfma_f32_16x16x32_bf16 v[44:47], v[178:181], v[186:189], v[44:47]
	v_mfma_f32_16x16x32_bf16 v[36:39], v[170:173], v[194:197], v[36:39]
	v_mfma_f32_16x16x32_bf16 v[28:31], v[178:181], v[194:197], v[28:31]
	v_mfma_f32_16x16x32_bf16 v[20:23], v[170:173], v[202:205], v[20:23]
	v_mfma_f32_16x16x32_bf16 v[12:15], v[178:181], v[202:205], v[12:15]
	v_mfma_f32_16x16x32_bf16 v[4:7], v[170:173], v[214:217], v[4:7]
	v_mfma_f32_16x16x32_bf16 v[0:3], v[178:181], v[214:217], v[0:3]
	s_barrier
; __device__ __forceinline__ float bf_lo(unsigned w) { return __uint_as_float(w << 16); }
; __device__ __forceinline__ float bf_hi(unsigned w) { return __uint_as_float(w & 0xffff0000u); }
; __device__ __forceinline__ u32x4 pack8(const f32x4 a, const f32x4 b) { u32x4 w; w.x = cvt_pk_bf16(a[0], a[1]); w.y = cvt_pk_bf16(a[2], a[3]); w.z = cvt_pk_bf16(b[0], b[1]); w.w = cvt_pk_bf16(b[2], b[3]); return w; }
;     __device__ __forceinline__ void operator()(const f32x4 (&acc)[2][2][4][2], const Unit& u, int wr, int wc, int fr, int fq) const {
;         const int row0 = u.pm * BM + wr * 64 + fr, col0 = u.pn * BM + wc * 32 + 8 * fq;
; #pragma unroll
;         for (int ai = 0; ai < 2; ++ai) { u32x4 gw[4][2], pw[4][2];
; #pragma unroll
;             for (int m = 0; m < 4; ++m) { const size_t off = (size_t)(row0 + ai * HALF + m * 16) * 2048 + col0;
; #pragma unroll
;                 for (int bj = 0; bj < 2; ++bj) { gw[m][bj] = *(const u32x4*)(G + off + bj * HALF); if (PASS == 1) pw[m][bj] = *(const u32x4*)(MIX + off + bj * HALF); } }
; #pragma unroll
;             for (int m = 0; m < 4; ++m) { const size_t off = (size_t)(row0 + ai * HALF + m * 16) * 2048 + col0;
; #pragma unroll
;                 for (int bj = 0; bj < 2; ++bj) { const u32x4 g4 = gw[m][bj];
;                     f32x4 v0 = (f32x4){bf_lo(g4.x), bf_hi(g4.x), bf_lo(g4.y), bf_hi(g4.y)} * acc[ai][bj][m][0], v1 = (f32x4){bf_lo(g4.z), bf_hi(g4.z), bf_lo(g4.w), bf_hi(g4.w)} * acc[ai][bj][m][1];
;                     if (PASS == 1) { const u32x4 p4 = pw[m][bj]; v0 += (f32x4){bf_lo(p4.x), bf_hi(p4.x), bf_lo(p4.y), bf_hi(p4.y)}; v1 += (f32x4){bf_lo(p4.z), bf_hi(p4.z), bf_lo(p4.w), bf_hi(p4.w)}; }
;                     *(u32x4*)(MIX + off + bj * HALF) = pack8(v0, v1); } } }
	s_add_i32 s69, s69, 2
	s_add_u32 s46, s46, 0x100
	s_addc_u32 s47, s47, 0
	s_add_u32 s67, s67, 0x100
	s_addc_u32 s68, s68, 0
	s_cmp_gt_u32 s69, 13
	s_cbranch_scc0 .LBB0_735
	v_lshl_add_u32 v150, s44, 8, v152
	v_lshl_or_b32 v144, s64, 8, v154
	v_ashrrev_i32_e32 v145, 31, v144
	v_or_b32_e32 v166, 16, v150
	v_lshlrev_b64 v[144:145], 1, v[144:145]
	v_ashrrev_i32_e32 v151, 31, v150
	v_ashrrev_i32_e32 v167, 31, v166
	v_lshl_add_u64 v[146:147], s[12:13], 0, v[144:145]
	v_lshlrev_b64 v[148:149], 12, v[150:151]
	v_lshlrev_b64 v[178:179], 12, v[166:167]
	v_lshl_add_u64 v[162:163], v[146:147], 0, v[148:149]
	v_lshl_add_u64 v[170:171], v[146:147], 0, v[178:179]
	global_load_dwordx4 v[158:161], v[162:163], off
	s_nop 0
	global_load_dwordx4 v[162:165], v[162:163], off offset:256
	s_nop 0
	global_load_dwordx4 v[166:169], v[170:171], off
	s_nop 0
	global_load_dwordx4 v[170:173], v[170:171], off offset:256
	v_or_b32_e32 v174, 32, v150
	v_ashrrev_i32_e32 v175, 31, v174
	v_lshlrev_b64 v[190:191], 12, v[174:175]
	v_lshl_add_u64 v[180:181], v[146:147], 0, v[190:191]
	global_load_dwordx4 v[174:177], v[180:181], off
	v_or_b32_e32 v150, 48, v150
	v_ashrrev_i32_e32 v151, 31, v150
	v_lshlrev_b64 v[150:151], 12, v[150:151]
	v_lshl_add_u64 v[182:183], s[14:15], 0, v[148:149]
	v_lshl_add_u64 v[186:187], v[146:147], 0, v[150:151]
	v_lshl_add_u64 v[192:193], v[182:183], 0, v[144:145]
	v_lshl_add_u64 v[194:195], s[14:15], 0, v[178:179]
	global_load_dwordx4 v[178:181], v[180:181], off offset:256
	s_nop 0
	global_load_dwordx4 v[182:185], v[186:187], off
	s_nop 0
	global_load_dwordx4 v[186:189], v[186:187], off offset:256
	v_lshl_add_u64 v[194:195], v[194:195], 0, v[144:145]
	s_and_b64 vcc, exec, s[10:11]
	s_mov_b32 s64, s36
	s_mov_b32 s44, s38
	s_mov_b64 s[48:49], s[42:43]
	s_mov_b64 s[46:47], s[40:41]
	s_waitcnt vmcnt(0)
	v_lshlrev_b32_e32 v196, 16, v158
	v_and_b32_e32 v197, 0xffff0000, v158
	v_lshlrev_b32_e32 v158, 16, v159
	v_and_b32_e32 v159, 0xffff0000, v159
	v_lshlrev_b32_e32 v198, 16, v160
	v_and_b32_e32 v199, 0xffff0000, v160
	v_lshlrev_b32_e32 v160, 16, v161
	v_and_b32_e32 v161, 0xffff0000, v161
	v_lshlrev_b32_e32 v200, 16, v162
	v_and_b32_e32 v201, 0xffff0000, v162
	v_lshlrev_b32_e32 v162, 16, v163
	v_and_b32_e32 v163, 0xffff0000, v163
	v_lshlrev_b32_e32 v202, 16, v164
	v_and_b32_e32 v203, 0xffff0000, v164
	v_lshlrev_b32_e32 v164, 16, v165
	v_and_b32_e32 v165, 0xffff0000, v165
	v_lshlrev_b32_e32 v204, 16, v166
	v_and_b32_e32 v205, 0xffff0000, v166
	v_lshlrev_b32_e32 v166, 16, v167
	v_and_b32_e32 v167, 0xffff0000, v167
	v_lshlrev_b32_e32 v206, 16, v168
	v_and_b32_e32 v207, 0xffff0000, v168
	v_lshlrev_b32_e32 v168, 16, v169
	v_and_b32_e32 v169, 0xffff0000, v169
	v_lshlrev_b32_e32 v208, 16, v170
	v_and_b32_e32 v209, 0xffff0000, v170
	v_lshlrev_b32_e32 v170, 16, v171
	v_and_b32_e32 v171, 0xffff0000, v171
	v_pk_mul_f32 v[126:127], v[126:127], v[158:159]
	v_pk_mul_f32 v[124:125], v[124:125], v[196:197]
	v_pk_mul_f32 v[122:123], v[122:123], v[160:161]
	v_pk_mul_f32 v[120:121], v[120:121], v[198:199]
	v_pk_mul_f32 v[110:111], v[110:111], v[162:163]
	v_pk_mul_f32 v[108:109], v[108:109], v[200:201]
	v_pk_mul_f32 v[158:159], v[106:107], v[164:165]
	v_pk_mul_f32 v[106:107], v[104:105], v[202:203]
	v_pk_mul_f32 v[118:119], v[118:119], v[166:167]
	v_pk_mul_f32 v[116:117], v[116:117], v[204:205]
	v_pk_mul_f32 v[114:115], v[114:115], v[168:169]
	v_pk_mul_f32 v[112:113], v[112:113], v[206:207]
	v_pk_mul_f32 v[160:161], v[102:103], v[170:171]
	v_pk_mul_f32 v[162:163], v[100:101], v[208:209]
	v_cvt_pk_bf16_f32 v100, v124, v125
	v_cvt_pk_bf16_f32 v101, v126, v127
	v_cvt_pk_bf16_f32 v102, v120, v121
	v_cvt_pk_bf16_f32 v103, v122, v123
	v_cvt_pk_bf16_f32 v104, v108, v109
	v_cvt_pk_bf16_f32 v105, v110, v111
	v_cvt_pk_bf16_f32 v106, v106, v107
	v_cvt_pk_bf16_f32 v107, v158, v159
	v_cvt_pk_bf16_f32 v108, v116, v117
	v_cvt_pk_bf16_f32 v109, v118, v119
	v_cvt_pk_bf16_f32 v110, v112, v113
	v_cvt_pk_bf16_f32 v111, v114, v115
	global_store_dwordx4 v[192:193], v[100:103], off
	global_store_dwordx4 v[192:193], v[104:107], off offset:256
	global_store_dwordx4 v[194:195], v[108:111], off
	v_lshlrev_b32_e32 v100, 16, v172
	v_and_b32_e32 v101, 0xffff0000, v172
	v_lshlrev_b32_e32 v102, 16, v173
	v_and_b32_e32 v103, 0xffff0000, v173
	v_pk_mul_f32 v[102:103], v[94:95], v[102:103]
	v_pk_mul_f32 v[94:95], v[92:93], v[100:101]
	v_cvt_pk_bf16_f32 v92, v162, v163
	v_cvt_pk_bf16_f32 v93, v160, v161
	v_cvt_pk_bf16_f32 v94, v94, v95
	v_cvt_pk_bf16_f32 v95, v102, v103
	global_store_dwordx4 v[194:195], v[92:95], off offset:256
	v_lshl_add_u64 v[100:101], v[148:149], 0, s[30:31]
	v_lshl_add_u64 v[102:103], v[148:149], 0, s[34:35]
	v_lshlrev_b32_e32 v92, 16, v174
	v_and_b32_e32 v93, 0xffff0000, v174
	v_lshlrev_b32_e32 v94, 16, v175
	v_and_b32_e32 v95, 0xffff0000, v175
	v_pk_mul_f32 v[94:95], v[98:99], v[94:95]
	v_pk_mul_f32 v[92:93], v[96:97], v[92:93]
	v_lshlrev_b32_e32 v96, 16, v176
	v_and_b32_e32 v97, 0xffff0000, v176
	v_lshlrev_b32_e32 v98, 16, v177
	v_and_b32_e32 v99, 0xffff0000, v177
	v_pk_mul_f32 v[98:99], v[90:91], v[98:99]
	v_pk_mul_f32 v[90:91], v[88:89], v[96:97]
	v_cvt_pk_bf16_f32 v88, v92, v93
	v_lshl_add_u64 v[92:93], s[14:15], 0, v[190:191]
	v_cvt_pk_bf16_f32 v89, v94, v95
	v_cvt_pk_bf16_f32 v90, v90, v91
	v_cvt_pk_bf16_f32 v91, v98, v99
	v_lshl_add_u64 v[92:93], v[92:93], 0, v[144:145]
	global_store_dwordx4 v[92:93], v[88:91], off
	v_lshl_add_u64 v[96:97], v[148:149], 0, s[26:27]
	v_lshl_add_u64 v[98:99], v[148:149], 0, s[28:29]
	v_lshlrev_b32_e32 v88, 16, v178
	v_and_b32_e32 v89, 0xffff0000, v178
	v_lshlrev_b32_e32 v90, 16, v179
	v_and_b32_e32 v91, 0xffff0000, v179
	v_pk_mul_f32 v[86:87], v[86:87], v[90:91]
; __device__ __forceinline__ float bf_lo(unsigned w) { return __uint_as_float(w << 16); }
; __device__ __forceinline__ float bf_hi(unsigned w) { return __uint_as_float(w & 0xffff0000u); }
; __device__ __forceinline__ u32x4 pack8(const f32x4 a, const f32x4 b) { u32x4 w; w.x = cvt_pk_bf16(a[0], a[1]); w.y = cvt_pk_bf16(a[2], a[3]); w.z = cvt_pk_bf16(b[0], b[1]); w.w = cvt_pk_bf16(b[2], b[3]); return w; }
;     __device__ __forceinline__ void operator()(const f32x4 (&acc)[2][2][4][2], const Unit& u, int wr, int wc, int fr, int fq) const {
;     ...
;         for (int ai = 0; ai < 2; ++ai) { u32x4 gw[4][2], pw[4][2];
; #pragma unroll
;             for (int m = 0; m < 4; ++m) { const size_t off = (size_t)(row0 + ai * HALF + m * 16) * 2048 + col0;
; #pragma unroll
;                 for (int bj = 0; bj < 2; ++bj) { gw[m][bj] = *(const u32x4*)(G + off + bj * HALF); if (PASS == 1) pw[m][bj] = *(const u32x4*)(MIX + off + bj * HALF); } }
; #pragma unroll
;             for (int m = 0; m < 4; ++m) { const size_t off = (size_t)(row0 + ai * HALF + m * 16) * 2048 + col0;
; #pragma unroll
;                 for (int bj = 0; bj < 2; ++bj) { const u32x4 g4 = gw[m][bj];
;                     f32x4 v0 = (f32x4){bf_lo(g4.x), bf_hi(g4.x), bf_lo(g4.y), bf_hi(g4.y)} * acc[ai][bj][m][0], v1 = (f32x4){bf_lo(g4.z), bf_hi(g4.z), bf_lo(g4.w), bf_hi(g4.w)} * acc[ai][bj][m][1];
;                     if (PASS == 1) { const u32x4 p4 = pw[m][bj]; v0 += (f32x4){bf_lo(p4.x), bf_hi(p4.x), bf_lo(p4.y), bf_hi(p4.y)}; v1 += (f32x4){bf_lo(p4.z), bf_hi(p4.z), bf_lo(p4.w), bf_hi(p4.w)}; }
;                     *(u32x4*)(MIX + off + bj * HALF) = pack8(v0, v1); } } }
	v_pk_mul_f32 v[84:85], v[84:85], v[88:89]
	v_lshlrev_b32_e32 v88, 16, v180
	v_and_b32_e32 v89, 0xffff0000, v180
	v_lshlrev_b32_e32 v90, 16, v181
	v_and_b32_e32 v91, 0xffff0000, v181
	v_pk_mul_f32 v[90:91], v[78:79], v[90:91]
	v_pk_mul_f32 v[78:79], v[76:77], v[88:89]
	v_cvt_pk_bf16_f32 v76, v84, v85
	v_cvt_pk_bf16_f32 v77, v86, v87
	v_cvt_pk_bf16_f32 v78, v78, v79
	v_cvt_pk_bf16_f32 v79, v90, v91
	global_store_dwordx4 v[92:93], v[76:79], off offset:256
	s_nop 1
	v_lshlrev_b32_e32 v76, 16, v182
	v_and_b32_e32 v77, 0xffff0000, v182
	v_lshlrev_b32_e32 v78, 16, v183
	v_and_b32_e32 v79, 0xffff0000, v183
	v_pk_mul_f32 v[78:79], v[82:83], v[78:79]
	v_pk_mul_f32 v[76:77], v[80:81], v[76:77]
	v_lshlrev_b32_e32 v80, 16, v184
	v_and_b32_e32 v81, 0xffff0000, v184
	v_lshlrev_b32_e32 v82, 16, v185
	v_and_b32_e32 v83, 0xffff0000, v185
	v_pk_mul_f32 v[82:83], v[74:75], v[82:83]
	v_pk_mul_f32 v[74:75], v[72:73], v[80:81]
	v_cvt_pk_bf16_f32 v72, v76, v77
	v_lshl_add_u64 v[76:77], s[14:15], 0, v[150:151]
	v_cvt_pk_bf16_f32 v73, v78, v79
	v_cvt_pk_bf16_f32 v74, v74, v75
	v_cvt_pk_bf16_f32 v75, v82, v83
	v_lshl_add_u64 v[76:77], v[76:77], 0, v[144:145]
	global_store_dwordx4 v[76:77], v[72:75], off
	s_nop 1
	v_lshlrev_b32_e32 v72, 16, v186
	v_and_b32_e32 v73, 0xffff0000, v186
	v_lshlrev_b32_e32 v74, 16, v187
	v_and_b32_e32 v75, 0xffff0000, v187
	v_pk_mul_f32 v[70:71], v[70:71], v[74:75]
	v_pk_mul_f32 v[68:69], v[68:69], v[72:73]
	v_lshlrev_b32_e32 v72, 16, v188
	v_and_b32_e32 v73, 0xffff0000, v188
	v_lshlrev_b32_e32 v74, 16, v189
	v_and_b32_e32 v75, 0xffff0000, v189
	v_pk_mul_f32 v[74:75], v[66:67], v[74:75]
	v_pk_mul_f32 v[66:67], v[64:65], v[72:73]
	v_cvt_pk_bf16_f32 v64, v68, v69
	v_cvt_pk_bf16_f32 v65, v70, v71
	v_cvt_pk_bf16_f32 v66, v66, v67
	v_cvt_pk_bf16_f32 v67, v74, v75
	global_store_dwordx4 v[76:77], v[64:67], off offset:256
	s_nop 1
	v_lshl_add_u64 v[64:65], v[146:147], 0, v[96:97]
	global_load_dwordx4 v[68:71], v[64:65], off
	global_load_dwordx4 v[72:75], v[64:65], off offset:256
	v_lshl_add_u64 v[64:65], v[146:147], 0, v[98:99]
	global_load_dwordx4 v[76:79], v[64:65], off
	global_load_dwordx4 v[80:83], v[64:65], off offset:256
	v_lshl_add_u64 v[64:65], v[146:147], 0, v[100:101]
	global_load_dwordx4 v[84:87], v[64:65], off
	global_load_dwordx4 v[88:91], v[64:65], off offset:256
	v_lshl_add_u64 v[64:65], v[146:147], 0, v[102:103]
	global_load_dwordx4 v[92:95], v[64:65], off
	s_nop 0
	global_load_dwordx4 v[64:67], v[64:65], off offset:256
	s_waitcnt vmcnt(7)
	v_lshlrev_b32_e32 v104, 16, v68
	v_and_b32_e32 v105, 0xffff0000, v68
	v_lshlrev_b32_e32 v68, 16, v69
	v_and_b32_e32 v69, 0xffff0000, v69
	v_pk_mul_f32 v[62:63], v[62:63], v[68:69]
	v_pk_mul_f32 v[60:61], v[60:61], v[104:105]
	v_lshlrev_b32_e32 v68, 16, v70
	v_and_b32_e32 v69, 0xffff0000, v70
	v_lshlrev_b32_e32 v70, 16, v71
	v_and_b32_e32 v71, 0xffff0000, v71
	v_pk_mul_f32 v[70:71], v[58:59], v[70:71]
	v_pk_mul_f32 v[58:59], v[56:57], v[68:69]
	v_cvt_pk_bf16_f32 v56, v60, v61
	v_lshl_add_u64 v[60:61], s[14:15], 0, v[96:97]
	v_cvt_pk_bf16_f32 v57, v62, v63
	v_cvt_pk_bf16_f32 v58, v58, v59
	v_cvt_pk_bf16_f32 v59, v70, v71
	v_lshl_add_u64 v[60:61], v[60:61], 0, v[144:145]
	global_store_dwordx4 v[60:61], v[56:59], off
	s_waitcnt vmcnt(7)
	s_nop 0
	v_lshlrev_b32_e32 v56, 16, v72
	v_and_b32_e32 v57, 0xffff0000, v72
	v_lshlrev_b32_e32 v58, 16, v73
	v_and_b32_e32 v59, 0xffff0000, v73
	v_pk_mul_f32 v[54:55], v[54:55], v[58:59]
	v_pk_mul_f32 v[52:53], v[52:53], v[56:57]
	v_lshlrev_b32_e32 v56, 16, v74
	v_and_b32_e32 v57, 0xffff0000, v74
	v_lshlrev_b32_e32 v58, 16, v75
	v_and_b32_e32 v59, 0xffff0000, v75
	v_pk_mul_f32 v[58:59], v[46:47], v[58:59]
	v_pk_mul_f32 v[46:47], v[44:45], v[56:57]
	v_cvt_pk_bf16_f32 v44, v52, v53
	v_cvt_pk_bf16_f32 v45, v54, v55
	v_cvt_pk_bf16_f32 v46, v46, v47
	v_cvt_pk_bf16_f32 v47, v58, v59
	global_store_dwordx4 v[60:61], v[44:47], off offset:256
	s_waitcnt vmcnt(7)
; __device__ __forceinline__ float bf_lo(unsigned w) { return __uint_as_float(w << 16); }
; __device__ __forceinline__ float bf_hi(unsigned w) { return __uint_as_float(w & 0xffff0000u); }
; __device__ __forceinline__ u32x4 pack8(const f32x4 a, const f32x4 b) { u32x4 w; w.x = cvt_pk_bf16(a[0], a[1]); w.y = cvt_pk_bf16(a[2], a[3]); w.z = cvt_pk_bf16(b[0], b[1]); w.w = cvt_pk_bf16(b[2], b[3]); return w; }
; #define PG8_WAIT_V(n) asm volatile("s_waitcnt vmcnt(" #n ")" ::: "memory")
; #define PG8_BAR __builtin_amdgcn_s_barrier()
;     __device__ __forceinline__ void operator()(const f32x4 (&acc)[2][2][4][2], const Unit& u, int wr, int wc, int fr, int fq) const {
;     ...
;             for (int m = 0; m < 4; ++m) { const size_t off = (size_t)(row0 + ai * HALF + m * 16) * 2048 + col0;
; #pragma unroll
;                 for (int bj = 0; bj < 2; ++bj) { const u32x4 g4 = gw[m][bj];
;                     f32x4 v0 = (f32x4){bf_lo(g4.x), bf_hi(g4.x), bf_lo(g4.y), bf_hi(g4.y)} * acc[ai][bj][m][0], v1 = (f32x4){bf_lo(g4.z), bf_hi(g4.z), bf_lo(g4.w), bf_hi(g4.w)} * acc[ai][bj][m][1];
;                     if (PASS == 1) { const u32x4 p4 = pw[m][bj]; v0 += (f32x4){bf_lo(p4.x), bf_hi(p4.x), bf_lo(p4.y), bf_hi(p4.y)}; v1 += (f32x4){bf_lo(p4.z), bf_hi(p4.z), bf_lo(p4.w), bf_hi(p4.w)}; }
;                     *(u32x4*)(MIX + off + bj * HALF) = pack8(v0, v1); } } }
; template <class Epi, class Sched, bool ALIGN_EPI = false, bool SP2 = false>
; __device__ __forceinline__ void gemm_phase(PG8_LAS unsigned char* lds, const Gemm g, const Sched& S, const Epi& E) {
;     ...
;         if constexpr (!Epi::AFTER_DRAIN) { E(acc, cur, wr, wc, fr, fq); S.done(cur); }
;         if (!has_next) break;
; #pragma unroll
;         for (int a = 0; a < 2; ++a)
; #pragma unroll
;             for (int b = 0; b < 2; ++b)
; #pragma unroll
;                 for (int m = 0; m < 4; ++m)
; #pragma unroll
;                     for (int n = 0; n < 2; ++n) acc[a][b][m][n] = (f32x4){0.f, 0.f, 0.f, 0.f};
;         cur = nxt; cA = nA; cB = nB; ++ui;
;         if constexpr (ALIGN_EPI) { if (wr == 1) PG8_BAR; }
;     }
;     PG8_WAIT_V(0);
;     if constexpr (!ALIGN_EPI) { if (wr == 0) PG8_BAR; }
;     PG8_BAR;
	s_nop 0
	v_lshlrev_b32_e32 v44, 16, v76
	v_and_b32_e32 v45, 0xffff0000, v76
	v_lshlrev_b32_e32 v46, 16, v77
	v_and_b32_e32 v47, 0xffff0000, v77
	v_pk_mul_f32 v[46:47], v[50:51], v[46:47]
	v_pk_mul_f32 v[44:45], v[48:49], v[44:45]
	v_lshlrev_b32_e32 v48, 16, v78
	v_and_b32_e32 v49, 0xffff0000, v78
	v_lshlrev_b32_e32 v50, 16, v79
	v_and_b32_e32 v51, 0xffff0000, v79
	v_pk_mul_f32 v[50:51], v[42:43], v[50:51]
	v_pk_mul_f32 v[42:43], v[40:41], v[48:49]
	v_cvt_pk_bf16_f32 v40, v44, v45
	v_lshl_add_u64 v[44:45], s[14:15], 0, v[98:99]
	v_cvt_pk_bf16_f32 v41, v46, v47
	v_cvt_pk_bf16_f32 v42, v42, v43
	v_cvt_pk_bf16_f32 v43, v50, v51
	v_lshl_add_u64 v[44:45], v[44:45], 0, v[144:145]
	global_store_dwordx4 v[44:45], v[40:43], off
	s_waitcnt vmcnt(7)
	s_nop 0
	v_lshlrev_b32_e32 v40, 16, v80
	v_and_b32_e32 v41, 0xffff0000, v80
	v_lshlrev_b32_e32 v42, 16, v81
	v_and_b32_e32 v43, 0xffff0000, v81
	v_pk_mul_f32 v[38:39], v[38:39], v[42:43]
	v_pk_mul_f32 v[36:37], v[36:37], v[40:41]
	v_lshlrev_b32_e32 v40, 16, v82
	v_and_b32_e32 v41, 0xffff0000, v82
	v_lshlrev_b32_e32 v42, 16, v83
	v_and_b32_e32 v43, 0xffff0000, v83
	v_pk_mul_f32 v[42:43], v[30:31], v[42:43]
	v_pk_mul_f32 v[30:31], v[28:29], v[40:41]
	v_cvt_pk_bf16_f32 v28, v36, v37
	v_cvt_pk_bf16_f32 v29, v38, v39
	v_cvt_pk_bf16_f32 v30, v30, v31
	v_cvt_pk_bf16_f32 v31, v42, v43
	global_store_dwordx4 v[44:45], v[28:31], off offset:256
	s_waitcnt vmcnt(7)
	s_nop 0
	v_lshlrev_b32_e32 v28, 16, v84
	v_and_b32_e32 v29, 0xffff0000, v84
	v_lshlrev_b32_e32 v30, 16, v85
	v_and_b32_e32 v31, 0xffff0000, v85
	v_pk_mul_f32 v[30:31], v[34:35], v[30:31]
	v_pk_mul_f32 v[28:29], v[32:33], v[28:29]
	v_lshlrev_b32_e32 v32, 16, v86
	v_and_b32_e32 v33, 0xffff0000, v86
	v_lshlrev_b32_e32 v34, 16, v87
	v_and_b32_e32 v35, 0xffff0000, v87
	v_pk_mul_f32 v[34:35], v[26:27], v[34:35]
	v_pk_mul_f32 v[26:27], v[24:25], v[32:33]
	v_cvt_pk_bf16_f32 v24, v28, v29
	v_lshl_add_u64 v[28:29], s[14:15], 0, v[100:101]
	v_cvt_pk_bf16_f32 v25, v30, v31
	v_cvt_pk_bf16_f32 v26, v26, v27
	v_cvt_pk_bf16_f32 v27, v34, v35
	v_lshl_add_u64 v[28:29], v[28:29], 0, v[144:145]
	global_store_dwordx4 v[28:29], v[24:27], off
	s_waitcnt vmcnt(7)
	s_nop 0
	v_lshlrev_b32_e32 v24, 16, v88
	v_and_b32_e32 v25, 0xffff0000, v88
	v_lshlrev_b32_e32 v26, 16, v89
	v_and_b32_e32 v27, 0xffff0000, v89
	v_pk_mul_f32 v[22:23], v[22:23], v[26:27]
	v_pk_mul_f32 v[20:21], v[20:21], v[24:25]
	v_lshlrev_b32_e32 v24, 16, v90
	v_and_b32_e32 v25, 0xffff0000, v90
	v_lshlrev_b32_e32 v26, 16, v91
	v_and_b32_e32 v27, 0xffff0000, v91
	v_pk_mul_f32 v[26:27], v[14:15], v[26:27]
	v_pk_mul_f32 v[14:15], v[12:13], v[24:25]
	v_cvt_pk_bf16_f32 v12, v20, v21
	v_cvt_pk_bf16_f32 v13, v22, v23
	v_cvt_pk_bf16_f32 v14, v14, v15
	v_cvt_pk_bf16_f32 v15, v26, v27
	global_store_dwordx4 v[28:29], v[12:15], off offset:256
	s_waitcnt vmcnt(7)
	s_nop 0
	v_lshlrev_b32_e32 v12, 16, v92
	v_and_b32_e32 v13, 0xffff0000, v92
	v_lshlrev_b32_e32 v14, 16, v93
	v_and_b32_e32 v15, 0xffff0000, v93
	v_pk_mul_f32 v[14:15], v[18:19], v[14:15]
	v_pk_mul_f32 v[12:13], v[16:17], v[12:13]
	v_lshlrev_b32_e32 v16, 16, v94
	v_and_b32_e32 v17, 0xffff0000, v94
	v_lshlrev_b32_e32 v18, 16, v95
	v_and_b32_e32 v19, 0xffff0000, v95
	v_pk_mul_f32 v[18:19], v[10:11], v[18:19]
	v_pk_mul_f32 v[10:11], v[8:9], v[16:17]
	v_cvt_pk_bf16_f32 v8, v12, v13
	v_lshl_add_u64 v[12:13], s[14:15], 0, v[102:103]
	v_cvt_pk_bf16_f32 v9, v14, v15
	v_cvt_pk_bf16_f32 v10, v10, v11
	v_cvt_pk_bf16_f32 v11, v18, v19
	v_lshl_add_u64 v[12:13], v[12:13], 0, v[144:145]
	global_store_dwordx4 v[12:13], v[8:11], off
	s_waitcnt vmcnt(7)
	s_nop 0
	v_lshlrev_b32_e32 v8, 16, v64
	v_and_b32_e32 v9, 0xffff0000, v64
	v_lshlrev_b32_e32 v10, 16, v65
	v_and_b32_e32 v11, 0xffff0000, v65
	v_pk_mul_f32 v[6:7], v[6:7], v[10:11]
	v_pk_mul_f32 v[4:5], v[4:5], v[8:9]
	v_lshlrev_b32_e32 v8, 16, v66
	v_and_b32_e32 v9, 0xffff0000, v66
	v_lshlrev_b32_e32 v10, 16, v67
	v_and_b32_e32 v11, 0xffff0000, v67
	v_pk_mul_f32 v[10:11], v[2:3], v[10:11]
	v_pk_mul_f32 v[2:3], v[0:1], v[8:9]
	v_cvt_pk_bf16_f32 v0, v4, v5
	v_cvt_pk_bf16_f32 v1, v6, v7
	v_cvt_pk_bf16_f32 v2, v2, v3
	v_cvt_pk_bf16_f32 v3, v10, v11
	global_store_dwordx4 v[12:13], v[0:3], off offset:256
	s_cbranch_vccz .LBB0_728
	s_waitcnt vmcnt(0)
	s_cmpk_gt_u32 s3, 0xff
	s_cbranch_scc1 .LBB0_739
	s_barrier

; #define PG8_STAGE(bufoff, gbase, voff) do { _Pragma("unroll") for (int _i = 0; _i < 2; ++_i) \
;         __builtin_amdgcn_global_load_lds((const unsigned*)((const char*)(gbase) + (voff)[_i]), (PG8_LAS unsigned*)(lds + (bufoff) + ldsw + _i * 8192), 16, 0, 0); } while (0)
; #define PG8_LDA(dst, b, h) do { _Pragma("unroll") for (int m = 0; m < 4; ++m) _Pragma("unroll") for (int k = 0; k < 2; ++k) dst[m][k] = *(const PG8_LAS bf16x8*)(lds + PG8_SA(b, h) + aoff + m * 2048 + k * 1024); } while (0)
; #define PG8_LDB(dst, b, h) do { _Pragma("unroll") for (int n = 0; n < 2; ++n) _Pragma("unroll") for (int k = 0; k < 2; ++k) dst[n][k] = *(const PG8_LAS bf16x8*)(lds + PG8_SB(b, h) + boff + n * 2048 + k * 1024); } while (0)
; #define PG8_MMA(ai, bj, At, Bt) do { __builtin_amdgcn_s_setprio(1); _Pragma("unroll") for (int m = 0; m < 4; ++m) _Pragma("unroll") for (int n = 0; n < 2; ++n) _Pragma("unroll") for (int k = 0; k < 2; ++k) \
;         acc[ai][bj][m][n] = __builtin_amdgcn_mfma_f32_16x16x32_bf16(Bt[n][k], At[m][k], acc[ai][bj][m][n], 0, 0, 0); __builtin_amdgcn_s_setprio(0); } while (0)
; #define PG8_WAIT_V(n) asm volatile("s_waitcnt vmcnt(" #n ")" ::: "memory")
; #define PG8_WAIT_L(n) asm volatile("s_waitcnt lgkmcnt(" #n ")" ::: "memory")
; #define PG8_BAR __builtin_amdgcn_s_barrier()
; #define PG8_SCHED __builtin_amdgcn_sched_barrier(0)
; template <class Epi, class Sched, bool ALIGN_EPI = false, bool SP2 = false>
; __device__ __forceinline__ void gemm_phase(PG8_LAS unsigned char* lds, const Gemm g, const Sched& S, const Epi& E) {
;     ...
;             PG8_LDB(B0, 0, 0); PG8_LDB(B1, 0, 1); PG8_SCHED; PG8_LDA(At, 0, 0); PG8_STAGE(PG8_SA(1, 1), a1 + hstep, voffA);
;             PG8_WAIT_V(8); PG8_WAIT_L(0); PG8_BAR; PG8_MMA(0, 0, At, B0); PG8_MMA(0, 1, At, B1); PG8_BAR; PG8_SCHED;
;             PG8_LDA(At, 0, 1); PG8_STAGE(PG8_SB(0, 0), b2, voffB); PG8_STAGE(PG8_SB(0, 1), b2 + hstep, voffB); PG8_STAGE(PG8_SA(0, 0), a2, voffA);
;             PG8_WAIT_V(8); PG8_WAIT_L(0); PG8_BAR; PG8_MMA(1, 0, At, B0); PG8_MMA(1, 1, At, B1); PG8_BAR; PG8_SCHED;
.LBB0_755:
	ds_read_b128 v[128:131], v177
	ds_read_b128 v[132:135], v177 offset:1024
	ds_read_b128 v[136:139], v177 offset:2048
	ds_read_b128 v[140:143], v177 offset:3072
	ds_read_b128 v[144:147], v178
	ds_read_b128 v[164:167], v178 offset:1024
	ds_read_b128 v[168:171], v178 offset:2048
	ds_read_b128 v[180:183], v178 offset:3072
	s_add_u32 s40, s38, 0xfffc0080
	s_addc_u32 s41, s39, -1
	s_cmp_eq_u32 s61, 12
	s_cselect_b32 s43, s29, s41
	s_cselect_b32 s42, s57, s40
	s_cselect_b32 s41, s27, s60
	s_cselect_b32 s40, s58, s59
	s_add_i32 m0, s37, 0xc000
	ds_read_b128 v[184:187], v179
	ds_read_b128 v[188:191], v179 offset:1024
	ds_read_b128 v[192:195], v179 offset:2048
	ds_read_b128 v[196:199], v179 offset:3072
	ds_read_b128 v[200:203], v179 offset:4096
	ds_read_b128 v[204:207], v179 offset:5120
	ds_read_b128 v[208:211], v179 offset:6144
	ds_read_b128 v[214:217], v179 offset:7168
	global_load_lds_dwordx4 v156, s[38:39]
	s_add_i32 m0, s37, 0xe000
	s_nop 0
	global_load_lds_dwordx4 v158, s[38:39]
	s_waitcnt vmcnt(8)
	s_waitcnt lgkmcnt(0)
	s_barrier
	s_waitcnt lgkmcnt(0)
	v_mfma_f32_16x16x32_bf16 v[124:127], v[128:131], v[184:187], v[124:127]
	v_mfma_f32_16x16x32_bf16 v[120:123], v[136:139], v[184:187], v[120:123]
	v_mfma_f32_16x16x32_bf16 v[108:111], v[128:131], v[192:195], v[108:111]
	v_mfma_f32_16x16x32_bf16 v[104:107], v[136:139], v[192:195], v[104:107]
	v_mfma_f32_16x16x32_bf16 v[92:95], v[128:131], v[200:203], v[92:95]
	v_mfma_f32_16x16x32_bf16 v[88:91], v[136:139], v[200:203], v[88:91]
	v_mfma_f32_16x16x32_bf16 v[76:79], v[128:131], v[208:211], v[76:79]
	v_mfma_f32_16x16x32_bf16 v[72:75], v[136:139], v[208:211], v[72:75]
	v_mfma_f32_16x16x32_bf16 v[124:127], v[132:135], v[188:191], v[124:127]
	v_mfma_f32_16x16x32_bf16 v[120:123], v[140:143], v[188:191], v[120:123]
	v_mfma_f32_16x16x32_bf16 v[108:111], v[132:135], v[196:199], v[108:111]
	v_mfma_f32_16x16x32_bf16 v[104:107], v[140:143], v[196:199], v[104:107]
	v_mfma_f32_16x16x32_bf16 v[92:95], v[132:135], v[204:207], v[92:95]
	v_mfma_f32_16x16x32_bf16 v[88:91], v[140:143], v[204:207], v[88:91]
	v_mfma_f32_16x16x32_bf16 v[76:79], v[132:135], v[214:217], v[76:79]
	v_mfma_f32_16x16x32_bf16 v[72:75], v[140:143], v[214:217], v[72:75]
	v_mfma_f32_16x16x32_bf16 v[116:119], v[144:147], v[184:187], v[116:119]
	v_mfma_f32_16x16x32_bf16 v[112:115], v[168:171], v[184:187], v[112:115]
	v_mfma_f32_16x16x32_bf16 v[100:103], v[144:147], v[192:195], v[100:103]
	v_mfma_f32_16x16x32_bf16 v[96:99], v[168:171], v[192:195], v[96:99]
	v_mfma_f32_16x16x32_bf16 v[84:87], v[144:147], v[200:203], v[84:87]
	v_mfma_f32_16x16x32_bf16 v[80:83], v[168:171], v[200:203], v[80:83]
	v_mfma_f32_16x16x32_bf16 v[68:71], v[144:147], v[208:211], v[68:71]
	v_mfma_f32_16x16x32_bf16 v[64:67], v[168:171], v[208:211], v[64:67]
	v_mfma_f32_16x16x32_bf16 v[116:119], v[164:167], v[188:191], v[116:119]
	v_mfma_f32_16x16x32_bf16 v[112:115], v[180:183], v[188:191], v[112:115]
	v_mfma_f32_16x16x32_bf16 v[100:103], v[164:167], v[196:199], v[100:103]
	v_mfma_f32_16x16x32_bf16 v[96:99], v[180:183], v[196:199], v[96:99]
	v_mfma_f32_16x16x32_bf16 v[84:87], v[164:167], v[204:207], v[84:87]
	v_mfma_f32_16x16x32_bf16 v[80:83], v[180:183], v[204:207], v[80:83]
	v_mfma_f32_16x16x32_bf16 v[68:71], v[164:167], v[214:217], v[68:71]
	v_mfma_f32_16x16x32_bf16 v[64:67], v[180:183], v[214:217], v[64:67]
	s_barrier
	s_add_i32 s62, s54, s45
	s_mov_b32 m0, s62
	ds_read_b128 v[184:187], v179 offset:16384
	ds_read_b128 v[188:191], v179 offset:17408
	ds_read_b128 v[192:195], v179 offset:18432
	ds_read_b128 v[196:199], v179 offset:19456
	ds_read_b128 v[200:203], v179 offset:20480
	ds_read_b128 v[204:207], v179 offset:21504
	ds_read_b128 v[208:211], v179 offset:22528
	ds_read_b128 v[214:217], v179 offset:23552
	global_load_lds_dwordx4 v150, s[40:41]
	s_add_i32 m0, s62, 0x2000
	s_add_u32 s62, s40, 0x40000
	s_addc_u32 s63, s41, 0
	s_add_i32 s64, s55, s45
	global_load_lds_dwordx4 v154, s[40:41]
	s_mov_b32 m0, s64
	s_nop 0
	global_load_lds_dwordx4 v150, s[62:63]
	s_add_i32 m0, s64, 0x2000
	s_nop 0
	global_load_lds_dwordx4 v154, s[62:63]
	s_mov_b32 m0, s37
	s_nop 0
	global_load_lds_dwordx4 v148, s[42:43]
	s_mov_b32 m0, s46
	s_nop 0
	global_load_lds_dwordx4 v152, s[42:43]
	s_waitcnt vmcnt(8)
	s_waitcnt lgkmcnt(0)
	s_barrier
	s_waitcnt lgkmcnt(0)
	v_mfma_f32_16x16x32_bf16 v[60:63], v[128:131], v[184:187], v[60:63]
	v_mfma_f32_16x16x32_bf16 v[56:59], v[136:139], v[184:187], v[56:59]
	v_mfma_f32_16x16x32_bf16 v[44:47], v[128:131], v[192:195], v[44:47]
	v_mfma_f32_16x16x32_bf16 v[40:43], v[136:139], v[192:195], v[40:43]
	v_mfma_f32_16x16x32_bf16 v[28:31], v[128:131], v[200:203], v[28:31]
	v_mfma_f32_16x16x32_bf16 v[24:27], v[136:139], v[200:203], v[24:27]
	v_mfma_f32_16x16x32_bf16 v[12:15], v[128:131], v[208:211], v[12:15]
	v_mfma_f32_16x16x32_bf16 v[8:11], v[136:139], v[208:211], v[8:11]
	v_mfma_f32_16x16x32_bf16 v[60:63], v[132:135], v[188:191], v[60:63]
	v_mfma_f32_16x16x32_bf16 v[56:59], v[140:143], v[188:191], v[56:59]
	v_mfma_f32_16x16x32_bf16 v[44:47], v[132:135], v[196:199], v[44:47]
	v_mfma_f32_16x16x32_bf16 v[40:43], v[140:143], v[196:199], v[40:43]
	v_mfma_f32_16x16x32_bf16 v[28:31], v[132:135], v[204:207], v[28:31]
	v_mfma_f32_16x16x32_bf16 v[24:27], v[140:143], v[204:207], v[24:27]
	v_mfma_f32_16x16x32_bf16 v[12:15], v[132:135], v[214:217], v[12:15]
	v_mfma_f32_16x16x32_bf16 v[8:11], v[140:143], v[214:217], v[8:11]
	v_mfma_f32_16x16x32_bf16 v[52:55], v[144:147], v[184:187], v[52:55]
	v_mfma_f32_16x16x32_bf16 v[48:51], v[168:171], v[184:187], v[48:51]
	v_mfma_f32_16x16x32_bf16 v[36:39], v[144:147], v[192:195], v[36:39]
	v_mfma_f32_16x16x32_bf16 v[32:35], v[168:171], v[192:195], v[32:35]
	v_mfma_f32_16x16x32_bf16 v[20:23], v[144:147], v[200:203], v[20:23]
	v_mfma_f32_16x16x32_bf16 v[16:19], v[168:171], v[200:203], v[16:19]
	v_mfma_f32_16x16x32_bf16 v[4:7], v[144:147], v[208:211], v[4:7]
	v_mfma_f32_16x16x32_bf16 v[0:3], v[168:171], v[208:211], v[0:3]
	v_mfma_f32_16x16x32_bf16 v[52:55], v[164:167], v[188:191], v[52:55]
	v_mfma_f32_16x16x32_bf16 v[48:51], v[180:183], v[188:191], v[48:51]
	v_mfma_f32_16x16x32_bf16 v[36:39], v[164:167], v[196:199], v[36:39]
	v_mfma_f32_16x16x32_bf16 v[32:35], v[180:183], v[196:199], v[32:35]
	v_mfma_f32_16x16x32_bf16 v[20:23], v[164:167], v[204:207], v[20:23]
	v_mfma_f32_16x16x32_bf16 v[16:19], v[180:183], v[204:207], v[16:19]
	v_mfma_f32_16x16x32_bf16 v[4:7], v[164:167], v[214:217], v[4:7]
	v_mfma_f32_16x16x32_bf16 v[0:3], v[180:183], v[214:217], v[0:3]
	s_barrier
; #define PG8_STAGE(bufoff, gbase, voff) do { _Pragma("unroll") for (int _i = 0; _i < 2; ++_i) \
;         __builtin_amdgcn_global_load_lds((const unsigned*)((const char*)(gbase) + (voff)[_i]), (PG8_LAS unsigned*)(lds + (bufoff) + ldsw + _i * 8192), 16, 0, 0); } while (0)
; #define PG8_LDA(dst, b, h) do { _Pragma("unroll") for (int m = 0; m < 4; ++m) _Pragma("unroll") for (int k = 0; k < 2; ++k) dst[m][k] = *(const PG8_LAS bf16x8*)(lds + PG8_SA(b, h) + aoff + m * 2048 + k * 1024); } while (0)
; #define PG8_LDB(dst, b, h) do { _Pragma("unroll") for (int n = 0; n < 2; ++n) _Pragma("unroll") for (int k = 0; k < 2; ++k) dst[n][k] = *(const PG8_LAS bf16x8*)(lds + PG8_SB(b, h) + boff + n * 2048 + k * 1024); } while (0)
; #define PG8_MMA(ai, bj, At, Bt) do { __builtin_amdgcn_s_setprio(1); _Pragma("unroll") for (int m = 0; m < 4; ++m) _Pragma("unroll") for (int n = 0; n < 2; ++n) _Pragma("unroll") for (int k = 0; k < 2; ++k) \
;         acc[ai][bj][m][n] = __builtin_amdgcn_mfma_f32_16x16x32_bf16(Bt[n][k], At[m][k], acc[ai][bj][m][n], 0, 0, 0); __builtin_amdgcn_s_setprio(0); } while (0)
; #define PG8_WAIT_V(n) asm volatile("s_waitcnt vmcnt(" #n ")" ::: "memory")
; #define PG8_WAIT_L(n) asm volatile("s_waitcnt lgkmcnt(" #n ")" ::: "memory")
; #define PG8_BAR __builtin_amdgcn_s_barrier()
; #define PG8_SCHED __builtin_amdgcn_sched_barrier(0)
; template <class Epi, class Sched, bool ALIGN_EPI = false, bool SP2 = false>
; __device__ __forceinline__ void gemm_phase(PG8_LAS unsigned char* lds, const Gemm g, const Sched& S, const Epi& E) {
;     ...
;             PG8_LDB(B0, 1, 0); PG8_LDB(B1, 1, 1); PG8_SCHED; PG8_LDA(At, 1, 0); PG8_STAGE(PG8_SA(0, 1), a2 + hstep, voffA);
;             PG8_WAIT_V(8); PG8_WAIT_L(0); PG8_BAR; PG8_MMA(0, 0, At, B0); PG8_MMA(0, 1, At, B1); PG8_BAR; PG8_SCHED;
;             PG8_LDA(At, 1, 1); PG8_STAGE(PG8_SB(1, 0), b3, voffB); PG8_STAGE(PG8_SB(1, 1), b3 + hstep, voffB); PG8_STAGE(PG8_SA(1, 0), a3, voffA);
;             PG8_WAIT_V(8); PG8_WAIT_L(0); PG8_BAR; PG8_MMA(1, 0, At, B0); PG8_MMA(1, 1, At, B1); PG8_BAR; PG8_SCHED;
	s_add_i32 s62, 0, 0x18000
	s_add_i32 s63, 0, 0x1c000
	v_add_u32_e32 v140, s62, v175
	v_add_u32_e32 v180, s63, v175
	ds_read_b128 v[128:131], v140
	ds_read_b128 v[132:135], v140 offset:1024
	ds_read_b128 v[136:139], v140 offset:2048
	ds_read_b128 v[140:143], v140 offset:3072
	ds_read_b128 v[144:147], v180
	ds_read_b128 v[164:167], v180 offset:1024
	ds_read_b128 v[168:171], v180 offset:2048
	ds_read_b128 v[180:183], v180 offset:3072
	s_add_u32 s84, s42, 0x80
	s_addc_u32 s85, s43, 0
	s_add_u32 s42, s42, 0x40000
	s_addc_u32 s43, s43, 0
	s_mov_b32 m0, s47
	ds_read_b128 v[184:187], v179 offset:32768
	ds_read_b128 v[188:191], v179 offset:33792
	ds_read_b128 v[192:195], v179 offset:34816
	ds_read_b128 v[196:199], v179 offset:35840
	ds_read_b128 v[200:203], v179 offset:36864
	ds_read_b128 v[204:207], v179 offset:37888
	ds_read_b128 v[208:211], v179 offset:38912
	ds_read_b128 v[214:217], v179 offset:39936
	global_load_lds_dwordx4 v148, s[42:43]
	s_mov_b32 m0, s48
	s_nop 0
	global_load_lds_dwordx4 v152, s[42:43]
	s_waitcnt vmcnt(8)
	s_waitcnt lgkmcnt(0)
	s_barrier
	s_waitcnt lgkmcnt(0)
	v_mfma_f32_16x16x32_bf16 v[124:127], v[128:131], v[184:187], v[124:127]
	v_mfma_f32_16x16x32_bf16 v[120:123], v[136:139], v[184:187], v[120:123]
	v_mfma_f32_16x16x32_bf16 v[108:111], v[128:131], v[192:195], v[108:111]
	v_mfma_f32_16x16x32_bf16 v[104:107], v[136:139], v[192:195], v[104:107]
	v_mfma_f32_16x16x32_bf16 v[92:95], v[128:131], v[200:203], v[92:95]
	v_mfma_f32_16x16x32_bf16 v[88:91], v[136:139], v[200:203], v[88:91]
	v_mfma_f32_16x16x32_bf16 v[76:79], v[128:131], v[208:211], v[76:79]
	v_mfma_f32_16x16x32_bf16 v[72:75], v[136:139], v[208:211], v[72:75]
	v_mfma_f32_16x16x32_bf16 v[124:127], v[132:135], v[188:191], v[124:127]
	v_mfma_f32_16x16x32_bf16 v[120:123], v[140:143], v[188:191], v[120:123]
	v_mfma_f32_16x16x32_bf16 v[108:111], v[132:135], v[196:199], v[108:111]
	v_mfma_f32_16x16x32_bf16 v[104:107], v[140:143], v[196:199], v[104:107]
	v_mfma_f32_16x16x32_bf16 v[92:95], v[132:135], v[204:207], v[92:95]
	v_mfma_f32_16x16x32_bf16 v[88:91], v[140:143], v[204:207], v[88:91]
	v_mfma_f32_16x16x32_bf16 v[76:79], v[132:135], v[214:217], v[76:79]
	v_mfma_f32_16x16x32_bf16 v[72:75], v[140:143], v[214:217], v[72:75]
	v_mfma_f32_16x16x32_bf16 v[116:119], v[144:147], v[184:187], v[116:119]
	v_mfma_f32_16x16x32_bf16 v[112:115], v[168:171], v[184:187], v[112:115]
	v_mfma_f32_16x16x32_bf16 v[100:103], v[144:147], v[192:195], v[100:103]
	v_mfma_f32_16x16x32_bf16 v[96:99], v[168:171], v[192:195], v[96:99]
	v_mfma_f32_16x16x32_bf16 v[84:87], v[144:147], v[200:203], v[84:87]
	v_mfma_f32_16x16x32_bf16 v[80:83], v[168:171], v[200:203], v[80:83]
	v_mfma_f32_16x16x32_bf16 v[68:71], v[144:147], v[208:211], v[68:71]
	v_mfma_f32_16x16x32_bf16 v[64:67], v[168:171], v[208:211], v[64:67]
	v_mfma_f32_16x16x32_bf16 v[116:119], v[164:167], v[188:191], v[116:119]
	v_mfma_f32_16x16x32_bf16 v[112:115], v[180:183], v[188:191], v[112:115]
	v_mfma_f32_16x16x32_bf16 v[100:103], v[164:167], v[196:199], v[100:103]
	v_mfma_f32_16x16x32_bf16 v[96:99], v[180:183], v[196:199], v[96:99]
	v_mfma_f32_16x16x32_bf16 v[84:87], v[164:167], v[204:207], v[84:87]
	v_mfma_f32_16x16x32_bf16 v[80:83], v[180:183], v[204:207], v[80:83]
	v_mfma_f32_16x16x32_bf16 v[68:71], v[164:167], v[214:217], v[68:71]
	v_mfma_f32_16x16x32_bf16 v[64:67], v[180:183], v[214:217], v[64:67]
	s_barrier
	s_add_i32 s42, s62, s45
	s_add_u32 s86, s40, 0x80
	s_addc_u32 s87, s41, 0
	s_mov_b32 m0, s42
	ds_read_b128 v[184:187], v179 offset:49152
	ds_read_b128 v[188:191], v179 offset:50176
	ds_read_b128 v[192:195], v179 offset:51200
	ds_read_b128 v[196:199], v179 offset:52224
	ds_read_b128 v[200:203], v179 offset:53248
	ds_read_b128 v[204:207], v179 offset:54272
	ds_read_b128 v[208:211], v179 offset:55296
	ds_read_b128 v[214:217], v179 offset:56320
	global_load_lds_dwordx4 v150, s[86:87]
	s_add_i32 m0, s42, 0x2000
	s_add_u32 s40, s40, 0x40080
	s_addc_u32 s41, s41, 0
	s_add_i32 s42, s63, s45
	global_load_lds_dwordx4 v154, s[86:87]
	s_mov_b32 m0, s42
	s_nop 0
	global_load_lds_dwordx4 v150, s[40:41]
	s_add_i32 m0, s42, 0x2000
	s_nop 0
	global_load_lds_dwordx4 v154, s[40:41]
	s_mov_b32 m0, s50
	s_nop 0
	global_load_lds_dwordx4 v148, s[84:85]
	s_mov_b32 m0, s51
	s_nop 0
	global_load_lds_dwordx4 v152, s[84:85]
	s_waitcnt vmcnt(8)
	s_waitcnt lgkmcnt(0)
	s_barrier
	s_waitcnt lgkmcnt(0)
	v_mfma_f32_16x16x32_bf16 v[60:63], v[128:131], v[184:187], v[60:63]
	v_mfma_f32_16x16x32_bf16 v[56:59], v[136:139], v[184:187], v[56:59]
	v_mfma_f32_16x16x32_bf16 v[44:47], v[128:131], v[192:195], v[44:47]
	v_mfma_f32_16x16x32_bf16 v[40:43], v[136:139], v[192:195], v[40:43]
	v_mfma_f32_16x16x32_bf16 v[28:31], v[128:131], v[200:203], v[28:31]
	v_mfma_f32_16x16x32_bf16 v[24:27], v[136:139], v[200:203], v[24:27]
	v_mfma_f32_16x16x32_bf16 v[12:15], v[128:131], v[208:211], v[12:15]
	v_mfma_f32_16x16x32_bf16 v[8:11], v[136:139], v[208:211], v[8:11]
	v_mfma_f32_16x16x32_bf16 v[60:63], v[132:135], v[188:191], v[60:63]
	v_mfma_f32_16x16x32_bf16 v[56:59], v[140:143], v[188:191], v[56:59]
	v_mfma_f32_16x16x32_bf16 v[44:47], v[132:135], v[196:199], v[44:47]
	v_mfma_f32_16x16x32_bf16 v[40:43], v[140:143], v[196:199], v[40:43]
	v_mfma_f32_16x16x32_bf16 v[28:31], v[132:135], v[204:207], v[28:31]
	v_mfma_f32_16x16x32_bf16 v[24:27], v[140:143], v[204:207], v[24:27]
	v_mfma_f32_16x16x32_bf16 v[12:15], v[132:135], v[214:217], v[12:15]
	v_mfma_f32_16x16x32_bf16 v[8:11], v[140:143], v[214:217], v[8:11]
	v_mfma_f32_16x16x32_bf16 v[52:55], v[144:147], v[184:187], v[52:55]
	v_mfma_f32_16x16x32_bf16 v[48:51], v[168:171], v[184:187], v[48:51]
	v_mfma_f32_16x16x32_bf16 v[36:39], v[144:147], v[192:195], v[36:39]
	v_mfma_f32_16x16x32_bf16 v[32:35], v[168:171], v[192:195], v[32:35]
	v_mfma_f32_16x16x32_bf16 v[20:23], v[144:147], v[200:203], v[20:23]
	v_mfma_f32_16x16x32_bf16 v[16:19], v[168:171], v[200:203], v[16:19]
	v_mfma_f32_16x16x32_bf16 v[4:7], v[144:147], v[208:211], v[4:7]
	v_mfma_f32_16x16x32_bf16 v[0:3], v[168:171], v[208:211], v[0:3]
	v_mfma_f32_16x16x32_bf16 v[52:55], v[164:167], v[188:191], v[52:55]
	v_mfma_f32_16x16x32_bf16 v[48:51], v[180:183], v[188:191], v[48:51]
	v_mfma_f32_16x16x32_bf16 v[36:39], v[164:167], v[196:199], v[36:39]
	v_mfma_f32_16x16x32_bf16 v[32:35], v[180:183], v[196:199], v[32:35]
	v_mfma_f32_16x16x32_bf16 v[20:23], v[164:167], v[204:207], v[20:23]
	v_mfma_f32_16x16x32_bf16 v[16:19], v[180:183], v[204:207], v[16:19]
	v_mfma_f32_16x16x32_bf16 v[4:7], v[164:167], v[214:217], v[4:7]
	v_mfma_f32_16x16x32_bf16 v[0:3], v[180:183], v[214:217], v[0:3]
	s_barrier
; __device__ __forceinline__ float bf_lo(unsigned w) { return __uint_as_float(w << 16); }
; __device__ __forceinline__ float bf_hi(unsigned w) { return __uint_as_float(w & 0xffff0000u); }
; __device__ __forceinline__ u32x4 pack8(const f32x4 a, const f32x4 b) { u32x4 w; w.x = cvt_pk_bf16(a[0], a[1]); w.y = cvt_pk_bf16(a[2], a[3]); w.z = cvt_pk_bf16(b[0], b[1]); w.w = cvt_pk_bf16(b[2], b[3]); return w; }
;     __device__ __forceinline__ void operator()(const f32x4 (&acc)[2][2][4][2], const Unit& u, int wr, int wc, int fr, int fq) const {
;         const int row0 = u.pm * BM + wr * 64 + fr, col0 = u.pn * BM + wc * 32 + 8 * fq;
; #pragma unroll
;         for (int ai = 0; ai < 2; ++ai) { u32x4 gw[4][2], pw[4][2];
; #pragma unroll
;             for (int m = 0; m < 4; ++m) { const size_t off = (size_t)(row0 + ai * HALF + m * 16) * 2048 + col0;
; #pragma unroll
;                 for (int bj = 0; bj < 2; ++bj) { gw[m][bj] = *(const u32x4*)(G + off + bj * HALF); if (PASS == 1) pw[m][bj] = *(const u32x4*)(MIX + off + bj * HALF); } }
; #pragma unroll
;             for (int m = 0; m < 4; ++m) { const size_t off = (size_t)(row0 + ai * HALF + m * 16) * 2048 + col0;
; #pragma unroll
;                 for (int bj = 0; bj < 2; ++bj) { const u32x4 g4 = gw[m][bj];
;                     f32x4 v0 = (f32x4){bf_lo(g4.x), bf_hi(g4.x), bf_lo(g4.y), bf_hi(g4.y)} * acc[ai][bj][m][0], v1 = (f32x4){bf_lo(g4.z), bf_hi(g4.z), bf_lo(g4.w), bf_hi(g4.w)} * acc[ai][bj][m][1];
;                     if (PASS == 1) { const u32x4 p4 = pw[m][bj]; v0 += (f32x4){bf_lo(p4.x), bf_hi(p4.x), bf_lo(p4.y), bf_hi(p4.y)}; v1 += (f32x4){bf_lo(p4.z), bf_hi(p4.z), bf_lo(p4.w), bf_hi(p4.w)}; }
;                     *(u32x4*)(MIX + off + bj * HALF) = pack8(v0, v1); } } }
	s_add_i32 s61, s61, 2
	s_add_u32 s38, s38, 0x100
	s_addc_u32 s39, s39, 0
	s_add_u32 s59, s59, 0x100
	s_addc_u32 s60, s60, 0
	s_cmp_gt_u32 s61, 13
	s_cbranch_scc0 .LBB0_755
	v_lshl_add_u32 v168, s36, 8, v174
	v_lshl_or_b32 v166, s56, 8, v176
	v_ashrrev_i32_e32 v169, 31, v168
	v_ashrrev_i32_e32 v167, 31, v166
	v_lshlrev_b64 v[128:129], 11, v[168:169]
	v_lshl_add_u64 v[128:129], v[128:129], 0, v[166:167]
	v_lshlrev_b64 v[128:129], 1, v[128:129]
	v_lshl_add_u64 v[130:131], s[12:13], 0, v[128:129]
	global_load_dwordx4 v[180:183], v[130:131], off
	v_lshl_add_u64 v[128:129], s[14:15], 0, v[128:129]
	v_or_b32_e32 v212, 16, v168
	global_load_dwordx4 v[184:187], v[128:129], off
	global_load_dwordx4 v[188:191], v[130:131], off offset:256
	global_load_dwordx4 v[192:195], v[128:129], off offset:256
	v_ashrrev_i32_e32 v213, 31, v212
	v_lshlrev_b64 v[128:129], 11, v[212:213]
	v_lshl_add_u64 v[128:129], v[128:129], 0, v[166:167]
	v_lshlrev_b64 v[128:129], 1, v[128:129]
	v_lshl_add_u64 v[130:131], s[12:13], 0, v[128:129]
	v_lshl_add_u64 v[128:129], s[14:15], 0, v[128:129]
	global_load_dwordx4 v[196:199], v[130:131], off
	global_load_dwordx4 v[200:203], v[128:129], off
	v_or_b32_e32 v172, 32, v168
	v_or_b32_e32 v170, 48, v168
	v_ashrrev_i32_e32 v173, 31, v172
	v_ashrrev_i32_e32 v171, 31, v170
	v_lshlrev_b64 v[132:133], 12, v[168:169]
	v_lshlrev_b64 v[134:135], 11, v[172:173]
	v_lshlrev_b64 v[136:137], 11, v[170:171]
	v_lshlrev_b64 v[164:165], 1, v[166:167]
	v_lshl_add_u64 v[132:133], s[14:15], 0, v[132:133]
	v_lshl_add_u64 v[134:135], v[134:135], 0, v[166:167]
	v_lshl_add_u64 v[136:137], v[136:137], 0, v[166:167]
	v_lshl_add_u64 v[218:219], v[132:133], 0, v[164:165]
	v_lshlrev_b64 v[132:133], 1, v[134:135]
	v_lshlrev_b64 v[134:135], 1, v[136:137]
	v_lshl_add_u64 v[136:137], s[12:13], 0, v[132:133]
	v_lshl_add_u64 v[132:133], s[14:15], 0, v[132:133]
	v_lshl_add_u64 v[138:139], s[12:13], 0, v[134:135]
	v_lshl_add_u64 v[230:231], s[14:15], 0, v[134:135]
	global_load_dwordx4 v[204:207], v[130:131], off offset:256
	global_load_dwordx4 v[208:211], v[128:129], off offset:256
	global_load_dwordx4 v[214:217], v[136:137], off
	global_load_dwordx4 v[222:225], v[136:137], off offset:256
	global_load_dwordx4 v[232:235], v[132:133], off
	global_load_dwordx4 v[144:147], v[132:133], off offset:256
	global_load_dwordx4 v[140:143], v[138:139], off
	s_nop 0
	global_load_dwordx4 v[132:135], v[138:139], off offset:256
	s_nop 0
	global_load_dwordx4 v[136:139], v[230:231], off
	global_load_dwordx4 v[128:131], v[230:231], off offset:256
	s_and_b64 vcc, exec, s[10:11]
	s_mov_b32 s56, s26
	s_mov_b32 s36, s28
	s_mov_b64 s[40:41], s[34:35]
	s_mov_b64 s[38:39], s[30:31]
	s_waitcnt vmcnt(0)
	v_lshlrev_b32_e32 v230, 16, v180
	v_and_b32_e32 v231, 0xffff0000, v180
	v_lshlrev_b32_e32 v180, 16, v181
	v_and_b32_e32 v181, 0xffff0000, v181
	v_lshlrev_b32_e32 v236, 16, v182
	v_and_b32_e32 v237, 0xffff0000, v182
	v_lshlrev_b32_e32 v182, 16, v183
	v_and_b32_e32 v183, 0xffff0000, v183
	v_lshlrev_b32_e32 v238, 16, v184
	v_and_b32_e32 v239, 0xffff0000, v184
	v_lshlrev_b32_e32 v184, 16, v185
	v_and_b32_e32 v185, 0xffff0000, v185
	v_lshlrev_b32_e32 v240, 16, v186
	v_and_b32_e32 v241, 0xffff0000, v186
	v_lshlrev_b32_e32 v186, 16, v187
	v_and_b32_e32 v187, 0xffff0000, v187
	v_lshlrev_b32_e32 v242, 16, v188
	v_and_b32_e32 v243, 0xffff0000, v188
	v_lshlrev_b32_e32 v188, 16, v189
	v_and_b32_e32 v189, 0xffff0000, v189
	v_lshlrev_b32_e32 v246, 16, v192
	v_and_b32_e32 v247, 0xffff0000, v192
	v_lshlrev_b32_e32 v192, 16, v193
	v_and_b32_e32 v193, 0xffff0000, v193
	v_pk_fma_f32 v[126:127], v[126:127], v[180:181], v[184:185]
	v_pk_fma_f32 v[124:125], v[124:125], v[230:231], v[238:239]
	v_pk_fma_f32 v[122:123], v[122:123], v[182:183], v[186:187]
	v_pk_fma_f32 v[120:121], v[120:121], v[236:237], v[240:241]
	v_pk_fma_f32 v[180:181], v[118:119], v[188:189], v[192:193]
	v_pk_fma_f32 v[182:183], v[116:117], v[242:243], v[246:247]
	v_cvt_pk_bf16_f32 v116, v124, v125
	v_cvt_pk_bf16_f32 v117, v126, v127
	v_cvt_pk_bf16_f32 v118, v120, v121
	v_cvt_pk_bf16_f32 v119, v122, v123
	v_lshlrev_b32_e32 v244, 16, v190
	v_and_b32_e32 v245, 0xffff0000, v190
	v_lshlrev_b32_e32 v190, 16, v191
	v_and_b32_e32 v191, 0xffff0000, v191
	v_lshlrev_b32_e32 v248, 16, v194
	global_store_dwordx4 v[218:219], v[116:119], off
	v_and_b32_e32 v249, 0xffff0000, v194
	v_lshlrev_b32_e32 v122, 16, v200
	v_lshlrev_b32_e32 v116, 16, v195
	v_and_b32_e32 v117, 0xffff0000, v195
	v_pk_fma_f32 v[116:117], v[114:115], v[190:191], v[116:117]
	v_pk_fma_f32 v[114:115], v[112:113], v[244:245], v[248:249]
	v_cvt_pk_bf16_f32 v112, v182, v183
	v_cvt_pk_bf16_f32 v113, v180, v181
	v_cvt_pk_bf16_f32 v114, v114, v115
	v_cvt_pk_bf16_f32 v115, v116, v117
	global_store_dwordx4 v[218:219], v[112:115], off offset:256
	v_lshlrev_b32_e32 v116, 16, v197
	v_and_b32_e32 v117, 0xffff0000, v197
	v_lshlrev_b32_e32 v114, 16, v196
	v_and_b32_e32 v115, 0xffff0000, v196
	v_and_b32_e32 v123, 0xffff0000, v200
	v_lshlrev_b32_e32 v124, 16, v201
	v_and_b32_e32 v125, 0xffff0000, v201
	v_lshlrev_b64 v[112:113], 12, v[212:213]
	v_lshlrev_b32_e32 v118, 16, v198
	v_and_b32_e32 v119, 0xffff0000, v198
	v_lshlrev_b32_e32 v120, 16, v199
	v_and_b32_e32 v121, 0xffff0000, v199
	v_pk_fma_f32 v[110:111], v[110:111], v[116:117], v[124:125]
	v_pk_fma_f32 v[108:109], v[108:109], v[114:115], v[122:123]
	v_lshlrev_b32_e32 v114, 16, v202
	v_and_b32_e32 v115, 0xffff0000, v202
	v_lshlrev_b32_e32 v116, 16, v203
	v_and_b32_e32 v117, 0xffff0000, v203
	v_pk_fma_f32 v[116:117], v[106:107], v[120:121], v[116:117]
	v_pk_fma_f32 v[106:107], v[104:105], v[118:119], v[114:115]
	v_cvt_pk_bf16_f32 v104, v108, v109
; __device__ __forceinline__ float bf_lo(unsigned w) { return __uint_as_float(w << 16); }
; __device__ __forceinline__ float bf_hi(unsigned w) { return __uint_as_float(w & 0xffff0000u); }
; __device__ __forceinline__ u32x4 pack8(const f32x4 a, const f32x4 b) { u32x4 w; w.x = cvt_pk_bf16(a[0], a[1]); w.y = cvt_pk_bf16(a[2], a[3]); w.z = cvt_pk_bf16(b[0], b[1]); w.w = cvt_pk_bf16(b[2], b[3]); return w; }
;     __device__ __forceinline__ void operator()(const f32x4 (&acc)[2][2][4][2], const Unit& u, int wr, int wc, int fr, int fq) const {
;     ...
;             for (int m = 0; m < 4; ++m) { const size_t off = (size_t)(row0 + ai * HALF + m * 16) * 2048 + col0;
; #pragma unroll
;                 for (int bj = 0; bj < 2; ++bj) { const u32x4 g4 = gw[m][bj];
;                     f32x4 v0 = (f32x4){bf_lo(g4.x), bf_hi(g4.x), bf_lo(g4.y), bf_hi(g4.y)} * acc[ai][bj][m][0], v1 = (f32x4){bf_lo(g4.z), bf_hi(g4.z), bf_lo(g4.w), bf_hi(g4.w)} * acc[ai][bj][m][1];
;                     if (PASS == 1) { const u32x4 p4 = pw[m][bj]; v0 += (f32x4){bf_lo(p4.x), bf_hi(p4.x), bf_lo(p4.y), bf_hi(p4.y)}; v1 += (f32x4){bf_lo(p4.z), bf_hi(p4.z), bf_lo(p4.w), bf_hi(p4.w)}; }
;                     *(u32x4*)(MIX + off + bj * HALF) = pack8(v0, v1); } } }
	v_lshl_add_u64 v[108:109], s[14:15], 0, v[112:113]
	v_cvt_pk_bf16_f32 v105, v110, v111
	v_cvt_pk_bf16_f32 v106, v106, v107
	v_cvt_pk_bf16_f32 v107, v116, v117
	v_lshl_add_u64 v[108:109], v[108:109], 0, v[164:165]
	global_store_dwordx4 v[108:109], v[104:107], off
	v_lshlrev_b32_e32 v114, 16, v208
	v_and_b32_e32 v115, 0xffff0000, v208
	v_lshlrev_b32_e32 v104, 16, v204
	v_and_b32_e32 v105, 0xffff0000, v204
	v_lshlrev_b32_e32 v106, 16, v205
	v_and_b32_e32 v107, 0xffff0000, v205
	v_lshlrev_b32_e32 v116, 16, v209
	v_and_b32_e32 v117, 0xffff0000, v209
	v_lshlrev_b32_e32 v110, 16, v206
	v_and_b32_e32 v111, 0xffff0000, v206
	v_lshlrev_b32_e32 v112, 16, v207
	v_and_b32_e32 v113, 0xffff0000, v207
	v_pk_fma_f32 v[102:103], v[102:103], v[106:107], v[116:117]
	v_pk_fma_f32 v[100:101], v[100:101], v[104:105], v[114:115]
	v_lshlrev_b32_e32 v104, 16, v210
	v_and_b32_e32 v105, 0xffff0000, v210
	v_lshlrev_b32_e32 v106, 16, v211
	v_and_b32_e32 v107, 0xffff0000, v211
	v_pk_fma_f32 v[106:107], v[98:99], v[112:113], v[106:107]
	v_pk_fma_f32 v[98:99], v[96:97], v[110:111], v[104:105]
	v_cvt_pk_bf16_f32 v96, v100, v101
	v_cvt_pk_bf16_f32 v97, v102, v103
	v_cvt_pk_bf16_f32 v98, v98, v99
	v_cvt_pk_bf16_f32 v99, v106, v107
	global_store_dwordx4 v[108:109], v[96:99], off offset:256
	v_lshlrev_b32_e32 v100, 16, v215
	v_and_b32_e32 v101, 0xffff0000, v215
	v_lshlrev_b32_e32 v98, 16, v214
	v_and_b32_e32 v99, 0xffff0000, v214
	v_lshlrev_b32_e32 v106, 16, v232
	v_and_b32_e32 v107, 0xffff0000, v232
	v_lshlrev_b32_e32 v108, 16, v233
	v_and_b32_e32 v109, 0xffff0000, v233
	v_lshlrev_b64 v[96:97], 12, v[172:173]
	v_lshlrev_b32_e32 v102, 16, v216
	v_and_b32_e32 v103, 0xffff0000, v216
	v_lshlrev_b32_e32 v104, 16, v217
	v_and_b32_e32 v105, 0xffff0000, v217
	v_pk_fma_f32 v[94:95], v[94:95], v[100:101], v[108:109]
	v_pk_fma_f32 v[92:93], v[92:93], v[98:99], v[106:107]
	v_lshlrev_b32_e32 v98, 16, v234
	v_and_b32_e32 v99, 0xffff0000, v234
	v_lshlrev_b32_e32 v100, 16, v235
	v_and_b32_e32 v101, 0xffff0000, v235
	v_pk_fma_f32 v[100:101], v[90:91], v[104:105], v[100:101]
	v_pk_fma_f32 v[90:91], v[88:89], v[102:103], v[98:99]
	v_cvt_pk_bf16_f32 v88, v92, v93
	v_lshl_add_u64 v[92:93], s[14:15], 0, v[96:97]
	v_cvt_pk_bf16_f32 v89, v94, v95
	v_cvt_pk_bf16_f32 v90, v90, v91
	v_cvt_pk_bf16_f32 v91, v100, v101
	v_lshl_add_u64 v[92:93], v[92:93], 0, v[164:165]
	global_store_dwordx4 v[92:93], v[88:91], off
	v_lshlrev_b32_e32 v98, 16, v144
	v_and_b32_e32 v99, 0xffff0000, v144
	v_lshlrev_b32_e32 v88, 16, v222
	v_and_b32_e32 v89, 0xffff0000, v222
	v_lshlrev_b32_e32 v90, 16, v223
	v_and_b32_e32 v91, 0xffff0000, v223
	v_lshlrev_b32_e32 v100, 16, v145
	v_and_b32_e32 v101, 0xffff0000, v145
	v_lshlrev_b32_e32 v94, 16, v224
	v_and_b32_e32 v95, 0xffff0000, v224
	v_lshlrev_b32_e32 v96, 16, v225
	v_and_b32_e32 v97, 0xffff0000, v225
	v_pk_fma_f32 v[86:87], v[86:87], v[90:91], v[100:101]
	v_pk_fma_f32 v[84:85], v[84:85], v[88:89], v[98:99]
	v_lshlrev_b32_e32 v88, 16, v146
	v_and_b32_e32 v89, 0xffff0000, v146
	v_lshlrev_b32_e32 v90, 16, v147
	v_and_b32_e32 v91, 0xffff0000, v147
	v_pk_fma_f32 v[90:91], v[82:83], v[96:97], v[90:91]
	v_pk_fma_f32 v[82:83], v[80:81], v[94:95], v[88:89]
	v_cvt_pk_bf16_f32 v80, v84, v85
	v_cvt_pk_bf16_f32 v81, v86, v87
	v_cvt_pk_bf16_f32 v82, v82, v83
	v_cvt_pk_bf16_f32 v83, v90, v91
	global_store_dwordx4 v[92:93], v[80:83], off offset:256
	v_lshlrev_b32_e32 v84, 16, v141
	v_and_b32_e32 v85, 0xffff0000, v141
	v_lshlrev_b32_e32 v82, 16, v140
	v_and_b32_e32 v83, 0xffff0000, v140
	v_lshlrev_b32_e32 v90, 16, v136
	v_and_b32_e32 v91, 0xffff0000, v136
	v_lshlrev_b32_e32 v92, 16, v137
	v_and_b32_e32 v93, 0xffff0000, v137
	v_lshlrev_b64 v[80:81], 12, v[170:171]
	v_lshlrev_b32_e32 v86, 16, v142
	v_and_b32_e32 v87, 0xffff0000, v142
	v_lshlrev_b32_e32 v88, 16, v143
	v_and_b32_e32 v89, 0xffff0000, v143
	v_pk_fma_f32 v[78:79], v[78:79], v[84:85], v[92:93]
	v_pk_fma_f32 v[76:77], v[76:77], v[82:83], v[90:91]
	v_lshlrev_b32_e32 v82, 16, v138
	v_and_b32_e32 v83, 0xffff0000, v138
	v_lshlrev_b32_e32 v84, 16, v139
	v_and_b32_e32 v85, 0xffff0000, v139
	v_pk_fma_f32 v[84:85], v[74:75], v[88:89], v[84:85]
	v_pk_fma_f32 v[74:75], v[72:73], v[86:87], v[82:83]
	v_cvt_pk_bf16_f32 v72, v76, v77
	v_lshl_add_u64 v[76:77], s[14:15], 0, v[80:81]
	v_cvt_pk_bf16_f32 v73, v78, v79
	v_cvt_pk_bf16_f32 v74, v74, v75
	v_cvt_pk_bf16_f32 v75, v84, v85
	v_lshl_add_u64 v[76:77], v[76:77], 0, v[164:165]
	global_store_dwordx4 v[76:77], v[72:75], off
	v_lshlrev_b32_e32 v82, 16, v128
	v_and_b32_e32 v83, 0xffff0000, v128
	v_lshlrev_b32_e32 v72, 16, v132
	v_and_b32_e32 v73, 0xffff0000, v132
	v_lshlrev_b32_e32 v74, 16, v133
	v_and_b32_e32 v75, 0xffff0000, v133
	v_lshlrev_b32_e32 v84, 16, v129
	v_and_b32_e32 v85, 0xffff0000, v129
	v_lshlrev_b32_e32 v78, 16, v134
	v_and_b32_e32 v79, 0xffff0000, v134
	v_lshlrev_b32_e32 v80, 16, v135
	v_and_b32_e32 v81, 0xffff0000, v135
	v_pk_fma_f32 v[70:71], v[70:71], v[74:75], v[84:85]
	v_pk_fma_f32 v[68:69], v[68:69], v[72:73], v[82:83]
	v_lshlrev_b32_e32 v72, 16, v130
	v_and_b32_e32 v73, 0xffff0000, v130
	v_lshlrev_b32_e32 v74, 16, v131
	v_and_b32_e32 v75, 0xffff0000, v131
	v_pk_fma_f32 v[74:75], v[66:67], v[80:81], v[74:75]
	v_pk_fma_f32 v[66:67], v[64:65], v[78:79], v[72:73]
	v_add_u32_e32 v130, 0x80, v168
	v_cvt_pk_bf16_f32 v64, v68, v69
	v_cvt_pk_bf16_f32 v65, v70, v71
	v_cvt_pk_bf16_f32 v66, v66, v67
	v_cvt_pk_bf16_f32 v67, v74, v75
	v_ashrrev_i32_e32 v131, 31, v130
	global_store_dwordx4 v[76:77], v[64:67], off offset:256
	v_add_u32_e32 v132, 0x90, v168
	v_ashrrev_i32_e32 v133, 31, v132
	v_lshlrev_b64 v[64:65], 11, v[130:131]
	v_lshl_add_u64 v[64:65], v[64:65], 0, v[166:167]
; __device__ __forceinline__ float bf_lo(unsigned w) { return __uint_as_float(w << 16); }
; __device__ __forceinline__ float bf_hi(unsigned w) { return __uint_as_float(w & 0xffff0000u); }
; __device__ __forceinline__ u32x4 pack8(const f32x4 a, const f32x4 b) { u32x4 w; w.x = cvt_pk_bf16(a[0], a[1]); w.y = cvt_pk_bf16(a[2], a[3]); w.z = cvt_pk_bf16(b[0], b[1]); w.w = cvt_pk_bf16(b[2], b[3]); return w; }
;     __device__ __forceinline__ void operator()(const f32x4 (&acc)[2][2][4][2], const Unit& u, int wr, int wc, int fr, int fq) const {
;     ...
;         for (int ai = 0; ai < 2; ++ai) { u32x4 gw[4][2], pw[4][2];
; #pragma unroll
;             for (int m = 0; m < 4; ++m) { const size_t off = (size_t)(row0 + ai * HALF + m * 16) * 2048 + col0;
; #pragma unroll
;                 for (int bj = 0; bj < 2; ++bj) { gw[m][bj] = *(const u32x4*)(G + off + bj * HALF); if (PASS == 1) pw[m][bj] = *(const u32x4*)(MIX + off + bj * HALF); } }
; #pragma unroll
;             for (int m = 0; m < 4; ++m) { const size_t off = (size_t)(row0 + ai * HALF + m * 16) * 2048 + col0;
; #pragma unroll
;                 for (int bj = 0; bj < 2; ++bj) { const u32x4 g4 = gw[m][bj];
;                     f32x4 v0 = (f32x4){bf_lo(g4.x), bf_hi(g4.x), bf_lo(g4.y), bf_hi(g4.y)} * acc[ai][bj][m][0], v1 = (f32x4){bf_lo(g4.z), bf_hi(g4.z), bf_lo(g4.w), bf_hi(g4.w)} * acc[ai][bj][m][1];
;                     if (PASS == 1) { const u32x4 p4 = pw[m][bj]; v0 += (f32x4){bf_lo(p4.x), bf_hi(p4.x), bf_lo(p4.y), bf_hi(p4.y)}; v1 += (f32x4){bf_lo(p4.z), bf_hi(p4.z), bf_lo(p4.w), bf_hi(p4.w)}; }
;                     *(u32x4*)(MIX + off + bj * HALF) = pack8(v0, v1); } } }
	v_lshlrev_b64 v[64:65], 1, v[64:65]
	v_lshl_add_u64 v[66:67], s[12:13], 0, v[64:65]
	global_load_dwordx4 v[90:93], v[66:67], off
	v_lshl_add_u64 v[64:65], s[14:15], 0, v[64:65]
	global_load_dwordx4 v[94:97], v[64:65], off
	global_load_dwordx4 v[98:101], v[66:67], off offset:256
	global_load_dwordx4 v[102:105], v[64:65], off offset:256
	v_lshlrev_b64 v[64:65], 11, v[132:133]
	v_lshl_add_u64 v[64:65], v[64:65], 0, v[166:167]
	v_lshlrev_b64 v[64:65], 1, v[64:65]
	v_lshl_add_u64 v[66:67], s[12:13], 0, v[64:65]
	v_lshl_add_u64 v[64:65], s[14:15], 0, v[64:65]
	global_load_dwordx4 v[106:109], v[66:67], off
	global_load_dwordx4 v[110:113], v[66:67], off offset:256
	global_load_dwordx4 v[114:117], v[64:65], off
	global_load_dwordx4 v[118:121], v[64:65], off offset:256
	v_add_u32_e32 v134, 0xa0, v168
	v_ashrrev_i32_e32 v135, 31, v134
	v_lshlrev_b64 v[64:65], 11, v[134:135]
	v_lshl_add_u64 v[64:65], v[64:65], 0, v[166:167]
	v_lshlrev_b64 v[64:65], 1, v[64:65]
	v_lshl_add_u64 v[66:67], s[12:13], 0, v[64:65]
	v_lshl_add_u64 v[64:65], s[14:15], 0, v[64:65]
	global_load_dwordx4 v[122:125], v[66:67], off
	global_load_dwordx4 v[84:87], v[66:67], off offset:256
	global_load_dwordx4 v[126:129], v[64:65], off
	global_load_dwordx4 v[80:83], v[64:65], off offset:256
	v_add_u32_e32 v88, 0xb0, v168
	v_ashrrev_i32_e32 v89, 31, v88
	v_lshlrev_b64 v[64:65], 11, v[88:89]
	v_lshl_add_u64 v[64:65], v[64:65], 0, v[166:167]
	v_lshlrev_b64 v[64:65], 1, v[64:65]
	v_lshl_add_u64 v[66:67], s[12:13], 0, v[64:65]
	v_lshl_add_u64 v[64:65], s[14:15], 0, v[64:65]
	global_load_dwordx4 v[76:79], v[66:67], off
	global_load_dwordx4 v[68:71], v[66:67], off offset:256
	global_load_dwordx4 v[72:75], v[64:65], off
	s_nop 0
	global_load_dwordx4 v[64:67], v[64:65], off offset:256
	v_lshlrev_b64 v[130:131], 12, v[130:131]
	s_waitcnt vmcnt(15)
	v_lshlrev_b32_e32 v136, 16, v90
	v_and_b32_e32 v137, 0xffff0000, v90
	v_lshlrev_b32_e32 v90, 16, v91
	v_and_b32_e32 v91, 0xffff0000, v91
	s_waitcnt vmcnt(14)
	v_lshlrev_b32_e32 v140, 16, v94
	v_and_b32_e32 v141, 0xffff0000, v94
	v_lshlrev_b32_e32 v94, 16, v95
	v_and_b32_e32 v95, 0xffff0000, v95
	v_lshlrev_b32_e32 v138, 16, v92
	v_and_b32_e32 v139, 0xffff0000, v92
	v_lshlrev_b32_e32 v92, 16, v93
	v_and_b32_e32 v93, 0xffff0000, v93
	v_pk_fma_f32 v[62:63], v[62:63], v[90:91], v[94:95]
	v_pk_fma_f32 v[60:61], v[60:61], v[136:137], v[140:141]
	v_lshlrev_b32_e32 v90, 16, v96
	v_and_b32_e32 v91, 0xffff0000, v96
	v_lshlrev_b32_e32 v94, 16, v97
	v_and_b32_e32 v95, 0xffff0000, v97
	v_pk_fma_f32 v[92:93], v[58:59], v[92:93], v[94:95]
	v_pk_fma_f32 v[58:59], v[56:57], v[138:139], v[90:91]
	v_cvt_pk_bf16_f32 v56, v60, v61
	v_lshl_add_u64 v[60:61], s[14:15], 0, v[130:131]
	v_cvt_pk_bf16_f32 v57, v62, v63
	v_cvt_pk_bf16_f32 v58, v58, v59
	v_cvt_pk_bf16_f32 v59, v92, v93
	v_lshl_add_u64 v[60:61], v[60:61], 0, v[164:165]
	global_store_dwordx4 v[60:61], v[56:59], off
	s_waitcnt vmcnt(13)
	v_lshlrev_b32_e32 v92, 16, v102
	v_and_b32_e32 v93, 0xffff0000, v102
	v_lshlrev_b32_e32 v56, 16, v98
	v_and_b32_e32 v57, 0xffff0000, v98
	v_lshlrev_b32_e32 v58, 16, v99
	v_and_b32_e32 v59, 0xffff0000, v99
	v_lshlrev_b32_e32 v94, 16, v103
	v_and_b32_e32 v95, 0xffff0000, v103
	v_lshlrev_b32_e32 v62, 16, v100
	v_and_b32_e32 v63, 0xffff0000, v100
	v_lshlrev_b32_e32 v90, 16, v101
	v_and_b32_e32 v91, 0xffff0000, v101
	v_pk_fma_f32 v[54:55], v[54:55], v[58:59], v[94:95]
	v_pk_fma_f32 v[52:53], v[52:53], v[56:57], v[92:93]
	v_lshlrev_b32_e32 v56, 16, v104
	v_and_b32_e32 v57, 0xffff0000, v104
	v_lshlrev_b32_e32 v58, 16, v105
	v_and_b32_e32 v59, 0xffff0000, v105
	v_pk_fma_f32 v[58:59], v[50:51], v[90:91], v[58:59]
	v_pk_fma_f32 v[50:51], v[48:49], v[62:63], v[56:57]
	v_cvt_pk_bf16_f32 v48, v52, v53
	v_cvt_pk_bf16_f32 v49, v54, v55
	v_cvt_pk_bf16_f32 v50, v50, v51
	v_cvt_pk_bf16_f32 v51, v58, v59
	global_store_dwordx4 v[60:61], v[48:51], off offset:256
	s_waitcnt vmcnt(13)
	v_lshlrev_b32_e32 v52, 16, v107
	v_and_b32_e32 v53, 0xffff0000, v107
	v_lshlrev_b32_e32 v50, 16, v106
	v_and_b32_e32 v51, 0xffff0000, v106
	s_waitcnt vmcnt(11)
	v_lshlrev_b32_e32 v58, 16, v114
	v_and_b32_e32 v59, 0xffff0000, v114
	v_lshlrev_b32_e32 v60, 16, v115
	v_and_b32_e32 v61, 0xffff0000, v115
	v_lshlrev_b64 v[48:49], 12, v[132:133]
	v_lshlrev_b32_e32 v54, 16, v108
	v_and_b32_e32 v55, 0xffff0000, v108
	v_lshlrev_b32_e32 v56, 16, v109
	v_and_b32_e32 v57, 0xffff0000, v109
	v_pk_fma_f32 v[46:47], v[46:47], v[52:53], v[60:61]
	v_pk_fma_f32 v[44:45], v[44:45], v[50:51], v[58:59]
	v_lshlrev_b32_e32 v50, 16, v116
	v_and_b32_e32 v51, 0xffff0000, v116
	v_lshlrev_b32_e32 v52, 16, v117
	v_and_b32_e32 v53, 0xffff0000, v117
	v_pk_fma_f32 v[52:53], v[42:43], v[56:57], v[52:53]
	v_pk_fma_f32 v[42:43], v[40:41], v[54:55], v[50:51]
	v_cvt_pk_bf16_f32 v40, v44, v45
	v_lshl_add_u64 v[44:45], s[14:15], 0, v[48:49]
	v_cvt_pk_bf16_f32 v41, v46, v47
	v_cvt_pk_bf16_f32 v42, v42, v43
	v_cvt_pk_bf16_f32 v43, v52, v53
	v_lshl_add_u64 v[44:45], v[44:45], 0, v[164:165]
	global_store_dwordx4 v[44:45], v[40:43], off
	s_waitcnt vmcnt(11)
; __device__ __forceinline__ float bf_lo(unsigned w) { return __uint_as_float(w << 16); }
; __device__ __forceinline__ float bf_hi(unsigned w) { return __uint_as_float(w & 0xffff0000u); }
; __device__ __forceinline__ u32x4 pack8(const f32x4 a, const f32x4 b) { u32x4 w; w.x = cvt_pk_bf16(a[0], a[1]); w.y = cvt_pk_bf16(a[2], a[3]); w.z = cvt_pk_bf16(b[0], b[1]); w.w = cvt_pk_bf16(b[2], b[3]); return w; }
; #define PG8_WAIT_V(n) asm volatile("s_waitcnt vmcnt(" #n ")" ::: "memory")
; #define PG8_BAR __builtin_amdgcn_s_barrier()
;     __device__ __forceinline__ void operator()(const f32x4 (&acc)[2][2][4][2], const Unit& u, int wr, int wc, int fr, int fq) const {
;     ...
;             for (int m = 0; m < 4; ++m) { const size_t off = (size_t)(row0 + ai * HALF + m * 16) * 2048 + col0;
; #pragma unroll
;                 for (int bj = 0; bj < 2; ++bj) { const u32x4 g4 = gw[m][bj];
;                     f32x4 v0 = (f32x4){bf_lo(g4.x), bf_hi(g4.x), bf_lo(g4.y), bf_hi(g4.y)} * acc[ai][bj][m][0], v1 = (f32x4){bf_lo(g4.z), bf_hi(g4.z), bf_lo(g4.w), bf_hi(g4.w)} * acc[ai][bj][m][1];
;                     if (PASS == 1) { const u32x4 p4 = pw[m][bj]; v0 += (f32x4){bf_lo(p4.x), bf_hi(p4.x), bf_lo(p4.y), bf_hi(p4.y)}; v1 += (f32x4){bf_lo(p4.z), bf_hi(p4.z), bf_lo(p4.w), bf_hi(p4.w)}; }
;                     *(u32x4*)(MIX + off + bj * HALF) = pack8(v0, v1); } } }
; template <class Epi, class Sched, bool ALIGN_EPI = false, bool SP2 = false>
; __device__ __forceinline__ void gemm_phase(PG8_LAS unsigned char* lds, const Gemm g, const Sched& S, const Epi& E) {
;     ...
;     PG8_WAIT_V(0);
;     if constexpr (!ALIGN_EPI) { if (wr == 0) PG8_BAR; }
;     PG8_BAR;
	v_lshlrev_b32_e32 v50, 16, v118
	v_and_b32_e32 v51, 0xffff0000, v118
	v_lshlrev_b32_e32 v40, 16, v110
	v_and_b32_e32 v41, 0xffff0000, v110
	v_lshlrev_b32_e32 v42, 16, v111
	v_and_b32_e32 v43, 0xffff0000, v111
	v_lshlrev_b32_e32 v52, 16, v119
	v_and_b32_e32 v53, 0xffff0000, v119
	v_lshlrev_b32_e32 v46, 16, v112
	v_and_b32_e32 v47, 0xffff0000, v112
	v_lshlrev_b32_e32 v48, 16, v113
	v_and_b32_e32 v49, 0xffff0000, v113
	v_pk_fma_f32 v[38:39], v[38:39], v[42:43], v[52:53]
	v_pk_fma_f32 v[36:37], v[36:37], v[40:41], v[50:51]
	v_lshlrev_b32_e32 v40, 16, v120
	v_and_b32_e32 v41, 0xffff0000, v120
	v_lshlrev_b32_e32 v42, 16, v121
	v_and_b32_e32 v43, 0xffff0000, v121
	v_pk_fma_f32 v[42:43], v[34:35], v[48:49], v[42:43]
	v_pk_fma_f32 v[34:35], v[32:33], v[46:47], v[40:41]
	v_cvt_pk_bf16_f32 v32, v36, v37
	v_cvt_pk_bf16_f32 v33, v38, v39
	v_cvt_pk_bf16_f32 v34, v34, v35
	v_cvt_pk_bf16_f32 v35, v42, v43
	global_store_dwordx4 v[44:45], v[32:35], off offset:256
	s_waitcnt vmcnt(11)
	v_lshlrev_b32_e32 v36, 16, v123
	v_and_b32_e32 v37, 0xffff0000, v123
	v_lshlrev_b32_e32 v34, 16, v122
	v_and_b32_e32 v35, 0xffff0000, v122
	s_waitcnt vmcnt(9)
	v_lshlrev_b32_e32 v42, 16, v126
	v_and_b32_e32 v43, 0xffff0000, v126
	v_lshlrev_b32_e32 v44, 16, v127
	v_and_b32_e32 v45, 0xffff0000, v127
	v_lshlrev_b64 v[32:33], 12, v[134:135]
	v_lshlrev_b32_e32 v38, 16, v124
	v_and_b32_e32 v39, 0xffff0000, v124
	v_lshlrev_b32_e32 v40, 16, v125
	v_and_b32_e32 v41, 0xffff0000, v125
	v_pk_fma_f32 v[30:31], v[30:31], v[36:37], v[44:45]
	v_pk_fma_f32 v[28:29], v[28:29], v[34:35], v[42:43]
	v_lshlrev_b32_e32 v34, 16, v128
	v_and_b32_e32 v35, 0xffff0000, v128
	v_lshlrev_b32_e32 v36, 16, v129
	v_and_b32_e32 v37, 0xffff0000, v129
	v_pk_fma_f32 v[36:37], v[26:27], v[40:41], v[36:37]
	v_pk_fma_f32 v[26:27], v[24:25], v[38:39], v[34:35]
	v_cvt_pk_bf16_f32 v24, v28, v29
	v_lshl_add_u64 v[28:29], s[14:15], 0, v[32:33]
	v_cvt_pk_bf16_f32 v25, v30, v31
	v_cvt_pk_bf16_f32 v26, v26, v27
	v_cvt_pk_bf16_f32 v27, v36, v37
	v_lshl_add_u64 v[28:29], v[28:29], 0, v[164:165]
	global_store_dwordx4 v[28:29], v[24:27], off
	s_waitcnt vmcnt(9)
	v_lshlrev_b32_e32 v34, 16, v80
	v_and_b32_e32 v35, 0xffff0000, v80
	v_lshlrev_b32_e32 v24, 16, v84
	v_and_b32_e32 v25, 0xffff0000, v84
	v_lshlrev_b32_e32 v26, 16, v85
	v_and_b32_e32 v27, 0xffff0000, v85
	v_lshlrev_b32_e32 v36, 16, v81
	v_and_b32_e32 v37, 0xffff0000, v81
	v_lshlrev_b32_e32 v30, 16, v86
	v_and_b32_e32 v31, 0xffff0000, v86
	v_lshlrev_b32_e32 v32, 16, v87
	v_and_b32_e32 v33, 0xffff0000, v87
	v_pk_fma_f32 v[22:23], v[22:23], v[26:27], v[36:37]
	v_pk_fma_f32 v[20:21], v[20:21], v[24:25], v[34:35]
	v_lshlrev_b32_e32 v24, 16, v82
	v_and_b32_e32 v25, 0xffff0000, v82
	v_lshlrev_b32_e32 v26, 16, v83
	v_and_b32_e32 v27, 0xffff0000, v83
	v_pk_fma_f32 v[26:27], v[18:19], v[32:33], v[26:27]
	v_pk_fma_f32 v[18:19], v[16:17], v[30:31], v[24:25]
	v_cvt_pk_bf16_f32 v16, v20, v21
	v_cvt_pk_bf16_f32 v17, v22, v23
	v_cvt_pk_bf16_f32 v18, v18, v19
	v_cvt_pk_bf16_f32 v19, v26, v27
	global_store_dwordx4 v[28:29], v[16:19], off offset:256
	s_waitcnt vmcnt(9)
	v_lshlrev_b32_e32 v20, 16, v77
	v_and_b32_e32 v21, 0xffff0000, v77
	v_lshlrev_b32_e32 v18, 16, v76
	v_and_b32_e32 v19, 0xffff0000, v76
	s_waitcnt vmcnt(7)
	v_lshlrev_b32_e32 v26, 16, v72
	v_and_b32_e32 v27, 0xffff0000, v72
	v_lshlrev_b32_e32 v28, 16, v73
	v_and_b32_e32 v29, 0xffff0000, v73
	v_lshlrev_b64 v[16:17], 12, v[88:89]
	v_lshlrev_b32_e32 v22, 16, v78
	v_and_b32_e32 v23, 0xffff0000, v78
	v_lshlrev_b32_e32 v24, 16, v79
	v_and_b32_e32 v25, 0xffff0000, v79
	v_pk_fma_f32 v[14:15], v[14:15], v[20:21], v[28:29]
	v_pk_fma_f32 v[12:13], v[12:13], v[18:19], v[26:27]
	v_lshlrev_b32_e32 v18, 16, v74
	v_and_b32_e32 v19, 0xffff0000, v74
	v_lshlrev_b32_e32 v20, 16, v75
	v_and_b32_e32 v21, 0xffff0000, v75
	v_pk_fma_f32 v[20:21], v[10:11], v[24:25], v[20:21]
	v_pk_fma_f32 v[10:11], v[8:9], v[22:23], v[18:19]
	v_cvt_pk_bf16_f32 v8, v12, v13
	v_lshl_add_u64 v[12:13], s[14:15], 0, v[16:17]
	v_cvt_pk_bf16_f32 v9, v14, v15
	v_cvt_pk_bf16_f32 v10, v10, v11
	v_cvt_pk_bf16_f32 v11, v20, v21
	v_lshl_add_u64 v[12:13], v[12:13], 0, v[164:165]
	global_store_dwordx4 v[12:13], v[8:11], off
	s_waitcnt vmcnt(7)
	v_lshlrev_b32_e32 v18, 16, v64
	v_and_b32_e32 v19, 0xffff0000, v64
	v_lshlrev_b32_e32 v8, 16, v68
	v_and_b32_e32 v9, 0xffff0000, v68
	v_lshlrev_b32_e32 v10, 16, v69
	v_and_b32_e32 v11, 0xffff0000, v69
	v_lshlrev_b32_e32 v20, 16, v65
	v_and_b32_e32 v21, 0xffff0000, v65
	v_lshlrev_b32_e32 v14, 16, v70
	v_and_b32_e32 v15, 0xffff0000, v70
	v_lshlrev_b32_e32 v16, 16, v71
	v_and_b32_e32 v17, 0xffff0000, v71
	v_pk_fma_f32 v[6:7], v[6:7], v[10:11], v[20:21]
	v_pk_fma_f32 v[4:5], v[4:5], v[8:9], v[18:19]
	v_lshlrev_b32_e32 v8, 16, v66
	v_and_b32_e32 v9, 0xffff0000, v66
	v_lshlrev_b32_e32 v10, 16, v67
	v_and_b32_e32 v11, 0xffff0000, v67
	v_pk_fma_f32 v[10:11], v[2:3], v[16:17], v[10:11]
	v_pk_fma_f32 v[2:3], v[0:1], v[14:15], v[8:9]
	v_cvt_pk_bf16_f32 v0, v4, v5
	v_cvt_pk_bf16_f32 v1, v6, v7
	v_cvt_pk_bf16_f32 v2, v2, v3
	v_cvt_pk_bf16_f32 v3, v10, v11
	global_store_dwordx4 v[12:13], v[0:3], off offset:256
	s_cbranch_vccz .LBB0_748
	s_waitcnt vmcnt(0)
	s_cmpk_gt_u32 s3, 0xff
	s_cbranch_scc1 .LBB0_759
	s_barrier

; #define PG8_STAGE(bufoff, gbase, voff) do { _Pragma("unroll") for (int _i = 0; _i < 2; ++_i) \
;         __builtin_amdgcn_global_load_lds((const unsigned*)((const char*)(gbase) + (voff)[_i]), (PG8_LAS unsigned*)(lds + (bufoff) + ldsw + _i * 8192), 16, 0, 0); } while (0)
; #define PG8_LDA(dst, b, h) do { _Pragma("unroll") for (int m = 0; m < 4; ++m) _Pragma("unroll") for (int k = 0; k < 2; ++k) dst[m][k] = *(const PG8_LAS bf16x8*)(lds + PG8_SA(b, h) + aoff + m * 2048 + k * 1024); } while (0)
; #define PG8_LDB(dst, b, h) do { _Pragma("unroll") for (int n = 0; n < 2; ++n) _Pragma("unroll") for (int k = 0; k < 2; ++k) dst[n][k] = *(const PG8_LAS bf16x8*)(lds + PG8_SB(b, h) + boff + n * 2048 + k * 1024); } while (0)
; #define PG8_MMA(ai, bj, At, Bt) do { __builtin_amdgcn_s_setprio(1); _Pragma("unroll") for (int m = 0; m < 4; ++m) _Pragma("unroll") for (int n = 0; n < 2; ++n) _Pragma("unroll") for (int k = 0; k < 2; ++k) \
;         acc[ai][bj][m][n] = __builtin_amdgcn_mfma_f32_16x16x32_bf16(Bt[n][k], At[m][k], acc[ai][bj][m][n], 0, 0, 0); __builtin_amdgcn_s_setprio(0); } while (0)
; #define PG8_WAIT_V(n) asm volatile("s_waitcnt vmcnt(" #n ")" ::: "memory")
; #define PG8_WAIT_L(n) asm volatile("s_waitcnt lgkmcnt(" #n ")" ::: "memory")
; #define PG8_BAR __builtin_amdgcn_s_barrier()
; #define PG8_SCHED __builtin_amdgcn_sched_barrier(0)
; template <class Epi, class Sched, bool ALIGN_EPI = false, bool SP2 = false>
; __device__ __forceinline__ void gemm_phase(PG8_LAS unsigned char* lds, const Gemm g, const Sched& S, const Epi& E) {
;     ...
;             PG8_LDB(B0, 0, 0); PG8_LDB(B1, 0, 1); PG8_SCHED; PG8_LDA(At, 0, 0); PG8_STAGE(PG8_SA(1, 1), a1 + hstep, voffA);
;             PG8_WAIT_V(8); PG8_WAIT_L(0); PG8_BAR; PG8_MMA(0, 0, At, B0); PG8_MMA(0, 1, At, B1); PG8_BAR; PG8_SCHED;
;             PG8_LDA(At, 0, 1); PG8_STAGE(PG8_SB(0, 0), b2, voffB); PG8_STAGE(PG8_SB(0, 1), b2 + hstep, voffB); PG8_STAGE(PG8_SA(0, 0), a2, voffA);
;             PG8_WAIT_V(8); PG8_WAIT_L(0); PG8_BAR; PG8_MMA(1, 0, At, B0); PG8_MMA(1, 1, At, B1); PG8_BAR; PG8_SCHED;
.LBB0_827:
	ds_read_b128 v[128:131], v169
	ds_read_b128 v[132:135], v169 offset:1024
	ds_read_b128 v[136:139], v169 offset:2048
	ds_read_b128 v[140:143], v169 offset:3072
	ds_read_b128 v[160:163], v170
	ds_read_b128 v[172:175], v170 offset:1024
	ds_read_b128 v[176:179], v170 offset:2048
	ds_read_b128 v[180:183], v170 offset:3072
	s_add_u32 s48, s46, 0xfff80080
	s_addc_u32 s49, s47, -1
	s_cmp_eq_u32 s71, 28
	s_cselect_b32 s51, s39, s49
	s_cselect_b32 s50, s67, s48
	s_cselect_b32 s49, s37, s70
	s_cselect_b32 s48, s68, s69
	s_add_i32 m0, s45, 0xc000
	ds_read_b128 v[184:187], v171
	ds_read_b128 v[188:191], v171 offset:1024
	ds_read_b128 v[192:195], v171 offset:2048
	ds_read_b128 v[196:199], v171 offset:3072
	ds_read_b128 v[200:203], v171 offset:4096
	ds_read_b128 v[204:207], v171 offset:5120
	ds_read_b128 v[208:211], v171 offset:6144
	ds_read_b128 v[214:217], v171 offset:7168
	global_load_lds_dwordx4 v152, s[46:47]
	s_add_i32 m0, s45, 0xe000
	s_nop 0
	global_load_lds_dwordx4 v154, s[46:47]
	s_waitcnt vmcnt(8)
	s_waitcnt lgkmcnt(0)
	s_barrier
	s_waitcnt lgkmcnt(0)
	v_mfma_f32_16x16x32_bf16 v[124:127], v[128:131], v[184:187], v[124:127]
	v_mfma_f32_16x16x32_bf16 v[120:123], v[136:139], v[184:187], v[120:123]
	v_mfma_f32_16x16x32_bf16 v[116:119], v[128:131], v[192:195], v[116:119]
	v_mfma_f32_16x16x32_bf16 v[112:115], v[136:139], v[192:195], v[112:115]
	v_mfma_f32_16x16x32_bf16 v[108:111], v[128:131], v[200:203], v[108:111]
	v_mfma_f32_16x16x32_bf16 v[96:99], v[136:139], v[200:203], v[96:99]
	v_mfma_f32_16x16x32_bf16 v[80:83], v[128:131], v[208:211], v[80:83]
	v_mfma_f32_16x16x32_bf16 v[72:75], v[136:139], v[208:211], v[72:75]
	v_mfma_f32_16x16x32_bf16 v[124:127], v[132:135], v[188:191], v[124:127]
	v_mfma_f32_16x16x32_bf16 v[120:123], v[140:143], v[188:191], v[120:123]
	v_mfma_f32_16x16x32_bf16 v[116:119], v[132:135], v[196:199], v[116:119]
	v_mfma_f32_16x16x32_bf16 v[112:115], v[140:143], v[196:199], v[112:115]
	v_mfma_f32_16x16x32_bf16 v[108:111], v[132:135], v[204:207], v[108:111]
	v_mfma_f32_16x16x32_bf16 v[96:99], v[140:143], v[204:207], v[96:99]
	v_mfma_f32_16x16x32_bf16 v[80:83], v[132:135], v[214:217], v[80:83]
	v_mfma_f32_16x16x32_bf16 v[72:75], v[140:143], v[214:217], v[72:75]
	v_mfma_f32_16x16x32_bf16 v[104:107], v[160:163], v[184:187], v[104:107]
	v_mfma_f32_16x16x32_bf16 v[100:103], v[176:179], v[184:187], v[100:103]
	v_mfma_f32_16x16x32_bf16 v[92:95], v[160:163], v[192:195], v[92:95]
	v_mfma_f32_16x16x32_bf16 v[88:91], v[176:179], v[192:195], v[88:91]
	v_mfma_f32_16x16x32_bf16 v[84:87], v[160:163], v[200:203], v[84:87]
	v_mfma_f32_16x16x32_bf16 v[76:79], v[176:179], v[200:203], v[76:79]
	v_mfma_f32_16x16x32_bf16 v[68:71], v[160:163], v[208:211], v[68:71]
	v_mfma_f32_16x16x32_bf16 v[64:67], v[176:179], v[208:211], v[64:67]
	v_mfma_f32_16x16x32_bf16 v[104:107], v[172:175], v[188:191], v[104:107]
	v_mfma_f32_16x16x32_bf16 v[100:103], v[180:183], v[188:191], v[100:103]
	v_mfma_f32_16x16x32_bf16 v[92:95], v[172:175], v[196:199], v[92:95]
	v_mfma_f32_16x16x32_bf16 v[88:91], v[180:183], v[196:199], v[88:91]
	v_mfma_f32_16x16x32_bf16 v[84:87], v[172:175], v[204:207], v[84:87]
	v_mfma_f32_16x16x32_bf16 v[76:79], v[180:183], v[204:207], v[76:79]
	v_mfma_f32_16x16x32_bf16 v[68:71], v[172:175], v[214:217], v[68:71]
	v_mfma_f32_16x16x32_bf16 v[64:67], v[180:183], v[214:217], v[64:67]
	s_barrier
	s_add_i32 s72, s64, s53
	s_mov_b32 m0, s72
	ds_read_b128 v[184:187], v171 offset:16384
	ds_read_b128 v[188:191], v171 offset:17408
	ds_read_b128 v[192:195], v171 offset:18432
	ds_read_b128 v[196:199], v171 offset:19456
	ds_read_b128 v[200:203], v171 offset:20480
	ds_read_b128 v[204:207], v171 offset:21504
	ds_read_b128 v[208:211], v171 offset:22528
	ds_read_b128 v[214:217], v171 offset:23552
	global_load_lds_dwordx4 v146, s[48:49]
	s_add_i32 m0, s72, 0x2000
	s_add_u32 s72, s48, 0x80000
	s_addc_u32 s73, s49, 0
	s_add_i32 s74, s65, s53
	global_load_lds_dwordx4 v150, s[48:49]
	s_mov_b32 m0, s74
	s_nop 0
	global_load_lds_dwordx4 v146, s[72:73]
	s_add_i32 m0, s74, 0x2000
	s_nop 0
	global_load_lds_dwordx4 v150, s[72:73]
	s_mov_b32 m0, s45
	s_nop 0
	global_load_lds_dwordx4 v144, s[50:51]
	s_mov_b32 m0, s54
	s_nop 0
	global_load_lds_dwordx4 v148, s[50:51]
	s_waitcnt vmcnt(8)
	s_waitcnt lgkmcnt(0)
	s_barrier
	s_waitcnt lgkmcnt(0)
	v_mfma_f32_16x16x32_bf16 v[60:63], v[128:131], v[184:187], v[60:63]
	v_mfma_f32_16x16x32_bf16 v[56:59], v[136:139], v[184:187], v[56:59]
	v_mfma_f32_16x16x32_bf16 v[52:55], v[128:131], v[192:195], v[52:55]
	v_mfma_f32_16x16x32_bf16 v[48:51], v[136:139], v[192:195], v[48:51]
	v_mfma_f32_16x16x32_bf16 v[44:47], v[128:131], v[200:203], v[44:47]
	v_mfma_f32_16x16x32_bf16 v[32:35], v[136:139], v[200:203], v[32:35]
	v_mfma_f32_16x16x32_bf16 v[20:23], v[128:131], v[208:211], v[20:23]
	v_mfma_f32_16x16x32_bf16 v[8:11], v[136:139], v[208:211], v[8:11]
	v_mfma_f32_16x16x32_bf16 v[60:63], v[132:135], v[188:191], v[60:63]
	v_mfma_f32_16x16x32_bf16 v[56:59], v[140:143], v[188:191], v[56:59]
	v_mfma_f32_16x16x32_bf16 v[52:55], v[132:135], v[196:199], v[52:55]
	v_mfma_f32_16x16x32_bf16 v[48:51], v[140:143], v[196:199], v[48:51]
	v_mfma_f32_16x16x32_bf16 v[44:47], v[132:135], v[204:207], v[44:47]
	v_mfma_f32_16x16x32_bf16 v[32:35], v[140:143], v[204:207], v[32:35]
	v_mfma_f32_16x16x32_bf16 v[20:23], v[132:135], v[214:217], v[20:23]
	v_mfma_f32_16x16x32_bf16 v[8:11], v[140:143], v[214:217], v[8:11]
	v_mfma_f32_16x16x32_bf16 v[40:43], v[160:163], v[184:187], v[40:43]
	v_mfma_f32_16x16x32_bf16 v[36:39], v[176:179], v[184:187], v[36:39]
	v_mfma_f32_16x16x32_bf16 v[28:31], v[160:163], v[192:195], v[28:31]
	v_mfma_f32_16x16x32_bf16 v[24:27], v[176:179], v[192:195], v[24:27]
	v_mfma_f32_16x16x32_bf16 v[16:19], v[160:163], v[200:203], v[16:19]
	v_mfma_f32_16x16x32_bf16 v[12:15], v[176:179], v[200:203], v[12:15]
	v_mfma_f32_16x16x32_bf16 v[4:7], v[160:163], v[208:211], v[4:7]
	v_mfma_f32_16x16x32_bf16 v[0:3], v[176:179], v[208:211], v[0:3]
	v_mfma_f32_16x16x32_bf16 v[40:43], v[172:175], v[188:191], v[40:43]
	v_mfma_f32_16x16x32_bf16 v[36:39], v[180:183], v[188:191], v[36:39]
	v_mfma_f32_16x16x32_bf16 v[28:31], v[172:175], v[196:199], v[28:31]
	v_mfma_f32_16x16x32_bf16 v[24:27], v[180:183], v[196:199], v[24:27]
	v_mfma_f32_16x16x32_bf16 v[16:19], v[172:175], v[204:207], v[16:19]
	v_mfma_f32_16x16x32_bf16 v[12:15], v[180:183], v[204:207], v[12:15]
	v_mfma_f32_16x16x32_bf16 v[4:7], v[172:175], v[214:217], v[4:7]
	v_mfma_f32_16x16x32_bf16 v[0:3], v[180:183], v[214:217], v[0:3]
	s_barrier
; #define PG8_STAGE(bufoff, gbase, voff) do { _Pragma("unroll") for (int _i = 0; _i < 2; ++_i) \
;         __builtin_amdgcn_global_load_lds((const unsigned*)((const char*)(gbase) + (voff)[_i]), (PG8_LAS unsigned*)(lds + (bufoff) + ldsw + _i * 8192), 16, 0, 0); } while (0)
; #define PG8_LDA(dst, b, h) do { _Pragma("unroll") for (int m = 0; m < 4; ++m) _Pragma("unroll") for (int k = 0; k < 2; ++k) dst[m][k] = *(const PG8_LAS bf16x8*)(lds + PG8_SA(b, h) + aoff + m * 2048 + k * 1024); } while (0)
; #define PG8_LDB(dst, b, h) do { _Pragma("unroll") for (int n = 0; n < 2; ++n) _Pragma("unroll") for (int k = 0; k < 2; ++k) dst[n][k] = *(const PG8_LAS bf16x8*)(lds + PG8_SB(b, h) + boff + n * 2048 + k * 1024); } while (0)
; #define PG8_MMA(ai, bj, At, Bt) do { __builtin_amdgcn_s_setprio(1); _Pragma("unroll") for (int m = 0; m < 4; ++m) _Pragma("unroll") for (int n = 0; n < 2; ++n) _Pragma("unroll") for (int k = 0; k < 2; ++k) \
;         acc[ai][bj][m][n] = __builtin_amdgcn_mfma_f32_16x16x32_bf16(Bt[n][k], At[m][k], acc[ai][bj][m][n], 0, 0, 0); __builtin_amdgcn_s_setprio(0); } while (0)
; #define PG8_WAIT_V(n) asm volatile("s_waitcnt vmcnt(" #n ")" ::: "memory")
; #define PG8_WAIT_L(n) asm volatile("s_waitcnt lgkmcnt(" #n ")" ::: "memory")
; #define PG8_BAR __builtin_amdgcn_s_barrier()
; #define PG8_SCHED __builtin_amdgcn_sched_barrier(0)
; template <class Epi, class Sched, bool ALIGN_EPI = false, bool SP2 = false>
; __device__ __forceinline__ void gemm_phase(PG8_LAS unsigned char* lds, const Gemm g, const Sched& S, const Epi& E) {
;     ...
;             PG8_LDB(B0, 1, 0); PG8_LDB(B1, 1, 1); PG8_SCHED; PG8_LDA(At, 1, 0); PG8_STAGE(PG8_SA(0, 1), a2 + hstep, voffA);
;             PG8_WAIT_V(8); PG8_WAIT_L(0); PG8_BAR; PG8_MMA(0, 0, At, B0); PG8_MMA(0, 1, At, B1); PG8_BAR; PG8_SCHED;
;             PG8_LDA(At, 1, 1); PG8_STAGE(PG8_SB(1, 0), b3, voffB); PG8_STAGE(PG8_SB(1, 1), b3 + hstep, voffB); PG8_STAGE(PG8_SA(1, 0), a3, voffA);
;             PG8_WAIT_V(8); PG8_WAIT_L(0); PG8_BAR; PG8_MMA(1, 0, At, B0); PG8_MMA(1, 1, At, B1); PG8_BAR; PG8_SCHED;
	s_add_i32 s72, 0, 0x18000
	s_add_i32 s73, 0, 0x1c000
	v_add_u32_e32 v140, s72, v167
	v_add_u32_e32 v180, s73, v167
	ds_read_b128 v[128:131], v140
	ds_read_b128 v[132:135], v140 offset:1024
	ds_read_b128 v[136:139], v140 offset:2048
	ds_read_b128 v[140:143], v140 offset:3072
	ds_read_b128 v[160:163], v180
	ds_read_b128 v[172:175], v180 offset:1024
	ds_read_b128 v[176:179], v180 offset:2048
	ds_read_b128 v[180:183], v180 offset:3072
	s_add_u32 s84, s50, 0x80
	s_addc_u32 s85, s51, 0
	s_add_u32 s50, s50, 0x80000
	s_addc_u32 s51, s51, 0
	s_mov_b32 m0, s55
	ds_read_b128 v[184:187], v171 offset:32768
	ds_read_b128 v[188:191], v171 offset:33792
	ds_read_b128 v[192:195], v171 offset:34816
	ds_read_b128 v[196:199], v171 offset:35840
	ds_read_b128 v[200:203], v171 offset:36864
	ds_read_b128 v[204:207], v171 offset:37888
	ds_read_b128 v[208:211], v171 offset:38912
	ds_read_b128 v[214:217], v171 offset:39936
	global_load_lds_dwordx4 v144, s[50:51]
	s_mov_b32 m0, s56
	s_nop 0
	global_load_lds_dwordx4 v148, s[50:51]
	s_waitcnt vmcnt(8)
	s_waitcnt lgkmcnt(0)
	s_barrier
	s_waitcnt lgkmcnt(0)
	v_mfma_f32_16x16x32_bf16 v[124:127], v[128:131], v[184:187], v[124:127]
	v_mfma_f32_16x16x32_bf16 v[120:123], v[136:139], v[184:187], v[120:123]
	v_mfma_f32_16x16x32_bf16 v[116:119], v[128:131], v[192:195], v[116:119]
	v_mfma_f32_16x16x32_bf16 v[112:115], v[136:139], v[192:195], v[112:115]
	v_mfma_f32_16x16x32_bf16 v[108:111], v[128:131], v[200:203], v[108:111]
	v_mfma_f32_16x16x32_bf16 v[96:99], v[136:139], v[200:203], v[96:99]
	v_mfma_f32_16x16x32_bf16 v[80:83], v[128:131], v[208:211], v[80:83]
	v_mfma_f32_16x16x32_bf16 v[72:75], v[136:139], v[208:211], v[72:75]
	v_mfma_f32_16x16x32_bf16 v[124:127], v[132:135], v[188:191], v[124:127]
	v_mfma_f32_16x16x32_bf16 v[120:123], v[140:143], v[188:191], v[120:123]
	v_mfma_f32_16x16x32_bf16 v[116:119], v[132:135], v[196:199], v[116:119]
	v_mfma_f32_16x16x32_bf16 v[112:115], v[140:143], v[196:199], v[112:115]
	v_mfma_f32_16x16x32_bf16 v[108:111], v[132:135], v[204:207], v[108:111]
	v_mfma_f32_16x16x32_bf16 v[96:99], v[140:143], v[204:207], v[96:99]
	v_mfma_f32_16x16x32_bf16 v[80:83], v[132:135], v[214:217], v[80:83]
	v_mfma_f32_16x16x32_bf16 v[72:75], v[140:143], v[214:217], v[72:75]
	v_mfma_f32_16x16x32_bf16 v[104:107], v[160:163], v[184:187], v[104:107]
	v_mfma_f32_16x16x32_bf16 v[100:103], v[176:179], v[184:187], v[100:103]
	v_mfma_f32_16x16x32_bf16 v[92:95], v[160:163], v[192:195], v[92:95]
	v_mfma_f32_16x16x32_bf16 v[88:91], v[176:179], v[192:195], v[88:91]
	v_mfma_f32_16x16x32_bf16 v[84:87], v[160:163], v[200:203], v[84:87]
	v_mfma_f32_16x16x32_bf16 v[76:79], v[176:179], v[200:203], v[76:79]
	v_mfma_f32_16x16x32_bf16 v[68:71], v[160:163], v[208:211], v[68:71]
	v_mfma_f32_16x16x32_bf16 v[64:67], v[176:179], v[208:211], v[64:67]
	v_mfma_f32_16x16x32_bf16 v[104:107], v[172:175], v[188:191], v[104:107]
	v_mfma_f32_16x16x32_bf16 v[100:103], v[180:183], v[188:191], v[100:103]
	v_mfma_f32_16x16x32_bf16 v[92:95], v[172:175], v[196:199], v[92:95]
	v_mfma_f32_16x16x32_bf16 v[88:91], v[180:183], v[196:199], v[88:91]
	v_mfma_f32_16x16x32_bf16 v[84:87], v[172:175], v[204:207], v[84:87]
	v_mfma_f32_16x16x32_bf16 v[76:79], v[180:183], v[204:207], v[76:79]
	v_mfma_f32_16x16x32_bf16 v[68:71], v[172:175], v[214:217], v[68:71]
	v_mfma_f32_16x16x32_bf16 v[64:67], v[180:183], v[214:217], v[64:67]
	s_barrier
	s_add_i32 s50, s72, s53
	s_add_u32 s86, s48, 0x80
	s_addc_u32 s87, s49, 0
	s_mov_b32 m0, s50
	ds_read_b128 v[184:187], v171 offset:49152
	ds_read_b128 v[188:191], v171 offset:50176
	ds_read_b128 v[192:195], v171 offset:51200
	ds_read_b128 v[196:199], v171 offset:52224
	ds_read_b128 v[200:203], v171 offset:53248
	ds_read_b128 v[204:207], v171 offset:54272
	ds_read_b128 v[208:211], v171 offset:55296
	ds_read_b128 v[214:217], v171 offset:56320
	global_load_lds_dwordx4 v146, s[86:87]
	s_add_i32 m0, s50, 0x2000
	s_add_u32 s48, s48, 0x80080
	s_addc_u32 s49, s49, 0
	s_add_i32 s50, s73, s53
	global_load_lds_dwordx4 v150, s[86:87]
	s_mov_b32 m0, s50
	s_nop 0
	global_load_lds_dwordx4 v146, s[48:49]
	s_add_i32 m0, s50, 0x2000
	s_nop 0
	global_load_lds_dwordx4 v150, s[48:49]
	s_mov_b32 m0, s60
	s_nop 0
	global_load_lds_dwordx4 v144, s[84:85]
	s_mov_b32 m0, s61
	s_nop 0
	global_load_lds_dwordx4 v148, s[84:85]
	s_waitcnt vmcnt(8)
	s_waitcnt lgkmcnt(0)
	s_barrier
	s_waitcnt lgkmcnt(0)
	v_mfma_f32_16x16x32_bf16 v[60:63], v[128:131], v[184:187], v[60:63]
	v_mfma_f32_16x16x32_bf16 v[56:59], v[136:139], v[184:187], v[56:59]
	v_mfma_f32_16x16x32_bf16 v[52:55], v[128:131], v[192:195], v[52:55]
	v_mfma_f32_16x16x32_bf16 v[48:51], v[136:139], v[192:195], v[48:51]
	v_mfma_f32_16x16x32_bf16 v[44:47], v[128:131], v[200:203], v[44:47]
	v_mfma_f32_16x16x32_bf16 v[32:35], v[136:139], v[200:203], v[32:35]
	v_mfma_f32_16x16x32_bf16 v[20:23], v[128:131], v[208:211], v[20:23]
	v_mfma_f32_16x16x32_bf16 v[8:11], v[136:139], v[208:211], v[8:11]
	v_mfma_f32_16x16x32_bf16 v[60:63], v[132:135], v[188:191], v[60:63]
	v_mfma_f32_16x16x32_bf16 v[56:59], v[140:143], v[188:191], v[56:59]
	v_mfma_f32_16x16x32_bf16 v[52:55], v[132:135], v[196:199], v[52:55]
	v_mfma_f32_16x16x32_bf16 v[48:51], v[140:143], v[196:199], v[48:51]
	v_mfma_f32_16x16x32_bf16 v[44:47], v[132:135], v[204:207], v[44:47]
	v_mfma_f32_16x16x32_bf16 v[32:35], v[140:143], v[204:207], v[32:35]
	v_mfma_f32_16x16x32_bf16 v[20:23], v[132:135], v[214:217], v[20:23]
	v_mfma_f32_16x16x32_bf16 v[8:11], v[140:143], v[214:217], v[8:11]
	v_mfma_f32_16x16x32_bf16 v[40:43], v[160:163], v[184:187], v[40:43]
	v_mfma_f32_16x16x32_bf16 v[36:39], v[176:179], v[184:187], v[36:39]
	v_mfma_f32_16x16x32_bf16 v[28:31], v[160:163], v[192:195], v[28:31]
	v_mfma_f32_16x16x32_bf16 v[24:27], v[176:179], v[192:195], v[24:27]
	v_mfma_f32_16x16x32_bf16 v[16:19], v[160:163], v[200:203], v[16:19]
	v_mfma_f32_16x16x32_bf16 v[12:15], v[176:179], v[200:203], v[12:15]
	v_mfma_f32_16x16x32_bf16 v[4:7], v[160:163], v[208:211], v[4:7]
	v_mfma_f32_16x16x32_bf16 v[0:3], v[176:179], v[208:211], v[0:3]
	v_mfma_f32_16x16x32_bf16 v[40:43], v[172:175], v[188:191], v[40:43]
	v_mfma_f32_16x16x32_bf16 v[36:39], v[180:183], v[188:191], v[36:39]
	v_mfma_f32_16x16x32_bf16 v[28:31], v[172:175], v[196:199], v[28:31]
	v_mfma_f32_16x16x32_bf16 v[24:27], v[180:183], v[196:199], v[24:27]
	v_mfma_f32_16x16x32_bf16 v[16:19], v[172:175], v[204:207], v[16:19]
	v_mfma_f32_16x16x32_bf16 v[12:15], v[180:183], v[204:207], v[12:15]
	v_mfma_f32_16x16x32_bf16 v[4:7], v[172:175], v[214:217], v[4:7]
	v_mfma_f32_16x16x32_bf16 v[0:3], v[180:183], v[214:217], v[0:3]
	s_barrier
;     __device__ __forceinline__ void operator()(const f32x4 (&acc)[2][2][4][2], const Unit& u, int wr, int wc, int fr, int fq) const {
;         const int row0 = u.pm * BM + wr * 64 + fr, col0 = u.pn * BM + wc * 32 + 8 * fq;
;         const float* gp = gate + (u.pm >> 5) * 18432 + col0;
;         f32x4 gv[2][2];
; #pragma unroll
;         for (int bj = 0; bj < 2; ++bj)
; #pragma unroll
;             for (int n = 0; n < 2; ++n) gv[bj][n] = *(const f32x4*)(gp + bj * HALF + 4 * n) * scale;
; #pragma unroll
;         for (int ai = 0; ai < 2; ++ai) { f32x4 r[4][2][2];
; #pragma unroll
;             for (int m = 0; m < 4; ++m) { const size_t off = (size_t)(row0 + ai * HALF + m * 16) * 2048 + col0;
; #pragma unroll
;                 for (int bj = 0; bj < 2; ++bj)
; #pragma unroll
;                     for (int n = 0; n < 2; ++n) r[m][bj][n] = *(const f32x4*)(res + off + bj * HALF + 4 * n); }
; #pragma unroll
;             for (int m = 0; m < 4; ++m) { const size_t off = (size_t)(row0 + ai * HALF + m * 16) * 2048 + col0;
; #pragma unroll
;                 for (int bj = 0; bj < 2; ++bj)
; #pragma unroll
;                     for (int n = 0; n < 2; ++n) *(f32x4*)(out + off + bj * HALF + 4 * n) = r[m][bj][n] + gv[bj][n] * acc[ai][bj][m][n]; } }
	s_add_i32 s71, s71, 2
	s_add_u32 s46, s46, 0x100
	s_addc_u32 s47, s47, 0
	s_add_u32 s69, s69, 0x100
	s_addc_u32 s70, s70, 0
	s_cmp_gt_u32 s71, 29
	s_cbranch_scc0 .LBB0_827
	s_lshr_b32 s37, s44, 5
	s_mul_i32 s46, s37, 0x4800
	v_lshl_or_b32 v128, s66, 8, v168
	s_ashr_i32 s47, s46, 31
	v_lshl_add_u32 v212, s44, 8, v166
	s_lshl_b64 s[46:47], s[46:47], 2
	v_ashrrev_i32_e32 v129, 31, v128
	v_or_b32_e32 v188, 16, v212
	v_or_b32_e32 v204, 32, v212
	s_add_u32 s46, s58, s46
	v_lshlrev_b64 v[160:161], 2, v[128:129]
	v_ashrrev_i32_e32 v213, 31, v212
	v_ashrrev_i32_e32 v189, 31, v188
	v_ashrrev_i32_e32 v205, 31, v204
	s_addc_u32 s47, s59, s47
	v_lshl_add_u64 v[162:163], s[12:13], 0, v[160:161]
	v_lshlrev_b64 v[164:165], 13, v[212:213]
	v_lshlrev_b64 v[218:219], 13, v[188:189]
	v_lshlrev_b64 v[230:231], 13, v[204:205]
	v_or_b32_e32 v212, 48, v212
	v_lshl_add_u64 v[136:137], s[46:47], 0, v[160:161]
	v_lshl_add_u64 v[184:185], v[162:163], 0, v[164:165]
	v_lshl_add_u64 v[200:201], v[162:163], 0, v[218:219]
	v_lshl_add_u64 v[222:223], v[162:163], 0, v[230:231]
	v_ashrrev_i32_e32 v213, 31, v212
	global_load_dwordx4 v[132:135], v[136:137], off offset:16
	global_load_dwordx4 v[140:143], v[136:137], off
	global_load_dwordx4 v[172:175], v[184:185], off offset:16
	global_load_dwordx4 v[176:179], v[184:185], off
	global_load_dwordx4 v[128:131], v[136:137], off offset:528
	s_nop 0
	global_load_dwordx4 v[136:139], v[136:137], off offset:512
	s_nop 0
	global_load_dwordx4 v[180:183], v[184:185], off offset:528
	s_nop 0
	global_load_dwordx4 v[184:187], v[184:185], off offset:512
	s_nop 0
	global_load_dwordx4 v[188:191], v[200:201], off
	global_load_dwordx4 v[192:195], v[200:201], off offset:16
	global_load_dwordx4 v[196:199], v[200:201], off offset:528
	s_nop 0
	global_load_dwordx4 v[200:203], v[200:201], off offset:512
	s_nop 0
	global_load_dwordx4 v[204:207], v[222:223], off
	global_load_dwordx4 v[208:211], v[222:223], off offset:16
	global_load_dwordx4 v[214:217], v[222:223], off offset:512
	s_nop 0
	global_load_dwordx4 v[222:225], v[222:223], off offset:528
	v_lshlrev_b64 v[212:213], 13, v[212:213]
	v_lshl_add_u64 v[244:245], v[162:163], 0, v[212:213]
	global_load_dwordx4 v[232:235], v[244:245], off
	global_load_dwordx4 v[236:239], v[244:245], off offset:16
	global_load_dwordx4 v[240:243], v[244:245], off offset:512
	s_nop 0
	global_load_dwordx4 v[244:247], v[244:245], off offset:528
	v_lshl_add_u64 v[248:249], s[14:15], 0, v[164:165]
	v_lshl_add_u64 v[248:249], v[248:249], 0, v[160:161]
	v_lshl_add_u64 v[218:219], s[14:15], 0, v[218:219]
	v_lshl_add_u64 v[230:231], s[14:15], 0, v[230:231]
	v_lshl_add_u64 v[218:219], v[218:219], 0, v[160:161]
	v_lshl_add_u64 v[230:231], v[230:231], 0, v[160:161]
	s_and_b64 vcc, exec, s[10:11]
	s_mov_b32 s66, s36
	s_mov_b32 s44, s38
	s_mov_b64 s[48:49], s[42:43]
	s_mov_b64 s[46:47], s[40:41]
	s_waitcnt vmcnt(0)
	v_pk_fma_f32 v[122:123], v[122:123], v[134:135], v[174:175]
	v_pk_fma_f32 v[126:127], v[126:127], v[142:143], v[178:179]
	v_pk_fma_f32 v[124:125], v[124:125], v[140:141], v[176:177]
	v_pk_fma_f32 v[120:121], v[120:121], v[132:133], v[172:173]
	v_pk_fma_f32 v[76:77], v[76:77], v[128:129], v[222:223]
	v_pk_fma_f32 v[106:107], v[106:107], v[138:139], v[186:187]
	v_pk_fma_f32 v[104:105], v[104:105], v[136:137], v[184:185]
	v_pk_fma_f32 v[102:103], v[102:103], v[130:131], v[182:183]
	v_pk_fma_f32 v[100:101], v[100:101], v[128:129], v[180:181]
	v_pk_fma_f32 v[118:119], v[118:119], v[142:143], v[190:191]
	v_pk_fma_f32 v[116:117], v[116:117], v[140:141], v[188:189]
	v_pk_fma_f32 v[114:115], v[114:115], v[134:135], v[194:195]
	v_pk_fma_f32 v[112:113], v[112:113], v[132:133], v[192:193]
	v_pk_fma_f32 v[94:95], v[94:95], v[138:139], v[202:203]
	v_pk_fma_f32 v[92:93], v[92:93], v[136:137], v[200:201]
	v_pk_fma_f32 v[90:91], v[90:91], v[130:131], v[198:199]
	v_pk_fma_f32 v[88:89], v[88:89], v[128:129], v[196:197]
	v_pk_fma_f32 v[110:111], v[110:111], v[142:143], v[206:207]
	v_pk_fma_f32 v[108:109], v[108:109], v[140:141], v[204:205]
	v_pk_fma_f32 v[98:99], v[98:99], v[134:135], v[210:211]
	v_pk_fma_f32 v[96:97], v[96:97], v[132:133], v[208:209]
	v_pk_fma_f32 v[86:87], v[86:87], v[138:139], v[216:217]
	v_pk_fma_f32 v[84:85], v[84:85], v[136:137], v[214:215]
	v_pk_fma_f32 v[78:79], v[78:79], v[130:131], v[224:225]
	global_store_dwordx4 v[248:249], v[124:127], off
	global_store_dwordx4 v[248:249], v[120:123], off offset:16
	global_store_dwordx4 v[248:249], v[104:107], off offset:512
	global_store_dwordx4 v[248:249], v[100:103], off offset:528
	global_store_dwordx4 v[218:219], v[116:119], off
	global_store_dwordx4 v[218:219], v[112:115], off offset:16
	global_store_dwordx4 v[218:219], v[92:95], off offset:512
	global_store_dwordx4 v[218:219], v[88:91], off offset:528
	global_store_dwordx4 v[230:231], v[108:111], off
	global_store_dwordx4 v[230:231], v[96:99], off offset:16
	global_store_dwordx4 v[230:231], v[84:87], off offset:512
	global_store_dwordx4 v[230:231], v[76:79], off offset:528
	v_pk_fma_f32 v[74:75], v[74:75], v[134:135], v[238:239]
	v_pk_fma_f32 v[72:73], v[72:73], v[132:133], v[236:237]
	v_pk_fma_f32 v[76:77], v[80:81], v[140:141], v[232:233]
	v_lshl_add_u64 v[80:81], s[14:15], 0, v[212:213]
; #define PG8_WAIT_V(n) asm volatile("s_waitcnt vmcnt(" #n ")" ::: "memory")
; #define PG8_BAR __builtin_amdgcn_s_barrier()
;     __device__ __forceinline__ void operator()(const f32x4 (&acc)[2][2][4][2], const Unit& u, int wr, int wc, int fr, int fq) const {
;     ...
;         for (int ai = 0; ai < 2; ++ai) { f32x4 r[4][2][2];
; #pragma unroll
;             for (int m = 0; m < 4; ++m) { const size_t off = (size_t)(row0 + ai * HALF + m * 16) * 2048 + col0;
; #pragma unroll
;                 for (int bj = 0; bj < 2; ++bj)
; #pragma unroll
;                     for (int n = 0; n < 2; ++n) r[m][bj][n] = *(const f32x4*)(res + off + bj * HALF + 4 * n); }
; #pragma unroll
;             for (int m = 0; m < 4; ++m) { const size_t off = (size_t)(row0 + ai * HALF + m * 16) * 2048 + col0;
; #pragma unroll
;                 for (int bj = 0; bj < 2; ++bj)
; #pragma unroll
;                     for (int n = 0; n < 2; ++n) *(f32x4*)(out + off + bj * HALF + 4 * n) = r[m][bj][n] + gv[bj][n] * acc[ai][bj][m][n]; } }
; template <class Epi, class Sched, bool ALIGN_EPI = false, bool SP2 = false>
; __device__ __forceinline__ void gemm_phase(PG8_LAS unsigned char* lds, const Gemm g, const Sched& S, const Epi& E) {
;     ...
;         if (!has_next) break;
; #pragma unroll
;         for (int a = 0; a < 2; ++a)
; #pragma unroll
;             for (int b = 0; b < 2; ++b)
; #pragma unroll
;                 for (int m = 0; m < 4; ++m)
; #pragma unroll
;                     for (int n = 0; n < 2; ++n) acc[a][b][m][n] = (f32x4){0.f, 0.f, 0.f, 0.f};
;         cur = nxt; cA = nA; cB = nB; ++ui;
;         if constexpr (ALIGN_EPI) { if (wr == 1) PG8_BAR; }
;     }
;     PG8_WAIT_V(0);
;     if constexpr (!ALIGN_EPI) { if (wr == 0) PG8_BAR; }
;     PG8_BAR;
	v_pk_fma_f32 v[78:79], v[82:83], v[142:143], v[234:235]
	v_lshl_add_u64 v[80:81], v[80:81], 0, v[160:161]
	v_pk_fma_f32 v[70:71], v[70:71], v[138:139], v[242:243]
	v_pk_fma_f32 v[68:69], v[68:69], v[136:137], v[240:241]
	v_pk_fma_f32 v[66:67], v[66:67], v[130:131], v[246:247]
	v_pk_fma_f32 v[64:65], v[64:65], v[128:129], v[244:245]
	v_lshl_add_u64 v[172:173], v[164:165], 0, s[26:27]
	v_lshl_add_u64 v[174:175], v[164:165], 0, s[28:29]
	v_lshl_add_u64 v[176:177], v[164:165], 0, s[30:31]
	global_store_dwordx4 v[80:81], v[76:79], off
	global_store_dwordx4 v[80:81], v[72:75], off offset:16
	global_store_dwordx4 v[80:81], v[68:71], off offset:512
	global_store_dwordx4 v[80:81], v[64:67], off offset:528
	v_lshl_add_u64 v[76:77], v[162:163], 0, v[172:173]
	v_lshl_add_u64 v[92:93], v[162:163], 0, v[174:175]
	v_lshl_add_u64 v[108:109], v[162:163], 0, v[176:177]
	global_load_dwordx4 v[64:67], v[76:77], off
	global_load_dwordx4 v[68:71], v[76:77], off offset:16
	global_load_dwordx4 v[72:75], v[76:77], off offset:512
	s_nop 0
	global_load_dwordx4 v[76:79], v[76:77], off offset:528
	s_nop 0
	global_load_dwordx4 v[80:83], v[92:93], off
	global_load_dwordx4 v[84:87], v[92:93], off offset:16
	global_load_dwordx4 v[88:91], v[92:93], off offset:512
	s_nop 0
	global_load_dwordx4 v[92:95], v[92:93], off offset:528
	s_nop 0
	global_load_dwordx4 v[96:99], v[108:109], off
	global_load_dwordx4 v[100:103], v[108:109], off offset:16
	global_load_dwordx4 v[104:107], v[108:109], off offset:512
	s_nop 0
	global_load_dwordx4 v[108:111], v[108:109], off offset:528
	v_lshl_add_u64 v[164:165], v[164:165], 0, s[34:35]
	v_lshl_add_u64 v[124:125], v[162:163], 0, v[164:165]
	global_load_dwordx4 v[112:115], v[124:125], off
	global_load_dwordx4 v[116:119], v[124:125], off offset:16
	global_load_dwordx4 v[120:123], v[124:125], off offset:512
	s_nop 0
	global_load_dwordx4 v[124:127], v[124:125], off offset:528
	v_lshl_add_u64 v[162:163], s[14:15], 0, v[172:173]
	v_lshl_add_u64 v[172:173], s[14:15], 0, v[174:175]
	v_lshl_add_u64 v[174:175], s[14:15], 0, v[176:177]
	v_lshl_add_u64 v[162:163], v[162:163], 0, v[160:161]
	v_lshl_add_u64 v[172:173], v[172:173], 0, v[160:161]
	v_lshl_add_u64 v[174:175], v[174:175], 0, v[160:161]
	s_waitcnt vmcnt(15)
	v_pk_fma_f32 v[62:63], v[62:63], v[142:143], v[66:67]
	v_pk_fma_f32 v[60:61], v[60:61], v[140:141], v[64:65]
	s_waitcnt vmcnt(14)
	v_pk_fma_f32 v[58:59], v[58:59], v[134:135], v[70:71]
	v_pk_fma_f32 v[56:57], v[56:57], v[132:133], v[68:69]
	s_waitcnt vmcnt(13)
	v_pk_fma_f32 v[42:43], v[42:43], v[138:139], v[74:75]
	s_waitcnt vmcnt(4)
	v_pk_fma_f32 v[12:13], v[12:13], v[128:129], v[108:109]
	v_pk_fma_f32 v[40:41], v[40:41], v[136:137], v[72:73]
	v_pk_fma_f32 v[38:39], v[38:39], v[130:131], v[78:79]
	v_pk_fma_f32 v[36:37], v[36:37], v[128:129], v[76:77]
	v_pk_fma_f32 v[54:55], v[54:55], v[142:143], v[82:83]
	v_pk_fma_f32 v[52:53], v[52:53], v[140:141], v[80:81]
	v_pk_fma_f32 v[50:51], v[50:51], v[134:135], v[86:87]
	v_pk_fma_f32 v[48:49], v[48:49], v[132:133], v[84:85]
	v_pk_fma_f32 v[30:31], v[30:31], v[138:139], v[90:91]
	v_pk_fma_f32 v[28:29], v[28:29], v[136:137], v[88:89]
	v_pk_fma_f32 v[26:27], v[26:27], v[130:131], v[94:95]
	v_pk_fma_f32 v[24:25], v[24:25], v[128:129], v[92:93]
	v_pk_fma_f32 v[46:47], v[46:47], v[142:143], v[98:99]
	v_pk_fma_f32 v[44:45], v[44:45], v[140:141], v[96:97]
	v_pk_fma_f32 v[34:35], v[34:35], v[134:135], v[102:103]
	v_pk_fma_f32 v[32:33], v[32:33], v[132:133], v[100:101]
	v_pk_fma_f32 v[18:19], v[18:19], v[138:139], v[106:107]
	v_pk_fma_f32 v[16:17], v[16:17], v[136:137], v[104:105]
	v_pk_fma_f32 v[14:15], v[14:15], v[130:131], v[110:111]
	global_store_dwordx4 v[162:163], v[60:63], off
	global_store_dwordx4 v[162:163], v[56:59], off offset:16
	global_store_dwordx4 v[162:163], v[40:43], off offset:512
	global_store_dwordx4 v[162:163], v[36:39], off offset:528
	global_store_dwordx4 v[172:173], v[52:55], off
	global_store_dwordx4 v[172:173], v[48:51], off offset:16
	global_store_dwordx4 v[172:173], v[28:31], off offset:512
	global_store_dwordx4 v[172:173], v[24:27], off offset:528
	global_store_dwordx4 v[174:175], v[44:47], off
	global_store_dwordx4 v[174:175], v[32:35], off offset:16
	global_store_dwordx4 v[174:175], v[16:19], off offset:512
	global_store_dwordx4 v[174:175], v[12:15], off offset:528
	s_waitcnt vmcnt(15)
	v_pk_fma_f32 v[22:23], v[22:23], v[142:143], v[114:115]
	v_pk_fma_f32 v[20:21], v[20:21], v[140:141], v[112:113]
	v_lshl_add_u64 v[12:13], s[14:15], 0, v[164:165]
	v_lshl_add_u64 v[12:13], v[12:13], 0, v[160:161]
	s_waitcnt vmcnt(14)
	v_pk_fma_f32 v[10:11], v[10:11], v[134:135], v[118:119]
	v_pk_fma_f32 v[8:9], v[8:9], v[132:133], v[116:117]
	s_waitcnt vmcnt(13)
	v_pk_fma_f32 v[6:7], v[6:7], v[138:139], v[122:123]
	v_pk_fma_f32 v[4:5], v[4:5], v[136:137], v[120:121]
	s_waitcnt vmcnt(12)
	v_pk_fma_f32 v[2:3], v[2:3], v[130:131], v[126:127]
	v_pk_fma_f32 v[0:1], v[0:1], v[128:129], v[124:125]
	global_store_dwordx4 v[12:13], v[20:23], off
	global_store_dwordx4 v[12:13], v[8:11], off offset:16
	global_store_dwordx4 v[12:13], v[4:7], off offset:512
	global_store_dwordx4 v[12:13], v[0:3], off offset:528
	s_cbranch_vccz .LBB0_820
	s_waitcnt vmcnt(0)
	s_cmpk_gt_u32 s3, 0xff
	s_cbranch_scc1 .LBB0_831
	s_barrier

; #define PG8_STAGE(bufoff, gbase, voff) do { _Pragma("unroll") for (int _i = 0; _i < 2; ++_i) \
;         __builtin_amdgcn_global_load_lds((const unsigned*)((const char*)(gbase) + (voff)[_i]), (PG8_LAS unsigned*)(lds + (bufoff) + ldsw + _i * 8192), 16, 0, 0); } while (0)
; #define PG8_LDA(dst, b, h) do { _Pragma("unroll") for (int m = 0; m < 4; ++m) _Pragma("unroll") for (int k = 0; k < 2; ++k) dst[m][k] = *(const PG8_LAS bf16x8*)(lds + PG8_SA(b, h) + aoff + m * 2048 + k * 1024); } while (0)
; #define PG8_LDB(dst, b, h) do { _Pragma("unroll") for (int n = 0; n < 2; ++n) _Pragma("unroll") for (int k = 0; k < 2; ++k) dst[n][k] = *(const PG8_LAS bf16x8*)(lds + PG8_SB(b, h) + boff + n * 2048 + k * 1024); } while (0)
; #define PG8_MMA(ai, bj, At, Bt) do { __builtin_amdgcn_s_setprio(1); _Pragma("unroll") for (int m = 0; m < 4; ++m) _Pragma("unroll") for (int n = 0; n < 2; ++n) _Pragma("unroll") for (int k = 0; k < 2; ++k) \
;         acc[ai][bj][m][n] = __builtin_amdgcn_mfma_f32_16x16x32_bf16(Bt[n][k], At[m][k], acc[ai][bj][m][n], 0, 0, 0); __builtin_amdgcn_s_setprio(0); } while (0)
; #define PG8_WAIT_V(n) asm volatile("s_waitcnt vmcnt(" #n ")" ::: "memory")
; #define PG8_WAIT_L(n) asm volatile("s_waitcnt lgkmcnt(" #n ")" ::: "memory")
; #define PG8_BAR __builtin_amdgcn_s_barrier()
; #define PG8_SCHED __builtin_amdgcn_sched_barrier(0)
; template <class Epi, class Sched, bool ALIGN_EPI = false, bool SP2 = false>
; __device__ __forceinline__ void gemm_phase(PG8_LAS unsigned char* lds, const Gemm g, const Sched& S, const Epi& E) {
;     ...
;             PG8_LDB(B0, 0, 0); PG8_LDB(B1, 0, 1); PG8_SCHED; PG8_LDA(At, 0, 0); PG8_STAGE(PG8_SA(1, 1), a1 + hstep, voffA);
;             PG8_WAIT_V(8); PG8_WAIT_L(0); PG8_BAR; PG8_MMA(0, 0, At, B0); PG8_MMA(0, 1, At, B1); PG8_BAR; PG8_SCHED;
;             PG8_LDA(At, 0, 1); PG8_STAGE(PG8_SB(0, 0), b2, voffB); PG8_STAGE(PG8_SB(0, 1), b2 + hstep, voffB); PG8_STAGE(PG8_SA(0, 0), a2, voffA);
;             PG8_WAIT_V(8); PG8_WAIT_L(0); PG8_BAR; PG8_MMA(1, 0, At, B0); PG8_MMA(1, 1, At, B1); PG8_BAR; PG8_SCHED;
.LBB0_945:
	ds_read_b128 v[152:155], v149
	ds_read_b128 v[156:159], v149 offset:1024
	ds_read_b128 v[160:163], v149 offset:2048
	ds_read_b128 v[164:167], v149 offset:3072
	ds_read_b128 v[168:171], v150
	ds_read_b128 v[172:175], v150 offset:1024
	ds_read_b128 v[176:179], v150 offset:2048
	ds_read_b128 v[180:183], v150 offset:3072
	s_add_u32 s34, s30, 0xfff80080
	s_addc_u32 s35, s31, -1
	s_cmp_eq_u32 s61, 28
	s_cselect_b32 s37, s23, s35
	s_cselect_b32 s36, s57, s34
	s_cselect_b32 s35, s15, s60
	s_cselect_b32 s34, s58, s59
	s_add_i32 m0, s29, 0xc000
	ds_read_b128 v[184:187], v151
	ds_read_b128 v[188:191], v151 offset:1024
	ds_read_b128 v[192:195], v151 offset:2048
	ds_read_b128 v[196:199], v151 offset:3072
	ds_read_b128 v[200:203], v151 offset:4096
	ds_read_b128 v[204:207], v151 offset:5120
	ds_read_b128 v[208:211], v151 offset:6144
	ds_read_b128 v[212:215], v151 offset:7168
	global_load_lds_dwordx4 v136, s[30:31]
	s_add_i32 m0, s29, 0xe000
	s_nop 0
	global_load_lds_dwordx4 v138, s[30:31]
	s_waitcnt vmcnt(8)
	s_waitcnt lgkmcnt(0)
	s_barrier
	s_waitcnt lgkmcnt(0)
	v_mfma_f32_16x16x32_bf16 v[124:127], v[152:155], v[184:187], v[124:127]
	v_mfma_f32_16x16x32_bf16 v[120:123], v[160:163], v[184:187], v[120:123]
	v_mfma_f32_16x16x32_bf16 v[108:111], v[152:155], v[192:195], v[108:111]
	v_mfma_f32_16x16x32_bf16 v[104:107], v[160:163], v[192:195], v[104:107]
	v_mfma_f32_16x16x32_bf16 v[92:95], v[152:155], v[200:203], v[92:95]
	v_mfma_f32_16x16x32_bf16 v[88:91], v[160:163], v[200:203], v[88:91]
	v_mfma_f32_16x16x32_bf16 v[76:79], v[152:155], v[208:211], v[76:79]
	v_mfma_f32_16x16x32_bf16 v[72:75], v[160:163], v[208:211], v[72:75]
	v_mfma_f32_16x16x32_bf16 v[124:127], v[156:159], v[188:191], v[124:127]
	v_mfma_f32_16x16x32_bf16 v[120:123], v[164:167], v[188:191], v[120:123]
	v_mfma_f32_16x16x32_bf16 v[108:111], v[156:159], v[196:199], v[108:111]
	v_mfma_f32_16x16x32_bf16 v[104:107], v[164:167], v[196:199], v[104:107]
	v_mfma_f32_16x16x32_bf16 v[92:95], v[156:159], v[204:207], v[92:95]
	v_mfma_f32_16x16x32_bf16 v[88:91], v[164:167], v[204:207], v[88:91]
	v_mfma_f32_16x16x32_bf16 v[76:79], v[156:159], v[212:215], v[76:79]
	v_mfma_f32_16x16x32_bf16 v[72:75], v[164:167], v[212:215], v[72:75]
	v_mfma_f32_16x16x32_bf16 v[116:119], v[168:171], v[184:187], v[116:119]
	v_mfma_f32_16x16x32_bf16 v[112:115], v[176:179], v[184:187], v[112:115]
	v_mfma_f32_16x16x32_bf16 v[100:103], v[168:171], v[192:195], v[100:103]
	v_mfma_f32_16x16x32_bf16 v[96:99], v[176:179], v[192:195], v[96:99]
	v_mfma_f32_16x16x32_bf16 v[84:87], v[168:171], v[200:203], v[84:87]
	v_mfma_f32_16x16x32_bf16 v[80:83], v[176:179], v[200:203], v[80:83]
	v_mfma_f32_16x16x32_bf16 v[68:71], v[168:171], v[208:211], v[68:71]
	v_mfma_f32_16x16x32_bf16 v[64:67], v[176:179], v[208:211], v[64:67]
	v_mfma_f32_16x16x32_bf16 v[116:119], v[172:175], v[188:191], v[116:119]
	v_mfma_f32_16x16x32_bf16 v[112:115], v[180:183], v[188:191], v[112:115]
	v_mfma_f32_16x16x32_bf16 v[100:103], v[172:175], v[196:199], v[100:103]
	v_mfma_f32_16x16x32_bf16 v[96:99], v[180:183], v[196:199], v[96:99]
	v_mfma_f32_16x16x32_bf16 v[84:87], v[172:175], v[204:207], v[84:87]
	v_mfma_f32_16x16x32_bf16 v[80:83], v[180:183], v[204:207], v[80:83]
	v_mfma_f32_16x16x32_bf16 v[68:71], v[172:175], v[212:215], v[68:71]
	v_mfma_f32_16x16x32_bf16 v[64:67], v[180:183], v[212:215], v[64:67]
	s_barrier
	s_add_i32 s62, s53, s42
	s_mov_b32 m0, s62
	ds_read_b128 v[184:187], v151 offset:16384
	ds_read_b128 v[188:191], v151 offset:17408
	ds_read_b128 v[192:195], v151 offset:18432
	ds_read_b128 v[196:199], v151 offset:19456
	ds_read_b128 v[200:203], v151 offset:20480
	ds_read_b128 v[204:207], v151 offset:21504
	ds_read_b128 v[208:211], v151 offset:22528
	ds_read_b128 v[212:215], v151 offset:23552
	global_load_lds_dwordx4 v132, s[34:35]
	s_add_i32 m0, s62, 0x2000
	s_add_u32 s62, s34, 0x80000
	s_addc_u32 s63, s35, 0
	s_add_i32 s64, s54, s42
	global_load_lds_dwordx4 v128, s[34:35]
	s_mov_b32 m0, s64
	s_nop 0
	global_load_lds_dwordx4 v132, s[62:63]
	s_add_i32 m0, s64, 0x2000
	s_nop 0
	global_load_lds_dwordx4 v128, s[62:63]
	s_mov_b32 m0, s29
	s_nop 0
	global_load_lds_dwordx4 v134, s[36:37]
	s_mov_b32 m0, s45
	s_nop 0
	global_load_lds_dwordx4 v130, s[36:37]
	s_waitcnt vmcnt(8)
	s_waitcnt lgkmcnt(0)
	s_barrier
	s_waitcnt lgkmcnt(0)
	v_mfma_f32_16x16x32_bf16 v[60:63], v[152:155], v[184:187], v[60:63]
	v_mfma_f32_16x16x32_bf16 v[56:59], v[160:163], v[184:187], v[56:59]
	v_mfma_f32_16x16x32_bf16 v[44:47], v[152:155], v[192:195], v[44:47]
	v_mfma_f32_16x16x32_bf16 v[40:43], v[160:163], v[192:195], v[40:43]
	v_mfma_f32_16x16x32_bf16 v[28:31], v[152:155], v[200:203], v[28:31]
	v_mfma_f32_16x16x32_bf16 v[24:27], v[160:163], v[200:203], v[24:27]
	v_mfma_f32_16x16x32_bf16 v[12:15], v[152:155], v[208:211], v[12:15]
	v_mfma_f32_16x16x32_bf16 v[8:11], v[160:163], v[208:211], v[8:11]
	v_mfma_f32_16x16x32_bf16 v[60:63], v[156:159], v[188:191], v[60:63]
	v_mfma_f32_16x16x32_bf16 v[56:59], v[164:167], v[188:191], v[56:59]
	v_mfma_f32_16x16x32_bf16 v[44:47], v[156:159], v[196:199], v[44:47]
	v_mfma_f32_16x16x32_bf16 v[40:43], v[164:167], v[196:199], v[40:43]
	v_mfma_f32_16x16x32_bf16 v[28:31], v[156:159], v[204:207], v[28:31]
	v_mfma_f32_16x16x32_bf16 v[24:27], v[164:167], v[204:207], v[24:27]
	v_mfma_f32_16x16x32_bf16 v[12:15], v[156:159], v[212:215], v[12:15]
	v_mfma_f32_16x16x32_bf16 v[8:11], v[164:167], v[212:215], v[8:11]
	v_mfma_f32_16x16x32_bf16 v[52:55], v[168:171], v[184:187], v[52:55]
	v_mfma_f32_16x16x32_bf16 v[48:51], v[176:179], v[184:187], v[48:51]
	v_mfma_f32_16x16x32_bf16 v[36:39], v[168:171], v[192:195], v[36:39]
	v_mfma_f32_16x16x32_bf16 v[32:35], v[176:179], v[192:195], v[32:35]
	v_mfma_f32_16x16x32_bf16 v[20:23], v[168:171], v[200:203], v[20:23]
	v_mfma_f32_16x16x32_bf16 v[16:19], v[176:179], v[200:203], v[16:19]
	v_mfma_f32_16x16x32_bf16 v[4:7], v[168:171], v[208:211], v[4:7]
	v_mfma_f32_16x16x32_bf16 v[0:3], v[176:179], v[208:211], v[0:3]
	v_mfma_f32_16x16x32_bf16 v[52:55], v[172:175], v[188:191], v[52:55]
	v_mfma_f32_16x16x32_bf16 v[48:51], v[180:183], v[188:191], v[48:51]
	v_mfma_f32_16x16x32_bf16 v[36:39], v[172:175], v[196:199], v[36:39]
	v_mfma_f32_16x16x32_bf16 v[32:35], v[180:183], v[196:199], v[32:35]
	v_mfma_f32_16x16x32_bf16 v[20:23], v[172:175], v[204:207], v[20:23]
	v_mfma_f32_16x16x32_bf16 v[16:19], v[180:183], v[204:207], v[16:19]
	v_mfma_f32_16x16x32_bf16 v[4:7], v[172:175], v[212:215], v[4:7]
	v_mfma_f32_16x16x32_bf16 v[0:3], v[180:183], v[212:215], v[0:3]
	s_barrier
; #define PG8_STAGE(bufoff, gbase, voff) do { _Pragma("unroll") for (int _i = 0; _i < 2; ++_i) \
;         __builtin_amdgcn_global_load_lds((const unsigned*)((const char*)(gbase) + (voff)[_i]), (PG8_LAS unsigned*)(lds + (bufoff) + ldsw + _i * 8192), 16, 0, 0); } while (0)
; #define PG8_LDA(dst, b, h) do { _Pragma("unroll") for (int m = 0; m < 4; ++m) _Pragma("unroll") for (int k = 0; k < 2; ++k) dst[m][k] = *(const PG8_LAS bf16x8*)(lds + PG8_SA(b, h) + aoff + m * 2048 + k * 1024); } while (0)
; #define PG8_LDB(dst, b, h) do { _Pragma("unroll") for (int n = 0; n < 2; ++n) _Pragma("unroll") for (int k = 0; k < 2; ++k) dst[n][k] = *(const PG8_LAS bf16x8*)(lds + PG8_SB(b, h) + boff + n * 2048 + k * 1024); } while (0)
; #define PG8_MMA(ai, bj, At, Bt) do { __builtin_amdgcn_s_setprio(1); _Pragma("unroll") for (int m = 0; m < 4; ++m) _Pragma("unroll") for (int n = 0; n < 2; ++n) _Pragma("unroll") for (int k = 0; k < 2; ++k) \
;         acc[ai][bj][m][n] = __builtin_amdgcn_mfma_f32_16x16x32_bf16(Bt[n][k], At[m][k], acc[ai][bj][m][n], 0, 0, 0); __builtin_amdgcn_s_setprio(0); } while (0)
; #define PG8_WAIT_V(n) asm volatile("s_waitcnt vmcnt(" #n ")" ::: "memory")
; #define PG8_WAIT_L(n) asm volatile("s_waitcnt lgkmcnt(" #n ")" ::: "memory")
; #define PG8_BAR __builtin_amdgcn_s_barrier()
; #define PG8_SCHED __builtin_amdgcn_sched_barrier(0)
; template <class Epi, class Sched, bool ALIGN_EPI = false, bool SP2 = false>
; __device__ __forceinline__ void gemm_phase(PG8_LAS unsigned char* lds, const Gemm g, const Sched& S, const Epi& E) {
;     ...
;             PG8_LDB(B0, 1, 0); PG8_LDB(B1, 1, 1); PG8_SCHED; PG8_LDA(At, 1, 0); PG8_STAGE(PG8_SA(0, 1), a2 + hstep, voffA);
;             PG8_WAIT_V(8); PG8_WAIT_L(0); PG8_BAR; PG8_MMA(0, 0, At, B0); PG8_MMA(0, 1, At, B1); PG8_BAR; PG8_SCHED;
;             PG8_LDA(At, 1, 1); PG8_STAGE(PG8_SB(1, 0), b3, voffB); PG8_STAGE(PG8_SB(1, 1), b3 + hstep, voffB); PG8_STAGE(PG8_SA(1, 0), a3, voffA);
;             PG8_WAIT_V(8); PG8_WAIT_L(0); PG8_BAR; PG8_MMA(1, 0, At, B0); PG8_MMA(1, 1, At, B1); PG8_BAR; PG8_SCHED;
	s_add_i32 s62, 0, 0x18000
	s_add_i32 s63, 0, 0x1c000
	v_add_u32_e32 v164, s62, v147
	v_add_u32_e32 v180, s63, v147
	ds_read_b128 v[152:155], v164
	ds_read_b128 v[156:159], v164 offset:1024
	ds_read_b128 v[160:163], v164 offset:2048
	ds_read_b128 v[164:167], v164 offset:3072
	ds_read_b128 v[168:171], v180
	ds_read_b128 v[172:175], v180 offset:1024
	ds_read_b128 v[176:179], v180 offset:2048
	ds_read_b128 v[180:183], v180 offset:3072
	s_add_u32 s84, s36, 0x80
	s_addc_u32 s85, s37, 0
	s_add_u32 s36, s36, 0x80000
	s_addc_u32 s37, s37, 0
	s_mov_b32 m0, s46
	ds_read_b128 v[184:187], v151 offset:32768
	ds_read_b128 v[188:191], v151 offset:33792
	ds_read_b128 v[192:195], v151 offset:34816
	ds_read_b128 v[196:199], v151 offset:35840
	ds_read_b128 v[200:203], v151 offset:36864
	ds_read_b128 v[204:207], v151 offset:37888
	ds_read_b128 v[208:211], v151 offset:38912
	ds_read_b128 v[212:215], v151 offset:39936
	global_load_lds_dwordx4 v134, s[36:37]
	s_mov_b32 m0, s47
	s_nop 0
	global_load_lds_dwordx4 v130, s[36:37]
	s_waitcnt vmcnt(8)
	s_waitcnt lgkmcnt(0)
	s_barrier
	s_waitcnt lgkmcnt(0)
	v_mfma_f32_16x16x32_bf16 v[124:127], v[152:155], v[184:187], v[124:127]
	v_mfma_f32_16x16x32_bf16 v[120:123], v[160:163], v[184:187], v[120:123]
	v_mfma_f32_16x16x32_bf16 v[108:111], v[152:155], v[192:195], v[108:111]
	v_mfma_f32_16x16x32_bf16 v[104:107], v[160:163], v[192:195], v[104:107]
	v_mfma_f32_16x16x32_bf16 v[92:95], v[152:155], v[200:203], v[92:95]
	v_mfma_f32_16x16x32_bf16 v[88:91], v[160:163], v[200:203], v[88:91]
	v_mfma_f32_16x16x32_bf16 v[76:79], v[152:155], v[208:211], v[76:79]
	v_mfma_f32_16x16x32_bf16 v[72:75], v[160:163], v[208:211], v[72:75]
	v_mfma_f32_16x16x32_bf16 v[124:127], v[156:159], v[188:191], v[124:127]
	v_mfma_f32_16x16x32_bf16 v[120:123], v[164:167], v[188:191], v[120:123]
	v_mfma_f32_16x16x32_bf16 v[108:111], v[156:159], v[196:199], v[108:111]
	v_mfma_f32_16x16x32_bf16 v[104:107], v[164:167], v[196:199], v[104:107]
	v_mfma_f32_16x16x32_bf16 v[92:95], v[156:159], v[204:207], v[92:95]
	v_mfma_f32_16x16x32_bf16 v[88:91], v[164:167], v[204:207], v[88:91]
	v_mfma_f32_16x16x32_bf16 v[76:79], v[156:159], v[212:215], v[76:79]
	v_mfma_f32_16x16x32_bf16 v[72:75], v[164:167], v[212:215], v[72:75]
	v_mfma_f32_16x16x32_bf16 v[116:119], v[168:171], v[184:187], v[116:119]
	v_mfma_f32_16x16x32_bf16 v[112:115], v[176:179], v[184:187], v[112:115]
	v_mfma_f32_16x16x32_bf16 v[100:103], v[168:171], v[192:195], v[100:103]
	v_mfma_f32_16x16x32_bf16 v[96:99], v[176:179], v[192:195], v[96:99]
	v_mfma_f32_16x16x32_bf16 v[84:87], v[168:171], v[200:203], v[84:87]
	v_mfma_f32_16x16x32_bf16 v[80:83], v[176:179], v[200:203], v[80:83]
	v_mfma_f32_16x16x32_bf16 v[68:71], v[168:171], v[208:211], v[68:71]
	v_mfma_f32_16x16x32_bf16 v[64:67], v[176:179], v[208:211], v[64:67]
	v_mfma_f32_16x16x32_bf16 v[116:119], v[172:175], v[188:191], v[116:119]
	v_mfma_f32_16x16x32_bf16 v[112:115], v[180:183], v[188:191], v[112:115]
	v_mfma_f32_16x16x32_bf16 v[100:103], v[172:175], v[196:199], v[100:103]
	v_mfma_f32_16x16x32_bf16 v[96:99], v[180:183], v[196:199], v[96:99]
	v_mfma_f32_16x16x32_bf16 v[84:87], v[172:175], v[204:207], v[84:87]
	v_mfma_f32_16x16x32_bf16 v[80:83], v[180:183], v[204:207], v[80:83]
	v_mfma_f32_16x16x32_bf16 v[68:71], v[172:175], v[212:215], v[68:71]
	v_mfma_f32_16x16x32_bf16 v[64:67], v[180:183], v[212:215], v[64:67]
	s_barrier
	s_add_i32 s36, s62, s42
	s_add_u32 s86, s34, 0x80
	s_addc_u32 s87, s35, 0
	s_mov_b32 m0, s36
	ds_read_b128 v[184:187], v151 offset:49152
	ds_read_b128 v[188:191], v151 offset:50176
	ds_read_b128 v[192:195], v151 offset:51200
	ds_read_b128 v[196:199], v151 offset:52224
	ds_read_b128 v[200:203], v151 offset:53248
	ds_read_b128 v[204:207], v151 offset:54272
	ds_read_b128 v[208:211], v151 offset:55296
	ds_read_b128 v[212:215], v151 offset:56320
	global_load_lds_dwordx4 v132, s[86:87]
	s_add_i32 m0, s36, 0x2000
	s_add_u32 s34, s34, 0x80080
	s_addc_u32 s35, s35, 0
	s_add_i32 s36, s63, s42
	global_load_lds_dwordx4 v128, s[86:87]
	s_mov_b32 m0, s36
	s_nop 0
	global_load_lds_dwordx4 v132, s[34:35]
	s_add_i32 m0, s36, 0x2000
	s_nop 0
	global_load_lds_dwordx4 v128, s[34:35]
	s_mov_b32 m0, s49
	s_nop 0
	global_load_lds_dwordx4 v134, s[84:85]
	s_mov_b32 m0, s50
	s_nop 0
	global_load_lds_dwordx4 v130, s[84:85]
	s_waitcnt vmcnt(8)
	s_waitcnt lgkmcnt(0)
	s_barrier
	s_waitcnt lgkmcnt(0)
	v_mfma_f32_16x16x32_bf16 v[60:63], v[152:155], v[184:187], v[60:63]
	v_mfma_f32_16x16x32_bf16 v[56:59], v[160:163], v[184:187], v[56:59]
	v_mfma_f32_16x16x32_bf16 v[44:47], v[152:155], v[192:195], v[44:47]
	v_mfma_f32_16x16x32_bf16 v[40:43], v[160:163], v[192:195], v[40:43]
	v_mfma_f32_16x16x32_bf16 v[28:31], v[152:155], v[200:203], v[28:31]
	v_mfma_f32_16x16x32_bf16 v[24:27], v[160:163], v[200:203], v[24:27]
	v_mfma_f32_16x16x32_bf16 v[12:15], v[152:155], v[208:211], v[12:15]
	v_mfma_f32_16x16x32_bf16 v[8:11], v[160:163], v[208:211], v[8:11]
	v_mfma_f32_16x16x32_bf16 v[60:63], v[156:159], v[188:191], v[60:63]
	v_mfma_f32_16x16x32_bf16 v[56:59], v[164:167], v[188:191], v[56:59]
	v_mfma_f32_16x16x32_bf16 v[44:47], v[156:159], v[196:199], v[44:47]
	v_mfma_f32_16x16x32_bf16 v[40:43], v[164:167], v[196:199], v[40:43]
	v_mfma_f32_16x16x32_bf16 v[28:31], v[156:159], v[204:207], v[28:31]
	v_mfma_f32_16x16x32_bf16 v[24:27], v[164:167], v[204:207], v[24:27]
	v_mfma_f32_16x16x32_bf16 v[12:15], v[156:159], v[212:215], v[12:15]
	v_mfma_f32_16x16x32_bf16 v[8:11], v[164:167], v[212:215], v[8:11]
	v_mfma_f32_16x16x32_bf16 v[52:55], v[168:171], v[184:187], v[52:55]
	v_mfma_f32_16x16x32_bf16 v[48:51], v[176:179], v[184:187], v[48:51]
	v_mfma_f32_16x16x32_bf16 v[36:39], v[168:171], v[192:195], v[36:39]
	v_mfma_f32_16x16x32_bf16 v[32:35], v[176:179], v[192:195], v[32:35]
	v_mfma_f32_16x16x32_bf16 v[20:23], v[168:171], v[200:203], v[20:23]
	v_mfma_f32_16x16x32_bf16 v[16:19], v[176:179], v[200:203], v[16:19]
	v_mfma_f32_16x16x32_bf16 v[4:7], v[168:171], v[208:211], v[4:7]
	v_mfma_f32_16x16x32_bf16 v[0:3], v[176:179], v[208:211], v[0:3]
	v_mfma_f32_16x16x32_bf16 v[52:55], v[172:175], v[188:191], v[52:55]
	v_mfma_f32_16x16x32_bf16 v[48:51], v[180:183], v[188:191], v[48:51]
	v_mfma_f32_16x16x32_bf16 v[36:39], v[172:175], v[196:199], v[36:39]
	v_mfma_f32_16x16x32_bf16 v[32:35], v[180:183], v[196:199], v[32:35]
	v_mfma_f32_16x16x32_bf16 v[20:23], v[172:175], v[204:207], v[20:23]
	v_mfma_f32_16x16x32_bf16 v[16:19], v[180:183], v[204:207], v[16:19]
	v_mfma_f32_16x16x32_bf16 v[4:7], v[172:175], v[212:215], v[4:7]
	v_mfma_f32_16x16x32_bf16 v[0:3], v[180:183], v[212:215], v[0:3]
	s_barrier
; __device__ __forceinline__ float fsilu(float v) { return v * fsigmoid(v); }
; __device__ __forceinline__ u32x4 pack8(const f32x4 a, const f32x4 b) { u32x4 w; w.x = cvt_pk_bf16(a[0], a[1]); w.y = cvt_pk_bf16(a[2], a[3]); w.z = cvt_pk_bf16(b[0], b[1]); w.w = cvt_pk_bf16(b[2], b[3]); return w; }
;     __device__ __forceinline__ void operator()(const f32x4 (&acc)[2][2][4][2], const Unit& u, int wr, int wc, int fr, int fq) const {
;         const int row0 = u.pm * BM + wr * 64 + fr, col0 = u.pn * 128 + wc * 32 + 8 * fq;
; #pragma unroll
;         for (int ai = 0; ai < 2; ++ai)
; #pragma unroll
;             for (int m = 0; m < 4; ++m) {
;                 bf16_t* rowp = O + (size_t)(row0 + ai * HALF + m * 16) * ldc + col0;
;                 f32x4 h0, h1;
; #pragma unroll
;                 for (int j = 0; j < 4; ++j) { h0[j] = fsilu(acc[ai][0][m][0][j]) * acc[ai][1][m][0][j]; h1[j] = fsilu(acc[ai][0][m][1][j]) * acc[ai][1][m][1][j]; }
;                 *(u32x4*)rowp = pack8(h0, h1);
	s_add_i32 s61, s61, 2
	s_add_u32 s30, s30, 0x100
	s_addc_u32 s31, s31, 0
	s_add_u32 s59, s59, 0x100
	s_addc_u32 s60, s60, 0
	s_cmp_gt_u32 s61, 29
	s_cbranch_scc0 .LBB0_945
	v_mul_f32_e32 v153, 0xbfb8aa3b, v124
	v_mul_f32_e32 v158, 0xbfb8aa3b, v120
	v_exp_f32_e32 v153, v153
	v_exp_f32_e32 v159, v158
	v_mul_f32_e32 v158, 0xbfb8aa3b, v125
	v_exp_f32_e32 v160, v158
	v_add_f32_e32 v153, 1.0, v153
	v_rcp_f32_e32 v158, v153
	v_add_f32_e32 v153, 1.0, v159
	v_add_f32_e32 v159, 1.0, v160
	v_rcp_f32_e32 v159, v159
	v_mul_f32_e32 v160, 0xbfb8aa3b, v121
	v_exp_f32_e32 v161, v160
	v_rcp_f32_e32 v160, v153
	v_pk_mul_f32 v[124:125], v[124:125], v[158:159]
	v_mul_f32_e32 v153, 0xbfb8aa3b, v127
	v_pk_mul_f32 v[116:117], v[124:125], v[116:117]
	v_add_f32_e32 v124, 1.0, v161
	v_mul_f32_e32 v125, 0xbfb8aa3b, v122
	v_rcp_f32_e32 v161, v124
	v_mul_f32_e32 v124, 0xbfb8aa3b, v126
	v_exp_f32_e32 v125, v125
	v_exp_f32_e32 v124, v124
	v_exp_f32_e32 v153, v153
	v_mul_f32_e32 v158, 0xbfb8aa3b, v123
	v_exp_f32_e32 v159, v158
	v_add_f32_e32 v125, 1.0, v125
	v_add_f32_e32 v124, 1.0, v124
	v_rcp_f32_e32 v158, v125
	v_add_f32_e32 v125, 1.0, v153
	v_rcp_f32_e32 v124, v124
	v_rcp_f32_e32 v125, v125
	v_add_f32_e32 v153, 1.0, v159
	v_rcp_f32_e32 v159, v153
	v_pk_mul_f32 v[120:121], v[120:121], v[160:161]
	v_lshl_or_b32 v154, s56, 7, v148
	v_pk_mul_f32 v[120:121], v[120:121], v[112:113]
	v_pk_mul_f32 v[112:113], v[126:127], v[124:125]
	v_lshl_add_u32 v152, s28, 8, v146
	v_ashrrev_i32_e32 v155, 31, v154
	v_mov_b64_e32 v[144:145], s[10:11]
	v_pk_mul_f32 v[118:119], v[112:113], v[118:119]
	v_pk_mul_f32 v[112:113], v[122:123], v[158:159]
	v_mad_i64_i32 v[156:157], s[30:31], v152, s55, v[144:145]
	v_pk_mul_f32 v[122:123], v[112:113], v[114:115]
	v_lshlrev_b64 v[112:113], 1, v[154:155]
	v_lshl_add_u64 v[124:125], v[156:157], 0, v[112:113]
	v_cvt_pk_bf16_f32 v114, v116, v117
	v_cvt_pk_bf16_f32 v115, v118, v119
	v_cvt_pk_bf16_f32 v116, v120, v121
	v_cvt_pk_bf16_f32 v117, v122, v123
	global_store_dwordx4 v[124:125], v[114:117], off
	v_mul_f32_e32 v118, 0xbfb8aa3b, v109
	v_exp_f32_e32 v118, v118
	v_mul_f32_e32 v116, 0xbfb8aa3b, v108
	v_mul_f32_e32 v117, 0xbfb8aa3b, v104
	v_exp_f32_e32 v116, v116
	v_exp_f32_e32 v117, v117
	v_or_b32_e32 v114, 16, v152
	v_mad_i64_i32 v[114:115], s[30:31], v114, s55, v[144:145]
	v_add_f32_e32 v116, 1.0, v116
	v_add_f32_e32 v119, 1.0, v117
	v_add_f32_e32 v117, 1.0, v118
	v_rcp_f32_e32 v116, v116
	v_rcp_f32_e32 v117, v117
	v_mul_f32_e32 v118, 0xbfb8aa3b, v105
	v_exp_f32_e32 v120, v118
	v_rcp_f32_e32 v118, v119
	v_pk_mul_f32 v[108:109], v[108:109], v[116:117]
	v_mul_f32_e32 v116, 0xbfb8aa3b, v111
	v_pk_mul_f32 v[100:101], v[108:109], v[100:101]
	v_add_f32_e32 v108, 1.0, v120
	v_rcp_f32_e32 v119, v108
	v_mul_f32_e32 v109, 0xbfb8aa3b, v106
	v_mul_f32_e32 v108, 0xbfb8aa3b, v110
	v_exp_f32_e32 v109, v109
	v_exp_f32_e32 v108, v108
	v_exp_f32_e32 v117, v116
	v_mul_f32_e32 v116, 0xbfb8aa3b, v107
	v_pk_mul_f32 v[104:105], v[104:105], v[118:119]
	v_exp_f32_e32 v118, v116
	v_add_f32_e32 v109, 1.0, v109
	v_add_f32_e32 v108, 1.0, v108
	v_rcp_f32_e32 v116, v109
	v_add_f32_e32 v109, 1.0, v117
	v_rcp_f32_e32 v108, v108
	v_rcp_f32_e32 v109, v109
	v_add_f32_e32 v117, 1.0, v118
	v_rcp_f32_e32 v117, v117
	v_pk_mul_f32 v[104:105], v[104:105], v[96:97]
	v_pk_mul_f32 v[96:97], v[110:111], v[108:109]
	v_lshl_add_u64 v[108:109], v[114:115], 0, v[112:113]
	v_pk_mul_f32 v[102:103], v[96:97], v[102:103]
	v_pk_mul_f32 v[96:97], v[106:107], v[116:117]
	s_and_b64 vcc, exec, s[8:9]
	v_pk_mul_f32 v[106:107], v[96:97], v[98:99]
	v_cvt_pk_bf16_f32 v96, v100, v101
	v_cvt_pk_bf16_f32 v97, v102, v103
	v_cvt_pk_bf16_f32 v98, v104, v105
	v_cvt_pk_bf16_f32 v99, v106, v107
	global_store_dwordx4 v[108:109], v[96:99], off
	v_mul_f32_e32 v100, 0xbfb8aa3b, v93
	v_exp_f32_e32 v100, v100
	v_mul_f32_e32 v98, 0xbfb8aa3b, v92
	v_mul_f32_e32 v99, 0xbfb8aa3b, v88
	v_exp_f32_e32 v98, v98
	v_exp_f32_e32 v99, v99
	v_or_b32_e32 v96, 32, v152
	v_mad_i64_i32 v[96:97], s[30:31], v96, s55, v[144:145]
	v_add_f32_e32 v98, 1.0, v98
	v_add_f32_e32 v101, 1.0, v99
	v_add_f32_e32 v99, 1.0, v100
	v_rcp_f32_e32 v98, v98
	v_rcp_f32_e32 v99, v99
	v_mul_f32_e32 v100, 0xbfb8aa3b, v89
	v_exp_f32_e32 v102, v100
	v_rcp_f32_e32 v100, v101
	v_pk_mul_f32 v[92:93], v[92:93], v[98:99]
	v_mul_f32_e32 v98, 0xbfb8aa3b, v95
	v_pk_mul_f32 v[84:85], v[92:93], v[84:85]
	v_add_f32_e32 v92, 1.0, v102
	v_rcp_f32_e32 v101, v92
	v_mul_f32_e32 v93, 0xbfb8aa3b, v90
	v_mul_f32_e32 v92, 0xbfb8aa3b, v94
	v_exp_f32_e32 v93, v93
	v_exp_f32_e32 v92, v92
	v_exp_f32_e32 v99, v98
	v_mul_f32_e32 v98, 0xbfb8aa3b, v91
	v_pk_mul_f32 v[88:89], v[88:89], v[100:101]
	v_exp_f32_e32 v100, v98
	v_add_f32_e32 v93, 1.0, v93
	v_add_f32_e32 v92, 1.0, v92
	v_rcp_f32_e32 v98, v93
	v_add_f32_e32 v93, 1.0, v99
	v_rcp_f32_e32 v92, v92
	v_rcp_f32_e32 v93, v93
	v_add_f32_e32 v99, 1.0, v100
	v_rcp_f32_e32 v99, v99
	v_pk_mul_f32 v[88:89], v[88:89], v[80:81]
	v_pk_mul_f32 v[80:81], v[94:95], v[92:93]
	v_lshl_add_u64 v[92:93], v[96:97], 0, v[112:113]
	v_pk_mul_f32 v[86:87], v[80:81], v[86:87]
	v_pk_mul_f32 v[80:81], v[90:91], v[98:99]
	s_mov_b32 s56, s14
	v_pk_mul_f32 v[90:91], v[80:81], v[82:83]
	v_cvt_pk_bf16_f32 v80, v84, v85
	v_cvt_pk_bf16_f32 v81, v86, v87
	v_cvt_pk_bf16_f32 v82, v88, v89
	v_cvt_pk_bf16_f32 v83, v90, v91
	global_store_dwordx4 v[92:93], v[80:83], off
	v_mul_f32_e32 v84, 0xbfb8aa3b, v77
	v_exp_f32_e32 v84, v84
	v_mul_f32_e32 v82, 0xbfb8aa3b, v76
	v_mul_f32_e32 v83, 0xbfb8aa3b, v72
	v_exp_f32_e32 v82, v82
	v_exp_f32_e32 v83, v83
	v_or_b32_e32 v80, 48, v152
	v_mad_i64_i32 v[80:81], s[30:31], v80, s55, v[144:145]
	v_add_f32_e32 v82, 1.0, v82
	v_add_f32_e32 v85, 1.0, v83
; __device__ __forceinline__ float fsilu(float v) { return v * fsigmoid(v); }
; __device__ __forceinline__ u32x4 pack8(const f32x4 a, const f32x4 b) { u32x4 w; w.x = cvt_pk_bf16(a[0], a[1]); w.y = cvt_pk_bf16(a[2], a[3]); w.z = cvt_pk_bf16(b[0], b[1]); w.w = cvt_pk_bf16(b[2], b[3]); return w; }
;     __device__ __forceinline__ void operator()(const f32x4 (&acc)[2][2][4][2], const Unit& u, int wr, int wc, int fr, int fq) const {
;         const int row0 = u.pm * BM + wr * 64 + fr, col0 = u.pn * 128 + wc * 32 + 8 * fq;
; #pragma unroll
;         for (int ai = 0; ai < 2; ++ai)
; #pragma unroll
;             for (int m = 0; m < 4; ++m) {
;                 bf16_t* rowp = O + (size_t)(row0 + ai * HALF + m * 16) * ldc + col0;
;                 f32x4 h0, h1;
; #pragma unroll
;                 for (int j = 0; j < 4; ++j) { h0[j] = fsilu(acc[ai][0][m][0][j]) * acc[ai][1][m][0][j]; h1[j] = fsilu(acc[ai][0][m][1][j]) * acc[ai][1][m][1][j]; }
;                 *(u32x4*)rowp = pack8(h0, h1);
	v_add_f32_e32 v83, 1.0, v84
	v_rcp_f32_e32 v82, v82
	v_rcp_f32_e32 v83, v83
	v_mul_f32_e32 v84, 0xbfb8aa3b, v73
	v_exp_f32_e32 v86, v84
	v_rcp_f32_e32 v84, v85
	v_pk_mul_f32 v[76:77], v[76:77], v[82:83]
	v_mul_f32_e32 v82, 0xbfb8aa3b, v79
	v_pk_mul_f32 v[68:69], v[76:77], v[68:69]
	v_add_f32_e32 v76, 1.0, v86
	v_rcp_f32_e32 v85, v76
	v_mul_f32_e32 v77, 0xbfb8aa3b, v74
	v_mul_f32_e32 v76, 0xbfb8aa3b, v78
	v_exp_f32_e32 v77, v77
	v_exp_f32_e32 v76, v76
	v_exp_f32_e32 v83, v82
	v_mul_f32_e32 v82, 0xbfb8aa3b, v75
	v_pk_mul_f32 v[72:73], v[72:73], v[84:85]
	v_exp_f32_e32 v84, v82
	v_add_f32_e32 v77, 1.0, v77
	v_add_f32_e32 v76, 1.0, v76
	v_rcp_f32_e32 v82, v77
	v_add_f32_e32 v77, 1.0, v83
	v_rcp_f32_e32 v76, v76
	v_rcp_f32_e32 v77, v77
	v_add_f32_e32 v83, 1.0, v84
	v_rcp_f32_e32 v83, v83
	v_pk_mul_f32 v[72:73], v[72:73], v[64:65]
	v_pk_mul_f32 v[64:65], v[78:79], v[76:77]
	v_lshl_add_u64 v[76:77], v[80:81], 0, v[112:113]
	v_pk_mul_f32 v[70:71], v[64:65], v[70:71]
	v_pk_mul_f32 v[64:65], v[74:75], v[82:83]
	s_mov_b32 s28, s22
	v_pk_mul_f32 v[74:75], v[64:65], v[66:67]
	v_cvt_pk_bf16_f32 v64, v68, v69
	v_cvt_pk_bf16_f32 v65, v70, v71
	v_cvt_pk_bf16_f32 v66, v72, v73
	v_cvt_pk_bf16_f32 v67, v74, v75
	global_store_dwordx4 v[76:77], v[64:67], off
	v_mul_f32_e32 v68, 0xbfb8aa3b, v61
	v_exp_f32_e32 v68, v68
	v_mul_f32_e32 v66, 0xbfb8aa3b, v60
	v_mul_f32_e32 v67, 0xbfb8aa3b, v56
	v_exp_f32_e32 v66, v66
	v_exp_f32_e32 v67, v67
	v_add_u32_e32 v64, 0x80, v152
	v_mad_i64_i32 v[64:65], s[30:31], v64, s55, v[144:145]
	v_add_f32_e32 v66, 1.0, v66
	v_add_f32_e32 v69, 1.0, v67
	v_add_f32_e32 v67, 1.0, v68
	v_rcp_f32_e32 v66, v66
	v_rcp_f32_e32 v67, v67
	v_mul_f32_e32 v68, 0xbfb8aa3b, v57
	v_exp_f32_e32 v70, v68
	v_rcp_f32_e32 v68, v69
	v_pk_mul_f32 v[60:61], v[60:61], v[66:67]
	v_mul_f32_e32 v66, 0xbfb8aa3b, v63
	v_pk_mul_f32 v[52:53], v[60:61], v[52:53]
	v_add_f32_e32 v60, 1.0, v70
	v_rcp_f32_e32 v69, v60
	v_mul_f32_e32 v61, 0xbfb8aa3b, v58
	v_mul_f32_e32 v60, 0xbfb8aa3b, v62
	v_exp_f32_e32 v61, v61
	v_exp_f32_e32 v60, v60
	v_exp_f32_e32 v67, v66
	v_mul_f32_e32 v66, 0xbfb8aa3b, v59
	v_pk_mul_f32 v[56:57], v[56:57], v[68:69]
	v_exp_f32_e32 v68, v66
	v_add_f32_e32 v61, 1.0, v61
	v_add_f32_e32 v60, 1.0, v60
	v_rcp_f32_e32 v66, v61
	v_add_f32_e32 v61, 1.0, v67
	v_rcp_f32_e32 v60, v60
	v_rcp_f32_e32 v61, v61
	v_add_f32_e32 v67, 1.0, v68
	v_rcp_f32_e32 v67, v67
	v_pk_mul_f32 v[56:57], v[56:57], v[48:49]
	v_pk_mul_f32 v[48:49], v[62:63], v[60:61]
	v_lshl_add_u64 v[60:61], v[64:65], 0, v[112:113]
	v_pk_mul_f32 v[54:55], v[48:49], v[54:55]
	v_pk_mul_f32 v[48:49], v[58:59], v[66:67]
	s_mov_b64 s[34:35], s[26:27]
	v_pk_mul_f32 v[58:59], v[48:49], v[50:51]
	v_cvt_pk_bf16_f32 v48, v52, v53
	v_cvt_pk_bf16_f32 v49, v54, v55
	v_cvt_pk_bf16_f32 v50, v56, v57
	v_cvt_pk_bf16_f32 v51, v58, v59
	global_store_dwordx4 v[60:61], v[48:51], off
	v_mul_f32_e32 v52, 0xbfb8aa3b, v45
	v_exp_f32_e32 v52, v52
	v_mul_f32_e32 v50, 0xbfb8aa3b, v44
	v_mul_f32_e32 v51, 0xbfb8aa3b, v40
	v_exp_f32_e32 v50, v50
	v_exp_f32_e32 v51, v51
	v_add_u32_e32 v48, 0x90, v152
	v_mad_i64_i32 v[48:49], s[30:31], v48, s55, v[144:145]
	v_add_f32_e32 v50, 1.0, v50
	v_add_f32_e32 v53, 1.0, v51
	v_add_f32_e32 v51, 1.0, v52
	v_rcp_f32_e32 v50, v50
	v_rcp_f32_e32 v51, v51
	v_mul_f32_e32 v52, 0xbfb8aa3b, v41
	v_exp_f32_e32 v54, v52
	v_rcp_f32_e32 v52, v53
	v_pk_mul_f32 v[44:45], v[44:45], v[50:51]
	v_mul_f32_e32 v50, 0xbfb8aa3b, v47
	v_pk_mul_f32 v[36:37], v[44:45], v[36:37]
	v_add_f32_e32 v44, 1.0, v54
	v_rcp_f32_e32 v53, v44
	v_mul_f32_e32 v45, 0xbfb8aa3b, v42
	v_mul_f32_e32 v44, 0xbfb8aa3b, v46
	v_exp_f32_e32 v45, v45
	v_exp_f32_e32 v44, v44
	v_exp_f32_e32 v51, v50
	v_mul_f32_e32 v50, 0xbfb8aa3b, v43
	v_pk_mul_f32 v[40:41], v[40:41], v[52:53]
	v_exp_f32_e32 v52, v50
	v_add_f32_e32 v45, 1.0, v45
	v_add_f32_e32 v44, 1.0, v44
; __device__ __forceinline__ float fsilu(float v) { return v * fsigmoid(v); }
; __device__ __forceinline__ u32x4 pack8(const f32x4 a, const f32x4 b) { u32x4 w; w.x = cvt_pk_bf16(a[0], a[1]); w.y = cvt_pk_bf16(a[2], a[3]); w.z = cvt_pk_bf16(b[0], b[1]); w.w = cvt_pk_bf16(b[2], b[3]); return w; }
; #define PG8_WAIT_V(n) asm volatile("s_waitcnt vmcnt(" #n ")" ::: "memory")
; #define PG8_BAR __builtin_amdgcn_s_barrier()
;     __device__ __forceinline__ void operator()(const f32x4 (&acc)[2][2][4][2], const Unit& u, int wr, int wc, int fr, int fq) const {
;         const int row0 = u.pm * BM + wr * 64 + fr, col0 = u.pn * 128 + wc * 32 + 8 * fq;
; #pragma unroll
;         for (int ai = 0; ai < 2; ++ai)
; #pragma unroll
;             for (int m = 0; m < 4; ++m) {
;                 bf16_t* rowp = O + (size_t)(row0 + ai * HALF + m * 16) * ldc + col0;
;                 f32x4 h0, h1;
; #pragma unroll
;                 for (int j = 0; j < 4; ++j) { h0[j] = fsilu(acc[ai][0][m][0][j]) * acc[ai][1][m][0][j]; h1[j] = fsilu(acc[ai][0][m][1][j]) * acc[ai][1][m][1][j]; }
;                 *(u32x4*)rowp = pack8(h0, h1);
; template <class Epi, class Sched, bool ALIGN_EPI = false, bool SP2 = false>
; __device__ __forceinline__ void gemm_phase(PG8_LAS unsigned char* lds, const Gemm g, const Sched& S, const Epi& E) {
;     ...
;         if (!has_next) break;
; #pragma unroll
;         for (int a = 0; a < 2; ++a)
; #pragma unroll
;             for (int b = 0; b < 2; ++b)
; #pragma unroll
;                 for (int m = 0; m < 4; ++m)
; #pragma unroll
;                     for (int n = 0; n < 2; ++n) acc[a][b][m][n] = (f32x4){0.f, 0.f, 0.f, 0.f};
;         cur = nxt; cA = nA; cB = nB; ++ui;
;         if constexpr (ALIGN_EPI) { if (wr == 1) PG8_BAR; }
;     }
;     PG8_WAIT_V(0);
;     if constexpr (!ALIGN_EPI) { if (wr == 0) PG8_BAR; }
;     PG8_BAR;
	v_rcp_f32_e32 v50, v45
	v_add_f32_e32 v45, 1.0, v51
	v_rcp_f32_e32 v44, v44
	v_rcp_f32_e32 v45, v45
	v_add_f32_e32 v51, 1.0, v52
	v_rcp_f32_e32 v51, v51
	v_pk_mul_f32 v[40:41], v[40:41], v[32:33]
	v_pk_mul_f32 v[32:33], v[46:47], v[44:45]
	v_lshl_add_u64 v[44:45], v[48:49], 0, v[112:113]
	v_pk_mul_f32 v[38:39], v[32:33], v[38:39]
	v_pk_mul_f32 v[32:33], v[42:43], v[50:51]
	s_nop 0
	v_pk_mul_f32 v[42:43], v[32:33], v[34:35]
	v_cvt_pk_bf16_f32 v32, v36, v37
	v_cvt_pk_bf16_f32 v33, v38, v39
	v_cvt_pk_bf16_f32 v34, v40, v41
	v_cvt_pk_bf16_f32 v35, v42, v43
	global_store_dwordx4 v[44:45], v[32:35], off
	v_mul_f32_e32 v36, 0xbfb8aa3b, v29
	v_exp_f32_e32 v36, v36
	v_mul_f32_e32 v34, 0xbfb8aa3b, v28
	v_mul_f32_e32 v35, 0xbfb8aa3b, v24
	v_exp_f32_e32 v34, v34
	v_exp_f32_e32 v35, v35
	v_add_u32_e32 v32, 0xa0, v152
	v_mad_i64_i32 v[32:33], s[30:31], v32, s55, v[144:145]
	v_add_f32_e32 v34, 1.0, v34
	v_add_f32_e32 v37, 1.0, v35
	v_add_f32_e32 v35, 1.0, v36
	v_rcp_f32_e32 v34, v34
	v_rcp_f32_e32 v35, v35
	v_mul_f32_e32 v36, 0xbfb8aa3b, v25
	v_exp_f32_e32 v38, v36
	v_rcp_f32_e32 v36, v37
	v_pk_mul_f32 v[28:29], v[28:29], v[34:35]
	v_mul_f32_e32 v34, 0xbfb8aa3b, v31
	v_pk_mul_f32 v[20:21], v[28:29], v[20:21]
	v_add_f32_e32 v28, 1.0, v38
	v_rcp_f32_e32 v37, v28
	v_mul_f32_e32 v29, 0xbfb8aa3b, v26
	v_mul_f32_e32 v28, 0xbfb8aa3b, v30
	v_exp_f32_e32 v29, v29
	v_exp_f32_e32 v28, v28
	v_exp_f32_e32 v35, v34
	v_mul_f32_e32 v34, 0xbfb8aa3b, v27
	v_pk_mul_f32 v[24:25], v[24:25], v[36:37]
	v_exp_f32_e32 v36, v34
	v_add_f32_e32 v29, 1.0, v29
	v_add_f32_e32 v28, 1.0, v28
	v_rcp_f32_e32 v34, v29
	v_add_f32_e32 v29, 1.0, v35
	v_rcp_f32_e32 v28, v28
	v_rcp_f32_e32 v29, v29
	v_add_f32_e32 v35, 1.0, v36
	v_rcp_f32_e32 v35, v35
	v_pk_mul_f32 v[24:25], v[24:25], v[16:17]
	v_pk_mul_f32 v[16:17], v[30:31], v[28:29]
	v_lshl_add_u64 v[28:29], v[32:33], 0, v[112:113]
	v_pk_mul_f32 v[22:23], v[16:17], v[22:23]
	v_pk_mul_f32 v[16:17], v[26:27], v[34:35]
	s_nop 0
	v_pk_mul_f32 v[26:27], v[16:17], v[18:19]
	v_cvt_pk_bf16_f32 v16, v20, v21
	v_cvt_pk_bf16_f32 v17, v22, v23
	v_cvt_pk_bf16_f32 v18, v24, v25
	v_cvt_pk_bf16_f32 v19, v26, v27
	global_store_dwordx4 v[28:29], v[16:19], off
	v_mul_f32_e32 v20, 0xbfb8aa3b, v13
	v_exp_f32_e32 v20, v20
	v_mul_f32_e32 v18, 0xbfb8aa3b, v12
	v_mul_f32_e32 v19, 0xbfb8aa3b, v8
	v_exp_f32_e32 v18, v18
	v_exp_f32_e32 v19, v19
	v_add_u32_e32 v16, 0xb0, v152
	v_mad_i64_i32 v[16:17], s[30:31], v16, s55, v[144:145]
	v_add_f32_e32 v18, 1.0, v18
	v_add_f32_e32 v21, 1.0, v19
	v_add_f32_e32 v19, 1.0, v20
	v_rcp_f32_e32 v18, v18
	v_rcp_f32_e32 v19, v19
	v_mul_f32_e32 v20, 0xbfb8aa3b, v9
	v_exp_f32_e32 v22, v20
	v_rcp_f32_e32 v20, v21
	v_pk_mul_f32 v[12:13], v[12:13], v[18:19]
	v_mul_f32_e32 v18, 0xbfb8aa3b, v15
	v_pk_mul_f32 v[4:5], v[12:13], v[4:5]
	v_add_f32_e32 v12, 1.0, v22
	v_rcp_f32_e32 v21, v12
	v_mul_f32_e32 v13, 0xbfb8aa3b, v10
	v_mul_f32_e32 v12, 0xbfb8aa3b, v14
	v_exp_f32_e32 v13, v13
	v_exp_f32_e32 v12, v12
	v_exp_f32_e32 v19, v18
	v_mul_f32_e32 v18, 0xbfb8aa3b, v11
	v_pk_mul_f32 v[8:9], v[8:9], v[20:21]
	v_exp_f32_e32 v20, v18
	v_add_f32_e32 v13, 1.0, v13
	v_add_f32_e32 v12, 1.0, v12
	v_rcp_f32_e32 v18, v13
	v_add_f32_e32 v13, 1.0, v19
	v_rcp_f32_e32 v12, v12
	v_rcp_f32_e32 v13, v13
	v_add_f32_e32 v19, 1.0, v20
	v_rcp_f32_e32 v19, v19
	v_pk_mul_f32 v[8:9], v[8:9], v[0:1]
	v_pk_mul_f32 v[0:1], v[14:15], v[12:13]
	v_lshl_add_u64 v[12:13], v[16:17], 0, v[112:113]
	v_pk_mul_f32 v[6:7], v[0:1], v[6:7]
	v_pk_mul_f32 v[0:1], v[10:11], v[18:19]
	s_mov_b64 s[30:31], s[24:25]
	v_pk_mul_f32 v[10:11], v[0:1], v[2:3]
	v_cvt_pk_bf16_f32 v0, v4, v5
	v_cvt_pk_bf16_f32 v1, v6, v7
	v_cvt_pk_bf16_f32 v2, v8, v9
	v_cvt_pk_bf16_f32 v3, v10, v11
	global_store_dwordx4 v[12:13], v[0:3], off
	s_cbranch_vccz .LBB0_942
	s_waitcnt vmcnt(0)
	s_cmpk_gt_u32 s3, 0xff
	s_cbranch_scc1 .LBB0_949
	s_barrier

; #define PG8_STAGE(bufoff, gbase, voff) do { _Pragma("unroll") for (int _i = 0; _i < 2; ++_i) \
;         __builtin_amdgcn_global_load_lds((const unsigned*)((const char*)(gbase) + (voff)[_i]), (PG8_LAS unsigned*)(lds + (bufoff) + ldsw + _i * 8192), 16, 0, 0); } while (0)
; #define PG8_LDA(dst, b, h) do { _Pragma("unroll") for (int m = 0; m < 4; ++m) _Pragma("unroll") for (int k = 0; k < 2; ++k) dst[m][k] = *(const PG8_LAS bf16x8*)(lds + PG8_SA(b, h) + aoff + m * 2048 + k * 1024); } while (0)
; #define PG8_LDB(dst, b, h) do { _Pragma("unroll") for (int n = 0; n < 2; ++n) _Pragma("unroll") for (int k = 0; k < 2; ++k) dst[n][k] = *(const PG8_LAS bf16x8*)(lds + PG8_SB(b, h) + boff + n * 2048 + k * 1024); } while (0)
; #define PG8_MMA(ai, bj, At, Bt) do { __builtin_amdgcn_s_setprio(1); _Pragma("unroll") for (int m = 0; m < 4; ++m) _Pragma("unroll") for (int n = 0; n < 2; ++n) _Pragma("unroll") for (int k = 0; k < 2; ++k) \
;         acc[ai][bj][m][n] = __builtin_amdgcn_mfma_f32_16x16x32_bf16(Bt[n][k], At[m][k], acc[ai][bj][m][n], 0, 0, 0); __builtin_amdgcn_s_setprio(0); } while (0)
; #define PG8_WAIT_V(n) asm volatile("s_waitcnt vmcnt(" #n ")" ::: "memory")
; #define PG8_WAIT_L(n) asm volatile("s_waitcnt lgkmcnt(" #n ")" ::: "memory")
; #define PG8_BAR __builtin_amdgcn_s_barrier()
; #define PG8_SCHED __builtin_amdgcn_sched_barrier(0)
; template <class Epi, class Sched, bool ALIGN_EPI = false, bool SP2 = false>
; __device__ __forceinline__ void gemm_phase(PG8_LAS unsigned char* lds, const Gemm g, const Sched& S, const Epi& E) {
;     ...
;             PG8_LDB(B0, 0, 0); PG8_LDB(B1, 0, 1); PG8_SCHED; PG8_LDA(At, 0, 0); PG8_STAGE(PG8_SA(1, 1), a1 + hstep, voffA);
;             PG8_WAIT_V(8); PG8_WAIT_L(0); PG8_BAR; PG8_MMA(0, 0, At, B0); PG8_MMA(0, 1, At, B1); PG8_BAR; PG8_SCHED;
;             PG8_LDA(At, 0, 1); PG8_STAGE(PG8_SB(0, 0), b2, voffB); PG8_STAGE(PG8_SB(0, 1), b2 + hstep, voffB); PG8_STAGE(PG8_SA(0, 0), a2, voffA);
;             PG8_WAIT_V(8); PG8_WAIT_L(0); PG8_BAR; PG8_MMA(1, 0, At, B0); PG8_MMA(1, 1, At, B1); PG8_BAR; PG8_SCHED;
.LBB0_1021:
	ds_read_b128 v[144:147], v169
	ds_read_b128 v[148:151], v169 offset:1024
	ds_read_b128 v[152:155], v169 offset:2048
	ds_read_b128 v[156:159], v169 offset:3072
	ds_read_b128 v[160:163], v170
	ds_read_b128 v[172:175], v170 offset:1024
	ds_read_b128 v[176:179], v170 offset:2048
	ds_read_b128 v[180:183], v170 offset:3072
	s_add_u32 s26, s24, 0x100
	s_addc_u32 s27, s25, 0
	s_cmpk_eq_i32 s56, 0x54
	s_cselect_b32 s31, s5, s27
	s_cselect_b32 s30, s4, s26
	s_cselect_b32 s29, s7, s55
	s_cselect_b32 s28, s6, s54
	s_add_i32 m0, s38, 0xc000
	ds_read_b128 v[184:187], v171
	ds_read_b128 v[188:191], v171 offset:1024
	ds_read_b128 v[192:195], v171 offset:2048
	ds_read_b128 v[196:199], v171 offset:3072
	ds_read_b128 v[200:203], v171 offset:4096
	ds_read_b128 v[204:207], v171 offset:5120
	ds_read_b128 v[208:211], v171 offset:6144
	ds_read_b128 v[212:215], v171 offset:7168
	global_load_lds_dwordx4 v136, s[24:25]
	s_add_i32 m0, s38, 0xe000
	s_nop 0
	global_load_lds_dwordx4 v138, s[24:25]
	s_waitcnt vmcnt(8)
	s_waitcnt lgkmcnt(0)
	s_barrier
	s_waitcnt lgkmcnt(0)
	v_mfma_f32_16x16x32_bf16 v[124:127], v[144:147], v[184:187], v[124:127]
	v_mfma_f32_16x16x32_bf16 v[120:123], v[152:155], v[184:187], v[120:123]
	v_mfma_f32_16x16x32_bf16 v[116:119], v[144:147], v[192:195], v[116:119]
	v_mfma_f32_16x16x32_bf16 v[112:115], v[152:155], v[192:195], v[112:115]
	v_mfma_f32_16x16x32_bf16 v[108:111], v[144:147], v[200:203], v[108:111]
	v_mfma_f32_16x16x32_bf16 v[96:99], v[152:155], v[200:203], v[96:99]
	v_mfma_f32_16x16x32_bf16 v[84:87], v[144:147], v[208:211], v[84:87]
	v_mfma_f32_16x16x32_bf16 v[76:79], v[152:155], v[208:211], v[76:79]
	v_mfma_f32_16x16x32_bf16 v[124:127], v[148:151], v[188:191], v[124:127]
	v_mfma_f32_16x16x32_bf16 v[120:123], v[156:159], v[188:191], v[120:123]
	v_mfma_f32_16x16x32_bf16 v[116:119], v[148:151], v[196:199], v[116:119]
	v_mfma_f32_16x16x32_bf16 v[112:115], v[156:159], v[196:199], v[112:115]
	v_mfma_f32_16x16x32_bf16 v[108:111], v[148:151], v[204:207], v[108:111]
	v_mfma_f32_16x16x32_bf16 v[96:99], v[156:159], v[204:207], v[96:99]
	v_mfma_f32_16x16x32_bf16 v[84:87], v[148:151], v[212:215], v[84:87]
	v_mfma_f32_16x16x32_bf16 v[76:79], v[156:159], v[212:215], v[76:79]
	v_mfma_f32_16x16x32_bf16 v[104:107], v[160:163], v[184:187], v[104:107]
	v_mfma_f32_16x16x32_bf16 v[100:103], v[176:179], v[184:187], v[100:103]
	v_mfma_f32_16x16x32_bf16 v[92:95], v[160:163], v[192:195], v[92:95]
	v_mfma_f32_16x16x32_bf16 v[88:91], v[176:179], v[192:195], v[88:91]
	v_mfma_f32_16x16x32_bf16 v[80:83], v[160:163], v[200:203], v[80:83]
	v_mfma_f32_16x16x32_bf16 v[72:75], v[176:179], v[200:203], v[72:75]
	v_mfma_f32_16x16x32_bf16 v[68:71], v[160:163], v[208:211], v[68:71]
	v_mfma_f32_16x16x32_bf16 v[64:67], v[176:179], v[208:211], v[64:67]
	v_mfma_f32_16x16x32_bf16 v[104:107], v[172:175], v[188:191], v[104:107]
	v_mfma_f32_16x16x32_bf16 v[100:103], v[180:183], v[188:191], v[100:103]
	v_mfma_f32_16x16x32_bf16 v[92:95], v[172:175], v[196:199], v[92:95]
	v_mfma_f32_16x16x32_bf16 v[88:91], v[180:183], v[196:199], v[88:91]
	v_mfma_f32_16x16x32_bf16 v[80:83], v[172:175], v[204:207], v[80:83]
	v_mfma_f32_16x16x32_bf16 v[72:75], v[180:183], v[204:207], v[72:75]
	v_mfma_f32_16x16x32_bf16 v[68:71], v[172:175], v[212:215], v[68:71]
	v_mfma_f32_16x16x32_bf16 v[64:67], v[180:183], v[212:215], v[64:67]
	s_barrier
	s_add_i32 s24, s48, s37
	s_mov_b32 m0, s24
	ds_read_b128 v[184:187], v171 offset:16384
	ds_read_b128 v[188:191], v171 offset:17408
	ds_read_b128 v[192:195], v171 offset:18432
	ds_read_b128 v[196:199], v171 offset:19456
	ds_read_b128 v[200:203], v171 offset:20480
	ds_read_b128 v[204:207], v171 offset:21504
	ds_read_b128 v[208:211], v171 offset:22528
	ds_read_b128 v[212:215], v171 offset:23552
	global_load_lds_dwordx4 v130, s[28:29]
	s_add_i32 m0, s24, 0x2000
	s_add_u32 s24, s28, 0x160000
	s_addc_u32 s25, s29, 0
	s_add_i32 s57, s49, s37
	global_load_lds_dwordx4 v134, s[28:29]
	s_mov_b32 m0, s57
	s_nop 0
	global_load_lds_dwordx4 v130, s[24:25]
	s_add_i32 m0, s57, 0x2000
	s_nop 0
	global_load_lds_dwordx4 v134, s[24:25]
	s_mov_b32 m0, s38
	s_nop 0
	global_load_lds_dwordx4 v128, s[30:31]
	s_mov_b32 m0, s39
	s_nop 0
	global_load_lds_dwordx4 v132, s[30:31]
	s_waitcnt vmcnt(8)
	s_waitcnt lgkmcnt(0)
	s_barrier
	s_waitcnt lgkmcnt(0)
	v_mfma_f32_16x16x32_bf16 v[60:63], v[144:147], v[184:187], v[60:63]
	v_mfma_f32_16x16x32_bf16 v[56:59], v[152:155], v[184:187], v[56:59]
	v_mfma_f32_16x16x32_bf16 v[52:55], v[144:147], v[192:195], v[52:55]
	v_mfma_f32_16x16x32_bf16 v[48:51], v[152:155], v[192:195], v[48:51]
	v_mfma_f32_16x16x32_bf16 v[44:47], v[144:147], v[200:203], v[44:47]
	v_mfma_f32_16x16x32_bf16 v[32:35], v[152:155], v[200:203], v[32:35]
	v_mfma_f32_16x16x32_bf16 v[20:23], v[144:147], v[208:211], v[20:23]
	v_mfma_f32_16x16x32_bf16 v[12:15], v[152:155], v[208:211], v[12:15]
	v_mfma_f32_16x16x32_bf16 v[60:63], v[148:151], v[188:191], v[60:63]
	v_mfma_f32_16x16x32_bf16 v[56:59], v[156:159], v[188:191], v[56:59]
	v_mfma_f32_16x16x32_bf16 v[52:55], v[148:151], v[196:199], v[52:55]
	v_mfma_f32_16x16x32_bf16 v[48:51], v[156:159], v[196:199], v[48:51]
	v_mfma_f32_16x16x32_bf16 v[44:47], v[148:151], v[204:207], v[44:47]
	v_mfma_f32_16x16x32_bf16 v[32:35], v[156:159], v[204:207], v[32:35]
	v_mfma_f32_16x16x32_bf16 v[20:23], v[148:151], v[212:215], v[20:23]
	v_mfma_f32_16x16x32_bf16 v[12:15], v[156:159], v[212:215], v[12:15]
	v_mfma_f32_16x16x32_bf16 v[40:43], v[160:163], v[184:187], v[40:43]
	v_mfma_f32_16x16x32_bf16 v[36:39], v[176:179], v[184:187], v[36:39]
	v_mfma_f32_16x16x32_bf16 v[28:31], v[160:163], v[192:195], v[28:31]
	v_mfma_f32_16x16x32_bf16 v[24:27], v[176:179], v[192:195], v[24:27]
	v_mfma_f32_16x16x32_bf16 v[16:19], v[160:163], v[200:203], v[16:19]
	v_mfma_f32_16x16x32_bf16 v[8:11], v[176:179], v[200:203], v[8:11]
	v_mfma_f32_16x16x32_bf16 v[4:7], v[160:163], v[208:211], v[4:7]
	v_mfma_f32_16x16x32_bf16 v[0:3], v[176:179], v[208:211], v[0:3]
	v_mfma_f32_16x16x32_bf16 v[40:43], v[172:175], v[188:191], v[40:43]
	v_mfma_f32_16x16x32_bf16 v[36:39], v[180:183], v[188:191], v[36:39]
	v_mfma_f32_16x16x32_bf16 v[28:31], v[172:175], v[196:199], v[28:31]
	v_mfma_f32_16x16x32_bf16 v[24:27], v[180:183], v[196:199], v[24:27]
	v_mfma_f32_16x16x32_bf16 v[16:19], v[172:175], v[204:207], v[16:19]
	v_mfma_f32_16x16x32_bf16 v[8:11], v[180:183], v[204:207], v[8:11]
	v_mfma_f32_16x16x32_bf16 v[4:7], v[172:175], v[212:215], v[4:7]
	v_mfma_f32_16x16x32_bf16 v[0:3], v[180:183], v[212:215], v[0:3]
	s_barrier
; #define PG8_STAGE(bufoff, gbase, voff) do { _Pragma("unroll") for (int _i = 0; _i < 2; ++_i) \
;         __builtin_amdgcn_global_load_lds((const unsigned*)((const char*)(gbase) + (voff)[_i]), (PG8_LAS unsigned*)(lds + (bufoff) + ldsw + _i * 8192), 16, 0, 0); } while (0)
; #define PG8_LDA(dst, b, h) do { _Pragma("unroll") for (int m = 0; m < 4; ++m) _Pragma("unroll") for (int k = 0; k < 2; ++k) dst[m][k] = *(const PG8_LAS bf16x8*)(lds + PG8_SA(b, h) + aoff + m * 2048 + k * 1024); } while (0)
; #define PG8_LDB(dst, b, h) do { _Pragma("unroll") for (int n = 0; n < 2; ++n) _Pragma("unroll") for (int k = 0; k < 2; ++k) dst[n][k] = *(const PG8_LAS bf16x8*)(lds + PG8_SB(b, h) + boff + n * 2048 + k * 1024); } while (0)
; #define PG8_MMA(ai, bj, At, Bt) do { __builtin_amdgcn_s_setprio(1); _Pragma("unroll") for (int m = 0; m < 4; ++m) _Pragma("unroll") for (int n = 0; n < 2; ++n) _Pragma("unroll") for (int k = 0; k < 2; ++k) \
;         acc[ai][bj][m][n] = __builtin_amdgcn_mfma_f32_16x16x32_bf16(Bt[n][k], At[m][k], acc[ai][bj][m][n], 0, 0, 0); __builtin_amdgcn_s_setprio(0); } while (0)
; #define PG8_WAIT_V(n) asm volatile("s_waitcnt vmcnt(" #n ")" ::: "memory")
; #define PG8_WAIT_L(n) asm volatile("s_waitcnt lgkmcnt(" #n ")" ::: "memory")
; #define PG8_BAR __builtin_amdgcn_s_barrier()
; #define PG8_SCHED __builtin_amdgcn_sched_barrier(0)
; template <class Epi, class Sched, bool ALIGN_EPI = false, bool SP2 = false>
; __device__ __forceinline__ void gemm_phase(PG8_LAS unsigned char* lds, const Gemm g, const Sched& S, const Epi& E) {
;     ...
;             PG8_LDB(B0, 1, 0); PG8_LDB(B1, 1, 1); PG8_SCHED; PG8_LDA(At, 1, 0); PG8_STAGE(PG8_SA(0, 1), a2 + hstep, voffA);
;             PG8_WAIT_V(8); PG8_WAIT_L(0); PG8_BAR; PG8_MMA(0, 0, At, B0); PG8_MMA(0, 1, At, B1); PG8_BAR; PG8_SCHED;
;             PG8_LDA(At, 1, 1); PG8_STAGE(PG8_SB(1, 0), b3, voffB); PG8_STAGE(PG8_SB(1, 1), b3 + hstep, voffB); PG8_STAGE(PG8_SA(1, 0), a3, voffA);
;             PG8_WAIT_V(8); PG8_WAIT_L(0); PG8_BAR; PG8_MMA(1, 0, At, B0); PG8_MMA(1, 1, At, B1); PG8_BAR; PG8_SCHED;
	s_add_i32 s57, 0, 0x18000
	s_add_i32 s58, 0, 0x1c000
	v_add_u32_e32 v156, s57, v167
	v_add_u32_e32 v180, s58, v167
	ds_read_b128 v[144:147], v156
	ds_read_b128 v[148:151], v156 offset:1024
	ds_read_b128 v[152:155], v156 offset:2048
	ds_read_b128 v[156:159], v156 offset:3072
	ds_read_b128 v[160:163], v180
	ds_read_b128 v[172:175], v180 offset:1024
	ds_read_b128 v[176:179], v180 offset:2048
	ds_read_b128 v[180:183], v180 offset:3072
	s_add_u32 s24, s30, 0x160000
	s_addc_u32 s25, s31, 0
	s_mov_b32 m0, s40
	ds_read_b128 v[184:187], v171 offset:32768
	ds_read_b128 v[188:191], v171 offset:33792
	ds_read_b128 v[192:195], v171 offset:34816
	ds_read_b128 v[196:199], v171 offset:35840
	ds_read_b128 v[200:203], v171 offset:36864
	ds_read_b128 v[204:207], v171 offset:37888
	ds_read_b128 v[208:211], v171 offset:38912
	ds_read_b128 v[212:215], v171 offset:39936
	global_load_lds_dwordx4 v128, s[24:25]
	s_mov_b32 m0, s41
	s_nop 0
	global_load_lds_dwordx4 v132, s[24:25]
	s_waitcnt vmcnt(8)
	s_waitcnt lgkmcnt(0)
	s_barrier
	s_waitcnt lgkmcnt(0)
	v_mfma_f32_16x16x32_bf16 v[124:127], v[144:147], v[184:187], v[124:127]
	v_mfma_f32_16x16x32_bf16 v[120:123], v[152:155], v[184:187], v[120:123]
	v_mfma_f32_16x16x32_bf16 v[116:119], v[144:147], v[192:195], v[116:119]
	v_mfma_f32_16x16x32_bf16 v[112:115], v[152:155], v[192:195], v[112:115]
	v_mfma_f32_16x16x32_bf16 v[108:111], v[144:147], v[200:203], v[108:111]
	v_mfma_f32_16x16x32_bf16 v[96:99], v[152:155], v[200:203], v[96:99]
	v_mfma_f32_16x16x32_bf16 v[84:87], v[144:147], v[208:211], v[84:87]
	v_mfma_f32_16x16x32_bf16 v[76:79], v[152:155], v[208:211], v[76:79]
	v_mfma_f32_16x16x32_bf16 v[124:127], v[148:151], v[188:191], v[124:127]
	v_mfma_f32_16x16x32_bf16 v[120:123], v[156:159], v[188:191], v[120:123]
	v_mfma_f32_16x16x32_bf16 v[116:119], v[148:151], v[196:199], v[116:119]
	v_mfma_f32_16x16x32_bf16 v[112:115], v[156:159], v[196:199], v[112:115]
	v_mfma_f32_16x16x32_bf16 v[108:111], v[148:151], v[204:207], v[108:111]
	v_mfma_f32_16x16x32_bf16 v[96:99], v[156:159], v[204:207], v[96:99]
	v_mfma_f32_16x16x32_bf16 v[84:87], v[148:151], v[212:215], v[84:87]
	v_mfma_f32_16x16x32_bf16 v[76:79], v[156:159], v[212:215], v[76:79]
	v_mfma_f32_16x16x32_bf16 v[104:107], v[160:163], v[184:187], v[104:107]
	v_mfma_f32_16x16x32_bf16 v[100:103], v[176:179], v[184:187], v[100:103]
	v_mfma_f32_16x16x32_bf16 v[92:95], v[160:163], v[192:195], v[92:95]
	v_mfma_f32_16x16x32_bf16 v[88:91], v[176:179], v[192:195], v[88:91]
	v_mfma_f32_16x16x32_bf16 v[80:83], v[160:163], v[200:203], v[80:83]
	v_mfma_f32_16x16x32_bf16 v[72:75], v[176:179], v[200:203], v[72:75]
	v_mfma_f32_16x16x32_bf16 v[68:71], v[160:163], v[208:211], v[68:71]
	v_mfma_f32_16x16x32_bf16 v[64:67], v[176:179], v[208:211], v[64:67]
	v_mfma_f32_16x16x32_bf16 v[104:107], v[172:175], v[188:191], v[104:107]
	v_mfma_f32_16x16x32_bf16 v[100:103], v[180:183], v[188:191], v[100:103]
	v_mfma_f32_16x16x32_bf16 v[92:95], v[172:175], v[196:199], v[92:95]
	v_mfma_f32_16x16x32_bf16 v[88:91], v[180:183], v[196:199], v[88:91]
	v_mfma_f32_16x16x32_bf16 v[80:83], v[172:175], v[204:207], v[80:83]
	v_mfma_f32_16x16x32_bf16 v[72:75], v[180:183], v[204:207], v[72:75]
	v_mfma_f32_16x16x32_bf16 v[68:71], v[172:175], v[212:215], v[68:71]
	v_mfma_f32_16x16x32_bf16 v[64:67], v[180:183], v[212:215], v[64:67]
	s_barrier
	s_add_i32 s24, s57, s37
	s_add_u32 s86, s28, 0x80
	s_addc_u32 s87, s29, 0
	s_mov_b32 m0, s24
	ds_read_b128 v[184:187], v171 offset:49152
	ds_read_b128 v[188:191], v171 offset:50176
	ds_read_b128 v[192:195], v171 offset:51200
	ds_read_b128 v[196:199], v171 offset:52224
	ds_read_b128 v[200:203], v171 offset:53248
	ds_read_b128 v[204:207], v171 offset:54272
	ds_read_b128 v[208:211], v171 offset:55296
	ds_read_b128 v[212:215], v171 offset:56320
	global_load_lds_dwordx4 v130, s[86:87]
	s_add_i32 m0, s24, 0x2000
	s_add_u32 s24, s28, 0x160080
	s_addc_u32 s25, s29, 0
	s_add_i32 s28, s58, s37
	global_load_lds_dwordx4 v134, s[86:87]
	s_mov_b32 m0, s28
	s_nop 0
	global_load_lds_dwordx4 v130, s[24:25]
	s_add_i32 m0, s28, 0x2000
	s_nop 0
	global_load_lds_dwordx4 v134, s[24:25]
	s_add_u32 s84, s30, 0x80
	s_addc_u32 s85, s31, 0
	s_mov_b32 m0, s45
	s_nop 0
	global_load_lds_dwordx4 v128, s[84:85]
	s_mov_b32 m0, s46
	s_nop 0
	global_load_lds_dwordx4 v132, s[84:85]
	s_waitcnt vmcnt(8)
	s_waitcnt lgkmcnt(0)
	s_barrier
	s_waitcnt lgkmcnt(0)
	v_mfma_f32_16x16x32_bf16 v[60:63], v[144:147], v[184:187], v[60:63]
	v_mfma_f32_16x16x32_bf16 v[56:59], v[152:155], v[184:187], v[56:59]
	v_mfma_f32_16x16x32_bf16 v[52:55], v[144:147], v[192:195], v[52:55]
	v_mfma_f32_16x16x32_bf16 v[48:51], v[152:155], v[192:195], v[48:51]
	v_mfma_f32_16x16x32_bf16 v[44:47], v[144:147], v[200:203], v[44:47]
	v_mfma_f32_16x16x32_bf16 v[32:35], v[152:155], v[200:203], v[32:35]
	v_mfma_f32_16x16x32_bf16 v[20:23], v[144:147], v[208:211], v[20:23]
	v_mfma_f32_16x16x32_bf16 v[12:15], v[152:155], v[208:211], v[12:15]
	v_mfma_f32_16x16x32_bf16 v[60:63], v[148:151], v[188:191], v[60:63]
	v_mfma_f32_16x16x32_bf16 v[56:59], v[156:159], v[188:191], v[56:59]
	v_mfma_f32_16x16x32_bf16 v[52:55], v[148:151], v[196:199], v[52:55]
	v_mfma_f32_16x16x32_bf16 v[48:51], v[156:159], v[196:199], v[48:51]
	v_mfma_f32_16x16x32_bf16 v[44:47], v[148:151], v[204:207], v[44:47]
	v_mfma_f32_16x16x32_bf16 v[32:35], v[156:159], v[204:207], v[32:35]
	v_mfma_f32_16x16x32_bf16 v[20:23], v[148:151], v[212:215], v[20:23]
	v_mfma_f32_16x16x32_bf16 v[12:15], v[156:159], v[212:215], v[12:15]
	v_mfma_f32_16x16x32_bf16 v[40:43], v[160:163], v[184:187], v[40:43]
	v_mfma_f32_16x16x32_bf16 v[36:39], v[176:179], v[184:187], v[36:39]
	v_mfma_f32_16x16x32_bf16 v[28:31], v[160:163], v[192:195], v[28:31]
	v_mfma_f32_16x16x32_bf16 v[24:27], v[176:179], v[192:195], v[24:27]
	v_mfma_f32_16x16x32_bf16 v[16:19], v[160:163], v[200:203], v[16:19]
	v_mfma_f32_16x16x32_bf16 v[8:11], v[176:179], v[200:203], v[8:11]
	v_mfma_f32_16x16x32_bf16 v[4:7], v[160:163], v[208:211], v[4:7]
	v_mfma_f32_16x16x32_bf16 v[0:3], v[176:179], v[208:211], v[0:3]
	v_mfma_f32_16x16x32_bf16 v[40:43], v[172:175], v[188:191], v[40:43]
	v_mfma_f32_16x16x32_bf16 v[36:39], v[180:183], v[188:191], v[36:39]
	v_mfma_f32_16x16x32_bf16 v[28:31], v[172:175], v[196:199], v[28:31]
	v_mfma_f32_16x16x32_bf16 v[24:27], v[180:183], v[196:199], v[24:27]
	v_mfma_f32_16x16x32_bf16 v[16:19], v[172:175], v[204:207], v[16:19]
	v_mfma_f32_16x16x32_bf16 v[8:11], v[180:183], v[204:207], v[8:11]
	v_mfma_f32_16x16x32_bf16 v[4:7], v[172:175], v[212:215], v[4:7]
	v_mfma_f32_16x16x32_bf16 v[0:3], v[180:183], v[212:215], v[0:3]
	s_barrier
;     __device__ __forceinline__ void operator()(const f32x4 (&acc)[2][2][4][2], const Unit& u, int wr, int wc, int fr, int fq) const {
;         const int row0 = u.pm * BM + wr * 64 + fr, col0 = u.pn * BM + wc * 32 + 8 * fq;
;         const float* gp = gate + (u.pm >> 5) * 18432 + col0;
;         f32x4 gv[2][2];
; #pragma unroll
;         for (int bj = 0; bj < 2; ++bj)
; #pragma unroll
;             for (int n = 0; n < 2; ++n) gv[bj][n] = *(const f32x4*)(gp + bj * HALF + 4 * n) * scale;
; #pragma unroll
;         for (int ai = 0; ai < 2; ++ai) { f32x4 r[4][2][2];
; #pragma unroll
;             for (int m = 0; m < 4; ++m) { const size_t off = (size_t)(row0 + ai * HALF + m * 16) * 2048 + col0;
; #pragma unroll
;                 for (int bj = 0; bj < 2; ++bj)
; #pragma unroll
;                     for (int n = 0; n < 2; ++n) r[m][bj][n] = *(const f32x4*)(res + off + bj * HALF + 4 * n); }
; #pragma unroll
;             for (int m = 0; m < 4; ++m) { const size_t off = (size_t)(row0 + ai * HALF + m * 16) * 2048 + col0;
; #pragma unroll
;                 for (int bj = 0; bj < 2; ++bj)
; #pragma unroll
;                     for (int n = 0; n < 2; ++n) *(f32x4*)(out + off + bj * HALF + 4 * n) = r[m][bj][n] + gv[bj][n] * acc[ai][bj][m][n]; } }
	s_add_i32 s56, s56, 2
	s_add_u32 s54, s54, 0x100
	s_addc_u32 s55, s55, 0
	s_cmpk_gt_u32 s56, 0x55
	s_mov_b64 s[24:25], s[26:27]
	s_cbranch_scc0 .LBB0_1021
	s_lshr_b32 s24, s52, 5
	s_mulk_i32 s24, 0x4800
	s_ashr_i32 s25, s24, 31
	v_lshl_or_b32 v144, s53, 8, v168
	s_lshl_b64 s[24:25], s[24:25], 2
	s_add_u32 s24, s43, s24
	v_ashrrev_i32_e32 v145, 31, v144
	s_addc_u32 s25, s44, s25
	v_lshlrev_b64 v[144:145], 2, v[144:145]
	v_lshl_add_u64 v[154:155], s[24:25], 0, v[144:145]
	global_load_dwordx4 v[146:149], v[154:155], off offset:16
	global_load_dwordx4 v[150:153], v[154:155], off
	global_load_dwordx4 v[172:175], v[154:155], off offset:528
	global_load_dwordx4 v[176:179], v[154:155], off offset:512
	v_lshl_add_u32 v154, s52, 8, v166
	v_ashrrev_i32_e32 v155, 31, v154
	v_lshl_add_u64 v[162:163], s[8:9], 0, v[144:145]
	v_lshlrev_b64 v[164:165], 13, v[154:155]
	v_lshl_add_u64 v[156:157], v[162:163], 0, v[164:165]
	global_load_dwordx4 v[180:183], v[156:157], off
	global_load_dwordx4 v[184:187], v[156:157], off offset:16
	global_load_dwordx4 v[188:191], v[156:157], off offset:528
	global_load_dwordx4 v[192:195], v[156:157], off offset:512
	v_or_b32_e32 v156, 16, v154
	v_ashrrev_i32_e32 v157, 31, v156
	v_lshlrev_b64 v[156:157], 13, v[156:157]
	v_lshl_add_u64 v[158:159], v[162:163], 0, v[156:157]
	global_load_dwordx4 v[196:199], v[158:159], off
	global_load_dwordx4 v[200:203], v[158:159], off offset:16
	global_load_dwordx4 v[204:207], v[158:159], off offset:528
	global_load_dwordx4 v[208:211], v[158:159], off offset:512
	v_or_b32_e32 v158, 32, v154
	v_ashrrev_i32_e32 v159, 31, v158
	v_lshlrev_b64 v[158:159], 13, v[158:159]
	v_or_b32_e32 v154, 48, v154
	v_lshl_add_u64 v[160:161], v[162:163], 0, v[158:159]
	v_ashrrev_i32_e32 v155, 31, v154
	global_load_dwordx4 v[212:215], v[160:161], off
	global_load_dwordx4 v[216:219], v[160:161], off offset:16
	global_load_dwordx4 v[220:223], v[160:161], off offset:512
	global_load_dwordx4 v[224:227], v[160:161], off offset:528
	v_lshlrev_b64 v[244:245], 13, v[154:155]
	v_lshl_add_u64 v[154:155], v[162:163], 0, v[244:245]
	global_load_dwordx4 v[228:231], v[154:155], off
	global_load_dwordx4 v[232:235], v[154:155], off offset:16
	global_load_dwordx4 v[236:239], v[154:155], off offset:512
	global_load_dwordx4 v[240:243], v[154:155], off offset:528
	v_lshl_add_u64 v[154:155], s[10:11], 0, v[164:165]
	v_lshl_add_u64 v[246:247], v[154:155], 0, v[144:145]
	v_lshl_add_u64 v[154:155], s[10:11], 0, v[156:157]
	v_lshl_add_u64 v[156:157], s[10:11], 0, v[158:159]
	v_lshl_add_u64 v[248:249], v[154:155], 0, v[144:145]
	v_lshl_add_u64 v[250:251], v[156:157], 0, v[144:145]
	s_and_b64 vcc, exec, s[0:1]
	s_mov_b32 s53, s50
	s_mov_b32 s52, s51
	s_mov_b64 s[26:27], s[6:7]
	s_mov_b64 s[24:25], s[4:5]
	s_waitcnt vmcnt(0)
	v_pk_mul_f32 v[154:155], v[148:149], 0.5 op_sel_hi:[1,0]
	v_pk_mul_f32 v[158:159], v[152:153], 0.5 op_sel_hi:[1,0]
	v_pk_mul_f32 v[160:161], v[150:151], 0.5 op_sel_hi:[1,0]
	v_pk_mul_f32 v[150:151], v[178:179], 0.5 op_sel_hi:[1,0]
	v_pk_mul_f32 v[152:153], v[176:177], 0.5 op_sel_hi:[1,0]
	v_pk_mul_f32 v[156:157], v[146:147], 0.5 op_sel_hi:[1,0]
	v_pk_mul_f32 v[146:147], v[174:175], 0.5 op_sel_hi:[1,0]
	v_pk_mul_f32 v[148:149], v[172:173], 0.5 op_sel_hi:[1,0]
	v_pk_fma_f32 v[126:127], v[126:127], v[158:159], v[182:183]
	v_pk_fma_f32 v[124:125], v[124:125], v[160:161], v[180:181]
	v_pk_fma_f32 v[122:123], v[122:123], v[154:155], v[186:187]
	v_pk_fma_f32 v[120:121], v[120:121], v[156:157], v[184:185]
	v_pk_fma_f32 v[106:107], v[106:107], v[150:151], v[194:195]
	v_pk_fma_f32 v[104:105], v[104:105], v[152:153], v[192:193]
	v_pk_fma_f32 v[102:103], v[102:103], v[146:147], v[190:191]
	v_pk_fma_f32 v[100:101], v[100:101], v[148:149], v[188:189]
	v_pk_fma_f32 v[118:119], v[118:119], v[158:159], v[198:199]
	v_pk_fma_f32 v[116:117], v[116:117], v[160:161], v[196:197]
	v_pk_fma_f32 v[114:115], v[114:115], v[154:155], v[202:203]
	v_pk_fma_f32 v[112:113], v[112:113], v[156:157], v[200:201]
	v_pk_fma_f32 v[82:83], v[82:83], v[150:151], v[222:223]
	v_pk_fma_f32 v[80:81], v[80:81], v[152:153], v[220:221]
	v_pk_fma_f32 v[94:95], v[94:95], v[150:151], v[210:211]
	v_pk_fma_f32 v[92:93], v[92:93], v[152:153], v[208:209]
	v_pk_fma_f32 v[90:91], v[90:91], v[146:147], v[206:207]
	v_pk_fma_f32 v[88:89], v[88:89], v[148:149], v[204:205]
	v_pk_fma_f32 v[110:111], v[110:111], v[158:159], v[214:215]
	v_pk_fma_f32 v[108:109], v[108:109], v[160:161], v[212:213]
	v_pk_fma_f32 v[98:99], v[98:99], v[154:155], v[218:219]
	v_pk_fma_f32 v[96:97], v[96:97], v[156:157], v[216:217]
	global_store_dwordx4 v[246:247], v[124:127], off
	global_store_dwordx4 v[246:247], v[120:123], off offset:16
	global_store_dwordx4 v[246:247], v[104:107], off offset:512
	global_store_dwordx4 v[246:247], v[100:103], off offset:528
	global_store_dwordx4 v[248:249], v[116:119], off
	global_store_dwordx4 v[248:249], v[112:115], off offset:16
	global_store_dwordx4 v[248:249], v[92:95], off offset:512
	global_store_dwordx4 v[248:249], v[88:91], off offset:528
	global_store_dwordx4 v[250:251], v[108:111], off
	global_store_dwordx4 v[250:251], v[96:99], off offset:16
	global_store_dwordx4 v[250:251], v[80:83], off offset:512
	v_pk_fma_f32 v[74:75], v[74:75], v[146:147], v[226:227]
	v_pk_fma_f32 v[72:73], v[72:73], v[148:149], v[224:225]
	v_lshl_add_u64 v[80:81], s[10:11], 0, v[244:245]
	global_store_dwordx4 v[250:251], v[72:75], off offset:528
; #define PG8_WAIT_V(n) asm volatile("s_waitcnt vmcnt(" #n ")" ::: "memory")
; #define PG8_BAR __builtin_amdgcn_s_barrier()
;     __device__ __forceinline__ void operator()(const f32x4 (&acc)[2][2][4][2], const Unit& u, int wr, int wc, int fr, int fq) const {
;     ...
;         for (int ai = 0; ai < 2; ++ai) { f32x4 r[4][2][2];
; #pragma unroll
;             for (int m = 0; m < 4; ++m) { const size_t off = (size_t)(row0 + ai * HALF + m * 16) * 2048 + col0;
; #pragma unroll
;                 for (int bj = 0; bj < 2; ++bj)
; #pragma unroll
;                     for (int n = 0; n < 2; ++n) r[m][bj][n] = *(const f32x4*)(res + off + bj * HALF + 4 * n); }
; #pragma unroll
;             for (int m = 0; m < 4; ++m) { const size_t off = (size_t)(row0 + ai * HALF + m * 16) * 2048 + col0;
; #pragma unroll
;                 for (int bj = 0; bj < 2; ++bj)
; #pragma unroll
;                     for (int n = 0; n < 2; ++n) *(f32x4*)(out + off + bj * HALF + 4 * n) = r[m][bj][n] + gv[bj][n] * acc[ai][bj][m][n]; } }
; template <class Epi, class Sched, bool ALIGN_EPI = false, bool SP2 = false>
; __device__ __forceinline__ void gemm_phase(PG8_LAS unsigned char* lds, const Gemm g, const Sched& S, const Epi& E) {
;     ...
;         if (!has_next) break;
; #pragma unroll
;         for (int a = 0; a < 2; ++a)
; #pragma unroll
;             for (int b = 0; b < 2; ++b)
; #pragma unroll
;                 for (int m = 0; m < 4; ++m)
; #pragma unroll
;                     for (int n = 0; n < 2; ++n) acc[a][b][m][n] = (f32x4){0.f, 0.f, 0.f, 0.f};
;         cur = nxt; cA = nA; cB = nB; ++ui;
;         if constexpr (ALIGN_EPI) { if (wr == 1) PG8_BAR; }
;     }
;     PG8_WAIT_V(0);
;     if constexpr (!ALIGN_EPI) { if (wr == 0) PG8_BAR; }
;     PG8_BAR;
	v_lshl_add_u64 v[80:81], v[80:81], 0, v[144:145]
	v_pk_fma_f32 v[70:71], v[70:71], v[150:151], v[238:239]
	v_pk_fma_f32 v[74:75], v[86:87], v[158:159], v[230:231]
	v_pk_fma_f32 v[72:73], v[84:85], v[160:161], v[228:229]
	global_store_dwordx4 v[80:81], v[72:75], off
	v_pk_fma_f32 v[68:69], v[68:69], v[152:153], v[236:237]
	v_pk_fma_f32 v[66:67], v[66:67], v[146:147], v[242:243]
	v_pk_fma_f32 v[74:75], v[78:79], v[154:155], v[234:235]
	v_pk_fma_f32 v[72:73], v[76:77], v[156:157], v[232:233]
	v_pk_fma_f32 v[64:65], v[64:65], v[148:149], v[240:241]
	v_lshl_add_u64 v[172:173], v[164:165], 0, s[18:19]
	v_lshl_add_u64 v[174:175], v[164:165], 0, s[20:21]
	v_lshl_add_u64 v[176:177], v[164:165], 0, s[22:23]
	global_store_dwordx4 v[80:81], v[72:75], off offset:16
	global_store_dwordx4 v[80:81], v[68:71], off offset:512
	global_store_dwordx4 v[80:81], v[64:67], off offset:528
	v_lshl_add_u64 v[80:81], v[162:163], 0, v[172:173]
	v_lshl_add_u64 v[92:93], v[162:163], 0, v[174:175]
	v_lshl_add_u64 v[108:109], v[162:163], 0, v[176:177]
	global_load_dwordx4 v[64:67], v[80:81], off
	global_load_dwordx4 v[68:71], v[80:81], off offset:16
	global_load_dwordx4 v[72:75], v[80:81], off offset:512
	global_load_dwordx4 v[76:79], v[80:81], off offset:528
	s_nop 0
	global_load_dwordx4 v[80:83], v[92:93], off
	global_load_dwordx4 v[84:87], v[92:93], off offset:16
	global_load_dwordx4 v[88:91], v[92:93], off offset:512
	s_nop 0
	global_load_dwordx4 v[92:95], v[92:93], off offset:528
	s_nop 0
	global_load_dwordx4 v[96:99], v[108:109], off
	global_load_dwordx4 v[100:103], v[108:109], off offset:16
	global_load_dwordx4 v[104:107], v[108:109], off offset:512
	s_nop 0
	global_load_dwordx4 v[108:111], v[108:109], off offset:528
	v_lshl_add_u64 v[164:165], v[164:165], 0, s[12:13]
	v_lshl_add_u64 v[124:125], v[162:163], 0, v[164:165]
	global_load_dwordx4 v[112:115], v[124:125], off
	global_load_dwordx4 v[116:119], v[124:125], off offset:16
	global_load_dwordx4 v[120:123], v[124:125], off offset:512
	s_nop 0
	global_load_dwordx4 v[124:127], v[124:125], off offset:528
	v_lshl_add_u64 v[162:163], s[10:11], 0, v[172:173]
	v_lshl_add_u64 v[172:173], s[10:11], 0, v[174:175]
	v_lshl_add_u64 v[174:175], s[10:11], 0, v[176:177]
	v_lshl_add_u64 v[162:163], v[162:163], 0, v[144:145]
	v_lshl_add_u64 v[174:175], v[174:175], 0, v[144:145]
	v_lshl_add_u64 v[172:173], v[172:173], 0, v[144:145]
	s_waitcnt vmcnt(15)
	v_pk_fma_f32 v[62:63], v[62:63], v[158:159], v[66:67]
	v_pk_fma_f32 v[60:61], v[60:61], v[160:161], v[64:65]
	s_waitcnt vmcnt(14)
	v_pk_fma_f32 v[58:59], v[58:59], v[154:155], v[70:71]
	v_pk_fma_f32 v[56:57], v[56:57], v[156:157], v[68:69]
	s_waitcnt vmcnt(5)
	v_pk_fma_f32 v[18:19], v[18:19], v[150:151], v[106:107]
	v_pk_fma_f32 v[16:17], v[16:17], v[152:153], v[104:105]
	v_pk_fma_f32 v[42:43], v[42:43], v[150:151], v[74:75]
	v_pk_fma_f32 v[40:41], v[40:41], v[152:153], v[72:73]
	v_pk_fma_f32 v[38:39], v[38:39], v[146:147], v[78:79]
	v_pk_fma_f32 v[36:37], v[36:37], v[148:149], v[76:77]
	v_pk_fma_f32 v[54:55], v[54:55], v[158:159], v[82:83]
	v_pk_fma_f32 v[52:53], v[52:53], v[160:161], v[80:81]
	v_pk_fma_f32 v[50:51], v[50:51], v[154:155], v[86:87]
	v_pk_fma_f32 v[48:49], v[48:49], v[156:157], v[84:85]
	v_pk_fma_f32 v[30:31], v[30:31], v[150:151], v[90:91]
	v_pk_fma_f32 v[28:29], v[28:29], v[152:153], v[88:89]
	v_pk_fma_f32 v[26:27], v[26:27], v[146:147], v[94:95]
	v_pk_fma_f32 v[24:25], v[24:25], v[148:149], v[92:93]
	v_pk_fma_f32 v[46:47], v[46:47], v[158:159], v[98:99]
	v_pk_fma_f32 v[44:45], v[44:45], v[160:161], v[96:97]
	v_pk_fma_f32 v[34:35], v[34:35], v[154:155], v[102:103]
	v_pk_fma_f32 v[32:33], v[32:33], v[156:157], v[100:101]
	global_store_dwordx4 v[162:163], v[60:63], off
	global_store_dwordx4 v[162:163], v[56:59], off offset:16
	global_store_dwordx4 v[162:163], v[40:43], off offset:512
	global_store_dwordx4 v[162:163], v[36:39], off offset:528
	global_store_dwordx4 v[172:173], v[52:55], off
	global_store_dwordx4 v[172:173], v[48:51], off offset:16
	global_store_dwordx4 v[172:173], v[28:31], off offset:512
	global_store_dwordx4 v[172:173], v[24:27], off offset:528
	global_store_dwordx4 v[174:175], v[44:47], off
	global_store_dwordx4 v[174:175], v[32:35], off offset:16
	global_store_dwordx4 v[174:175], v[16:19], off offset:512
	s_waitcnt vmcnt(15)
	v_pk_fma_f32 v[10:11], v[10:11], v[146:147], v[110:111]
	v_pk_fma_f32 v[8:9], v[8:9], v[148:149], v[108:109]
	v_lshl_add_u64 v[16:17], s[10:11], 0, v[164:165]
	global_store_dwordx4 v[174:175], v[8:11], off offset:528
	v_lshl_add_u64 v[16:17], v[16:17], 0, v[144:145]
	s_waitcnt vmcnt(13)
	v_pk_fma_f32 v[6:7], v[6:7], v[150:151], v[122:123]
	v_pk_fma_f32 v[10:11], v[22:23], v[158:159], v[114:115]
	v_pk_fma_f32 v[8:9], v[20:21], v[160:161], v[112:113]
	global_store_dwordx4 v[16:17], v[8:11], off
	v_pk_fma_f32 v[4:5], v[4:5], v[152:153], v[120:121]
	s_waitcnt vmcnt(13)
	v_pk_fma_f32 v[2:3], v[2:3], v[146:147], v[126:127]
	v_pk_fma_f32 v[10:11], v[14:15], v[154:155], v[118:119]
	v_pk_fma_f32 v[8:9], v[12:13], v[156:157], v[116:117]
	v_pk_fma_f32 v[0:1], v[0:1], v[148:149], v[124:125]
	global_store_dwordx4 v[16:17], v[8:11], off offset:16
	global_store_dwordx4 v[16:17], v[4:7], off offset:512
	global_store_dwordx4 v[16:17], v[0:3], off offset:528
	s_cbranch_vccz .LBB0_1010
	s_waitcnt vmcnt(0)
	s_cmpk_gt_u32 s3, 0xff
	s_cbranch_scc1 .LBB0_1025
	s_barrier
